# norm fix + GEMM: closing barrier of each MFMA block moved 4 MFMAs earlier (rendezvous overlaps block tail)
# baseline (speedup 1.0000x reference)
; template <class Epi, class Sched, bool ALIGN_EPI = true, bool SP2 = true, bool FULLLINE = false, bool NOSTAGE = false, bool FP8 = false>
; __device__ __forceinline__ void gemm_phase(PG8_LAS unsigned char* lds, const Gemm g, const Sched& S, const Epi& E) {
;     ...
;         const bool has_next = S.next(ui + 1, nxt);
;         const char* nA = has_next ? PG8_ABASE(nxt) : cA; const char* nB = has_next ? PG8_BBASE(nxt) : cB;
.LBB0_261:
	s_ashr_i32 s75, s74, 31
	s_lshl_b64 s[40:41], s[74:75], 20
	s_add_u32 s76, s58, s40
	ds_read_b128 v[2:5], v156
	ds_read_b128 v[6:9], v156 offset:1024
	ds_read_b128 v[10:13], v156 offset:2048
	ds_read_b128 v[14:17], v156 offset:3072
	ds_read_b128 v[18:21], v157
	ds_read_b128 v[22:25], v157 offset:1024
	ds_read_b128 v[26:29], v157 offset:2048
	ds_read_b128 v[30:33], v157 offset:3072
	s_addc_u32 s77, s59, s41
	s_ashr_i32 s73, s72, 31
	s_lshl_b64 s[40:41], s[72:73], 20
	s_add_u32 s78, s84, s40
	s_addc_u32 s79, s85, s41
	s_and_b64 s[40:41], s[8:9], exec
	s_cselect_b32 s3, s77, s83
	s_cselect_b32 s11, s76, s82
	s_cselect_b32 s13, s79, s81
	s_cselect_b32 s42, s78, s80
	v_lshl_add_u64 v[138:139], s[82:83], 0, v[140:141]
	s_mov_b32 m0, s89
	v_lshl_add_u64 v[66:67], v[138:139], 0, s[20:21]
	ds_read_b128 v[34:37], v158
	ds_read_b128 v[38:41], v158 offset:1024
	ds_read_b128 v[42:45], v158 offset:2048
	ds_read_b128 v[46:49], v158 offset:3072
	ds_read_b128 v[50:53], v158 offset:4096
	ds_read_b128 v[54:57], v158 offset:5120
	ds_read_b128 v[58:61], v158 offset:6144
	ds_read_b128 v[62:65], v158 offset:7168
	global_load_lds_dwordx4 v[66:67], off
	v_lshl_add_u64 v[66:67], v[138:139], 0, s[22:23]
	s_mov_b32 m0, s45
	s_nop 0
	global_load_lds_dwordx4 v[66:67], off
	s_waitcnt vmcnt(24)
	s_waitcnt lgkmcnt(0)
	s_barrier
	s_waitcnt lgkmcnt(0)
	v_mfma_f32_16x16x32_bf16 v[86:89], v[10:13], v[50:53], 0
	v_mfma_f32_16x16x32_bf16 v[90:93], v[14:17], v[54:57], v[86:89]
	v_mfma_f32_16x16x32_bf16 v[86:89], v[2:5], v[58:61], 0
	v_mfma_f32_16x16x32_bf16 v[66:69], v[2:5], v[34:37], 0
	v_mfma_f32_16x16x32_bf16 v[70:73], v[10:13], v[34:37], 0
	v_mfma_f32_16x16x32_bf16 v[74:77], v[2:5], v[42:45], 0
	v_mfma_f32_16x16x32_bf16 v[78:81], v[10:13], v[42:45], 0
	v_mfma_f32_16x16x32_bf16 v[82:85], v[2:5], v[50:53], 0
	v_mfma_f32_16x16x32_bf16 v[94:97], v[6:9], v[62:65], v[86:89]
	v_mfma_f32_16x16x32_bf16 v[86:89], v[10:13], v[58:61], 0
	v_mfma_f32_16x16x32_bf16 v[66:69], v[6:9], v[38:41], v[66:69]
	v_mfma_f32_16x16x32_bf16 v[70:73], v[14:17], v[38:41], v[70:73]
	v_mfma_f32_16x16x32_bf16 v[74:77], v[6:9], v[46:49], v[74:77]
	v_mfma_f32_16x16x32_bf16 v[78:81], v[14:17], v[46:49], v[78:81]
	v_mfma_f32_16x16x32_bf16 v[82:85], v[6:9], v[54:57], v[82:85]
	v_mfma_f32_16x16x32_bf16 v[106:109], v[14:17], v[62:65], v[86:89]
	v_mfma_f32_16x16x32_bf16 v[86:89], v[18:21], v[34:37], 0
	v_mfma_f32_16x16x32_bf16 v[34:37], v[26:29], v[34:37], 0
	v_mfma_f32_16x16x32_bf16 v[110:113], v[22:25], v[38:41], v[86:89]
	v_mfma_f32_16x16x32_bf16 v[34:37], v[30:33], v[38:41], v[34:37]
	v_mfma_f32_16x16x32_bf16 v[38:41], v[18:21], v[42:45], 0
	v_mfma_f32_16x16x32_bf16 v[42:45], v[26:29], v[42:45], 0
	v_mfma_f32_16x16x32_bf16 v[38:41], v[22:25], v[46:49], v[38:41]
	v_mfma_f32_16x16x32_bf16 v[42:45], v[30:33], v[46:49], v[42:45]
	v_mfma_f32_16x16x32_bf16 v[46:49], v[18:21], v[50:53], 0
	v_mfma_f32_16x16x32_bf16 v[50:53], v[26:29], v[50:53], 0
	v_mfma_f32_16x16x32_bf16 v[46:49], v[22:25], v[54:57], v[46:49]
	v_mfma_f32_16x16x32_bf16 v[50:53], v[30:33], v[54:57], v[50:53]
	s_barrier
	v_mfma_f32_16x16x32_bf16 v[54:57], v[18:21], v[58:61], 0
	v_mfma_f32_16x16x32_bf16 v[58:61], v[26:29], v[58:61], 0
	v_mfma_f32_16x16x32_bf16 v[54:57], v[22:25], v[62:65], v[54:57]
	v_mfma_f32_16x16x32_bf16 v[58:61], v[30:33], v[62:65], v[58:61]
	v_lshl_add_u64 v[154:155], s[80:81], 0, v[142:143]
	s_add_i32 s43, s62, s88
	v_lshl_add_u64 v[130:131], v[154:155], 0, s[24:25]
	s_mov_b32 m0, s43
	s_add_i32 s53, s43, 0x2000
	ds_read_b128 v[62:65], v158 offset:16384
	ds_read_b128 v[86:89], v158 offset:17408
	ds_read_b128 v[98:101], v158 offset:18432
	ds_read_b128 v[102:105], v158 offset:19456
	ds_read_b128 v[114:117], v158 offset:20480
	ds_read_b128 v[118:121], v158 offset:21504
	ds_read_b128 v[122:125], v158 offset:22528
	ds_read_b128 v[126:129], v158 offset:23552
	global_load_lds_dwordx4 v[130:131], off
	v_lshl_add_u64 v[130:131], v[154:155], 0, s[26:27]
	s_mov_b32 m0, s53
	s_add_i32 s73, s63, s88
	global_load_lds_dwordx4 v[130:131], off
	v_lshl_add_u64 v[130:131], v[154:155], 0, s[28:29]
	s_mov_b32 m0, s73
	s_add_i32 s40, s73, 0x2000
	global_load_lds_dwordx4 v[130:131], off
	v_lshl_add_u64 v[130:131], v[154:155], 0, s[30:31]
	s_mov_b32 m0, s40
	s_nop 0
	global_load_lds_dwordx4 v[130:131], off
	v_lshl_add_u64 v[130:131], v[138:139], 0, s[24:25]
	s_mov_b32 m0, s44
	s_nop 0
	global_load_lds_dwordx4 v[130:131], off
	v_lshl_add_u64 v[130:131], v[138:139], 0, s[26:27]
	s_mov_b32 m0, s90
	s_nop 0
	global_load_lds_dwordx4 v[130:131], off
	s_waitcnt vmcnt(24)
	s_waitcnt lgkmcnt(0)
	s_barrier
	s_waitcnt lgkmcnt(0)
	v_mfma_f32_16x16x32_bf16 v[130:133], v[2:5], v[62:65], 0
	v_mfma_f32_16x16x32_bf16 v[150:153], v[2:5], v[98:101], 0
	v_mfma_f32_16x16x32_bf16 v[170:173], v[2:5], v[114:117], 0
	v_mfma_f32_16x16x32_bf16 v[2:5], v[2:5], v[122:125], 0
	v_mfma_f32_16x16x32_bf16 v[130:133], v[6:9], v[86:89], v[130:133]
	v_mfma_f32_16x16x32_bf16 v[150:153], v[6:9], v[102:105], v[150:153]
	v_mfma_f32_16x16x32_bf16 v[170:173], v[6:9], v[118:121], v[170:173]
	v_mfma_f32_16x16x32_bf16 v[2:5], v[6:9], v[126:129], v[2:5]
	v_mfma_f32_16x16x32_bf16 v[6:9], v[10:13], v[122:125], 0
	v_mfma_f32_16x16x32_bf16 v[134:137], v[10:13], v[62:65], 0
	v_mfma_f32_16x16x32_bf16 v[166:169], v[10:13], v[98:101], 0
	v_mfma_f32_16x16x32_bf16 v[174:177], v[10:13], v[114:117], 0
	v_mfma_f32_16x16x32_bf16 v[6:9], v[14:17], v[126:129], v[6:9]
	v_mfma_f32_16x16x32_bf16 v[134:137], v[14:17], v[86:89], v[134:137]
	v_mfma_f32_16x16x32_bf16 v[166:169], v[14:17], v[102:105], v[166:169]
	v_mfma_f32_16x16x32_bf16 v[174:177], v[14:17], v[118:121], v[174:177]
	v_mfma_f32_16x16x32_bf16 v[10:13], v[18:21], v[62:65], 0
	v_mfma_f32_16x16x32_bf16 v[14:17], v[26:29], v[62:65], 0
	v_mfma_f32_16x16x32_bf16 v[62:65], v[18:21], v[98:101], 0
	v_mfma_f32_16x16x32_bf16 v[178:181], v[22:25], v[102:105], v[62:65]
	v_mfma_f32_16x16x32_bf16 v[62:65], v[26:29], v[98:101], 0
	v_mfma_f32_16x16x32_bf16 v[182:185], v[30:33], v[102:105], v[62:65]
	v_mfma_f32_16x16x32_bf16 v[62:65], v[18:21], v[114:117], 0
	v_mfma_f32_16x16x32_bf16 v[18:21], v[18:21], v[122:125], 0
	v_mfma_f32_16x16x32_bf16 v[10:13], v[22:25], v[86:89], v[10:13]
	v_mfma_f32_16x16x32_bf16 v[14:17], v[30:33], v[86:89], v[14:17]
	v_mfma_f32_16x16x32_bf16 v[186:189], v[22:25], v[118:121], v[62:65]
	v_mfma_f32_16x16x32_bf16 v[62:65], v[26:29], v[114:117], 0
	s_barrier
	v_mfma_f32_16x16x32_bf16 v[194:197], v[22:25], v[126:129], v[18:21]
	v_mfma_f32_16x16x32_bf16 v[18:21], v[26:29], v[122:125], 0
	v_mfma_f32_16x16x32_bf16 v[190:193], v[30:33], v[118:121], v[62:65]
	v_mfma_f32_16x16x32_bf16 v[198:201], v[30:33], v[126:129], v[18:21]
	ds_read_b128 v[26:29], v159
	ds_read_b128 v[30:33], v159 offset:1024
	s_nop 0
	ds_read_b128 v[62:65], v159 offset:2048
	ds_read_b128 v[202:205], v159 offset:3072
	ds_read_b128 v[206:209], v160
	ds_read_b128 v[210:213], v160 offset:1024
	ds_read_b128 v[214:217], v160 offset:2048
	ds_read_b128 v[218:221], v160 offset:3072
	s_mov_b32 m0, s91
	v_lshl_add_u64 v[86:87], v[138:139], 0, s[28:29]
	ds_read_b128 v[18:21], v158 offset:32768
	ds_read_b128 v[22:25], v158 offset:33792
	ds_read_b128 v[222:225], v158 offset:34816
	ds_read_b128 v[226:229], v158 offset:35840
	ds_read_b128 v[230:233], v158 offset:36864
	ds_read_b128 v[234:237], v158 offset:37888
	ds_read_b128 v[238:241], v158 offset:38912
	ds_read_b128 v[242:245], v158 offset:39936
	global_load_lds_dwordx4 v[86:87], off
	v_lshl_add_u64 v[86:87], v[138:139], 0, s[30:31]
	s_mov_b32 m0, s92
	s_nop 0
	global_load_lds_dwordx4 v[86:87], off
	s_waitcnt vmcnt(8)
	s_waitcnt lgkmcnt(0)
	s_barrier
	s_waitcnt lgkmcnt(0)
	v_mfma_f32_16x16x32_bf16 v[66:69], v[26:29], v[18:21], v[66:69]
	v_mfma_f32_16x16x32_bf16 v[118:121], v[30:33], v[22:25], v[66:69]
	v_mfma_f32_16x16x32_bf16 v[66:69], v[62:65], v[18:21], v[70:73]
	v_mfma_f32_16x16x32_bf16 v[114:117], v[202:205], v[22:25], v[66:69]
	v_mfma_f32_16x16x32_bf16 v[66:69], v[26:29], v[222:225], v[74:77]
	v_mfma_f32_16x16x32_bf16 v[102:105], v[30:33], v[226:229], v[66:69]
	v_mfma_f32_16x16x32_bf16 v[66:69], v[62:65], v[222:225], v[78:81]
	v_mfma_f32_16x16x32_bf16 v[98:101], v[202:205], v[226:229], v[66:69]
	v_mfma_f32_16x16x32_bf16 v[66:69], v[26:29], v[230:233], v[82:85]
	v_mfma_f32_16x16x32_bf16 v[86:89], v[30:33], v[234:237], v[66:69]
	v_mfma_f32_16x16x32_bf16 v[66:69], v[62:65], v[230:233], v[90:93]
	v_mfma_f32_16x16x32_bf16 v[82:85], v[202:205], v[234:237], v[66:69]
	v_mfma_f32_16x16x32_bf16 v[66:69], v[26:29], v[238:241], v[94:97]
	v_mfma_f32_16x16x32_bf16 v[70:73], v[62:65], v[238:241], v[106:109]
	v_mfma_f32_16x16x32_bf16 v[66:69], v[30:33], v[242:245], v[66:69]
	v_mfma_f32_16x16x32_bf16 v[70:73], v[202:205], v[242:245], v[70:73]
	v_mfma_f32_16x16x32_bf16 v[74:77], v[206:209], v[18:21], v[110:113]
	v_mfma_f32_16x16x32_bf16 v[18:21], v[214:217], v[18:21], v[34:37]
	v_mfma_f32_16x16x32_bf16 v[122:125], v[218:221], v[22:25], v[18:21]
	v_mfma_f32_16x16x32_bf16 v[18:21], v[206:209], v[222:225], v[38:41]
	v_mfma_f32_16x16x32_bf16 v[110:113], v[210:213], v[226:229], v[18:21]
	v_mfma_f32_16x16x32_bf16 v[18:21], v[214:217], v[222:225], v[42:45]
	v_mfma_f32_16x16x32_bf16 v[106:109], v[218:221], v[226:229], v[18:21]
	v_mfma_f32_16x16x32_bf16 v[18:21], v[206:209], v[230:233], v[46:49]
	v_mfma_f32_16x16x32_bf16 v[94:97], v[210:213], v[234:237], v[18:21]
	v_mfma_f32_16x16x32_bf16 v[18:21], v[214:217], v[230:233], v[50:53]
	v_mfma_f32_16x16x32_bf16 v[90:93], v[218:221], v[234:237], v[18:21]
	v_mfma_f32_16x16x32_bf16 v[18:21], v[206:209], v[238:241], v[54:57]
	s_barrier
	v_mfma_f32_16x16x32_bf16 v[126:129], v[210:213], v[22:25], v[74:77]
	v_mfma_f32_16x16x32_bf16 v[74:77], v[210:213], v[242:245], v[18:21]
	v_mfma_f32_16x16x32_bf16 v[18:21], v[214:217], v[238:241], v[58:61]
	v_mfma_f32_16x16x32_bf16 v[78:81], v[218:221], v[242:245], v[18:21]
	s_add_i32 s41, s46, s88
	s_nop 4
	v_lshl_add_u64 v[18:19], v[154:155], 0, s[34:35]
	s_mov_b32 m0, s41
	s_add_i32 s50, s41, 0x2000
	ds_read_b128 v[42:45], v158 offset:49152
	ds_read_b128 v[46:49], v158 offset:50176
	ds_read_b128 v[222:225], v158 offset:51200
	ds_read_b128 v[226:229], v158 offset:52224
	ds_read_b128 v[230:233], v158 offset:53248
	ds_read_b128 v[234:237], v158 offset:54272
	ds_read_b128 v[238:241], v158 offset:55296
	ds_read_b128 v[242:245], v158 offset:56320
	global_load_lds_dwordx4 v[18:19], off
	v_lshl_add_u64 v[18:19], v[154:155], 0, s[36:37]
	s_mov_b32 m0, s50
	s_mov_b64 s[56:57], 0x80180
	s_add_i32 s51, s47, s88
	global_load_lds_dwordx4 v[18:19], off
	v_lshl_add_u64 v[18:19], v[154:155], 0, s[56:57]
	s_mov_b32 m0, s51
	s_mov_b64 s[56:57], 0xc0180
	s_add_i32 s33, s51, 0x2000
	global_load_lds_dwordx4 v[18:19], off
	v_lshl_add_u64 v[18:19], v[154:155], 0, s[56:57]
	s_mov_b32 m0, s33
	s_nop 0
	global_load_lds_dwordx4 v[18:19], off
	v_lshl_add_u64 v[18:19], v[138:139], 0, s[34:35]
	s_mov_b32 m0, s93
	s_nop 0
	global_load_lds_dwordx4 v[18:19], off
	v_lshl_add_u64 v[18:19], v[138:139], 0, s[36:37]
	s_mov_b32 m0, s94
	s_nop 0
	global_load_lds_dwordx4 v[18:19], off
	s_waitcnt vmcnt(8)
	s_waitcnt lgkmcnt(0)
	s_barrier
	s_waitcnt lgkmcnt(0)
	v_mfma_f32_16x16x32_bf16 v[18:21], v[26:29], v[42:45], v[130:133]
	v_mfma_f32_16x16x32_bf16 v[50:53], v[30:33], v[46:49], v[18:21]
	v_mfma_f32_16x16x32_bf16 v[18:21], v[62:65], v[42:45], v[134:137]
	v_mfma_f32_16x16x32_bf16 v[54:57], v[202:205], v[46:49], v[18:21]
	v_mfma_f32_16x16x32_bf16 v[18:21], v[26:29], v[222:225], v[150:153]
	v_mfma_f32_16x16x32_bf16 v[34:37], v[30:33], v[226:229], v[18:21]
	v_mfma_f32_16x16x32_bf16 v[18:21], v[62:65], v[222:225], v[166:169]
	v_mfma_f32_16x16x32_bf16 v[38:41], v[202:205], v[226:229], v[18:21]
	v_mfma_f32_16x16x32_bf16 v[18:21], v[26:29], v[230:233], v[170:173]
	v_mfma_f32_16x16x32_bf16 v[22:25], v[62:65], v[230:233], v[174:177]
	v_mfma_f32_16x16x32_bf16 v[2:5], v[26:29], v[238:241], v[2:5]
	v_mfma_f32_16x16x32_bf16 v[6:9], v[62:65], v[238:241], v[6:9]
	v_mfma_f32_16x16x32_bf16 v[18:21], v[30:33], v[234:237], v[18:21]
	v_mfma_f32_16x16x32_bf16 v[22:25], v[202:205], v[234:237], v[22:25]
	v_mfma_f32_16x16x32_bf16 v[2:5], v[30:33], v[242:245], v[2:5]
	v_mfma_f32_16x16x32_bf16 v[6:9], v[202:205], v[242:245], v[6:9]
	v_mfma_f32_16x16x32_bf16 v[10:13], v[206:209], v[42:45], v[10:13]
	v_mfma_f32_16x16x32_bf16 v[58:61], v[210:213], v[46:49], v[10:13]
	v_mfma_f32_16x16x32_bf16 v[10:13], v[214:217], v[42:45], v[14:17]
	v_mfma_f32_16x16x32_bf16 v[62:65], v[218:221], v[46:49], v[10:13]
	v_mfma_f32_16x16x32_bf16 v[10:13], v[206:209], v[222:225], v[178:181]
	v_mfma_f32_16x16x32_bf16 v[42:45], v[210:213], v[226:229], v[10:13]
	v_mfma_f32_16x16x32_bf16 v[10:13], v[214:217], v[222:225], v[182:185]
	v_mfma_f32_16x16x32_bf16 v[46:49], v[218:221], v[226:229], v[10:13]
	v_mfma_f32_16x16x32_bf16 v[10:13], v[206:209], v[230:233], v[186:189]
	v_mfma_f32_16x16x32_bf16 v[26:29], v[210:213], v[234:237], v[10:13]
	v_mfma_f32_16x16x32_bf16 v[10:13], v[214:217], v[230:233], v[190:193]
	v_mfma_f32_16x16x32_bf16 v[30:33], v[218:221], v[234:237], v[10:13]
	s_barrier
	v_mfma_f32_16x16x32_bf16 v[10:13], v[206:209], v[238:241], v[194:197]
	v_mfma_f32_16x16x32_bf16 v[14:17], v[214:217], v[238:241], v[198:201]
	v_mfma_f32_16x16x32_bf16 v[10:13], v[210:213], v[242:245], v[10:13]
	v_mfma_f32_16x16x32_bf16 v[14:17], v[218:221], v[242:245], v[14:17]
	s_add_u32 s82, s82, 0x80180
	s_addc_u32 s83, s83, 0
	s_add_u32 s56, s80, 0x200
	s_addc_u32 s57, s81, 0
	s_mov_b32 s75, 0
.LBB0_262:
	ds_read_b128 v[130:133], v156
	ds_read_b128 v[134:137], v156 offset:1024
	ds_read_b128 v[150:153], v156 offset:2048
	ds_read_b128 v[166:169], v156 offset:3072
	ds_read_b128 v[170:173], v157
	ds_read_b128 v[174:177], v157 offset:1024
	ds_read_b128 v[178:181], v157 offset:2048
	ds_read_b128 v[182:185], v157 offset:3072
	s_add_u32 s0, s82, 0xfff80080
	s_addc_u32 s1, s83, -1
	s_cmp_eq_u32 s75, 28
	s_cselect_b32 s81, s3, s1
	s_cselect_b32 s80, s11, s0
	s_cselect_b32 vcc_hi, s13, s57
	s_cselect_b32 vcc_lo, s42, s56
	s_mov_b32 m0, s89
	v_lshl_add_u64 v[138:139], s[82:83], 0, v[144:145]
	ds_read_b128 v[186:189], v158
	ds_read_b128 v[190:193], v158 offset:1024
	ds_read_b128 v[194:197], v158 offset:2048
	ds_read_b128 v[198:201], v158 offset:3072
	ds_read_b128 v[202:205], v158 offset:4096
	ds_read_b128 v[206:209], v158 offset:5120
	ds_read_b128 v[210:213], v158 offset:6144
	ds_read_b128 v[214:217], v158 offset:7168
	global_load_lds_dwordx4 v[138:139], off
	v_lshl_add_u64 v[138:139], v[138:139], 0, s[38:39]
	s_mov_b32 m0, s45
	s_nop 0
	global_load_lds_dwordx4 v[138:139], off
	s_waitcnt vmcnt(8)
	s_waitcnt lgkmcnt(0)
	s_barrier
	s_waitcnt lgkmcnt(0)
	v_mfma_f32_16x16x32_bf16 v[118:121], v[130:133], v[186:189], v[118:121]
	v_mfma_f32_16x16x32_bf16 v[114:117], v[150:153], v[186:189], v[114:117]
	v_mfma_f32_16x16x32_bf16 v[102:105], v[130:133], v[194:197], v[102:105]
	v_mfma_f32_16x16x32_bf16 v[98:101], v[150:153], v[194:197], v[98:101]
	v_mfma_f32_16x16x32_bf16 v[86:89], v[130:133], v[202:205], v[86:89]
	v_mfma_f32_16x16x32_bf16 v[82:85], v[150:153], v[202:205], v[82:85]
	v_mfma_f32_16x16x32_bf16 v[66:69], v[130:133], v[210:213], v[66:69]
	v_mfma_f32_16x16x32_bf16 v[70:73], v[150:153], v[210:213], v[70:73]
	v_mfma_f32_16x16x32_bf16 v[118:121], v[134:137], v[190:193], v[118:121]
	v_mfma_f32_16x16x32_bf16 v[114:117], v[166:169], v[190:193], v[114:117]
	v_mfma_f32_16x16x32_bf16 v[102:105], v[134:137], v[198:201], v[102:105]
	v_mfma_f32_16x16x32_bf16 v[98:101], v[166:169], v[198:201], v[98:101]
	v_mfma_f32_16x16x32_bf16 v[86:89], v[134:137], v[206:209], v[86:89]
	v_mfma_f32_16x16x32_bf16 v[82:85], v[166:169], v[206:209], v[82:85]
	v_mfma_f32_16x16x32_bf16 v[66:69], v[134:137], v[214:217], v[66:69]
	v_mfma_f32_16x16x32_bf16 v[70:73], v[166:169], v[214:217], v[70:73]
	v_mfma_f32_16x16x32_bf16 v[126:129], v[170:173], v[186:189], v[126:129]
	v_mfma_f32_16x16x32_bf16 v[122:125], v[178:181], v[186:189], v[122:125]
	v_mfma_f32_16x16x32_bf16 v[110:113], v[170:173], v[194:197], v[110:113]
	v_mfma_f32_16x16x32_bf16 v[106:109], v[178:181], v[194:197], v[106:109]
	v_mfma_f32_16x16x32_bf16 v[94:97], v[170:173], v[202:205], v[94:97]
	v_mfma_f32_16x16x32_bf16 v[90:93], v[178:181], v[202:205], v[90:93]
	v_mfma_f32_16x16x32_bf16 v[74:77], v[170:173], v[210:213], v[74:77]
	v_mfma_f32_16x16x32_bf16 v[78:81], v[178:181], v[210:213], v[78:81]
	v_mfma_f32_16x16x32_bf16 v[126:129], v[174:177], v[190:193], v[126:129]
	v_mfma_f32_16x16x32_bf16 v[122:125], v[182:185], v[190:193], v[122:125]
	v_mfma_f32_16x16x32_bf16 v[110:113], v[174:177], v[198:201], v[110:113]
	v_mfma_f32_16x16x32_bf16 v[106:109], v[182:185], v[198:201], v[106:109]
	s_barrier
	v_mfma_f32_16x16x32_bf16 v[94:97], v[174:177], v[206:209], v[94:97]
	v_mfma_f32_16x16x32_bf16 v[90:93], v[182:185], v[206:209], v[90:93]
	v_mfma_f32_16x16x32_bf16 v[74:77], v[174:177], v[214:217], v[74:77]
	v_mfma_f32_16x16x32_bf16 v[78:81], v[182:185], v[214:217], v[78:81]
	s_mov_b32 m0, s43
	v_lshl_add_u64 v[138:139], vcc, 0, v[142:143]
	ds_read_b128 v[186:189], v158 offset:16384
	ds_read_b128 v[190:193], v158 offset:17408
	ds_read_b128 v[194:197], v158 offset:18432
	ds_read_b128 v[198:201], v158 offset:19456
	ds_read_b128 v[202:205], v158 offset:20480
	ds_read_b128 v[206:209], v158 offset:21504
	ds_read_b128 v[210:213], v158 offset:22528
	ds_read_b128 v[214:217], v158 offset:23552
	global_load_lds_dwordx4 v[138:139], off
	v_lshl_add_u64 v[154:155], v[138:139], 0, s[38:39]
	s_mov_b32 m0, s53
	s_nop 0
	global_load_lds_dwordx4 v[154:155], off
	v_lshl_add_u64 v[154:155], v[138:139], 0, s[60:61]
	s_mov_b32 m0, s73
	s_nop 0
	global_load_lds_dwordx4 v[154:155], off
	v_lshl_add_u64 v[154:155], v[138:139], 0, s[66:67]
	s_mov_b32 m0, s40
	s_nop 0
	global_load_lds_dwordx4 v[154:155], off
	v_lshl_add_u64 v[154:155], s[80:81], 0, v[140:141]
	s_mov_b32 m0, s44
	v_lshl_add_u64 v[218:219], v[154:155], 0, s[38:39]
	global_load_lds_dwordx4 v[154:155], off
	s_mov_b32 m0, s90
	s_nop 0
	global_load_lds_dwordx4 v[218:219], off
	s_waitcnt vmcnt(8)
	s_waitcnt lgkmcnt(0)
	s_barrier
	s_waitcnt lgkmcnt(0)
	v_mfma_f32_16x16x32_bf16 v[50:53], v[130:133], v[186:189], v[50:53]
	v_mfma_f32_16x16x32_bf16 v[54:57], v[150:153], v[186:189], v[54:57]
	v_mfma_f32_16x16x32_bf16 v[34:37], v[130:133], v[194:197], v[34:37]
	v_mfma_f32_16x16x32_bf16 v[38:41], v[150:153], v[194:197], v[38:41]
	v_mfma_f32_16x16x32_bf16 v[18:21], v[130:133], v[202:205], v[18:21]
	v_mfma_f32_16x16x32_bf16 v[22:25], v[150:153], v[202:205], v[22:25]
	v_mfma_f32_16x16x32_bf16 v[2:5], v[130:133], v[210:213], v[2:5]
	v_mfma_f32_16x16x32_bf16 v[6:9], v[150:153], v[210:213], v[6:9]
	v_mfma_f32_16x16x32_bf16 v[50:53], v[134:137], v[190:193], v[50:53]
	v_mfma_f32_16x16x32_bf16 v[54:57], v[166:169], v[190:193], v[54:57]
	v_mfma_f32_16x16x32_bf16 v[34:37], v[134:137], v[198:201], v[34:37]
	v_mfma_f32_16x16x32_bf16 v[38:41], v[166:169], v[198:201], v[38:41]
	v_mfma_f32_16x16x32_bf16 v[18:21], v[134:137], v[206:209], v[18:21]
	v_mfma_f32_16x16x32_bf16 v[22:25], v[166:169], v[206:209], v[22:25]
	v_mfma_f32_16x16x32_bf16 v[2:5], v[134:137], v[214:217], v[2:5]
	v_mfma_f32_16x16x32_bf16 v[6:9], v[166:169], v[214:217], v[6:9]
	v_mfma_f32_16x16x32_bf16 v[58:61], v[170:173], v[186:189], v[58:61]
	v_mfma_f32_16x16x32_bf16 v[62:65], v[178:181], v[186:189], v[62:65]
	v_mfma_f32_16x16x32_bf16 v[42:45], v[170:173], v[194:197], v[42:45]
	v_mfma_f32_16x16x32_bf16 v[46:49], v[178:181], v[194:197], v[46:49]
	v_mfma_f32_16x16x32_bf16 v[26:29], v[170:173], v[202:205], v[26:29]
	v_mfma_f32_16x16x32_bf16 v[30:33], v[178:181], v[202:205], v[30:33]
	v_mfma_f32_16x16x32_bf16 v[10:13], v[170:173], v[210:213], v[10:13]
	v_mfma_f32_16x16x32_bf16 v[14:17], v[178:181], v[210:213], v[14:17]
	v_mfma_f32_16x16x32_bf16 v[58:61], v[174:177], v[190:193], v[58:61]
	v_mfma_f32_16x16x32_bf16 v[62:65], v[182:185], v[190:193], v[62:65]
	v_mfma_f32_16x16x32_bf16 v[42:45], v[174:177], v[198:201], v[42:45]
	v_mfma_f32_16x16x32_bf16 v[46:49], v[182:185], v[198:201], v[46:49]
	s_barrier
	v_mfma_f32_16x16x32_bf16 v[26:29], v[174:177], v[206:209], v[26:29]
	v_mfma_f32_16x16x32_bf16 v[30:33], v[182:185], v[206:209], v[30:33]
	v_mfma_f32_16x16x32_bf16 v[10:13], v[174:177], v[214:217], v[10:13]
	v_mfma_f32_16x16x32_bf16 v[14:17], v[182:185], v[214:217], v[14:17]
	ds_read_b128 v[130:133], v159
	ds_read_b128 v[134:137], v159 offset:1024
	ds_read_b128 v[150:153], v159 offset:2048
	ds_read_b128 v[166:169], v159 offset:3072
	ds_read_b128 v[170:173], v160
	ds_read_b128 v[174:177], v160 offset:1024
	ds_read_b128 v[178:181], v160 offset:2048
	ds_read_b128 v[182:185], v160 offset:3072
	s_mov_b32 m0, s91
	v_lshl_add_u64 v[218:219], v[154:155], 0, s[60:61]
	ds_read_b128 v[186:189], v158 offset:32768
	ds_read_b128 v[190:193], v158 offset:33792
	ds_read_b128 v[194:197], v158 offset:34816
	ds_read_b128 v[198:201], v158 offset:35840
	ds_read_b128 v[202:205], v158 offset:36864
	ds_read_b128 v[206:209], v158 offset:37888
	ds_read_b128 v[210:213], v158 offset:38912
	ds_read_b128 v[214:217], v158 offset:39936
	global_load_lds_dwordx4 v[218:219], off
	v_lshl_add_u64 v[218:219], v[154:155], 0, s[66:67]
	s_mov_b32 m0, s92
	s_nop 0
	global_load_lds_dwordx4 v[218:219], off
	s_waitcnt vmcnt(8)
	s_waitcnt lgkmcnt(0)
	s_barrier
	s_waitcnt lgkmcnt(0)
	v_mfma_f32_16x16x32_bf16 v[118:121], v[130:133], v[186:189], v[118:121]
	v_mfma_f32_16x16x32_bf16 v[114:117], v[150:153], v[186:189], v[114:117]
	v_mfma_f32_16x16x32_bf16 v[102:105], v[130:133], v[194:197], v[102:105]
	v_mfma_f32_16x16x32_bf16 v[98:101], v[150:153], v[194:197], v[98:101]
	v_mfma_f32_16x16x32_bf16 v[86:89], v[130:133], v[202:205], v[86:89]
	v_mfma_f32_16x16x32_bf16 v[82:85], v[150:153], v[202:205], v[82:85]
	v_mfma_f32_16x16x32_bf16 v[66:69], v[130:133], v[210:213], v[66:69]
	v_mfma_f32_16x16x32_bf16 v[70:73], v[150:153], v[210:213], v[70:73]
	v_mfma_f32_16x16x32_bf16 v[118:121], v[134:137], v[190:193], v[118:121]
	v_mfma_f32_16x16x32_bf16 v[114:117], v[166:169], v[190:193], v[114:117]
	v_mfma_f32_16x16x32_bf16 v[102:105], v[134:137], v[198:201], v[102:105]
	v_mfma_f32_16x16x32_bf16 v[98:101], v[166:169], v[198:201], v[98:101]
	v_mfma_f32_16x16x32_bf16 v[86:89], v[134:137], v[206:209], v[86:89]
	v_mfma_f32_16x16x32_bf16 v[82:85], v[166:169], v[206:209], v[82:85]
	v_mfma_f32_16x16x32_bf16 v[66:69], v[134:137], v[214:217], v[66:69]
	v_mfma_f32_16x16x32_bf16 v[70:73], v[166:169], v[214:217], v[70:73]
	v_mfma_f32_16x16x32_bf16 v[126:129], v[170:173], v[186:189], v[126:129]
	v_mfma_f32_16x16x32_bf16 v[122:125], v[178:181], v[186:189], v[122:125]
	v_mfma_f32_16x16x32_bf16 v[110:113], v[170:173], v[194:197], v[110:113]
	v_mfma_f32_16x16x32_bf16 v[106:109], v[178:181], v[194:197], v[106:109]
	v_mfma_f32_16x16x32_bf16 v[94:97], v[170:173], v[202:205], v[94:97]
	v_mfma_f32_16x16x32_bf16 v[90:93], v[178:181], v[202:205], v[90:93]
	v_mfma_f32_16x16x32_bf16 v[74:77], v[170:173], v[210:213], v[74:77]
	v_mfma_f32_16x16x32_bf16 v[78:81], v[178:181], v[210:213], v[78:81]
	v_mfma_f32_16x16x32_bf16 v[126:129], v[174:177], v[190:193], v[126:129]
	v_mfma_f32_16x16x32_bf16 v[122:125], v[182:185], v[190:193], v[122:125]
	v_mfma_f32_16x16x32_bf16 v[110:113], v[174:177], v[198:201], v[110:113]
	v_mfma_f32_16x16x32_bf16 v[106:109], v[182:185], v[198:201], v[106:109]
	s_barrier
; #define PG8_WAIT_V(n) asm volatile("s_waitcnt vmcnt(" #n ")" ::: "memory")
; template <class Epi, class Sched, bool ALIGN_EPI = true, bool SP2 = true, bool FULLLINE = false, bool NOSTAGE = false, bool FP8 = false>
; __device__ __forceinline__ void gemm_phase(PG8_LAS unsigned char* lds, const Gemm g, const Sched& S, const Epi& E) {
;     ...
;         static_assert(SP2, "only the SP2 loop is kept");
;         { const int t = 0; if constexpr (Epi::NST == 16) PG8_ITER(PG8_WAIT_V(24)); else if constexpr (Epi::NST == 8) PG8_ITER(PG8_WAIT_V(16)); else PG8_ITER(PG8_WAIT_V(8)); }
;         for (int t = 2; t < nt; t += 2) PG8_ITER(PG8_WAIT_V(8));
	v_mfma_f32_16x16x32_bf16 v[94:97], v[174:177], v[206:209], v[94:97]
	v_mfma_f32_16x16x32_bf16 v[90:93], v[182:185], v[206:209], v[90:93]
	v_mfma_f32_16x16x32_bf16 v[74:77], v[174:177], v[214:217], v[74:77]
	v_mfma_f32_16x16x32_bf16 v[78:81], v[182:185], v[214:217], v[78:81]
	s_mov_b32 m0, s41
	v_lshl_add_u64 v[218:219], v[138:139], 0, s[68:69]
	ds_read_b128 v[186:189], v158 offset:49152
	ds_read_b128 v[190:193], v158 offset:50176
	ds_read_b128 v[194:197], v158 offset:51200
	ds_read_b128 v[198:201], v158 offset:52224
	ds_read_b128 v[202:205], v158 offset:53248
	ds_read_b128 v[206:209], v158 offset:54272
	ds_read_b128 v[210:213], v158 offset:55296
	ds_read_b128 v[214:217], v158 offset:56320
	global_load_lds_dwordx4 v[218:219], off
	v_lshl_add_u64 v[218:219], v[138:139], 0, s[70:71]
	s_mov_b32 m0, s50
	s_nop 0
	global_load_lds_dwordx4 v[218:219], off
	v_lshl_add_u64 v[218:219], v[138:139], 0, s[20:21]
	s_mov_b32 m0, s51
	v_lshl_add_u64 v[138:139], v[138:139], 0, s[22:23]
	global_load_lds_dwordx4 v[218:219], off
	s_mov_b32 m0, s33
	s_nop 0
	global_load_lds_dwordx4 v[138:139], off
	v_lshl_add_u64 v[138:139], v[154:155], 0, s[68:69]
	s_mov_b32 m0, s93
	s_nop 0
	global_load_lds_dwordx4 v[138:139], off
	v_lshl_add_u64 v[138:139], v[154:155], 0, s[70:71]
	s_mov_b32 m0, s94
	s_nop 0
	global_load_lds_dwordx4 v[138:139], off
	s_waitcnt vmcnt(8)
	s_waitcnt lgkmcnt(0)
	s_barrier
	s_waitcnt lgkmcnt(0)
	v_mfma_f32_16x16x32_bf16 v[50:53], v[130:133], v[186:189], v[50:53]
	v_mfma_f32_16x16x32_bf16 v[54:57], v[150:153], v[186:189], v[54:57]
	v_mfma_f32_16x16x32_bf16 v[34:37], v[130:133], v[194:197], v[34:37]
	v_mfma_f32_16x16x32_bf16 v[38:41], v[150:153], v[194:197], v[38:41]
	v_mfma_f32_16x16x32_bf16 v[18:21], v[130:133], v[202:205], v[18:21]
	v_mfma_f32_16x16x32_bf16 v[22:25], v[150:153], v[202:205], v[22:25]
	v_mfma_f32_16x16x32_bf16 v[2:5], v[130:133], v[210:213], v[2:5]
	v_mfma_f32_16x16x32_bf16 v[6:9], v[150:153], v[210:213], v[6:9]
	v_mfma_f32_16x16x32_bf16 v[50:53], v[134:137], v[190:193], v[50:53]
	v_mfma_f32_16x16x32_bf16 v[54:57], v[166:169], v[190:193], v[54:57]
	v_mfma_f32_16x16x32_bf16 v[34:37], v[134:137], v[198:201], v[34:37]
	v_mfma_f32_16x16x32_bf16 v[38:41], v[166:169], v[198:201], v[38:41]
	v_mfma_f32_16x16x32_bf16 v[18:21], v[134:137], v[206:209], v[18:21]
	v_mfma_f32_16x16x32_bf16 v[22:25], v[166:169], v[206:209], v[22:25]
	v_mfma_f32_16x16x32_bf16 v[2:5], v[134:137], v[214:217], v[2:5]
	v_mfma_f32_16x16x32_bf16 v[6:9], v[166:169], v[214:217], v[6:9]
	v_mfma_f32_16x16x32_bf16 v[58:61], v[170:173], v[186:189], v[58:61]
	v_mfma_f32_16x16x32_bf16 v[62:65], v[178:181], v[186:189], v[62:65]
	v_mfma_f32_16x16x32_bf16 v[42:45], v[170:173], v[194:197], v[42:45]
	v_mfma_f32_16x16x32_bf16 v[46:49], v[178:181], v[194:197], v[46:49]
	v_mfma_f32_16x16x32_bf16 v[26:29], v[170:173], v[202:205], v[26:29]
	v_mfma_f32_16x16x32_bf16 v[30:33], v[178:181], v[202:205], v[30:33]
	v_mfma_f32_16x16x32_bf16 v[10:13], v[170:173], v[210:213], v[10:13]
	v_mfma_f32_16x16x32_bf16 v[14:17], v[178:181], v[210:213], v[14:17]
	v_mfma_f32_16x16x32_bf16 v[58:61], v[174:177], v[190:193], v[58:61]
	v_mfma_f32_16x16x32_bf16 v[62:65], v[182:185], v[190:193], v[62:65]
	v_mfma_f32_16x16x32_bf16 v[42:45], v[174:177], v[198:201], v[42:45]
	v_mfma_f32_16x16x32_bf16 v[46:49], v[182:185], v[198:201], v[46:49]
	s_barrier
	v_mfma_f32_16x16x32_bf16 v[26:29], v[174:177], v[206:209], v[26:29]
	v_mfma_f32_16x16x32_bf16 v[30:33], v[182:185], v[206:209], v[30:33]
	v_mfma_f32_16x16x32_bf16 v[10:13], v[174:177], v[214:217], v[10:13]
	v_mfma_f32_16x16x32_bf16 v[14:17], v[182:185], v[214:217], v[14:17]
	s_add_i32 s75, s75, 2
	s_add_u32 s82, s82, 0x100
	s_addc_u32 s83, s83, 0
	s_add_u32 s56, s56, 0x100
	s_addc_u32 s57, s57, 0
	s_cmp_gt_u32 s75, 29
	s_cbranch_scc0 .LBB0_262
	s_and_b64 vcc, exec, s[18:19]
	s_cbranch_vccz .LBB0_265
	s_barrier

; template <class Epi, class Sched, bool ALIGN_EPI = true, bool SP2 = true, bool FULLLINE = false, bool NOSTAGE = false, bool FP8 = false>
; __device__ __forceinline__ void gemm_phase(PG8_LAS unsigned char* lds, const Gemm g, const Sched& S, const Epi& E) {
;     ...
;         const bool has_next = S.next(ui + 1, nxt);
;         const char* nA = has_next ? PG8_ABASE(nxt) : cA; const char* nB = has_next ? PG8_BBASE(nxt) : cB;
.LBB0_593:
	s_ashr_i32 s69, s68, 31
	s_lshl_b64 s[40:41], s[68:69], 21
	s_add_u32 s70, s42, s40
	ds_read_b128 v[2:5], v160
	ds_read_b128 v[6:9], v160 offset:1024
	ds_read_b128 v[10:13], v160 offset:2048
	ds_read_b128 v[14:17], v160 offset:3072
	ds_read_b128 v[18:21], v161
	ds_read_b128 v[22:25], v161 offset:1024
	ds_read_b128 v[26:29], v161 offset:2048
	ds_read_b128 v[30:33], v161 offset:3072
	s_addc_u32 s71, s43, s41
	s_ashr_i32 s67, s66, 31
	s_lshl_b64 s[40:41], s[66:67], 21
	s_add_u32 s72, s44, s40
	s_addc_u32 s73, s45, s41
	s_and_b64 s[40:41], s[8:9], exec
	s_cselect_b32 s67, s71, s79
	s_cselect_b32 s69, s70, s78
	s_cselect_b32 s92, s73, s77
	s_cselect_b32 s93, s72, s76
	v_lshl_add_u64 v[246:247], s[78:79], 0, v[146:147]
	s_mov_b32 m0, s88
	v_lshl_add_u64 v[66:67], v[246:247], 0, s[12:13]
	ds_read_b128 v[34:37], v162
	ds_read_b128 v[38:41], v162 offset:1024
	ds_read_b128 v[42:45], v162 offset:2048
	ds_read_b128 v[46:49], v162 offset:3072
	ds_read_b128 v[50:53], v162 offset:4096
	ds_read_b128 v[54:57], v162 offset:5120
	ds_read_b128 v[58:61], v162 offset:6144
	ds_read_b128 v[62:65], v162 offset:7168
	global_load_lds_dwordx4 v[66:67], off
	v_lshl_add_u64 v[66:67], v[246:247], 0, s[14:15]
	s_mov_b32 m0, s89
	s_nop 0
	global_load_lds_dwordx4 v[66:67], off
	s_waitcnt vmcnt(24)
	s_waitcnt lgkmcnt(0)
	s_barrier
	s_waitcnt lgkmcnt(0)
	v_mfma_f32_16x16x32_bf16 v[66:69], v[2:5], v[34:37], 0
	v_mfma_f32_16x16x32_bf16 v[70:73], v[10:13], v[34:37], 0
	v_mfma_f32_16x16x32_bf16 v[74:77], v[2:5], v[42:45], 0
	v_mfma_f32_16x16x32_bf16 v[78:81], v[10:13], v[42:45], 0
	v_mfma_f32_16x16x32_bf16 v[82:85], v[2:5], v[50:53], 0
	v_mfma_f32_16x16x32_bf16 v[86:89], v[10:13], v[50:53], 0
	v_mfma_f32_16x16x32_bf16 v[90:93], v[2:5], v[58:61], 0
	v_mfma_f32_16x16x32_bf16 v[94:97], v[10:13], v[58:61], 0
	v_mfma_f32_16x16x32_bf16 v[66:69], v[6:9], v[38:41], v[66:69]
	v_mfma_f32_16x16x32_bf16 v[70:73], v[14:17], v[38:41], v[70:73]
	v_mfma_f32_16x16x32_bf16 v[74:77], v[6:9], v[46:49], v[74:77]
	v_mfma_f32_16x16x32_bf16 v[78:81], v[14:17], v[46:49], v[78:81]
	v_mfma_f32_16x16x32_bf16 v[82:85], v[6:9], v[54:57], v[82:85]
	v_mfma_f32_16x16x32_bf16 v[86:89], v[14:17], v[54:57], v[86:89]
	v_mfma_f32_16x16x32_bf16 v[90:93], v[6:9], v[62:65], v[90:93]
	v_mfma_f32_16x16x32_bf16 v[94:97], v[14:17], v[62:65], v[94:97]
	v_mfma_f32_16x16x32_bf16 v[98:101], v[18:21], v[34:37], 0
	v_mfma_f32_16x16x32_bf16 v[34:37], v[26:29], v[34:37], 0
	v_mfma_f32_16x16x32_bf16 v[106:109], v[22:25], v[38:41], v[98:101]
	v_mfma_f32_16x16x32_bf16 v[34:37], v[30:33], v[38:41], v[34:37]
	v_mfma_f32_16x16x32_bf16 v[38:41], v[18:21], v[42:45], 0
	v_mfma_f32_16x16x32_bf16 v[42:45], v[26:29], v[42:45], 0
	v_mfma_f32_16x16x32_bf16 v[38:41], v[22:25], v[46:49], v[38:41]
	v_mfma_f32_16x16x32_bf16 v[42:45], v[30:33], v[46:49], v[42:45]
	v_mfma_f32_16x16x32_bf16 v[46:49], v[18:21], v[50:53], 0
	v_mfma_f32_16x16x32_bf16 v[50:53], v[26:29], v[50:53], 0
	v_mfma_f32_16x16x32_bf16 v[46:49], v[22:25], v[54:57], v[46:49]
	v_mfma_f32_16x16x32_bf16 v[50:53], v[30:33], v[54:57], v[50:53]
	s_barrier
	v_mfma_f32_16x16x32_bf16 v[54:57], v[18:21], v[58:61], 0
	v_mfma_f32_16x16x32_bf16 v[58:61], v[26:29], v[58:61], 0
	v_mfma_f32_16x16x32_bf16 v[54:57], v[22:25], v[62:65], v[54:57]
	v_mfma_f32_16x16x32_bf16 v[58:61], v[30:33], v[62:65], v[58:61]
	v_lshl_add_u64 v[248:249], s[76:77], 0, v[148:149]
	s_add_i32 s94, s85, s46
	v_lshl_add_u64 v[130:131], v[248:249], 0, s[16:17]
	s_mov_b32 m0, s94
	s_add_i32 s95, s94, 0x2000
	ds_read_b128 v[62:65], v162 offset:16384
	ds_read_b128 v[98:101], v162 offset:17408
	ds_read_b128 v[102:105], v162 offset:18432
	ds_read_b128 v[110:113], v162 offset:19456
	ds_read_b128 v[114:117], v162 offset:20480
	ds_read_b128 v[118:121], v162 offset:21504
	ds_read_b128 v[122:125], v162 offset:22528
	ds_read_b128 v[126:129], v162 offset:23552
	global_load_lds_dwordx4 v[130:131], off
	v_lshl_add_u64 v[130:131], v[248:249], 0, s[18:19]
	s_mov_b32 m0, s95
	s_add_i32 s96, s87, s46
	global_load_lds_dwordx4 v[130:131], off
	v_lshl_add_u64 v[130:131], v[248:249], 0, s[20:21]
	s_mov_b32 m0, s96
	s_add_i32 s40, s96, 0x2000
	global_load_lds_dwordx4 v[130:131], off
	v_lshl_add_u64 v[130:131], v[248:249], 0, s[22:23]
	s_mov_b32 m0, s40
	s_nop 0
	global_load_lds_dwordx4 v[130:131], off
	v_lshl_add_u64 v[130:131], v[246:247], 0, s[16:17]
	s_mov_b32 m0, s47
	s_nop 0
	global_load_lds_dwordx4 v[130:131], off
	v_lshl_add_u64 v[130:131], v[246:247], 0, s[18:19]
	s_mov_b32 m0, s52
	s_nop 0
	global_load_lds_dwordx4 v[130:131], off
	s_waitcnt vmcnt(24)
	s_waitcnt lgkmcnt(0)
	s_barrier
	s_waitcnt lgkmcnt(0)
	v_mfma_f32_16x16x32_bf16 v[130:133], v[2:5], v[62:65], 0
	v_mfma_f32_16x16x32_bf16 v[156:159], v[6:9], v[98:101], v[130:133]
	v_mfma_f32_16x16x32_bf16 v[130:133], v[10:13], v[62:65], 0
	v_mfma_f32_16x16x32_bf16 v[166:169], v[14:17], v[98:101], v[130:133]
	v_mfma_f32_16x16x32_bf16 v[130:133], v[2:5], v[102:105], 0
	v_mfma_f32_16x16x32_bf16 v[170:173], v[6:9], v[110:113], v[130:133]
	v_mfma_f32_16x16x32_bf16 v[130:133], v[10:13], v[102:105], 0
	v_mfma_f32_16x16x32_bf16 v[174:177], v[14:17], v[110:113], v[130:133]
	v_mfma_f32_16x16x32_bf16 v[130:133], v[2:5], v[114:117], 0
	v_mfma_f32_16x16x32_bf16 v[2:5], v[2:5], v[122:125], 0
	v_mfma_f32_16x16x32_bf16 v[178:181], v[6:9], v[118:121], v[130:133]
	v_mfma_f32_16x16x32_bf16 v[2:5], v[6:9], v[126:129], v[2:5]
	v_mfma_f32_16x16x32_bf16 v[6:9], v[10:13], v[122:125], 0
	v_mfma_f32_16x16x32_bf16 v[130:133], v[10:13], v[114:117], 0
	v_mfma_f32_16x16x32_bf16 v[6:9], v[14:17], v[126:129], v[6:9]
	v_mfma_f32_16x16x32_bf16 v[182:185], v[14:17], v[118:121], v[130:133]
	v_mfma_f32_16x16x32_bf16 v[10:13], v[18:21], v[62:65], 0
	v_mfma_f32_16x16x32_bf16 v[186:189], v[22:25], v[98:101], v[10:13]
	v_mfma_f32_16x16x32_bf16 v[10:13], v[26:29], v[62:65], 0
	v_mfma_f32_16x16x32_bf16 v[62:65], v[30:33], v[98:101], v[10:13]
	v_mfma_f32_16x16x32_bf16 v[10:13], v[18:21], v[102:105], 0
	v_mfma_f32_16x16x32_bf16 v[190:193], v[22:25], v[110:113], v[10:13]
	v_mfma_f32_16x16x32_bf16 v[10:13], v[26:29], v[102:105], 0
	v_mfma_f32_16x16x32_bf16 v[194:197], v[30:33], v[110:113], v[10:13]
	v_mfma_f32_16x16x32_bf16 v[10:13], v[18:21], v[114:117], 0
	v_mfma_f32_16x16x32_bf16 v[198:201], v[22:25], v[118:121], v[10:13]
	v_mfma_f32_16x16x32_bf16 v[10:13], v[26:29], v[114:117], 0
	v_mfma_f32_16x16x32_bf16 v[202:205], v[30:33], v[118:121], v[10:13]
	s_barrier
	v_mfma_f32_16x16x32_bf16 v[10:13], v[18:21], v[122:125], 0
	v_mfma_f32_16x16x32_bf16 v[206:209], v[22:25], v[126:129], v[10:13]
	v_mfma_f32_16x16x32_bf16 v[10:13], v[26:29], v[122:125], 0
	v_mfma_f32_16x16x32_bf16 v[210:213], v[30:33], v[126:129], v[10:13]
	s_nop 5
	ds_read_b128 v[10:13], v163
	ds_read_b128 v[14:17], v163 offset:1024
	ds_read_b128 v[26:29], v163 offset:2048
	ds_read_b128 v[30:33], v163 offset:3072
	ds_read_b128 v[214:217], v164
	ds_read_b128 v[218:221], v164 offset:1024
	ds_read_b128 v[222:225], v164 offset:2048
	ds_read_b128 v[226:229], v164 offset:3072
	s_mov_b32 m0, s53
	v_lshl_add_u64 v[98:99], v[246:247], 0, s[20:21]
	ds_read_b128 v[18:21], v162 offset:32768
	ds_read_b128 v[22:25], v162 offset:33792
	ds_read_b128 v[110:113], v162 offset:34816
	ds_read_b128 v[122:125], v162 offset:35840
	ds_read_b128 v[230:233], v162 offset:36864
	ds_read_b128 v[234:237], v162 offset:37888
	ds_read_b128 v[238:241], v162 offset:38912
	ds_read_b128 v[242:245], v162 offset:39936
	global_load_lds_dwordx4 v[98:99], off
	v_lshl_add_u64 v[98:99], v[246:247], 0, s[22:23]
	s_mov_b32 m0, s54
	s_nop 0
	global_load_lds_dwordx4 v[98:99], off
	s_waitcnt vmcnt(8)
	s_waitcnt lgkmcnt(0)
	s_barrier
	s_waitcnt lgkmcnt(0)
	v_mfma_f32_16x16x32_bf16 v[66:69], v[10:13], v[18:21], v[66:69]
	v_mfma_f32_16x16x32_bf16 v[142:145], v[14:17], v[22:25], v[66:69]
	v_mfma_f32_16x16x32_bf16 v[66:69], v[26:29], v[18:21], v[70:73]
	v_mfma_f32_16x16x32_bf16 v[138:141], v[30:33], v[22:25], v[66:69]
	v_mfma_f32_16x16x32_bf16 v[66:69], v[10:13], v[110:113], v[74:77]
	v_mfma_f32_16x16x32_bf16 v[118:121], v[14:17], v[122:125], v[66:69]
	v_mfma_f32_16x16x32_bf16 v[66:69], v[26:29], v[110:113], v[78:81]
	v_mfma_f32_16x16x32_bf16 v[114:117], v[30:33], v[122:125], v[66:69]
	v_mfma_f32_16x16x32_bf16 v[66:69], v[10:13], v[230:233], v[82:85]
	v_mfma_f32_16x16x32_bf16 v[102:105], v[14:17], v[234:237], v[66:69]
	v_mfma_f32_16x16x32_bf16 v[66:69], v[26:29], v[230:233], v[86:89]
	v_mfma_f32_16x16x32_bf16 v[98:101], v[30:33], v[234:237], v[66:69]
	v_mfma_f32_16x16x32_bf16 v[66:69], v[10:13], v[238:241], v[90:93]
	v_mfma_f32_16x16x32_bf16 v[86:89], v[14:17], v[242:245], v[66:69]
	v_mfma_f32_16x16x32_bf16 v[66:69], v[26:29], v[238:241], v[94:97]
	v_mfma_f32_16x16x32_bf16 v[82:85], v[30:33], v[242:245], v[66:69]
	v_mfma_f32_16x16x32_bf16 v[66:69], v[214:217], v[18:21], v[106:109]
	v_mfma_f32_16x16x32_bf16 v[18:21], v[222:225], v[18:21], v[34:37]
	v_mfma_f32_16x16x32_bf16 v[130:133], v[226:229], v[22:25], v[18:21]
	v_mfma_f32_16x16x32_bf16 v[18:21], v[214:217], v[110:113], v[38:41]
	v_mfma_f32_16x16x32_bf16 v[126:129], v[218:221], v[122:125], v[18:21]
	v_mfma_f32_16x16x32_bf16 v[18:21], v[222:225], v[110:113], v[42:45]
	v_mfma_f32_16x16x32_bf16 v[122:125], v[226:229], v[122:125], v[18:21]
	v_mfma_f32_16x16x32_bf16 v[18:21], v[214:217], v[230:233], v[46:49]
	v_mfma_f32_16x16x32_bf16 v[110:113], v[218:221], v[234:237], v[18:21]
	v_mfma_f32_16x16x32_bf16 v[18:21], v[222:225], v[230:233], v[50:53]
	v_mfma_f32_16x16x32_bf16 v[106:109], v[226:229], v[234:237], v[18:21]
	v_mfma_f32_16x16x32_bf16 v[18:21], v[214:217], v[238:241], v[54:57]
	s_barrier
	v_mfma_f32_16x16x32_bf16 v[94:97], v[218:221], v[242:245], v[18:21]
	v_mfma_f32_16x16x32_bf16 v[18:21], v[222:225], v[238:241], v[58:61]
	v_mfma_f32_16x16x32_bf16 v[134:137], v[218:221], v[22:25], v[66:69]
	v_mfma_f32_16x16x32_bf16 v[90:93], v[226:229], v[242:245], v[18:21]
	s_add_i32 s41, s90, s46
	s_nop 3
	v_lshl_add_u64 v[18:19], v[248:249], 0, s[24:25]
	s_mov_b32 m0, s41
	s_add_i32 s50, s41, 0x2000
	ds_read_b128 v[34:37], v162 offset:49152
	ds_read_b128 v[38:41], v162 offset:50176
	ds_read_b128 v[42:45], v162 offset:51200
	ds_read_b128 v[46:49], v162 offset:52224
	ds_read_b128 v[230:233], v162 offset:53248
	ds_read_b128 v[234:237], v162 offset:54272
	ds_read_b128 v[238:241], v162 offset:55296
	ds_read_b128 v[242:245], v162 offset:56320
	global_load_lds_dwordx4 v[18:19], off
	v_lshl_add_u64 v[18:19], v[248:249], 0, s[26:27]
	s_mov_b32 m0, s50
	s_mov_b64 s[56:57], 0x100180
	s_add_i32 s51, s91, s46
	global_load_lds_dwordx4 v[18:19], off
	v_lshl_add_u64 v[18:19], v[248:249], 0, s[56:57]
	s_mov_b32 m0, s51
	s_mov_b64 s[56:57], 0x180180
	s_add_i32 s33, s51, 0x2000
	global_load_lds_dwordx4 v[18:19], off
	v_lshl_add_u64 v[18:19], v[248:249], 0, s[56:57]
	s_mov_b32 m0, s33
	s_nop 0
	global_load_lds_dwordx4 v[18:19], off
	v_lshl_add_u64 v[18:19], v[246:247], 0, s[24:25]
	s_mov_b32 m0, s55
	s_nop 0
	global_load_lds_dwordx4 v[18:19], off
	v_lshl_add_u64 v[18:19], v[246:247], 0, s[26:27]
	s_mov_b32 m0, s62
	s_nop 0
	global_load_lds_dwordx4 v[18:19], off
	s_waitcnt vmcnt(8)
	s_waitcnt lgkmcnt(0)
	s_barrier
	s_waitcnt lgkmcnt(0)
	v_mfma_f32_16x16x32_bf16 v[18:21], v[10:13], v[34:37], v[156:159]
	v_mfma_f32_16x16x32_bf16 v[70:73], v[14:17], v[38:41], v[18:21]
	v_mfma_f32_16x16x32_bf16 v[18:21], v[26:29], v[34:37], v[166:169]
	v_mfma_f32_16x16x32_bf16 v[66:69], v[30:33], v[38:41], v[18:21]
	v_mfma_f32_16x16x32_bf16 v[18:21], v[10:13], v[42:45], v[170:173]
	v_mfma_f32_16x16x32_bf16 v[54:57], v[14:17], v[46:49], v[18:21]
	v_mfma_f32_16x16x32_bf16 v[18:21], v[26:29], v[42:45], v[174:177]
	v_mfma_f32_16x16x32_bf16 v[50:53], v[30:33], v[46:49], v[18:21]
	v_mfma_f32_16x16x32_bf16 v[18:21], v[10:13], v[230:233], v[178:181]
	v_mfma_f32_16x16x32_bf16 v[2:5], v[10:13], v[238:241], v[2:5]
	v_mfma_f32_16x16x32_bf16 v[22:25], v[14:17], v[234:237], v[18:21]
	v_mfma_f32_16x16x32_bf16 v[18:21], v[26:29], v[230:233], v[182:185]
	v_mfma_f32_16x16x32_bf16 v[14:17], v[14:17], v[242:245], v[2:5]
	v_mfma_f32_16x16x32_bf16 v[2:5], v[26:29], v[238:241], v[6:9]
	v_mfma_f32_16x16x32_bf16 v[18:21], v[30:33], v[234:237], v[18:21]
	v_mfma_f32_16x16x32_bf16 v[10:13], v[30:33], v[242:245], v[2:5]
	v_mfma_f32_16x16x32_bf16 v[2:5], v[214:217], v[34:37], v[186:189]
	v_mfma_f32_16x16x32_bf16 v[78:81], v[218:221], v[38:41], v[2:5]
	v_mfma_f32_16x16x32_bf16 v[2:5], v[222:225], v[34:37], v[62:65]
	v_mfma_f32_16x16x32_bf16 v[74:77], v[226:229], v[38:41], v[2:5]
	v_mfma_f32_16x16x32_bf16 v[2:5], v[214:217], v[42:45], v[190:193]
	v_mfma_f32_16x16x32_bf16 v[62:65], v[218:221], v[46:49], v[2:5]
	v_mfma_f32_16x16x32_bf16 v[2:5], v[222:225], v[42:45], v[194:197]
	v_mfma_f32_16x16x32_bf16 v[58:61], v[226:229], v[46:49], v[2:5]
	v_mfma_f32_16x16x32_bf16 v[2:5], v[214:217], v[230:233], v[198:201]
	v_mfma_f32_16x16x32_bf16 v[30:33], v[218:221], v[234:237], v[2:5]
	v_mfma_f32_16x16x32_bf16 v[2:5], v[222:225], v[230:233], v[202:205]
	v_mfma_f32_16x16x32_bf16 v[26:29], v[226:229], v[234:237], v[2:5]
	s_barrier
	v_mfma_f32_16x16x32_bf16 v[2:5], v[214:217], v[238:241], v[206:209]
	v_mfma_f32_16x16x32_bf16 v[6:9], v[218:221], v[242:245], v[2:5]
	v_mfma_f32_16x16x32_bf16 v[2:5], v[222:225], v[238:241], v[210:213]
	v_mfma_f32_16x16x32_bf16 v[2:5], v[226:229], v[242:245], v[2:5]
	s_add_u32 s78, s78, 0x100180
	s_addc_u32 s79, s79, 0
	s_add_u32 s56, s76, 0x200
	s_addc_u32 s57, s77, 0
	s_mov_b32 s76, 0
.LBB0_594:
	ds_read_b128 v[34:37], v160
	ds_read_b128 v[38:41], v160 offset:1024
	ds_read_b128 v[42:45], v160 offset:2048
	ds_read_b128 v[46:49], v160 offset:3072
	ds_read_b128 v[156:159], v161
	ds_read_b128 v[166:169], v161 offset:1024
	ds_read_b128 v[170:173], v161 offset:2048
	ds_read_b128 v[174:177], v161 offset:3072
	s_add_u32 s0, s78, 0xfff00080
	s_addc_u32 s1, s79, -1
	s_cmp_eq_u32 s76, 60
	s_cselect_b32 vcc_hi, s67, s1
	s_cselect_b32 vcc_lo, s69, s0
	s_cselect_b32 s65, s92, s57
	s_cselect_b32 s64, s93, s56
	s_mov_b32 m0, s88
	v_lshl_add_u64 v[210:211], s[78:79], 0, v[150:151]
	ds_read_b128 v[178:181], v162
	ds_read_b128 v[182:185], v162 offset:1024
	ds_read_b128 v[186:189], v162 offset:2048
	ds_read_b128 v[190:193], v162 offset:3072
	ds_read_b128 v[194:197], v162 offset:4096
	ds_read_b128 v[198:201], v162 offset:5120
	ds_read_b128 v[202:205], v162 offset:6144
	ds_read_b128 v[206:209], v162 offset:7168
	global_load_lds_dwordx4 v[210:211], off
	v_lshl_add_u64 v[210:211], v[210:211], 0, s[28:29]
	s_mov_b32 m0, s89
	s_nop 0
	global_load_lds_dwordx4 v[210:211], off
	s_waitcnt vmcnt(8)
	s_waitcnt lgkmcnt(0)
	s_barrier
	s_waitcnt lgkmcnt(0)
	v_mfma_f32_16x16x32_bf16 v[142:145], v[34:37], v[178:181], v[142:145]
	v_mfma_f32_16x16x32_bf16 v[138:141], v[42:45], v[178:181], v[138:141]
	v_mfma_f32_16x16x32_bf16 v[118:121], v[34:37], v[186:189], v[118:121]
	v_mfma_f32_16x16x32_bf16 v[114:117], v[42:45], v[186:189], v[114:117]
	v_mfma_f32_16x16x32_bf16 v[102:105], v[34:37], v[194:197], v[102:105]
	v_mfma_f32_16x16x32_bf16 v[98:101], v[42:45], v[194:197], v[98:101]
	v_mfma_f32_16x16x32_bf16 v[86:89], v[34:37], v[202:205], v[86:89]
	v_mfma_f32_16x16x32_bf16 v[82:85], v[42:45], v[202:205], v[82:85]
	v_mfma_f32_16x16x32_bf16 v[142:145], v[38:41], v[182:185], v[142:145]
	v_mfma_f32_16x16x32_bf16 v[138:141], v[46:49], v[182:185], v[138:141]
	v_mfma_f32_16x16x32_bf16 v[118:121], v[38:41], v[190:193], v[118:121]
	v_mfma_f32_16x16x32_bf16 v[114:117], v[46:49], v[190:193], v[114:117]
	v_mfma_f32_16x16x32_bf16 v[102:105], v[38:41], v[198:201], v[102:105]
	v_mfma_f32_16x16x32_bf16 v[98:101], v[46:49], v[198:201], v[98:101]
	v_mfma_f32_16x16x32_bf16 v[86:89], v[38:41], v[206:209], v[86:89]
	v_mfma_f32_16x16x32_bf16 v[82:85], v[46:49], v[206:209], v[82:85]
	v_mfma_f32_16x16x32_bf16 v[134:137], v[156:159], v[178:181], v[134:137]
	v_mfma_f32_16x16x32_bf16 v[130:133], v[170:173], v[178:181], v[130:133]
	v_mfma_f32_16x16x32_bf16 v[126:129], v[156:159], v[186:189], v[126:129]
	v_mfma_f32_16x16x32_bf16 v[122:125], v[170:173], v[186:189], v[122:125]
	v_mfma_f32_16x16x32_bf16 v[110:113], v[156:159], v[194:197], v[110:113]
	v_mfma_f32_16x16x32_bf16 v[106:109], v[170:173], v[194:197], v[106:109]
	v_mfma_f32_16x16x32_bf16 v[94:97], v[156:159], v[202:205], v[94:97]
	v_mfma_f32_16x16x32_bf16 v[90:93], v[170:173], v[202:205], v[90:93]
	v_mfma_f32_16x16x32_bf16 v[134:137], v[166:169], v[182:185], v[134:137]
	v_mfma_f32_16x16x32_bf16 v[130:133], v[174:177], v[182:185], v[130:133]
	v_mfma_f32_16x16x32_bf16 v[126:129], v[166:169], v[190:193], v[126:129]
	v_mfma_f32_16x16x32_bf16 v[122:125], v[174:177], v[190:193], v[122:125]
	s_barrier
	v_mfma_f32_16x16x32_bf16 v[110:113], v[166:169], v[198:201], v[110:113]
	v_mfma_f32_16x16x32_bf16 v[106:109], v[174:177], v[198:201], v[106:109]
	v_mfma_f32_16x16x32_bf16 v[94:97], v[166:169], v[206:209], v[94:97]
	v_mfma_f32_16x16x32_bf16 v[90:93], v[174:177], v[206:209], v[90:93]
	s_mov_b32 m0, s94
	v_lshl_add_u64 v[210:211], s[64:65], 0, v[148:149]
	ds_read_b128 v[178:181], v162 offset:16384
	ds_read_b128 v[182:185], v162 offset:17408
	ds_read_b128 v[186:189], v162 offset:18432
	ds_read_b128 v[190:193], v162 offset:19456
	ds_read_b128 v[194:197], v162 offset:20480
	ds_read_b128 v[198:201], v162 offset:21504
	ds_read_b128 v[202:205], v162 offset:22528
	ds_read_b128 v[206:209], v162 offset:23552
	global_load_lds_dwordx4 v[210:211], off
	v_lshl_add_u64 v[212:213], v[210:211], 0, s[28:29]
	s_mov_b32 m0, s95
	s_nop 0
	global_load_lds_dwordx4 v[212:213], off
	v_lshl_add_u64 v[212:213], v[210:211], 0, s[30:31]
	s_mov_b32 m0, s96
	s_nop 0
	global_load_lds_dwordx4 v[212:213], off
	v_lshl_add_u64 v[212:213], v[210:211], 0, s[34:35]
	s_mov_b32 m0, s40
	s_nop 0
	global_load_lds_dwordx4 v[212:213], off
	v_lshl_add_u64 v[212:213], vcc, 0, v[146:147]
	s_mov_b32 m0, s47
	v_lshl_add_u64 v[214:215], v[212:213], 0, s[28:29]
	global_load_lds_dwordx4 v[212:213], off
	s_mov_b32 m0, s52
	s_nop 0
	global_load_lds_dwordx4 v[214:215], off
	s_waitcnt vmcnt(8)
	s_waitcnt lgkmcnt(0)
	s_barrier
	s_waitcnt lgkmcnt(0)
	v_mfma_f32_16x16x32_bf16 v[70:73], v[34:37], v[178:181], v[70:73]
	v_mfma_f32_16x16x32_bf16 v[66:69], v[42:45], v[178:181], v[66:69]
	v_mfma_f32_16x16x32_bf16 v[54:57], v[34:37], v[186:189], v[54:57]
	v_mfma_f32_16x16x32_bf16 v[50:53], v[42:45], v[186:189], v[50:53]
	v_mfma_f32_16x16x32_bf16 v[22:25], v[34:37], v[194:197], v[22:25]
	v_mfma_f32_16x16x32_bf16 v[18:21], v[42:45], v[194:197], v[18:21]
	v_mfma_f32_16x16x32_bf16 v[14:17], v[34:37], v[202:205], v[14:17]
	v_mfma_f32_16x16x32_bf16 v[10:13], v[42:45], v[202:205], v[10:13]
	v_mfma_f32_16x16x32_bf16 v[70:73], v[38:41], v[182:185], v[70:73]
	v_mfma_f32_16x16x32_bf16 v[66:69], v[46:49], v[182:185], v[66:69]
	v_mfma_f32_16x16x32_bf16 v[54:57], v[38:41], v[190:193], v[54:57]
	v_mfma_f32_16x16x32_bf16 v[50:53], v[46:49], v[190:193], v[50:53]
	v_mfma_f32_16x16x32_bf16 v[22:25], v[38:41], v[198:201], v[22:25]
	v_mfma_f32_16x16x32_bf16 v[18:21], v[46:49], v[198:201], v[18:21]
	v_mfma_f32_16x16x32_bf16 v[14:17], v[38:41], v[206:209], v[14:17]
	v_mfma_f32_16x16x32_bf16 v[10:13], v[46:49], v[206:209], v[10:13]
	v_mfma_f32_16x16x32_bf16 v[30:33], v[156:159], v[194:197], v[30:33]
	v_mfma_f32_16x16x32_bf16 v[26:29], v[170:173], v[194:197], v[26:29]
	v_mfma_f32_16x16x32_bf16 v[6:9], v[156:159], v[202:205], v[6:9]
	v_mfma_f32_16x16x32_bf16 v[2:5], v[170:173], v[202:205], v[2:5]
	v_mfma_f32_16x16x32_bf16 v[34:37], v[156:159], v[178:181], v[78:81]
	v_mfma_f32_16x16x32_bf16 v[38:41], v[170:173], v[178:181], v[74:77]
	v_mfma_f32_16x16x32_bf16 v[42:45], v[156:159], v[186:189], v[62:65]
	v_mfma_f32_16x16x32_bf16 v[46:49], v[170:173], v[186:189], v[58:61]
	v_mfma_f32_16x16x32_bf16 v[30:33], v[166:169], v[198:201], v[30:33]
	v_mfma_f32_16x16x32_bf16 v[26:29], v[174:177], v[198:201], v[26:29]
	v_mfma_f32_16x16x32_bf16 v[6:9], v[166:169], v[206:209], v[6:9]
	v_mfma_f32_16x16x32_bf16 v[2:5], v[174:177], v[206:209], v[2:5]
	s_barrier
	v_mfma_f32_16x16x32_bf16 v[34:37], v[166:169], v[182:185], v[34:37]
	v_mfma_f32_16x16x32_bf16 v[38:41], v[174:177], v[182:185], v[38:41]
	v_mfma_f32_16x16x32_bf16 v[42:45], v[166:169], v[190:193], v[42:45]
	v_mfma_f32_16x16x32_bf16 v[46:49], v[174:177], v[190:193], v[46:49]
	ds_read_b128 v[58:61], v163
	ds_read_b128 v[62:65], v163 offset:1024
	ds_read_b128 v[74:77], v163 offset:2048
	ds_read_b128 v[78:81], v163 offset:3072
	ds_read_b128 v[156:159], v164
	ds_read_b128 v[166:169], v164 offset:1024
	ds_read_b128 v[170:173], v164 offset:2048
	ds_read_b128 v[174:177], v164 offset:3072
	s_mov_b32 m0, s53
	v_lshl_add_u64 v[214:215], v[212:213], 0, s[30:31]
	ds_read_b128 v[178:181], v162 offset:32768
	ds_read_b128 v[182:185], v162 offset:33792
	ds_read_b128 v[186:189], v162 offset:34816
	ds_read_b128 v[190:193], v162 offset:35840
	ds_read_b128 v[194:197], v162 offset:36864
	ds_read_b128 v[198:201], v162 offset:37888
	ds_read_b128 v[202:205], v162 offset:38912
	ds_read_b128 v[206:209], v162 offset:39936
	global_load_lds_dwordx4 v[214:215], off
	v_lshl_add_u64 v[214:215], v[212:213], 0, s[34:35]
	s_mov_b32 m0, s54
	s_nop 0
	global_load_lds_dwordx4 v[214:215], off
	s_waitcnt vmcnt(8)
	s_waitcnt lgkmcnt(0)
	s_barrier
	s_waitcnt lgkmcnt(0)
	v_mfma_f32_16x16x32_bf16 v[142:145], v[58:61], v[178:181], v[142:145]
	v_mfma_f32_16x16x32_bf16 v[138:141], v[74:77], v[178:181], v[138:141]
	v_mfma_f32_16x16x32_bf16 v[118:121], v[58:61], v[186:189], v[118:121]
	v_mfma_f32_16x16x32_bf16 v[114:117], v[74:77], v[186:189], v[114:117]
	v_mfma_f32_16x16x32_bf16 v[102:105], v[58:61], v[194:197], v[102:105]
	v_mfma_f32_16x16x32_bf16 v[98:101], v[74:77], v[194:197], v[98:101]
	v_mfma_f32_16x16x32_bf16 v[86:89], v[58:61], v[202:205], v[86:89]
	v_mfma_f32_16x16x32_bf16 v[82:85], v[74:77], v[202:205], v[82:85]
	v_mfma_f32_16x16x32_bf16 v[142:145], v[62:65], v[182:185], v[142:145]
	v_mfma_f32_16x16x32_bf16 v[138:141], v[78:81], v[182:185], v[138:141]
	v_mfma_f32_16x16x32_bf16 v[118:121], v[62:65], v[190:193], v[118:121]
	v_mfma_f32_16x16x32_bf16 v[114:117], v[78:81], v[190:193], v[114:117]
	v_mfma_f32_16x16x32_bf16 v[102:105], v[62:65], v[198:201], v[102:105]
	v_mfma_f32_16x16x32_bf16 v[98:101], v[78:81], v[198:201], v[98:101]
	v_mfma_f32_16x16x32_bf16 v[86:89], v[62:65], v[206:209], v[86:89]
	v_mfma_f32_16x16x32_bf16 v[82:85], v[78:81], v[206:209], v[82:85]
	v_mfma_f32_16x16x32_bf16 v[134:137], v[156:159], v[178:181], v[134:137]
	v_mfma_f32_16x16x32_bf16 v[130:133], v[170:173], v[178:181], v[130:133]
	v_mfma_f32_16x16x32_bf16 v[126:129], v[156:159], v[186:189], v[126:129]
	v_mfma_f32_16x16x32_bf16 v[122:125], v[170:173], v[186:189], v[122:125]
	v_mfma_f32_16x16x32_bf16 v[110:113], v[156:159], v[194:197], v[110:113]
	v_mfma_f32_16x16x32_bf16 v[106:109], v[170:173], v[194:197], v[106:109]
	v_mfma_f32_16x16x32_bf16 v[94:97], v[156:159], v[202:205], v[94:97]
	v_mfma_f32_16x16x32_bf16 v[90:93], v[170:173], v[202:205], v[90:93]
	v_mfma_f32_16x16x32_bf16 v[134:137], v[166:169], v[182:185], v[134:137]
	v_mfma_f32_16x16x32_bf16 v[130:133], v[174:177], v[182:185], v[130:133]
	v_mfma_f32_16x16x32_bf16 v[126:129], v[166:169], v[190:193], v[126:129]
	v_mfma_f32_16x16x32_bf16 v[122:125], v[174:177], v[190:193], v[122:125]
	s_barrier
; #define PG8_WAIT_V(n) asm volatile("s_waitcnt vmcnt(" #n ")" ::: "memory")
; template <class Epi, class Sched, bool ALIGN_EPI = true, bool SP2 = true, bool FULLLINE = false, bool NOSTAGE = false, bool FP8 = false>
; __device__ __forceinline__ void gemm_phase(PG8_LAS unsigned char* lds, const Gemm g, const Sched& S, const Epi& E) {
;     ...
;         static_assert(SP2, "only the SP2 loop is kept");
;         { const int t = 0; if constexpr (Epi::NST == 16) PG8_ITER(PG8_WAIT_V(24)); else if constexpr (Epi::NST == 8) PG8_ITER(PG8_WAIT_V(16)); else PG8_ITER(PG8_WAIT_V(8)); }
;         for (int t = 2; t < nt; t += 2) PG8_ITER(PG8_WAIT_V(8));
	v_mfma_f32_16x16x32_bf16 v[110:113], v[166:169], v[198:201], v[110:113]
	v_mfma_f32_16x16x32_bf16 v[106:109], v[174:177], v[198:201], v[106:109]
	v_mfma_f32_16x16x32_bf16 v[94:97], v[166:169], v[206:209], v[94:97]
	v_mfma_f32_16x16x32_bf16 v[90:93], v[174:177], v[206:209], v[90:93]
	s_mov_b32 m0, s41
	v_lshl_add_u64 v[214:215], v[210:211], 0, s[36:37]
	ds_read_b128 v[178:181], v162 offset:49152
	ds_read_b128 v[182:185], v162 offset:50176
	ds_read_b128 v[186:189], v162 offset:51200
	ds_read_b128 v[190:193], v162 offset:52224
	ds_read_b128 v[194:197], v162 offset:53248
	ds_read_b128 v[198:201], v162 offset:54272
	ds_read_b128 v[202:205], v162 offset:55296
	ds_read_b128 v[206:209], v162 offset:56320
	global_load_lds_dwordx4 v[214:215], off
	v_lshl_add_u64 v[214:215], v[210:211], 0, s[38:39]
	s_mov_b32 m0, s50
	s_nop 0
	global_load_lds_dwordx4 v[214:215], off
	v_lshl_add_u64 v[214:215], v[210:211], 0, s[12:13]
	s_mov_b32 m0, s51
	v_lshl_add_u64 v[210:211], v[210:211], 0, s[14:15]
	global_load_lds_dwordx4 v[214:215], off
	s_mov_b32 m0, s33
	s_nop 0
	global_load_lds_dwordx4 v[210:211], off
	v_lshl_add_u64 v[210:211], v[212:213], 0, s[36:37]
	s_mov_b32 m0, s55
	s_nop 0
	global_load_lds_dwordx4 v[210:211], off
	v_lshl_add_u64 v[210:211], v[212:213], 0, s[38:39]
	s_mov_b32 m0, s62
	s_nop 0
	global_load_lds_dwordx4 v[210:211], off
	s_waitcnt vmcnt(8)
	s_waitcnt lgkmcnt(0)
	s_barrier
	s_waitcnt lgkmcnt(0)
	v_mfma_f32_16x16x32_bf16 v[70:73], v[58:61], v[178:181], v[70:73]
	v_mfma_f32_16x16x32_bf16 v[66:69], v[74:77], v[178:181], v[66:69]
	v_mfma_f32_16x16x32_bf16 v[54:57], v[58:61], v[186:189], v[54:57]
	v_mfma_f32_16x16x32_bf16 v[50:53], v[74:77], v[186:189], v[50:53]
	v_mfma_f32_16x16x32_bf16 v[22:25], v[58:61], v[194:197], v[22:25]
	v_mfma_f32_16x16x32_bf16 v[18:21], v[74:77], v[194:197], v[18:21]
	v_mfma_f32_16x16x32_bf16 v[14:17], v[58:61], v[202:205], v[14:17]
	v_mfma_f32_16x16x32_bf16 v[10:13], v[74:77], v[202:205], v[10:13]
	v_mfma_f32_16x16x32_bf16 v[70:73], v[62:65], v[182:185], v[70:73]
	v_mfma_f32_16x16x32_bf16 v[66:69], v[78:81], v[182:185], v[66:69]
	v_mfma_f32_16x16x32_bf16 v[54:57], v[62:65], v[190:193], v[54:57]
	v_mfma_f32_16x16x32_bf16 v[50:53], v[78:81], v[190:193], v[50:53]
	v_mfma_f32_16x16x32_bf16 v[22:25], v[62:65], v[198:201], v[22:25]
	v_mfma_f32_16x16x32_bf16 v[18:21], v[78:81], v[198:201], v[18:21]
	v_mfma_f32_16x16x32_bf16 v[14:17], v[62:65], v[206:209], v[14:17]
	v_mfma_f32_16x16x32_bf16 v[10:13], v[78:81], v[206:209], v[10:13]
	v_mfma_f32_16x16x32_bf16 v[34:37], v[156:159], v[178:181], v[34:37]
	v_mfma_f32_16x16x32_bf16 v[78:81], v[166:169], v[182:185], v[34:37]
	v_mfma_f32_16x16x32_bf16 v[34:37], v[170:173], v[178:181], v[38:41]
	v_mfma_f32_16x16x32_bf16 v[74:77], v[174:177], v[182:185], v[34:37]
	v_mfma_f32_16x16x32_bf16 v[34:37], v[156:159], v[186:189], v[42:45]
	v_mfma_f32_16x16x32_bf16 v[62:65], v[166:169], v[190:193], v[34:37]
	v_mfma_f32_16x16x32_bf16 v[34:37], v[170:173], v[186:189], v[46:49]
	v_mfma_f32_16x16x32_bf16 v[30:33], v[156:159], v[194:197], v[30:33]
	v_mfma_f32_16x16x32_bf16 v[26:29], v[170:173], v[194:197], v[26:29]
	v_mfma_f32_16x16x32_bf16 v[6:9], v[156:159], v[202:205], v[6:9]
	v_mfma_f32_16x16x32_bf16 v[2:5], v[170:173], v[202:205], v[2:5]
	v_mfma_f32_16x16x32_bf16 v[58:61], v[174:177], v[190:193], v[34:37]
	s_barrier
	v_mfma_f32_16x16x32_bf16 v[30:33], v[166:169], v[198:201], v[30:33]
	v_mfma_f32_16x16x32_bf16 v[26:29], v[174:177], v[198:201], v[26:29]
	v_mfma_f32_16x16x32_bf16 v[6:9], v[166:169], v[206:209], v[6:9]
	v_mfma_f32_16x16x32_bf16 v[2:5], v[174:177], v[206:209], v[2:5]
	s_add_i32 s76, s76, 2
	s_add_u32 s78, s78, 0x100
	s_addc_u32 s79, s79, 0
	s_add_u32 s56, s56, 0x100
	s_addc_u32 s57, s57, 0
	s_cmp_gt_u32 s76, 61
	s_cbranch_scc0 .LBB0_594
	s_and_b64 vcc, exec, s[10:11]
	s_cbranch_vccz .LBB0_597
	s_barrier

; template <class Epi, class Sched, bool ALIGN_EPI = true, bool SP2 = true, bool FULLLINE = false, bool NOSTAGE = false, bool FP8 = false>
; __device__ __forceinline__ void gemm_phase(PG8_LAS unsigned char* lds, const Gemm g, const Sched& S, const Epi& E) {
;     ...
;         const bool has_next = S.next(ui + 1, nxt);
;         const char* nA = has_next ? PG8_ABASE(nxt) : cA; const char* nB = has_next ? PG8_BBASE(nxt) : cB;
.LBB0_766:
	s_ashr_i32 s69, s68, 31
	s_lshl_b64 s[40:41], s[68:69], 20
	s_add_u32 s70, s58, s40
	ds_read_b128 v[2:5], v1
	ds_read_b128 v[6:9], v1 offset:1024
	ds_read_b128 v[10:13], v1 offset:2048
	ds_read_b128 v[14:17], v1 offset:3072
	ds_read_b128 v[18:21], v142
	ds_read_b128 v[22:25], v142 offset:1024
	ds_read_b128 v[26:29], v142 offset:2048
	ds_read_b128 v[30:33], v142 offset:3072
	s_addc_u32 s71, s59, s41
	s_ashr_i32 s67, s66, 31
	s_lshl_b64 s[40:41], s[66:67], 20
	s_add_u32 s72, s3, s40
	s_addc_u32 s73, s42, s41
	s_and_b64 s[40:41], s[8:9], exec
	s_cselect_b32 s67, s71, s79
	s_cselect_b32 s69, s70, s78
	s_cselect_b32 s89, s73, s77
	s_cselect_b32 s90, s72, s76
	v_lshl_add_u64 v[140:141], s[78:79], 0, v[132:133]
	s_mov_b32 m0, s81
	v_lshl_add_u64 v[66:67], v[140:141], 0, s[12:13]
	ds_read_b128 v[34:37], v143
	ds_read_b128 v[38:41], v143 offset:1024
	ds_read_b128 v[42:45], v143 offset:2048
	ds_read_b128 v[46:49], v143 offset:3072
	ds_read_b128 v[50:53], v143 offset:4096
	ds_read_b128 v[54:57], v143 offset:5120
	ds_read_b128 v[58:61], v143 offset:6144
	ds_read_b128 v[62:65], v143 offset:7168
	global_load_lds_dwordx4 v[66:67], off
	v_lshl_add_u64 v[66:67], v[140:141], 0, s[14:15]
	s_mov_b32 m0, s82
	s_nop 0
	global_load_lds_dwordx4 v[66:67], off
	s_waitcnt vmcnt(16)
	s_waitcnt lgkmcnt(0)
	s_barrier
	s_waitcnt lgkmcnt(0)
	v_mfma_f32_16x16x32_bf16 v[86:89], v[10:13], v[50:53], 0
	v_mfma_f32_16x16x32_bf16 v[90:93], v[14:17], v[54:57], v[86:89]
	v_mfma_f32_16x16x32_bf16 v[86:89], v[2:5], v[58:61], 0
	v_mfma_f32_16x16x32_bf16 v[66:69], v[2:5], v[34:37], 0
	v_mfma_f32_16x16x32_bf16 v[70:73], v[10:13], v[34:37], 0
	v_mfma_f32_16x16x32_bf16 v[74:77], v[2:5], v[42:45], 0
	v_mfma_f32_16x16x32_bf16 v[78:81], v[10:13], v[42:45], 0
	v_mfma_f32_16x16x32_bf16 v[82:85], v[2:5], v[50:53], 0
	v_mfma_f32_16x16x32_bf16 v[94:97], v[6:9], v[62:65], v[86:89]
	v_mfma_f32_16x16x32_bf16 v[86:89], v[10:13], v[58:61], 0
	v_mfma_f32_16x16x32_bf16 v[66:69], v[6:9], v[38:41], v[66:69]
	v_mfma_f32_16x16x32_bf16 v[70:73], v[14:17], v[38:41], v[70:73]
	v_mfma_f32_16x16x32_bf16 v[74:77], v[6:9], v[46:49], v[74:77]
	v_mfma_f32_16x16x32_bf16 v[78:81], v[14:17], v[46:49], v[78:81]
	v_mfma_f32_16x16x32_bf16 v[82:85], v[6:9], v[54:57], v[82:85]
	v_mfma_f32_16x16x32_bf16 v[106:109], v[14:17], v[62:65], v[86:89]
	v_mfma_f32_16x16x32_bf16 v[86:89], v[18:21], v[34:37], 0
	v_mfma_f32_16x16x32_bf16 v[34:37], v[26:29], v[34:37], 0
	v_mfma_f32_16x16x32_bf16 v[110:113], v[22:25], v[38:41], v[86:89]
	v_mfma_f32_16x16x32_bf16 v[34:37], v[30:33], v[38:41], v[34:37]
	v_mfma_f32_16x16x32_bf16 v[38:41], v[18:21], v[42:45], 0
	v_mfma_f32_16x16x32_bf16 v[42:45], v[26:29], v[42:45], 0
	v_mfma_f32_16x16x32_bf16 v[38:41], v[22:25], v[46:49], v[38:41]
	v_mfma_f32_16x16x32_bf16 v[42:45], v[30:33], v[46:49], v[42:45]
	v_mfma_f32_16x16x32_bf16 v[46:49], v[18:21], v[50:53], 0
	v_mfma_f32_16x16x32_bf16 v[50:53], v[26:29], v[50:53], 0
	v_mfma_f32_16x16x32_bf16 v[46:49], v[22:25], v[54:57], v[46:49]
	v_mfma_f32_16x16x32_bf16 v[50:53], v[30:33], v[54:57], v[50:53]
	s_barrier
	v_mfma_f32_16x16x32_bf16 v[54:57], v[18:21], v[58:61], 0
	v_mfma_f32_16x16x32_bf16 v[58:61], v[26:29], v[58:61], 0
	v_mfma_f32_16x16x32_bf16 v[54:57], v[22:25], v[62:65], v[54:57]
	v_mfma_f32_16x16x32_bf16 v[58:61], v[30:33], v[62:65], v[58:61]
	v_lshl_add_u64 v[238:239], s[76:77], 0, v[130:131]
	s_mov_b32 m0, s83
	v_lshl_add_u64 v[146:147], v[238:239], 0, s[16:17]
	s_add_i32 s91, s83, 0x2000
	ds_read_b128 v[62:65], v143 offset:16384
	ds_read_b128 v[86:89], v143 offset:17408
	ds_read_b128 v[98:101], v143 offset:18432
	ds_read_b128 v[102:105], v143 offset:19456
	ds_read_b128 v[114:117], v143 offset:20480
	ds_read_b128 v[118:121], v143 offset:21504
	ds_read_b128 v[122:125], v143 offset:22528
	ds_read_b128 v[126:129], v143 offset:23552
	global_load_lds_dwordx4 v[146:147], off
	v_lshl_add_u64 v[146:147], v[238:239], 0, s[18:19]
	s_mov_b32 m0, s91
	s_add_i32 s92, s80, s43
	global_load_lds_dwordx4 v[146:147], off
	v_lshl_add_u64 v[146:147], v[238:239], 0, s[20:21]
	s_mov_b32 m0, s92
	s_add_i32 s40, s92, 0x2000
	global_load_lds_dwordx4 v[146:147], off
	v_lshl_add_u64 v[146:147], v[238:239], 0, s[22:23]
	s_mov_b32 m0, s40
	s_nop 0
	global_load_lds_dwordx4 v[146:147], off
	v_lshl_add_u64 v[146:147], v[140:141], 0, s[16:17]
	s_mov_b32 m0, s45
	s_nop 0
	global_load_lds_dwordx4 v[146:147], off
	v_lshl_add_u64 v[146:147], v[140:141], 0, s[18:19]
	s_mov_b32 m0, s46
	s_nop 0
	global_load_lds_dwordx4 v[146:147], off
	s_waitcnt vmcnt(16)
	s_waitcnt lgkmcnt(0)
	s_barrier
	s_waitcnt lgkmcnt(0)
	v_mfma_f32_16x16x32_bf16 v[146:149], v[2:5], v[62:65], 0
	v_mfma_f32_16x16x32_bf16 v[154:157], v[2:5], v[98:101], 0
	v_mfma_f32_16x16x32_bf16 v[162:165], v[2:5], v[114:117], 0
	v_mfma_f32_16x16x32_bf16 v[2:5], v[2:5], v[122:125], 0
	v_mfma_f32_16x16x32_bf16 v[146:149], v[6:9], v[86:89], v[146:149]
	v_mfma_f32_16x16x32_bf16 v[154:157], v[6:9], v[102:105], v[154:157]
	v_mfma_f32_16x16x32_bf16 v[162:165], v[6:9], v[118:121], v[162:165]
	v_mfma_f32_16x16x32_bf16 v[2:5], v[6:9], v[126:129], v[2:5]
	v_mfma_f32_16x16x32_bf16 v[6:9], v[10:13], v[122:125], 0
	v_mfma_f32_16x16x32_bf16 v[150:153], v[10:13], v[62:65], 0
	v_mfma_f32_16x16x32_bf16 v[158:161], v[10:13], v[98:101], 0
	v_mfma_f32_16x16x32_bf16 v[166:169], v[10:13], v[114:117], 0
	v_mfma_f32_16x16x32_bf16 v[10:13], v[14:17], v[126:129], v[6:9]
	v_mfma_f32_16x16x32_bf16 v[150:153], v[14:17], v[86:89], v[150:153]
	v_mfma_f32_16x16x32_bf16 v[158:161], v[14:17], v[102:105], v[158:161]
	v_mfma_f32_16x16x32_bf16 v[166:169], v[14:17], v[118:121], v[166:169]
	v_mfma_f32_16x16x32_bf16 v[6:9], v[18:21], v[62:65], 0
	v_mfma_f32_16x16x32_bf16 v[14:17], v[22:25], v[86:89], v[6:9]
	v_mfma_f32_16x16x32_bf16 v[6:9], v[26:29], v[62:65], 0
	v_mfma_f32_16x16x32_bf16 v[170:173], v[30:33], v[86:89], v[6:9]
	v_mfma_f32_16x16x32_bf16 v[6:9], v[18:21], v[98:101], 0
	v_mfma_f32_16x16x32_bf16 v[174:177], v[22:25], v[102:105], v[6:9]
	v_mfma_f32_16x16x32_bf16 v[6:9], v[26:29], v[98:101], 0
	v_mfma_f32_16x16x32_bf16 v[178:181], v[30:33], v[102:105], v[6:9]
	v_mfma_f32_16x16x32_bf16 v[6:9], v[18:21], v[114:117], 0
	v_mfma_f32_16x16x32_bf16 v[182:185], v[22:25], v[118:121], v[6:9]
	v_mfma_f32_16x16x32_bf16 v[6:9], v[26:29], v[114:117], 0
	v_mfma_f32_16x16x32_bf16 v[186:189], v[30:33], v[118:121], v[6:9]
	s_barrier
	v_mfma_f32_16x16x32_bf16 v[6:9], v[18:21], v[122:125], 0
	v_mfma_f32_16x16x32_bf16 v[190:193], v[22:25], v[126:129], v[6:9]
	v_mfma_f32_16x16x32_bf16 v[6:9], v[26:29], v[122:125], 0
	v_mfma_f32_16x16x32_bf16 v[194:197], v[30:33], v[126:129], v[6:9]
	s_nop 5
	ds_read_b128 v[6:9], v144
	ds_read_b128 v[26:29], v144 offset:1024
	ds_read_b128 v[30:33], v144 offset:2048
	ds_read_b128 v[62:65], v144 offset:3072
	ds_read_b128 v[198:201], v145
	ds_read_b128 v[202:205], v145 offset:1024
	ds_read_b128 v[206:209], v145 offset:2048
	ds_read_b128 v[210:213], v145 offset:3072
	s_mov_b32 m0, s47
	v_lshl_add_u64 v[86:87], v[140:141], 0, s[20:21]
	ds_read_b128 v[18:21], v143 offset:32768
	ds_read_b128 v[22:25], v143 offset:33792
	ds_read_b128 v[214:217], v143 offset:34816
	ds_read_b128 v[218:221], v143 offset:35840
	ds_read_b128 v[222:225], v143 offset:36864
	ds_read_b128 v[226:229], v143 offset:37888
	ds_read_b128 v[230:233], v143 offset:38912
	ds_read_b128 v[234:237], v143 offset:39936
	global_load_lds_dwordx4 v[86:87], off
	v_lshl_add_u64 v[86:87], v[140:141], 0, s[22:23]
	s_mov_b32 m0, s52
	s_nop 0
	global_load_lds_dwordx4 v[86:87], off
	s_waitcnt vmcnt(8)
	s_waitcnt lgkmcnt(0)
	s_barrier
	s_waitcnt lgkmcnt(0)
	v_mfma_f32_16x16x32_bf16 v[66:69], v[6:9], v[18:21], v[66:69]
	v_mfma_f32_16x16x32_bf16 v[118:121], v[26:29], v[22:25], v[66:69]
	v_mfma_f32_16x16x32_bf16 v[66:69], v[30:33], v[18:21], v[70:73]
	v_mfma_f32_16x16x32_bf16 v[114:117], v[62:65], v[22:25], v[66:69]
	v_mfma_f32_16x16x32_bf16 v[66:69], v[6:9], v[214:217], v[74:77]
	v_mfma_f32_16x16x32_bf16 v[102:105], v[26:29], v[218:221], v[66:69]
	v_mfma_f32_16x16x32_bf16 v[66:69], v[30:33], v[214:217], v[78:81]
	v_mfma_f32_16x16x32_bf16 v[98:101], v[62:65], v[218:221], v[66:69]
	v_mfma_f32_16x16x32_bf16 v[66:69], v[6:9], v[222:225], v[82:85]
	v_mfma_f32_16x16x32_bf16 v[86:89], v[26:29], v[226:229], v[66:69]
	v_mfma_f32_16x16x32_bf16 v[66:69], v[30:33], v[222:225], v[90:93]
	v_mfma_f32_16x16x32_bf16 v[82:85], v[62:65], v[226:229], v[66:69]
	v_mfma_f32_16x16x32_bf16 v[66:69], v[6:9], v[230:233], v[94:97]
	v_mfma_f32_16x16x32_bf16 v[70:73], v[26:29], v[234:237], v[66:69]
	v_mfma_f32_16x16x32_bf16 v[66:69], v[30:33], v[230:233], v[106:109]
	v_mfma_f32_16x16x32_bf16 v[66:69], v[62:65], v[234:237], v[66:69]
	v_mfma_f32_16x16x32_bf16 v[74:77], v[198:201], v[18:21], v[110:113]
	v_mfma_f32_16x16x32_bf16 v[18:21], v[206:209], v[18:21], v[34:37]
	v_mfma_f32_16x16x32_bf16 v[122:125], v[210:213], v[22:25], v[18:21]
	v_mfma_f32_16x16x32_bf16 v[18:21], v[198:201], v[214:217], v[38:41]
	v_mfma_f32_16x16x32_bf16 v[110:113], v[202:205], v[218:221], v[18:21]
	v_mfma_f32_16x16x32_bf16 v[18:21], v[206:209], v[214:217], v[42:45]
	v_mfma_f32_16x16x32_bf16 v[106:109], v[210:213], v[218:221], v[18:21]
	v_mfma_f32_16x16x32_bf16 v[18:21], v[198:201], v[222:225], v[46:49]
	v_mfma_f32_16x16x32_bf16 v[94:97], v[202:205], v[226:229], v[18:21]
	v_mfma_f32_16x16x32_bf16 v[18:21], v[206:209], v[222:225], v[50:53]
	v_mfma_f32_16x16x32_bf16 v[90:93], v[210:213], v[226:229], v[18:21]
	v_mfma_f32_16x16x32_bf16 v[18:21], v[198:201], v[230:233], v[54:57]
	s_barrier
	v_mfma_f32_16x16x32_bf16 v[78:81], v[202:205], v[234:237], v[18:21]
	v_mfma_f32_16x16x32_bf16 v[18:21], v[206:209], v[230:233], v[58:61]
	v_mfma_f32_16x16x32_bf16 v[126:129], v[202:205], v[22:25], v[74:77]
	v_mfma_f32_16x16x32_bf16 v[74:77], v[210:213], v[234:237], v[18:21]
	s_add_i32 s41, s84, s43
	s_nop 3
	v_lshl_add_u64 v[18:19], v[238:239], 0, s[24:25]
	s_mov_b32 m0, s41
	s_add_i32 s50, s41, 0x2000
	ds_read_b128 v[42:45], v143 offset:49152
	ds_read_b128 v[46:49], v143 offset:50176
	ds_read_b128 v[214:217], v143 offset:51200
	ds_read_b128 v[218:221], v143 offset:52224
	ds_read_b128 v[222:225], v143 offset:53248
	ds_read_b128 v[226:229], v143 offset:54272
	ds_read_b128 v[230:233], v143 offset:55296
	ds_read_b128 v[234:237], v143 offset:56320
	global_load_lds_dwordx4 v[18:19], off
	v_lshl_add_u64 v[18:19], v[238:239], 0, s[26:27]
	s_mov_b32 m0, s50
	s_mov_b64 s[56:57], 0x80180
	s_add_i32 s51, s85, s43
	global_load_lds_dwordx4 v[18:19], off
	v_lshl_add_u64 v[18:19], v[238:239], 0, s[56:57]
	s_mov_b32 m0, s51
	s_mov_b64 s[56:57], 0xc0180
	s_add_i32 s33, s51, 0x2000
	global_load_lds_dwordx4 v[18:19], off
	v_lshl_add_u64 v[18:19], v[238:239], 0, s[56:57]
	s_mov_b32 m0, s33
	s_nop 0
	global_load_lds_dwordx4 v[18:19], off
	v_lshl_add_u64 v[18:19], v[140:141], 0, s[24:25]
	s_mov_b32 m0, s53
	s_nop 0
	global_load_lds_dwordx4 v[18:19], off
	v_lshl_add_u64 v[18:19], v[140:141], 0, s[26:27]
	s_mov_b32 m0, s54
	s_nop 0
	global_load_lds_dwordx4 v[18:19], off
	s_waitcnt vmcnt(8)
	s_waitcnt lgkmcnt(0)
	s_barrier
	s_waitcnt lgkmcnt(0)
	v_mfma_f32_16x16x32_bf16 v[18:21], v[6:9], v[42:45], v[146:149]
	v_mfma_f32_16x16x32_bf16 v[54:57], v[26:29], v[46:49], v[18:21]
	v_mfma_f32_16x16x32_bf16 v[18:21], v[30:33], v[42:45], v[150:153]
	v_mfma_f32_16x16x32_bf16 v[50:53], v[62:65], v[46:49], v[18:21]
	v_mfma_f32_16x16x32_bf16 v[18:21], v[6:9], v[214:217], v[154:157]
	v_mfma_f32_16x16x32_bf16 v[38:41], v[26:29], v[218:221], v[18:21]
	v_mfma_f32_16x16x32_bf16 v[18:21], v[30:33], v[214:217], v[158:161]
	v_mfma_f32_16x16x32_bf16 v[34:37], v[62:65], v[218:221], v[18:21]
	v_mfma_f32_16x16x32_bf16 v[18:21], v[6:9], v[222:225], v[162:165]
	v_mfma_f32_16x16x32_bf16 v[2:5], v[6:9], v[230:233], v[2:5]
	v_mfma_f32_16x16x32_bf16 v[22:25], v[26:29], v[226:229], v[18:21]
	v_mfma_f32_16x16x32_bf16 v[18:21], v[30:33], v[222:225], v[166:169]
	v_mfma_f32_16x16x32_bf16 v[6:9], v[26:29], v[234:237], v[2:5]
	v_mfma_f32_16x16x32_bf16 v[2:5], v[30:33], v[230:233], v[10:13]
	v_mfma_f32_16x16x32_bf16 v[18:21], v[62:65], v[226:229], v[18:21]
	v_mfma_f32_16x16x32_bf16 v[2:5], v[62:65], v[234:237], v[2:5]
	v_mfma_f32_16x16x32_bf16 v[10:13], v[198:201], v[42:45], v[14:17]
	v_mfma_f32_16x16x32_bf16 v[62:65], v[202:205], v[46:49], v[10:13]
	v_mfma_f32_16x16x32_bf16 v[10:13], v[206:209], v[42:45], v[170:173]
	v_mfma_f32_16x16x32_bf16 v[58:61], v[210:213], v[46:49], v[10:13]
	v_mfma_f32_16x16x32_bf16 v[10:13], v[198:201], v[214:217], v[174:177]
	v_mfma_f32_16x16x32_bf16 v[46:49], v[202:205], v[218:221], v[10:13]
	v_mfma_f32_16x16x32_bf16 v[10:13], v[206:209], v[214:217], v[178:181]
	v_mfma_f32_16x16x32_bf16 v[42:45], v[210:213], v[218:221], v[10:13]
	v_mfma_f32_16x16x32_bf16 v[10:13], v[198:201], v[222:225], v[182:185]
	v_mfma_f32_16x16x32_bf16 v[30:33], v[202:205], v[226:229], v[10:13]
	v_mfma_f32_16x16x32_bf16 v[10:13], v[206:209], v[222:225], v[186:189]
	v_mfma_f32_16x16x32_bf16 v[26:29], v[210:213], v[226:229], v[10:13]
	s_barrier
	v_mfma_f32_16x16x32_bf16 v[10:13], v[198:201], v[230:233], v[190:193]
	v_mfma_f32_16x16x32_bf16 v[14:17], v[202:205], v[234:237], v[10:13]
	v_mfma_f32_16x16x32_bf16 v[10:13], v[206:209], v[230:233], v[194:197]
	v_mfma_f32_16x16x32_bf16 v[10:13], v[210:213], v[234:237], v[10:13]
	s_add_u32 s78, s78, 0x80180
	s_addc_u32 s79, s79, 0
	s_add_u32 s56, s76, 0x200
	s_addc_u32 s57, s77, 0
	s_mov_b32 s76, 0
.LBB0_767:
	ds_read_b128 v[146:149], v1
	ds_read_b128 v[150:153], v1 offset:1024
	ds_read_b128 v[154:157], v1 offset:2048
	ds_read_b128 v[158:161], v1 offset:3072
	ds_read_b128 v[162:165], v142
	ds_read_b128 v[166:169], v142 offset:1024
	ds_read_b128 v[170:173], v142 offset:2048
	ds_read_b128 v[174:177], v142 offset:3072
	s_add_u32 s0, s78, 0xfff80080
	s_addc_u32 s1, s79, -1
	s_cmp_eq_u32 s76, 28
	s_cselect_b32 s95, s67, s1
	s_cselect_b32 s94, s69, s0
	s_cselect_b32 s97, s89, s57
	s_cselect_b32 s96, s90, s56
	s_mov_b32 m0, s81
	v_lshl_add_u64 v[140:141], s[78:79], 0, v[134:135]
	ds_read_b128 v[178:181], v143
	ds_read_b128 v[182:185], v143 offset:1024
	ds_read_b128 v[186:189], v143 offset:2048
	ds_read_b128 v[190:193], v143 offset:3072
	ds_read_b128 v[194:197], v143 offset:4096
	ds_read_b128 v[198:201], v143 offset:5120
	ds_read_b128 v[202:205], v143 offset:6144
	ds_read_b128 v[206:209], v143 offset:7168
	global_load_lds_dwordx4 v[140:141], off
	v_lshl_add_u64 v[140:141], v[140:141], 0, s[28:29]
	s_mov_b32 m0, s82
	s_nop 0
	global_load_lds_dwordx4 v[140:141], off
	s_waitcnt vmcnt(8)
	s_waitcnt lgkmcnt(0)
	s_barrier
	s_waitcnt lgkmcnt(0)
	v_mfma_f32_16x16x32_bf16 v[118:121], v[146:149], v[178:181], v[118:121]
	v_mfma_f32_16x16x32_bf16 v[114:117], v[154:157], v[178:181], v[114:117]
	v_mfma_f32_16x16x32_bf16 v[102:105], v[146:149], v[186:189], v[102:105]
	v_mfma_f32_16x16x32_bf16 v[98:101], v[154:157], v[186:189], v[98:101]
	v_mfma_f32_16x16x32_bf16 v[86:89], v[146:149], v[194:197], v[86:89]
	v_mfma_f32_16x16x32_bf16 v[82:85], v[154:157], v[194:197], v[82:85]
	v_mfma_f32_16x16x32_bf16 v[70:73], v[146:149], v[202:205], v[70:73]
	v_mfma_f32_16x16x32_bf16 v[66:69], v[154:157], v[202:205], v[66:69]
	v_mfma_f32_16x16x32_bf16 v[118:121], v[150:153], v[182:185], v[118:121]
	v_mfma_f32_16x16x32_bf16 v[114:117], v[158:161], v[182:185], v[114:117]
	v_mfma_f32_16x16x32_bf16 v[102:105], v[150:153], v[190:193], v[102:105]
	v_mfma_f32_16x16x32_bf16 v[98:101], v[158:161], v[190:193], v[98:101]
	v_mfma_f32_16x16x32_bf16 v[86:89], v[150:153], v[198:201], v[86:89]
	v_mfma_f32_16x16x32_bf16 v[82:85], v[158:161], v[198:201], v[82:85]
	v_mfma_f32_16x16x32_bf16 v[70:73], v[150:153], v[206:209], v[70:73]
	v_mfma_f32_16x16x32_bf16 v[66:69], v[158:161], v[206:209], v[66:69]
	v_mfma_f32_16x16x32_bf16 v[126:129], v[162:165], v[178:181], v[126:129]
	v_mfma_f32_16x16x32_bf16 v[122:125], v[170:173], v[178:181], v[122:125]
	v_mfma_f32_16x16x32_bf16 v[110:113], v[162:165], v[186:189], v[110:113]
	v_mfma_f32_16x16x32_bf16 v[106:109], v[170:173], v[186:189], v[106:109]
	v_mfma_f32_16x16x32_bf16 v[94:97], v[162:165], v[194:197], v[94:97]
	v_mfma_f32_16x16x32_bf16 v[90:93], v[170:173], v[194:197], v[90:93]
	v_mfma_f32_16x16x32_bf16 v[78:81], v[162:165], v[202:205], v[78:81]
	v_mfma_f32_16x16x32_bf16 v[74:77], v[170:173], v[202:205], v[74:77]
	v_mfma_f32_16x16x32_bf16 v[126:129], v[166:169], v[182:185], v[126:129]
	v_mfma_f32_16x16x32_bf16 v[122:125], v[174:177], v[182:185], v[122:125]
	v_mfma_f32_16x16x32_bf16 v[110:113], v[166:169], v[190:193], v[110:113]
	v_mfma_f32_16x16x32_bf16 v[106:109], v[174:177], v[190:193], v[106:109]
	s_barrier
	v_mfma_f32_16x16x32_bf16 v[94:97], v[166:169], v[198:201], v[94:97]
	v_mfma_f32_16x16x32_bf16 v[90:93], v[174:177], v[198:201], v[90:93]
	v_mfma_f32_16x16x32_bf16 v[78:81], v[166:169], v[206:209], v[78:81]
	v_mfma_f32_16x16x32_bf16 v[74:77], v[174:177], v[206:209], v[74:77]
	s_mov_b32 m0, s83
	v_lshl_add_u64 v[140:141], s[96:97], 0, v[130:131]
	ds_read_b128 v[178:181], v143 offset:16384
	ds_read_b128 v[182:185], v143 offset:17408
	ds_read_b128 v[186:189], v143 offset:18432
	ds_read_b128 v[190:193], v143 offset:19456
	ds_read_b128 v[194:197], v143 offset:20480
	ds_read_b128 v[198:201], v143 offset:21504
	ds_read_b128 v[202:205], v143 offset:22528
	ds_read_b128 v[206:209], v143 offset:23552
	global_load_lds_dwordx4 v[140:141], off
	v_lshl_add_u64 v[210:211], v[140:141], 0, s[28:29]
	s_mov_b32 m0, s91
	s_nop 0
	global_load_lds_dwordx4 v[210:211], off
	v_lshl_add_u64 v[210:211], v[140:141], 0, s[30:31]
	s_mov_b32 m0, s92
	s_nop 0
	global_load_lds_dwordx4 v[210:211], off
	v_lshl_add_u64 v[210:211], v[140:141], 0, s[34:35]
	s_mov_b32 m0, s40
	s_nop 0
	global_load_lds_dwordx4 v[210:211], off
	v_lshl_add_u64 v[210:211], s[94:95], 0, v[132:133]
	s_mov_b32 m0, s45
	v_lshl_add_u64 v[212:213], v[210:211], 0, s[28:29]
	global_load_lds_dwordx4 v[210:211], off
	s_mov_b32 m0, s46
	s_nop 0
	global_load_lds_dwordx4 v[212:213], off
	s_waitcnt vmcnt(8)
	s_waitcnt lgkmcnt(0)
	s_barrier
	s_waitcnt lgkmcnt(0)
	v_mfma_f32_16x16x32_bf16 v[54:57], v[146:149], v[178:181], v[54:57]
	v_mfma_f32_16x16x32_bf16 v[50:53], v[154:157], v[178:181], v[50:53]
	v_mfma_f32_16x16x32_bf16 v[38:41], v[146:149], v[186:189], v[38:41]
	v_mfma_f32_16x16x32_bf16 v[34:37], v[154:157], v[186:189], v[34:37]
	v_mfma_f32_16x16x32_bf16 v[22:25], v[146:149], v[194:197], v[22:25]
	v_mfma_f32_16x16x32_bf16 v[18:21], v[154:157], v[194:197], v[18:21]
	v_mfma_f32_16x16x32_bf16 v[6:9], v[146:149], v[202:205], v[6:9]
	v_mfma_f32_16x16x32_bf16 v[2:5], v[154:157], v[202:205], v[2:5]
	v_mfma_f32_16x16x32_bf16 v[54:57], v[150:153], v[182:185], v[54:57]
	v_mfma_f32_16x16x32_bf16 v[50:53], v[158:161], v[182:185], v[50:53]
	v_mfma_f32_16x16x32_bf16 v[38:41], v[150:153], v[190:193], v[38:41]
	v_mfma_f32_16x16x32_bf16 v[34:37], v[158:161], v[190:193], v[34:37]
	v_mfma_f32_16x16x32_bf16 v[22:25], v[150:153], v[198:201], v[22:25]
	v_mfma_f32_16x16x32_bf16 v[18:21], v[158:161], v[198:201], v[18:21]
	v_mfma_f32_16x16x32_bf16 v[6:9], v[150:153], v[206:209], v[6:9]
	v_mfma_f32_16x16x32_bf16 v[2:5], v[158:161], v[206:209], v[2:5]
	v_mfma_f32_16x16x32_bf16 v[62:65], v[162:165], v[178:181], v[62:65]
	v_mfma_f32_16x16x32_bf16 v[58:61], v[170:173], v[178:181], v[58:61]
	v_mfma_f32_16x16x32_bf16 v[46:49], v[162:165], v[186:189], v[46:49]
	v_mfma_f32_16x16x32_bf16 v[42:45], v[170:173], v[186:189], v[42:45]
	v_mfma_f32_16x16x32_bf16 v[30:33], v[162:165], v[194:197], v[30:33]
	v_mfma_f32_16x16x32_bf16 v[26:29], v[170:173], v[194:197], v[26:29]
	v_mfma_f32_16x16x32_bf16 v[14:17], v[162:165], v[202:205], v[14:17]
	v_mfma_f32_16x16x32_bf16 v[10:13], v[170:173], v[202:205], v[10:13]
	v_mfma_f32_16x16x32_bf16 v[62:65], v[166:169], v[182:185], v[62:65]
	v_mfma_f32_16x16x32_bf16 v[58:61], v[174:177], v[182:185], v[58:61]
	v_mfma_f32_16x16x32_bf16 v[46:49], v[166:169], v[190:193], v[46:49]
	v_mfma_f32_16x16x32_bf16 v[42:45], v[174:177], v[190:193], v[42:45]
	s_barrier
	v_mfma_f32_16x16x32_bf16 v[30:33], v[166:169], v[198:201], v[30:33]
	v_mfma_f32_16x16x32_bf16 v[26:29], v[174:177], v[198:201], v[26:29]
	v_mfma_f32_16x16x32_bf16 v[14:17], v[166:169], v[206:209], v[14:17]
	v_mfma_f32_16x16x32_bf16 v[10:13], v[174:177], v[206:209], v[10:13]
	ds_read_b128 v[146:149], v144
	ds_read_b128 v[150:153], v144 offset:1024
	ds_read_b128 v[154:157], v144 offset:2048
	ds_read_b128 v[158:161], v144 offset:3072
	ds_read_b128 v[162:165], v145
	ds_read_b128 v[166:169], v145 offset:1024
	ds_read_b128 v[170:173], v145 offset:2048
	ds_read_b128 v[174:177], v145 offset:3072
	s_mov_b32 m0, s47
	v_lshl_add_u64 v[212:213], v[210:211], 0, s[30:31]
	ds_read_b128 v[178:181], v143 offset:32768
	ds_read_b128 v[182:185], v143 offset:33792
	ds_read_b128 v[186:189], v143 offset:34816
	ds_read_b128 v[190:193], v143 offset:35840
	ds_read_b128 v[194:197], v143 offset:36864
	ds_read_b128 v[198:201], v143 offset:37888
	ds_read_b128 v[202:205], v143 offset:38912
	ds_read_b128 v[206:209], v143 offset:39936
	global_load_lds_dwordx4 v[212:213], off
	v_lshl_add_u64 v[212:213], v[210:211], 0, s[34:35]
	s_mov_b32 m0, s52
	s_nop 0
	global_load_lds_dwordx4 v[212:213], off
	s_waitcnt vmcnt(8)
	s_waitcnt lgkmcnt(0)
	s_barrier
	s_waitcnt lgkmcnt(0)
	v_mfma_f32_16x16x32_bf16 v[118:121], v[146:149], v[178:181], v[118:121]
	v_mfma_f32_16x16x32_bf16 v[114:117], v[154:157], v[178:181], v[114:117]
	v_mfma_f32_16x16x32_bf16 v[102:105], v[146:149], v[186:189], v[102:105]
	v_mfma_f32_16x16x32_bf16 v[98:101], v[154:157], v[186:189], v[98:101]
	v_mfma_f32_16x16x32_bf16 v[86:89], v[146:149], v[194:197], v[86:89]
	v_mfma_f32_16x16x32_bf16 v[82:85], v[154:157], v[194:197], v[82:85]
	v_mfma_f32_16x16x32_bf16 v[70:73], v[146:149], v[202:205], v[70:73]
	v_mfma_f32_16x16x32_bf16 v[66:69], v[154:157], v[202:205], v[66:69]
	v_mfma_f32_16x16x32_bf16 v[118:121], v[150:153], v[182:185], v[118:121]
	v_mfma_f32_16x16x32_bf16 v[114:117], v[158:161], v[182:185], v[114:117]
	v_mfma_f32_16x16x32_bf16 v[102:105], v[150:153], v[190:193], v[102:105]
	v_mfma_f32_16x16x32_bf16 v[98:101], v[158:161], v[190:193], v[98:101]
	v_mfma_f32_16x16x32_bf16 v[86:89], v[150:153], v[198:201], v[86:89]
	v_mfma_f32_16x16x32_bf16 v[82:85], v[158:161], v[198:201], v[82:85]
	v_mfma_f32_16x16x32_bf16 v[70:73], v[150:153], v[206:209], v[70:73]
	v_mfma_f32_16x16x32_bf16 v[66:69], v[158:161], v[206:209], v[66:69]
	v_mfma_f32_16x16x32_bf16 v[126:129], v[162:165], v[178:181], v[126:129]
	v_mfma_f32_16x16x32_bf16 v[122:125], v[170:173], v[178:181], v[122:125]
	v_mfma_f32_16x16x32_bf16 v[110:113], v[162:165], v[186:189], v[110:113]
	v_mfma_f32_16x16x32_bf16 v[106:109], v[170:173], v[186:189], v[106:109]
	v_mfma_f32_16x16x32_bf16 v[94:97], v[162:165], v[194:197], v[94:97]
	v_mfma_f32_16x16x32_bf16 v[90:93], v[170:173], v[194:197], v[90:93]
	v_mfma_f32_16x16x32_bf16 v[78:81], v[162:165], v[202:205], v[78:81]
	v_mfma_f32_16x16x32_bf16 v[74:77], v[170:173], v[202:205], v[74:77]
	v_mfma_f32_16x16x32_bf16 v[126:129], v[166:169], v[182:185], v[126:129]
	v_mfma_f32_16x16x32_bf16 v[122:125], v[174:177], v[182:185], v[122:125]
	v_mfma_f32_16x16x32_bf16 v[110:113], v[166:169], v[190:193], v[110:113]
	v_mfma_f32_16x16x32_bf16 v[106:109], v[174:177], v[190:193], v[106:109]
	s_barrier
; #define PG8_WAIT_V(n) asm volatile("s_waitcnt vmcnt(" #n ")" ::: "memory")
; template <class Epi, class Sched, bool ALIGN_EPI = true, bool SP2 = true, bool FULLLINE = false, bool NOSTAGE = false, bool FP8 = false>
; __device__ __forceinline__ void gemm_phase(PG8_LAS unsigned char* lds, const Gemm g, const Sched& S, const Epi& E) {
;     ...
;         static_assert(SP2, "only the SP2 loop is kept");
;         { const int t = 0; if constexpr (Epi::NST == 16) PG8_ITER(PG8_WAIT_V(24)); else if constexpr (Epi::NST == 8) PG8_ITER(PG8_WAIT_V(16)); else PG8_ITER(PG8_WAIT_V(8)); }
;         for (int t = 2; t < nt; t += 2) PG8_ITER(PG8_WAIT_V(8));
	v_mfma_f32_16x16x32_bf16 v[94:97], v[166:169], v[198:201], v[94:97]
	v_mfma_f32_16x16x32_bf16 v[90:93], v[174:177], v[198:201], v[90:93]
	v_mfma_f32_16x16x32_bf16 v[78:81], v[166:169], v[206:209], v[78:81]
	v_mfma_f32_16x16x32_bf16 v[74:77], v[174:177], v[206:209], v[74:77]
	s_mov_b32 m0, s41
	v_lshl_add_u64 v[212:213], v[140:141], 0, s[36:37]
	ds_read_b128 v[178:181], v143 offset:49152
	ds_read_b128 v[182:185], v143 offset:50176
	ds_read_b128 v[186:189], v143 offset:51200
	ds_read_b128 v[190:193], v143 offset:52224
	ds_read_b128 v[194:197], v143 offset:53248
	ds_read_b128 v[198:201], v143 offset:54272
	ds_read_b128 v[202:205], v143 offset:55296
	ds_read_b128 v[206:209], v143 offset:56320
	global_load_lds_dwordx4 v[212:213], off
	v_lshl_add_u64 v[212:213], v[140:141], 0, s[38:39]
	s_mov_b32 m0, s50
	s_nop 0
	global_load_lds_dwordx4 v[212:213], off
	v_lshl_add_u64 v[212:213], v[140:141], 0, s[12:13]
	s_mov_b32 m0, s51
	v_lshl_add_u64 v[140:141], v[140:141], 0, s[14:15]
	global_load_lds_dwordx4 v[212:213], off
	s_mov_b32 m0, s33
	s_nop 0
	global_load_lds_dwordx4 v[140:141], off
	v_lshl_add_u64 v[140:141], v[210:211], 0, s[36:37]
	s_mov_b32 m0, s53
	s_nop 0
	global_load_lds_dwordx4 v[140:141], off
	v_lshl_add_u64 v[140:141], v[210:211], 0, s[38:39]
	s_mov_b32 m0, s54
	s_nop 0
	global_load_lds_dwordx4 v[140:141], off
	s_waitcnt vmcnt(8)
	s_waitcnt lgkmcnt(0)
	s_barrier
	s_waitcnt lgkmcnt(0)
	v_mfma_f32_16x16x32_bf16 v[54:57], v[146:149], v[178:181], v[54:57]
	v_mfma_f32_16x16x32_bf16 v[50:53], v[154:157], v[178:181], v[50:53]
	v_mfma_f32_16x16x32_bf16 v[38:41], v[146:149], v[186:189], v[38:41]
	v_mfma_f32_16x16x32_bf16 v[34:37], v[154:157], v[186:189], v[34:37]
	v_mfma_f32_16x16x32_bf16 v[22:25], v[146:149], v[194:197], v[22:25]
	v_mfma_f32_16x16x32_bf16 v[18:21], v[154:157], v[194:197], v[18:21]
	v_mfma_f32_16x16x32_bf16 v[6:9], v[146:149], v[202:205], v[6:9]
	v_mfma_f32_16x16x32_bf16 v[2:5], v[154:157], v[202:205], v[2:5]
	v_mfma_f32_16x16x32_bf16 v[54:57], v[150:153], v[182:185], v[54:57]
	v_mfma_f32_16x16x32_bf16 v[50:53], v[158:161], v[182:185], v[50:53]
	v_mfma_f32_16x16x32_bf16 v[38:41], v[150:153], v[190:193], v[38:41]
	v_mfma_f32_16x16x32_bf16 v[34:37], v[158:161], v[190:193], v[34:37]
	v_mfma_f32_16x16x32_bf16 v[22:25], v[150:153], v[198:201], v[22:25]
	v_mfma_f32_16x16x32_bf16 v[18:21], v[158:161], v[198:201], v[18:21]
	v_mfma_f32_16x16x32_bf16 v[6:9], v[150:153], v[206:209], v[6:9]
	v_mfma_f32_16x16x32_bf16 v[2:5], v[158:161], v[206:209], v[2:5]
	v_mfma_f32_16x16x32_bf16 v[62:65], v[162:165], v[178:181], v[62:65]
	v_mfma_f32_16x16x32_bf16 v[58:61], v[170:173], v[178:181], v[58:61]
	v_mfma_f32_16x16x32_bf16 v[46:49], v[162:165], v[186:189], v[46:49]
	v_mfma_f32_16x16x32_bf16 v[42:45], v[170:173], v[186:189], v[42:45]
	v_mfma_f32_16x16x32_bf16 v[30:33], v[162:165], v[194:197], v[30:33]
	v_mfma_f32_16x16x32_bf16 v[26:29], v[170:173], v[194:197], v[26:29]
	v_mfma_f32_16x16x32_bf16 v[14:17], v[162:165], v[202:205], v[14:17]
	v_mfma_f32_16x16x32_bf16 v[10:13], v[170:173], v[202:205], v[10:13]
	v_mfma_f32_16x16x32_bf16 v[62:65], v[166:169], v[182:185], v[62:65]
	v_mfma_f32_16x16x32_bf16 v[58:61], v[174:177], v[182:185], v[58:61]
	v_mfma_f32_16x16x32_bf16 v[46:49], v[166:169], v[190:193], v[46:49]
	v_mfma_f32_16x16x32_bf16 v[42:45], v[174:177], v[190:193], v[42:45]
	s_barrier
	v_mfma_f32_16x16x32_bf16 v[30:33], v[166:169], v[198:201], v[30:33]
	v_mfma_f32_16x16x32_bf16 v[26:29], v[174:177], v[198:201], v[26:29]
	v_mfma_f32_16x16x32_bf16 v[14:17], v[166:169], v[206:209], v[14:17]
	v_mfma_f32_16x16x32_bf16 v[10:13], v[174:177], v[206:209], v[10:13]
	s_add_i32 s76, s76, 2
	s_add_u32 s78, s78, 0x100
	s_addc_u32 s79, s79, 0
	s_add_u32 s56, s56, 0x100
	s_addc_u32 s57, s57, 0
	s_cmp_gt_u32 s76, 29
	s_cbranch_scc0 .LBB0_767
	s_and_b64 vcc, exec, s[10:11]
	s_cbranch_vccz .LBB0_770
	s_barrier

.LBB0_869:
	ds_read_b128 v[2:5], v1
	ds_read_b128 v[6:9], v1 offset:1024
	ds_read_b128 v[10:13], v1 offset:2048
	ds_read_b128 v[14:17], v1 offset:3072
	ds_read_b128 v[18:21], v192
	ds_read_b128 v[22:25], v192 offset:1024
	ds_read_b128 v[26:29], v192 offset:2048
	ds_read_b128 v[30:33], v192 offset:3072
	v_lshl_add_u64 v[248:249], s[70:71], 0, v[170:171]
	s_add_i32 s85, s45, 0xc000
	v_lshl_add_u64 v[66:67], v[248:249], 0, s[14:15]
	s_mov_b32 m0, s85
	s_add_i32 s87, s45, 0xe000
	ds_read_b128 v[34:37], v193
	ds_read_b128 v[38:41], v193 offset:1024
	ds_read_b128 v[42:45], v193 offset:2048
	ds_read_b128 v[46:49], v193 offset:3072
	ds_read_b128 v[50:53], v193 offset:4096
	ds_read_b128 v[54:57], v193 offset:5120
	ds_read_b128 v[58:61], v193 offset:6144
	ds_read_b128 v[62:65], v193 offset:7168
	global_load_lds_dwordx4 v[66:67], off
	v_lshl_add_u64 v[66:67], v[248:249], 0, s[16:17]
	s_mov_b32 m0, s87
	s_nop 0
	global_load_lds_dwordx4 v[66:67], off
	s_waitcnt vmcnt(24)
	s_waitcnt lgkmcnt(0)
	s_barrier
	s_waitcnt lgkmcnt(0)
	v_mfma_f32_16x16x32_bf16 v[66:69], v[2:5], v[34:37], 0
	v_mfma_f32_16x16x32_bf16 v[70:73], v[10:13], v[34:37], 0
	v_mfma_f32_16x16x32_bf16 v[78:81], v[10:13], v[42:45], 0
	v_mfma_f32_16x16x32_bf16 v[86:89], v[10:13], v[50:53], 0
	v_mfma_f32_16x16x32_bf16 v[66:69], v[6:9], v[38:41], v[66:69]
	v_mfma_f32_16x16x32_bf16 v[70:73], v[14:17], v[38:41], v[70:73]
	v_mfma_f32_16x16x32_bf16 v[74:77], v[2:5], v[42:45], 0
	v_mfma_f32_16x16x32_bf16 v[78:81], v[14:17], v[46:49], v[78:81]
	v_mfma_f32_16x16x32_bf16 v[82:85], v[2:5], v[50:53], 0
	v_mfma_f32_16x16x32_bf16 v[86:89], v[14:17], v[54:57], v[86:89]
	v_mfma_f32_16x16x32_bf16 v[90:93], v[2:5], v[58:61], 0
	v_mfma_f32_16x16x32_bf16 v[94:97], v[10:13], v[58:61], 0
	v_mfma_f32_16x16x32_bf16 v[74:77], v[6:9], v[46:49], v[74:77]
	v_mfma_f32_16x16x32_bf16 v[82:85], v[6:9], v[54:57], v[82:85]
	v_mfma_f32_16x16x32_bf16 v[90:93], v[6:9], v[62:65], v[90:93]
	v_mfma_f32_16x16x32_bf16 v[94:97], v[14:17], v[62:65], v[94:97]
	v_mfma_f32_16x16x32_bf16 v[98:101], v[18:21], v[34:37], 0
	v_mfma_f32_16x16x32_bf16 v[34:37], v[26:29], v[34:37], 0
	v_mfma_f32_16x16x32_bf16 v[98:101], v[22:25], v[38:41], v[98:101]
	v_mfma_f32_16x16x32_bf16 v[34:37], v[30:33], v[38:41], v[34:37]
	v_mfma_f32_16x16x32_bf16 v[38:41], v[18:21], v[42:45], 0
	v_mfma_f32_16x16x32_bf16 v[42:45], v[26:29], v[42:45], 0
	v_mfma_f32_16x16x32_bf16 v[38:41], v[22:25], v[46:49], v[38:41]
	v_mfma_f32_16x16x32_bf16 v[42:45], v[30:33], v[46:49], v[42:45]
	v_mfma_f32_16x16x32_bf16 v[46:49], v[18:21], v[50:53], 0
	v_mfma_f32_16x16x32_bf16 v[50:53], v[26:29], v[50:53], 0
	v_mfma_f32_16x16x32_bf16 v[46:49], v[22:25], v[54:57], v[46:49]
	v_mfma_f32_16x16x32_bf16 v[50:53], v[30:33], v[54:57], v[50:53]
	s_barrier
	v_mfma_f32_16x16x32_bf16 v[54:57], v[18:21], v[58:61], 0
	v_mfma_f32_16x16x32_bf16 v[58:61], v[26:29], v[58:61], 0
	v_mfma_f32_16x16x32_bf16 v[54:57], v[22:25], v[62:65], v[54:57]
	v_mfma_f32_16x16x32_bf16 v[58:61], v[30:33], v[62:65], v[58:61]
	v_lshl_add_u64 v[250:251], s[72:73], 0, v[172:173]
	s_add_i32 s88, s77, s44
	v_lshl_add_u64 v[130:131], v[250:251], 0, s[18:19]
	s_mov_b32 m0, s88
	s_add_i32 s89, s88, 0x2000
	ds_read_b128 v[62:65], v193 offset:16384
	ds_read_b128 v[102:105], v193 offset:17408
	ds_read_b128 v[106:109], v193 offset:18432
	ds_read_b128 v[110:113], v193 offset:19456
	ds_read_b128 v[114:117], v193 offset:20480
	ds_read_b128 v[118:121], v193 offset:21504
	ds_read_b128 v[122:125], v193 offset:22528
	ds_read_b128 v[126:129], v193 offset:23552
	global_load_lds_dwordx4 v[130:131], off
	v_lshl_add_u64 v[130:131], v[250:251], 0, s[20:21]
	s_mov_b32 m0, s89
	s_add_i32 s90, s78, s44
	global_load_lds_dwordx4 v[130:131], off
	v_lshl_add_u64 v[130:131], v[250:251], 0, s[22:23]
	s_mov_b32 m0, s90
	s_add_i32 s40, s90, 0x2000
	global_load_lds_dwordx4 v[130:131], off
	v_lshl_add_u64 v[130:131], v[250:251], 0, s[24:25]
	s_mov_b32 m0, s40
	s_nop 0
	global_load_lds_dwordx4 v[130:131], off
	v_lshl_add_u64 v[130:131], v[248:249], 0, s[18:19]
	s_mov_b32 m0, s45
	s_nop 0
	global_load_lds_dwordx4 v[130:131], off
	v_lshl_add_u64 v[130:131], v[248:249], 0, s[20:21]
	s_mov_b32 m0, s46
	s_nop 0
	global_load_lds_dwordx4 v[130:131], off
	s_waitcnt vmcnt(24)
	s_waitcnt lgkmcnt(0)
	s_barrier
	s_waitcnt lgkmcnt(0)
	v_mfma_f32_16x16x32_bf16 v[130:133], v[2:5], v[62:65], 0
	v_mfma_f32_16x16x32_bf16 v[138:141], v[6:9], v[102:105], v[130:133]
	v_mfma_f32_16x16x32_bf16 v[130:133], v[10:13], v[62:65], 0
	v_mfma_f32_16x16x32_bf16 v[150:153], v[14:17], v[102:105], v[130:133]
	v_mfma_f32_16x16x32_bf16 v[130:133], v[2:5], v[106:109], 0
	v_mfma_f32_16x16x32_bf16 v[154:157], v[6:9], v[110:113], v[130:133]
	v_mfma_f32_16x16x32_bf16 v[130:133], v[10:13], v[106:109], 0
	v_mfma_f32_16x16x32_bf16 v[158:161], v[14:17], v[110:113], v[130:133]
	v_mfma_f32_16x16x32_bf16 v[130:133], v[2:5], v[114:117], 0
	v_mfma_f32_16x16x32_bf16 v[2:5], v[2:5], v[122:125], 0
	v_mfma_f32_16x16x32_bf16 v[162:165], v[6:9], v[118:121], v[130:133]
	v_mfma_f32_16x16x32_bf16 v[2:5], v[6:9], v[126:129], v[2:5]
	v_mfma_f32_16x16x32_bf16 v[6:9], v[10:13], v[122:125], 0
	v_mfma_f32_16x16x32_bf16 v[130:133], v[10:13], v[114:117], 0
	v_mfma_f32_16x16x32_bf16 v[6:9], v[14:17], v[126:129], v[6:9]
	v_mfma_f32_16x16x32_bf16 v[166:169], v[14:17], v[118:121], v[130:133]
	v_mfma_f32_16x16x32_bf16 v[10:13], v[18:21], v[62:65], 0
	v_mfma_f32_16x16x32_bf16 v[180:183], v[22:25], v[102:105], v[10:13]
	v_mfma_f32_16x16x32_bf16 v[10:13], v[26:29], v[62:65], 0
	v_mfma_f32_16x16x32_bf16 v[184:187], v[30:33], v[102:105], v[10:13]
	v_mfma_f32_16x16x32_bf16 v[10:13], v[18:21], v[106:109], 0
	v_mfma_f32_16x16x32_bf16 v[188:191], v[22:25], v[110:113], v[10:13]
	v_mfma_f32_16x16x32_bf16 v[10:13], v[26:29], v[106:109], 0
	v_mfma_f32_16x16x32_bf16 v[196:199], v[30:33], v[110:113], v[10:13]
	v_mfma_f32_16x16x32_bf16 v[10:13], v[18:21], v[114:117], 0
	v_mfma_f32_16x16x32_bf16 v[200:203], v[22:25], v[118:121], v[10:13]
	v_mfma_f32_16x16x32_bf16 v[10:13], v[26:29], v[114:117], 0
	v_mfma_f32_16x16x32_bf16 v[204:207], v[30:33], v[118:121], v[10:13]
	s_barrier
	v_mfma_f32_16x16x32_bf16 v[10:13], v[18:21], v[122:125], 0
	v_mfma_f32_16x16x32_bf16 v[208:211], v[22:25], v[126:129], v[10:13]
	v_mfma_f32_16x16x32_bf16 v[10:13], v[26:29], v[122:125], 0
	v_mfma_f32_16x16x32_bf16 v[212:215], v[30:33], v[126:129], v[10:13]
	s_nop 5
	ds_read_b128 v[10:13], v194
	ds_read_b128 v[14:17], v194 offset:1024
	ds_read_b128 v[18:21], v194 offset:2048
	ds_read_b128 v[22:25], v194 offset:3072
	ds_read_b128 v[216:219], v195
	ds_read_b128 v[220:223], v195 offset:1024
	ds_read_b128 v[224:227], v195 offset:2048
	ds_read_b128 v[228:231], v195 offset:3072
	s_mov_b32 m0, s47
	v_lshl_add_u64 v[106:107], v[248:249], 0, s[22:23]
	ds_read_b128 v[26:29], v193 offset:32768
	ds_read_b128 v[30:33], v193 offset:33792
	ds_read_b128 v[62:65], v193 offset:34816
	ds_read_b128 v[102:105], v193 offset:35840
	ds_read_b128 v[232:235], v193 offset:36864
	ds_read_b128 v[236:239], v193 offset:37888
	ds_read_b128 v[240:243], v193 offset:38912
	ds_read_b128 v[244:247], v193 offset:39936
	global_load_lds_dwordx4 v[106:107], off
	v_lshl_add_u64 v[106:107], v[248:249], 0, s[24:25]
	s_mov_b32 m0, s52
	s_nop 0
	global_load_lds_dwordx4 v[106:107], off
	s_waitcnt vmcnt(8)
	s_waitcnt lgkmcnt(0)
	s_barrier
	s_waitcnt lgkmcnt(0)
	v_mfma_f32_16x16x32_bf16 v[66:69], v[10:13], v[26:29], v[66:69]
	v_mfma_f32_16x16x32_bf16 v[146:149], v[14:17], v[30:33], v[66:69]
	v_mfma_f32_16x16x32_bf16 v[66:69], v[18:21], v[26:29], v[70:73]
	v_mfma_f32_16x16x32_bf16 v[142:145], v[22:25], v[30:33], v[66:69]
	v_mfma_f32_16x16x32_bf16 v[66:69], v[10:13], v[62:65], v[74:77]
	v_mfma_f32_16x16x32_bf16 v[126:129], v[14:17], v[102:105], v[66:69]
	v_mfma_f32_16x16x32_bf16 v[66:69], v[18:21], v[62:65], v[78:81]
	v_mfma_f32_16x16x32_bf16 v[122:125], v[22:25], v[102:105], v[66:69]
	v_mfma_f32_16x16x32_bf16 v[66:69], v[10:13], v[232:235], v[82:85]
	v_mfma_f32_16x16x32_bf16 v[110:113], v[14:17], v[236:239], v[66:69]
	v_mfma_f32_16x16x32_bf16 v[66:69], v[18:21], v[232:235], v[86:89]
	v_mfma_f32_16x16x32_bf16 v[106:109], v[22:25], v[236:239], v[66:69]
	v_mfma_f32_16x16x32_bf16 v[66:69], v[10:13], v[240:243], v[90:93]
	v_mfma_f32_16x16x32_bf16 v[86:89], v[14:17], v[244:247], v[66:69]
	v_mfma_f32_16x16x32_bf16 v[66:69], v[18:21], v[240:243], v[94:97]
	v_mfma_f32_16x16x32_bf16 v[78:81], v[22:25], v[244:247], v[66:69]
	v_mfma_f32_16x16x32_bf16 v[66:69], v[216:219], v[26:29], v[98:101]
	v_mfma_f32_16x16x32_bf16 v[26:29], v[224:227], v[26:29], v[34:37]
	v_mfma_f32_16x16x32_bf16 v[130:133], v[228:231], v[30:33], v[26:29]
	v_mfma_f32_16x16x32_bf16 v[26:29], v[216:219], v[62:65], v[38:41]
	v_mfma_f32_16x16x32_bf16 v[118:121], v[220:223], v[102:105], v[26:29]
	v_mfma_f32_16x16x32_bf16 v[26:29], v[224:227], v[62:65], v[42:45]
	v_mfma_f32_16x16x32_bf16 v[114:117], v[228:231], v[102:105], v[26:29]
	v_mfma_f32_16x16x32_bf16 v[26:29], v[216:219], v[232:235], v[46:49]
	v_mfma_f32_16x16x32_bf16 v[102:105], v[220:223], v[236:239], v[26:29]
	v_mfma_f32_16x16x32_bf16 v[26:29], v[224:227], v[232:235], v[50:53]
	v_mfma_f32_16x16x32_bf16 v[98:101], v[228:231], v[236:239], v[26:29]
	v_mfma_f32_16x16x32_bf16 v[26:29], v[216:219], v[240:243], v[54:57]
	s_barrier
	v_mfma_f32_16x16x32_bf16 v[70:73], v[220:223], v[244:247], v[26:29]
	v_mfma_f32_16x16x32_bf16 v[26:29], v[224:227], v[240:243], v[58:61]
	v_mfma_f32_16x16x32_bf16 v[134:137], v[220:223], v[30:33], v[66:69]
	v_mfma_f32_16x16x32_bf16 v[66:69], v[228:231], v[244:247], v[26:29]
	s_add_i32 s41, s79, s44
	s_nop 3
	v_lshl_add_u64 v[26:27], v[250:251], 0, s[26:27]
	s_mov_b32 m0, s41
	s_add_i32 s50, s41, 0x2000
	ds_read_b128 v[34:37], v193 offset:49152
	ds_read_b128 v[38:41], v193 offset:50176
	ds_read_b128 v[74:77], v193 offset:51200
	ds_read_b128 v[82:85], v193 offset:52224
	ds_read_b128 v[90:93], v193 offset:53248
	ds_read_b128 v[94:97], v193 offset:54272
	ds_read_b128 v[232:235], v193 offset:55296
	ds_read_b128 v[236:239], v193 offset:56320
	global_load_lds_dwordx4 v[26:27], off
	v_lshl_add_u64 v[26:27], v[250:251], 0, s[28:29]
	s_mov_b32 m0, s50
	s_mov_b64 s[56:57], 0x160180
	s_add_i32 s51, s80, s44
	global_load_lds_dwordx4 v[26:27], off
	v_lshl_add_u64 v[26:27], v[250:251], 0, s[56:57]
	s_mov_b32 m0, s51
	s_mov_b64 s[56:57], 0x210180
	s_add_i32 s33, s51, 0x2000
	global_load_lds_dwordx4 v[26:27], off
	v_lshl_add_u64 v[26:27], v[250:251], 0, s[56:57]
	s_mov_b32 m0, s33
	s_nop 0
	global_load_lds_dwordx4 v[26:27], off
	v_lshl_add_u64 v[26:27], v[248:249], 0, s[26:27]
	s_mov_b32 m0, s53
	s_nop 0
	global_load_lds_dwordx4 v[26:27], off
	v_lshl_add_u64 v[26:27], v[248:249], 0, s[28:29]
	s_mov_b32 m0, s54
	s_nop 0
	global_load_lds_dwordx4 v[26:27], off
	s_waitcnt vmcnt(8)
	s_waitcnt lgkmcnt(0)
	s_barrier
	s_waitcnt lgkmcnt(0)
	v_mfma_f32_16x16x32_bf16 v[26:29], v[10:13], v[34:37], v[138:141]
	v_mfma_f32_16x16x32_bf16 v[62:65], v[14:17], v[38:41], v[26:29]
	v_mfma_f32_16x16x32_bf16 v[26:29], v[18:21], v[34:37], v[150:153]
	v_mfma_f32_16x16x32_bf16 v[58:61], v[22:25], v[38:41], v[26:29]
	v_mfma_f32_16x16x32_bf16 v[26:29], v[10:13], v[74:77], v[154:157]
	v_mfma_f32_16x16x32_bf16 v[46:49], v[14:17], v[82:85], v[26:29]
	v_mfma_f32_16x16x32_bf16 v[26:29], v[18:21], v[74:77], v[158:161]
	v_mfma_f32_16x16x32_bf16 v[42:45], v[22:25], v[82:85], v[26:29]
	v_mfma_f32_16x16x32_bf16 v[26:29], v[10:13], v[90:93], v[162:165]
	v_mfma_f32_16x16x32_bf16 v[2:5], v[10:13], v[232:235], v[2:5]
	v_mfma_f32_16x16x32_bf16 v[30:33], v[14:17], v[94:97], v[26:29]
	v_mfma_f32_16x16x32_bf16 v[26:29], v[18:21], v[90:93], v[166:169]
	v_mfma_f32_16x16x32_bf16 v[14:17], v[14:17], v[236:239], v[2:5]
	v_mfma_f32_16x16x32_bf16 v[2:5], v[18:21], v[232:235], v[6:9]
	v_mfma_f32_16x16x32_bf16 v[26:29], v[22:25], v[94:97], v[26:29]
	v_mfma_f32_16x16x32_bf16 v[10:13], v[22:25], v[236:239], v[2:5]
	v_mfma_f32_16x16x32_bf16 v[2:5], v[216:219], v[34:37], v[180:183]
	v_mfma_f32_16x16x32_bf16 v[54:57], v[220:223], v[38:41], v[2:5]
	v_mfma_f32_16x16x32_bf16 v[2:5], v[224:227], v[34:37], v[184:187]
	v_mfma_f32_16x16x32_bf16 v[50:53], v[228:231], v[38:41], v[2:5]
	v_mfma_f32_16x16x32_bf16 v[2:5], v[216:219], v[74:77], v[188:191]
	v_mfma_f32_16x16x32_bf16 v[38:41], v[220:223], v[82:85], v[2:5]
	v_mfma_f32_16x16x32_bf16 v[2:5], v[224:227], v[74:77], v[196:199]
	v_mfma_f32_16x16x32_bf16 v[34:37], v[228:231], v[82:85], v[2:5]
	v_mfma_f32_16x16x32_bf16 v[2:5], v[216:219], v[90:93], v[200:203]
	v_mfma_f32_16x16x32_bf16 v[22:25], v[220:223], v[94:97], v[2:5]
	v_mfma_f32_16x16x32_bf16 v[2:5], v[224:227], v[90:93], v[204:207]
	v_mfma_f32_16x16x32_bf16 v[18:21], v[228:231], v[94:97], v[2:5]
	s_barrier
	v_mfma_f32_16x16x32_bf16 v[2:5], v[216:219], v[232:235], v[208:211]
	v_mfma_f32_16x16x32_bf16 v[6:9], v[220:223], v[236:239], v[2:5]
	v_mfma_f32_16x16x32_bf16 v[2:5], v[224:227], v[232:235], v[212:215]
	v_mfma_f32_16x16x32_bf16 v[2:5], v[228:231], v[236:239], v[2:5]
	s_add_u32 s70, s70, 0x160180
	s_addc_u32 s71, s71, 0
	s_add_u32 s56, s72, 0x200
	s_addc_u32 s57, s73, 0
	s_mov_b32 s72, 0
.LBB0_870:
	ds_read_b128 v[74:77], v1
	ds_read_b128 v[82:85], v1 offset:1024
	ds_read_b128 v[90:93], v1 offset:2048
	ds_read_b128 v[94:97], v1 offset:3072
	ds_read_b128 v[138:141], v192
	ds_read_b128 v[150:153], v192 offset:1024
	ds_read_b128 v[154:157], v192 offset:2048
	ds_read_b128 v[158:161], v192 offset:3072
	s_add_u32 s0, s70, 0xffea0080
	s_addc_u32 s1, s71, -1
	s_cmpk_eq_i32 s72, 0x54
	s_cselect_b32 s93, s11, s1
	s_cselect_b32 s92, s10, s0
	s_cselect_b32 s95, s69, s57
	s_cselect_b32 s94, s68, s56
	s_mov_b32 m0, s85
	v_lshl_add_u64 v[208:209], s[70:71], 0, v[174:175]
	ds_read_b128 v[162:165], v193
	ds_read_b128 v[166:169], v193 offset:1024
	ds_read_b128 v[180:183], v193 offset:2048
	ds_read_b128 v[184:187], v193 offset:3072
	ds_read_b128 v[188:191], v193 offset:4096
	ds_read_b128 v[196:199], v193 offset:5120
	ds_read_b128 v[200:203], v193 offset:6144
	ds_read_b128 v[204:207], v193 offset:7168
	global_load_lds_dwordx4 v[208:209], off
	v_lshl_add_u64 v[208:209], v[208:209], 0, s[30:31]
	s_mov_b32 m0, s87
	s_nop 0
	global_load_lds_dwordx4 v[208:209], off
	s_waitcnt vmcnt(8)
	s_waitcnt lgkmcnt(0)
	s_barrier
	s_waitcnt lgkmcnt(0)
	v_mfma_f32_16x16x32_bf16 v[146:149], v[74:77], v[162:165], v[146:149]
	v_mfma_f32_16x16x32_bf16 v[142:145], v[90:93], v[162:165], v[142:145]
	v_mfma_f32_16x16x32_bf16 v[126:129], v[74:77], v[180:183], v[126:129]
	v_mfma_f32_16x16x32_bf16 v[122:125], v[90:93], v[180:183], v[122:125]
	v_mfma_f32_16x16x32_bf16 v[110:113], v[74:77], v[188:191], v[110:113]
	v_mfma_f32_16x16x32_bf16 v[106:109], v[90:93], v[188:191], v[106:109]
	v_mfma_f32_16x16x32_bf16 v[86:89], v[74:77], v[200:203], v[86:89]
	v_mfma_f32_16x16x32_bf16 v[78:81], v[90:93], v[200:203], v[78:81]
	v_mfma_f32_16x16x32_bf16 v[146:149], v[82:85], v[166:169], v[146:149]
	v_mfma_f32_16x16x32_bf16 v[142:145], v[94:97], v[166:169], v[142:145]
	v_mfma_f32_16x16x32_bf16 v[126:129], v[82:85], v[184:187], v[126:129]
	v_mfma_f32_16x16x32_bf16 v[122:125], v[94:97], v[184:187], v[122:125]
	v_mfma_f32_16x16x32_bf16 v[110:113], v[82:85], v[196:199], v[110:113]
	v_mfma_f32_16x16x32_bf16 v[106:109], v[94:97], v[196:199], v[106:109]
	v_mfma_f32_16x16x32_bf16 v[86:89], v[82:85], v[204:207], v[86:89]
	v_mfma_f32_16x16x32_bf16 v[78:81], v[94:97], v[204:207], v[78:81]
	v_mfma_f32_16x16x32_bf16 v[134:137], v[138:141], v[162:165], v[134:137]
	v_mfma_f32_16x16x32_bf16 v[130:133], v[154:157], v[162:165], v[130:133]
	v_mfma_f32_16x16x32_bf16 v[118:121], v[138:141], v[180:183], v[118:121]
	v_mfma_f32_16x16x32_bf16 v[114:117], v[154:157], v[180:183], v[114:117]
	v_mfma_f32_16x16x32_bf16 v[102:105], v[138:141], v[188:191], v[102:105]
	v_mfma_f32_16x16x32_bf16 v[98:101], v[154:157], v[188:191], v[98:101]
	v_mfma_f32_16x16x32_bf16 v[70:73], v[138:141], v[200:203], v[70:73]
	v_mfma_f32_16x16x32_bf16 v[66:69], v[154:157], v[200:203], v[66:69]
	v_mfma_f32_16x16x32_bf16 v[134:137], v[150:153], v[166:169], v[134:137]
	v_mfma_f32_16x16x32_bf16 v[130:133], v[158:161], v[166:169], v[130:133]
	v_mfma_f32_16x16x32_bf16 v[118:121], v[150:153], v[184:187], v[118:121]
	v_mfma_f32_16x16x32_bf16 v[114:117], v[158:161], v[184:187], v[114:117]
	s_barrier
	v_mfma_f32_16x16x32_bf16 v[102:105], v[150:153], v[196:199], v[102:105]
	v_mfma_f32_16x16x32_bf16 v[98:101], v[158:161], v[196:199], v[98:101]
	v_mfma_f32_16x16x32_bf16 v[70:73], v[150:153], v[204:207], v[70:73]
	v_mfma_f32_16x16x32_bf16 v[66:69], v[158:161], v[204:207], v[66:69]
	s_mov_b32 m0, s88
	v_lshl_add_u64 v[208:209], s[94:95], 0, v[172:173]
	ds_read_b128 v[162:165], v193 offset:16384
	ds_read_b128 v[166:169], v193 offset:17408
	ds_read_b128 v[180:183], v193 offset:18432
	ds_read_b128 v[184:187], v193 offset:19456
	ds_read_b128 v[188:191], v193 offset:20480
	ds_read_b128 v[196:199], v193 offset:21504
	ds_read_b128 v[200:203], v193 offset:22528
	ds_read_b128 v[204:207], v193 offset:23552
	global_load_lds_dwordx4 v[208:209], off
	v_lshl_add_u64 v[210:211], v[208:209], 0, s[30:31]
	s_mov_b32 m0, s89
	s_nop 0
	global_load_lds_dwordx4 v[210:211], off
	v_lshl_add_u64 v[210:211], v[208:209], 0, s[34:35]
	s_mov_b32 m0, s90
	s_nop 0
	global_load_lds_dwordx4 v[210:211], off
	v_lshl_add_u64 v[210:211], v[208:209], 0, s[36:37]
	s_mov_b32 m0, s40
	s_nop 0
	global_load_lds_dwordx4 v[210:211], off
	v_lshl_add_u64 v[210:211], s[92:93], 0, v[170:171]
	s_mov_b32 m0, s45
	v_lshl_add_u64 v[212:213], v[210:211], 0, s[30:31]
	global_load_lds_dwordx4 v[210:211], off
	s_mov_b32 m0, s46
	s_nop 0
	global_load_lds_dwordx4 v[212:213], off
	s_waitcnt vmcnt(8)
	s_waitcnt lgkmcnt(0)
	s_barrier
	s_waitcnt lgkmcnt(0)
	v_mfma_f32_16x16x32_bf16 v[62:65], v[74:77], v[162:165], v[62:65]
	v_mfma_f32_16x16x32_bf16 v[58:61], v[90:93], v[162:165], v[58:61]
	v_mfma_f32_16x16x32_bf16 v[46:49], v[74:77], v[180:183], v[46:49]
	v_mfma_f32_16x16x32_bf16 v[42:45], v[90:93], v[180:183], v[42:45]
	v_mfma_f32_16x16x32_bf16 v[30:33], v[74:77], v[188:191], v[30:33]
	v_mfma_f32_16x16x32_bf16 v[26:29], v[90:93], v[188:191], v[26:29]
	v_mfma_f32_16x16x32_bf16 v[14:17], v[74:77], v[200:203], v[14:17]
	v_mfma_f32_16x16x32_bf16 v[10:13], v[90:93], v[200:203], v[10:13]
	v_mfma_f32_16x16x32_bf16 v[62:65], v[82:85], v[166:169], v[62:65]
	v_mfma_f32_16x16x32_bf16 v[58:61], v[94:97], v[166:169], v[58:61]
	v_mfma_f32_16x16x32_bf16 v[46:49], v[82:85], v[184:187], v[46:49]
	v_mfma_f32_16x16x32_bf16 v[42:45], v[94:97], v[184:187], v[42:45]
	v_mfma_f32_16x16x32_bf16 v[30:33], v[82:85], v[196:199], v[30:33]
	v_mfma_f32_16x16x32_bf16 v[26:29], v[94:97], v[196:199], v[26:29]
	v_mfma_f32_16x16x32_bf16 v[14:17], v[82:85], v[204:207], v[14:17]
	v_mfma_f32_16x16x32_bf16 v[10:13], v[94:97], v[204:207], v[10:13]
	v_mfma_f32_16x16x32_bf16 v[54:57], v[138:141], v[162:165], v[54:57]
	v_mfma_f32_16x16x32_bf16 v[50:53], v[154:157], v[162:165], v[50:53]
	v_mfma_f32_16x16x32_bf16 v[38:41], v[138:141], v[180:183], v[38:41]
	v_mfma_f32_16x16x32_bf16 v[34:37], v[154:157], v[180:183], v[34:37]
	v_mfma_f32_16x16x32_bf16 v[22:25], v[138:141], v[188:191], v[22:25]
	v_mfma_f32_16x16x32_bf16 v[18:21], v[154:157], v[188:191], v[18:21]
	v_mfma_f32_16x16x32_bf16 v[6:9], v[138:141], v[200:203], v[6:9]
	v_mfma_f32_16x16x32_bf16 v[2:5], v[154:157], v[200:203], v[2:5]
	v_mfma_f32_16x16x32_bf16 v[54:57], v[150:153], v[166:169], v[54:57]
	v_mfma_f32_16x16x32_bf16 v[50:53], v[158:161], v[166:169], v[50:53]
	v_mfma_f32_16x16x32_bf16 v[38:41], v[150:153], v[184:187], v[38:41]
	v_mfma_f32_16x16x32_bf16 v[34:37], v[158:161], v[184:187], v[34:37]
	s_barrier
	v_mfma_f32_16x16x32_bf16 v[22:25], v[150:153], v[196:199], v[22:25]
	v_mfma_f32_16x16x32_bf16 v[18:21], v[158:161], v[196:199], v[18:21]
	v_mfma_f32_16x16x32_bf16 v[6:9], v[150:153], v[204:207], v[6:9]
	v_mfma_f32_16x16x32_bf16 v[2:5], v[158:161], v[204:207], v[2:5]
	ds_read_b128 v[74:77], v194
	ds_read_b128 v[82:85], v194 offset:1024
	ds_read_b128 v[90:93], v194 offset:2048
	ds_read_b128 v[94:97], v194 offset:3072
	ds_read_b128 v[138:141], v195
	ds_read_b128 v[150:153], v195 offset:1024
	ds_read_b128 v[154:157], v195 offset:2048
	ds_read_b128 v[158:161], v195 offset:3072
	s_mov_b32 m0, s47
	v_lshl_add_u64 v[212:213], v[210:211], 0, s[34:35]
	ds_read_b128 v[162:165], v193 offset:32768
	ds_read_b128 v[166:169], v193 offset:33792
	ds_read_b128 v[180:183], v193 offset:34816
	ds_read_b128 v[184:187], v193 offset:35840
	ds_read_b128 v[188:191], v193 offset:36864
	ds_read_b128 v[196:199], v193 offset:37888
	ds_read_b128 v[200:203], v193 offset:38912
	ds_read_b128 v[204:207], v193 offset:39936
	global_load_lds_dwordx4 v[212:213], off
	v_lshl_add_u64 v[212:213], v[210:211], 0, s[36:37]
	s_mov_b32 m0, s52
	s_nop 0
	global_load_lds_dwordx4 v[212:213], off
	s_waitcnt vmcnt(8)
	s_waitcnt lgkmcnt(0)
	s_barrier
	s_waitcnt lgkmcnt(0)
	v_mfma_f32_16x16x32_bf16 v[146:149], v[74:77], v[162:165], v[146:149]
	v_mfma_f32_16x16x32_bf16 v[142:145], v[90:93], v[162:165], v[142:145]
	v_mfma_f32_16x16x32_bf16 v[126:129], v[74:77], v[180:183], v[126:129]
	v_mfma_f32_16x16x32_bf16 v[122:125], v[90:93], v[180:183], v[122:125]
	v_mfma_f32_16x16x32_bf16 v[110:113], v[74:77], v[188:191], v[110:113]
	v_mfma_f32_16x16x32_bf16 v[106:109], v[90:93], v[188:191], v[106:109]
	v_mfma_f32_16x16x32_bf16 v[86:89], v[74:77], v[200:203], v[86:89]
	v_mfma_f32_16x16x32_bf16 v[78:81], v[90:93], v[200:203], v[78:81]
	v_mfma_f32_16x16x32_bf16 v[146:149], v[82:85], v[166:169], v[146:149]
	v_mfma_f32_16x16x32_bf16 v[142:145], v[94:97], v[166:169], v[142:145]
	v_mfma_f32_16x16x32_bf16 v[126:129], v[82:85], v[184:187], v[126:129]
	v_mfma_f32_16x16x32_bf16 v[122:125], v[94:97], v[184:187], v[122:125]
	v_mfma_f32_16x16x32_bf16 v[110:113], v[82:85], v[196:199], v[110:113]
	v_mfma_f32_16x16x32_bf16 v[106:109], v[94:97], v[196:199], v[106:109]
	v_mfma_f32_16x16x32_bf16 v[86:89], v[82:85], v[204:207], v[86:89]
	v_mfma_f32_16x16x32_bf16 v[78:81], v[94:97], v[204:207], v[78:81]
	v_mfma_f32_16x16x32_bf16 v[134:137], v[138:141], v[162:165], v[134:137]
	v_mfma_f32_16x16x32_bf16 v[130:133], v[154:157], v[162:165], v[130:133]
	v_mfma_f32_16x16x32_bf16 v[118:121], v[138:141], v[180:183], v[118:121]
	v_mfma_f32_16x16x32_bf16 v[114:117], v[154:157], v[180:183], v[114:117]
	v_mfma_f32_16x16x32_bf16 v[102:105], v[138:141], v[188:191], v[102:105]
	v_mfma_f32_16x16x32_bf16 v[98:101], v[154:157], v[188:191], v[98:101]
	v_mfma_f32_16x16x32_bf16 v[70:73], v[138:141], v[200:203], v[70:73]
	v_mfma_f32_16x16x32_bf16 v[66:69], v[154:157], v[200:203], v[66:69]
	v_mfma_f32_16x16x32_bf16 v[134:137], v[150:153], v[166:169], v[134:137]
	v_mfma_f32_16x16x32_bf16 v[130:133], v[158:161], v[166:169], v[130:133]
	v_mfma_f32_16x16x32_bf16 v[118:121], v[150:153], v[184:187], v[118:121]
	v_mfma_f32_16x16x32_bf16 v[114:117], v[158:161], v[184:187], v[114:117]
	s_barrier
; #define PG8_WAIT_V(n) asm volatile("s_waitcnt vmcnt(" #n ")" ::: "memory")
; template <class Epi, class Sched, bool ALIGN_EPI = true, bool SP2 = true, bool FULLLINE = false, bool NOSTAGE = false, bool FP8 = false>
; __device__ __forceinline__ void gemm_phase(PG8_LAS unsigned char* lds, const Gemm g, const Sched& S, const Epi& E) {
;     ...
;         static_assert(SP2, "only the SP2 loop is kept");
;         { const int t = 0; if constexpr (Epi::NST == 16) PG8_ITER(PG8_WAIT_V(24)); else if constexpr (Epi::NST == 8) PG8_ITER(PG8_WAIT_V(16)); else PG8_ITER(PG8_WAIT_V(8)); }
;         for (int t = 2; t < nt; t += 2) PG8_ITER(PG8_WAIT_V(8));
	v_mfma_f32_16x16x32_bf16 v[102:105], v[150:153], v[196:199], v[102:105]
	v_mfma_f32_16x16x32_bf16 v[98:101], v[158:161], v[196:199], v[98:101]
	v_mfma_f32_16x16x32_bf16 v[70:73], v[150:153], v[204:207], v[70:73]
	v_mfma_f32_16x16x32_bf16 v[66:69], v[158:161], v[204:207], v[66:69]
	s_mov_b32 m0, s41
	v_lshl_add_u64 v[212:213], v[208:209], 0, s[38:39]
	ds_read_b128 v[162:165], v193 offset:49152
	ds_read_b128 v[166:169], v193 offset:50176
	ds_read_b128 v[180:183], v193 offset:51200
	ds_read_b128 v[184:187], v193 offset:52224
	ds_read_b128 v[188:191], v193 offset:53248
	ds_read_b128 v[196:199], v193 offset:54272
	ds_read_b128 v[200:203], v193 offset:55296
	ds_read_b128 v[204:207], v193 offset:56320
	global_load_lds_dwordx4 v[212:213], off
	v_lshl_add_u64 v[212:213], v[208:209], 0, s[66:67]
	s_mov_b32 m0, s50
	s_nop 0
	global_load_lds_dwordx4 v[212:213], off
	v_lshl_add_u64 v[212:213], v[208:209], 0, s[14:15]
	s_mov_b32 m0, s51
	v_lshl_add_u64 v[208:209], v[208:209], 0, s[16:17]
	global_load_lds_dwordx4 v[212:213], off
	s_mov_b32 m0, s33
	s_nop 0
	global_load_lds_dwordx4 v[208:209], off
	v_lshl_add_u64 v[208:209], v[210:211], 0, s[38:39]
	s_mov_b32 m0, s53
	s_nop 0
	global_load_lds_dwordx4 v[208:209], off
	v_lshl_add_u64 v[208:209], v[210:211], 0, s[66:67]
	s_mov_b32 m0, s54
	s_nop 0
	global_load_lds_dwordx4 v[208:209], off
	s_waitcnt vmcnt(8)
	s_waitcnt lgkmcnt(0)
	s_barrier
	s_waitcnt lgkmcnt(0)
	v_mfma_f32_16x16x32_bf16 v[62:65], v[74:77], v[162:165], v[62:65]
	v_mfma_f32_16x16x32_bf16 v[58:61], v[90:93], v[162:165], v[58:61]
	v_mfma_f32_16x16x32_bf16 v[46:49], v[74:77], v[180:183], v[46:49]
	v_mfma_f32_16x16x32_bf16 v[42:45], v[90:93], v[180:183], v[42:45]
	v_mfma_f32_16x16x32_bf16 v[30:33], v[74:77], v[188:191], v[30:33]
	v_mfma_f32_16x16x32_bf16 v[26:29], v[90:93], v[188:191], v[26:29]
	v_mfma_f32_16x16x32_bf16 v[14:17], v[74:77], v[200:203], v[14:17]
	v_mfma_f32_16x16x32_bf16 v[10:13], v[90:93], v[200:203], v[10:13]
	v_mfma_f32_16x16x32_bf16 v[62:65], v[82:85], v[166:169], v[62:65]
	v_mfma_f32_16x16x32_bf16 v[58:61], v[94:97], v[166:169], v[58:61]
	v_mfma_f32_16x16x32_bf16 v[46:49], v[82:85], v[184:187], v[46:49]
	v_mfma_f32_16x16x32_bf16 v[42:45], v[94:97], v[184:187], v[42:45]
	v_mfma_f32_16x16x32_bf16 v[30:33], v[82:85], v[196:199], v[30:33]
	v_mfma_f32_16x16x32_bf16 v[26:29], v[94:97], v[196:199], v[26:29]
	v_mfma_f32_16x16x32_bf16 v[14:17], v[82:85], v[204:207], v[14:17]
	v_mfma_f32_16x16x32_bf16 v[10:13], v[94:97], v[204:207], v[10:13]
	v_mfma_f32_16x16x32_bf16 v[54:57], v[138:141], v[162:165], v[54:57]
	v_mfma_f32_16x16x32_bf16 v[50:53], v[154:157], v[162:165], v[50:53]
	v_mfma_f32_16x16x32_bf16 v[38:41], v[138:141], v[180:183], v[38:41]
	v_mfma_f32_16x16x32_bf16 v[34:37], v[154:157], v[180:183], v[34:37]
	v_mfma_f32_16x16x32_bf16 v[22:25], v[138:141], v[188:191], v[22:25]
	v_mfma_f32_16x16x32_bf16 v[18:21], v[154:157], v[188:191], v[18:21]
	v_mfma_f32_16x16x32_bf16 v[6:9], v[138:141], v[200:203], v[6:9]
	v_mfma_f32_16x16x32_bf16 v[2:5], v[154:157], v[200:203], v[2:5]
	v_mfma_f32_16x16x32_bf16 v[54:57], v[150:153], v[166:169], v[54:57]
	v_mfma_f32_16x16x32_bf16 v[50:53], v[158:161], v[166:169], v[50:53]
	v_mfma_f32_16x16x32_bf16 v[38:41], v[150:153], v[184:187], v[38:41]
	v_mfma_f32_16x16x32_bf16 v[34:37], v[158:161], v[184:187], v[34:37]
	s_barrier
	v_mfma_f32_16x16x32_bf16 v[22:25], v[150:153], v[196:199], v[22:25]
	v_mfma_f32_16x16x32_bf16 v[18:21], v[158:161], v[196:199], v[18:21]
	v_mfma_f32_16x16x32_bf16 v[6:9], v[150:153], v[204:207], v[6:9]
	v_mfma_f32_16x16x32_bf16 v[2:5], v[158:161], v[204:207], v[2:5]
	s_add_i32 s72, s72, 2
	s_add_u32 s70, s70, 0x100
	s_addc_u32 s71, s71, 0
	s_add_u32 s56, s56, 0x100
	s_addc_u32 s57, s57, 0
	s_cmpk_gt_u32 s72, 0x55
	s_cbranch_scc0 .LBB0_870
	s_and_b64 vcc, exec, s[12:13]
	s_cbranch_vccz .LBB0_873
	s_barrier

; #define PG8_WAIT_V(n) asm volatile("s_waitcnt vmcnt(" #n ")" ::: "memory")
; template <class Epi, class Sched, bool ALIGN_EPI = true, bool SP2 = true, bool FULLLINE = false, bool NOSTAGE = false, bool FP8 = false>
; __device__ __forceinline__ void gemm_phase(PG8_LAS unsigned char* lds, const Gemm g, const Sched& S, const Epi& E) {
;     ...
;         { const int t = 0; if constexpr (Epi::NST == 16) PG8_ITER(PG8_WAIT_V(24)); else if constexpr (Epi::NST == 8) PG8_ITER(PG8_WAIT_V(16)); else PG8_ITER(PG8_WAIT_V(8)); }
.LBB0_1024:
	s_ashr_i32 s75, s74, 31
	s_lshl_b64 s[40:41], s[74:75], 20
	s_add_u32 s76, s58, s40
	ds_read_b128 v[2:5], v1
	ds_read_b128 v[6:9], v1 offset:1024
	ds_read_b128 v[10:13], v1 offset:2048
	ds_read_b128 v[14:17], v1 offset:3072
	ds_read_b128 v[18:21], v152
	ds_read_b128 v[22:25], v152 offset:1024
	ds_read_b128 v[26:29], v152 offset:2048
	ds_read_b128 v[30:33], v152 offset:3072
	s_addc_u32 s77, s59, s41
	s_ashr_i32 s73, s72, 31
	s_lshl_b64 s[40:41], s[72:73], 20
	s_add_u32 s78, s3, s40
	s_addc_u32 s79, s42, s41
	s_and_b64 s[40:41], s[8:9], exec
	s_cselect_b32 s73, s77, s83
	s_cselect_b32 s75, s76, s82
	s_cselect_b32 s96, s79, s81
	s_cselect_b32 s97, s78, s80
	v_lshl_add_u64 v[244:245], s[82:83], 0, v[132:133]
	s_mov_b32 m0, s87
	v_lshl_add_u64 v[66:67], v[244:245], 0, s[18:19]
	ds_read_b128 v[34:37], v153
	ds_read_b128 v[38:41], v153 offset:1024
	ds_read_b128 v[42:45], v153 offset:2048
	ds_read_b128 v[46:49], v153 offset:3072
	ds_read_b128 v[50:53], v153 offset:4096
	ds_read_b128 v[54:57], v153 offset:5120
	ds_read_b128 v[58:61], v153 offset:6144
	ds_read_b128 v[62:65], v153 offset:7168
	global_load_lds_dwordx4 v[66:67], off
	v_lshl_add_u64 v[66:67], v[244:245], 0, s[20:21]
	s_mov_b32 m0, s88
	s_nop 0
	global_load_lds_dwordx4 v[66:67], off
	s_waitcnt vmcnt(16)
	s_waitcnt lgkmcnt(0)
	s_barrier
	s_waitcnt lgkmcnt(0)
	v_mfma_f32_16x16x32_bf16 v[90:93], v[2:5], v[58:61], 0
	v_mfma_f32_16x16x32_bf16 v[66:69], v[2:5], v[34:37], 0
	v_mfma_f32_16x16x32_bf16 v[70:73], v[10:13], v[34:37], 0
	v_mfma_f32_16x16x32_bf16 v[74:77], v[2:5], v[42:45], 0
	v_mfma_f32_16x16x32_bf16 v[78:81], v[10:13], v[42:45], 0
	v_mfma_f32_16x16x32_bf16 v[82:85], v[2:5], v[50:53], 0
	v_mfma_f32_16x16x32_bf16 v[86:89], v[10:13], v[50:53], 0
	v_mfma_f32_16x16x32_bf16 v[94:97], v[6:9], v[62:65], v[90:93]
	v_mfma_f32_16x16x32_bf16 v[90:93], v[10:13], v[58:61], 0
	v_mfma_f32_16x16x32_bf16 v[66:69], v[6:9], v[38:41], v[66:69]
	v_mfma_f32_16x16x32_bf16 v[70:73], v[14:17], v[38:41], v[70:73]
	v_mfma_f32_16x16x32_bf16 v[74:77], v[6:9], v[46:49], v[74:77]
	v_mfma_f32_16x16x32_bf16 v[78:81], v[14:17], v[46:49], v[78:81]
	v_mfma_f32_16x16x32_bf16 v[82:85], v[6:9], v[54:57], v[82:85]
	v_mfma_f32_16x16x32_bf16 v[86:89], v[14:17], v[54:57], v[86:89]
	v_mfma_f32_16x16x32_bf16 v[102:105], v[14:17], v[62:65], v[90:93]
	v_mfma_f32_16x16x32_bf16 v[90:93], v[18:21], v[34:37], 0
	v_mfma_f32_16x16x32_bf16 v[34:37], v[26:29], v[34:37], 0
	v_mfma_f32_16x16x32_bf16 v[110:113], v[22:25], v[38:41], v[90:93]
	v_mfma_f32_16x16x32_bf16 v[34:37], v[30:33], v[38:41], v[34:37]
	v_mfma_f32_16x16x32_bf16 v[38:41], v[18:21], v[42:45], 0
	v_mfma_f32_16x16x32_bf16 v[42:45], v[26:29], v[42:45], 0
	v_mfma_f32_16x16x32_bf16 v[38:41], v[22:25], v[46:49], v[38:41]
	v_mfma_f32_16x16x32_bf16 v[42:45], v[30:33], v[46:49], v[42:45]
	v_mfma_f32_16x16x32_bf16 v[46:49], v[18:21], v[50:53], 0
	v_mfma_f32_16x16x32_bf16 v[50:53], v[26:29], v[50:53], 0
	v_mfma_f32_16x16x32_bf16 v[46:49], v[22:25], v[54:57], v[46:49]
	v_mfma_f32_16x16x32_bf16 v[54:57], v[30:33], v[54:57], v[50:53]
	s_barrier
	v_mfma_f32_16x16x32_bf16 v[50:53], v[18:21], v[58:61], 0
	v_mfma_f32_16x16x32_bf16 v[140:143], v[22:25], v[62:65], v[50:53]
	v_mfma_f32_16x16x32_bf16 v[50:53], v[26:29], v[58:61], 0
	v_mfma_f32_16x16x32_bf16 v[144:147], v[30:33], v[62:65], v[50:53]
	v_lshl_add_u64 v[246:247], s[80:81], 0, v[130:131]
	s_add_i32 vcc_lo, s84, s43
	v_lshl_add_u64 v[122:123], v[246:247], 0, s[22:23]
	s_mov_b32 m0, vcc_lo
	s_add_i32 vcc_hi, vcc_lo, 0x2000
	s_nop 0
	ds_read_b128 v[50:53], v153 offset:16384
	ds_read_b128 v[58:61], v153 offset:17408
	ds_read_b128 v[62:65], v153 offset:18432
	ds_read_b128 v[90:93], v153 offset:19456
	ds_read_b128 v[98:101], v153 offset:20480
	ds_read_b128 v[106:109], v153 offset:21504
	ds_read_b128 v[114:117], v153 offset:22528
	ds_read_b128 v[118:121], v153 offset:23552
	global_load_lds_dwordx4 v[122:123], off
	v_lshl_add_u64 v[122:123], v[246:247], 0, s[24:25]
	s_mov_b32 m0, vcc_hi
	s_add_i32 s40, s85, s43
	global_load_lds_dwordx4 v[122:123], off
	v_lshl_add_u64 v[122:123], v[246:247], 0, s[26:27]
	s_mov_b32 m0, s40
	s_add_i32 s41, s40, 0x2000
	global_load_lds_dwordx4 v[122:123], off
	v_lshl_add_u64 v[122:123], v[246:247], 0, s[28:29]
	s_mov_b32 m0, s41
	s_nop 0
	global_load_lds_dwordx4 v[122:123], off
	v_lshl_add_u64 v[122:123], v[244:245], 0, s[22:23]
	s_mov_b32 m0, s45
	s_nop 0
	global_load_lds_dwordx4 v[122:123], off
	v_lshl_add_u64 v[122:123], v[244:245], 0, s[24:25]
	s_mov_b32 m0, s46
	s_nop 0
	global_load_lds_dwordx4 v[122:123], off
	s_waitcnt vmcnt(16)
	s_waitcnt lgkmcnt(0)
	s_barrier
	s_waitcnt lgkmcnt(0)
	v_mfma_f32_16x16x32_bf16 v[122:125], v[2:5], v[50:53], 0
	v_mfma_f32_16x16x32_bf16 v[148:151], v[6:9], v[58:61], v[122:125]
	v_mfma_f32_16x16x32_bf16 v[122:125], v[10:13], v[50:53], 0
	v_mfma_f32_16x16x32_bf16 v[156:159], v[14:17], v[58:61], v[122:125]
	v_mfma_f32_16x16x32_bf16 v[122:125], v[2:5], v[62:65], 0
	v_mfma_f32_16x16x32_bf16 v[160:163], v[6:9], v[90:93], v[122:125]
	v_mfma_f32_16x16x32_bf16 v[122:125], v[10:13], v[62:65], 0
	v_mfma_f32_16x16x32_bf16 v[164:167], v[14:17], v[90:93], v[122:125]
	v_mfma_f32_16x16x32_bf16 v[122:125], v[2:5], v[98:101], 0
	v_mfma_f32_16x16x32_bf16 v[2:5], v[2:5], v[114:117], 0
	v_mfma_f32_16x16x32_bf16 v[168:171], v[6:9], v[106:109], v[122:125]
	v_mfma_f32_16x16x32_bf16 v[2:5], v[6:9], v[118:121], v[2:5]
	v_mfma_f32_16x16x32_bf16 v[6:9], v[10:13], v[114:117], 0
	v_mfma_f32_16x16x32_bf16 v[122:125], v[10:13], v[98:101], 0
	v_mfma_f32_16x16x32_bf16 v[6:9], v[14:17], v[118:121], v[6:9]
	v_mfma_f32_16x16x32_bf16 v[172:175], v[14:17], v[106:109], v[122:125]
	v_mfma_f32_16x16x32_bf16 v[10:13], v[18:21], v[50:53], 0
	v_mfma_f32_16x16x32_bf16 v[176:179], v[22:25], v[58:61], v[10:13]
	v_mfma_f32_16x16x32_bf16 v[10:13], v[26:29], v[50:53], 0
	v_mfma_f32_16x16x32_bf16 v[180:183], v[30:33], v[58:61], v[10:13]
	v_mfma_f32_16x16x32_bf16 v[10:13], v[18:21], v[62:65], 0
	v_mfma_f32_16x16x32_bf16 v[184:187], v[22:25], v[90:93], v[10:13]
	v_mfma_f32_16x16x32_bf16 v[10:13], v[26:29], v[62:65], 0
	v_mfma_f32_16x16x32_bf16 v[188:191], v[30:33], v[90:93], v[10:13]
	v_mfma_f32_16x16x32_bf16 v[10:13], v[18:21], v[98:101], 0
	v_mfma_f32_16x16x32_bf16 v[192:195], v[22:25], v[106:109], v[10:13]
	v_mfma_f32_16x16x32_bf16 v[10:13], v[26:29], v[98:101], 0
	v_mfma_f32_16x16x32_bf16 v[196:199], v[30:33], v[106:109], v[10:13]
	s_barrier
	v_mfma_f32_16x16x32_bf16 v[10:13], v[18:21], v[114:117], 0
	v_mfma_f32_16x16x32_bf16 v[200:203], v[22:25], v[118:121], v[10:13]
	v_mfma_f32_16x16x32_bf16 v[10:13], v[26:29], v[114:117], 0
	v_mfma_f32_16x16x32_bf16 v[204:207], v[30:33], v[118:121], v[10:13]
	s_nop 5
	ds_read_b128 v[10:13], v154
	ds_read_b128 v[14:17], v154 offset:1024
	ds_read_b128 v[18:21], v154 offset:2048
	ds_read_b128 v[26:29], v154 offset:3072
	ds_read_b128 v[208:211], v155
	ds_read_b128 v[212:215], v155 offset:1024
	ds_read_b128 v[216:219], v155 offset:2048
	ds_read_b128 v[220:223], v155 offset:3072
	s_mov_b32 m0, s47
	v_lshl_add_u64 v[50:51], v[244:245], 0, s[26:27]
	ds_read_b128 v[22:25], v153 offset:32768
	ds_read_b128 v[30:33], v153 offset:33792
	ds_read_b128 v[62:65], v153 offset:34816
	ds_read_b128 v[224:227], v153 offset:35840
	ds_read_b128 v[228:231], v153 offset:36864
	ds_read_b128 v[232:235], v153 offset:37888
	ds_read_b128 v[236:239], v153 offset:38912
	ds_read_b128 v[240:243], v153 offset:39936
	global_load_lds_dwordx4 v[50:51], off
	v_lshl_add_u64 v[50:51], v[244:245], 0, s[28:29]
	s_mov_b32 m0, s52
	s_nop 0
	global_load_lds_dwordx4 v[50:51], off
	s_waitcnt vmcnt(8)
	s_waitcnt lgkmcnt(0)
	s_barrier
	s_waitcnt lgkmcnt(0)
	v_mfma_f32_16x16x32_bf16 v[50:53], v[10:13], v[22:25], v[66:69]
	v_mfma_f32_16x16x32_bf16 v[122:125], v[14:17], v[30:33], v[50:53]
	v_mfma_f32_16x16x32_bf16 v[50:53], v[18:21], v[22:25], v[70:73]
	v_mfma_f32_16x16x32_bf16 v[114:117], v[26:29], v[30:33], v[50:53]
	v_mfma_f32_16x16x32_bf16 v[50:53], v[10:13], v[62:65], v[74:77]
	v_mfma_f32_16x16x32_bf16 v[106:109], v[14:17], v[224:227], v[50:53]
	v_mfma_f32_16x16x32_bf16 v[50:53], v[18:21], v[62:65], v[78:81]
	v_mfma_f32_16x16x32_bf16 v[98:101], v[26:29], v[224:227], v[50:53]
	v_mfma_f32_16x16x32_bf16 v[50:53], v[10:13], v[228:231], v[82:85]
	v_mfma_f32_16x16x32_bf16 v[90:93], v[14:17], v[232:235], v[50:53]
	v_mfma_f32_16x16x32_bf16 v[50:53], v[18:21], v[228:231], v[86:89]
	v_mfma_f32_16x16x32_bf16 v[82:85], v[26:29], v[232:235], v[50:53]
	v_mfma_f32_16x16x32_bf16 v[50:53], v[10:13], v[236:239], v[94:97]
	v_mfma_f32_16x16x32_bf16 v[58:61], v[14:17], v[240:243], v[50:53]
	v_mfma_f32_16x16x32_bf16 v[50:53], v[18:21], v[236:239], v[102:105]
	v_mfma_f32_16x16x32_bf16 v[50:53], v[26:29], v[240:243], v[50:53]
	v_mfma_f32_16x16x32_bf16 v[66:69], v[208:211], v[22:25], v[110:113]
	v_mfma_f32_16x16x32_bf16 v[22:25], v[216:219], v[22:25], v[34:37]
	v_mfma_f32_16x16x32_bf16 v[118:121], v[220:223], v[30:33], v[22:25]
	v_mfma_f32_16x16x32_bf16 v[22:25], v[208:211], v[62:65], v[38:41]
	v_mfma_f32_16x16x32_bf16 v[110:113], v[212:215], v[224:227], v[22:25]
	v_mfma_f32_16x16x32_bf16 v[22:25], v[216:219], v[62:65], v[42:45]
	v_mfma_f32_16x16x32_bf16 v[102:105], v[220:223], v[224:227], v[22:25]
	v_mfma_f32_16x16x32_bf16 v[22:25], v[208:211], v[228:231], v[46:49]
	v_mfma_f32_16x16x32_bf16 v[94:97], v[212:215], v[232:235], v[22:25]
	v_mfma_f32_16x16x32_bf16 v[22:25], v[216:219], v[228:231], v[54:57]
	v_mfma_f32_16x16x32_bf16 v[86:89], v[220:223], v[232:235], v[22:25]
	v_mfma_f32_16x16x32_bf16 v[22:25], v[208:211], v[236:239], v[140:143]
	s_barrier
	v_mfma_f32_16x16x32_bf16 v[62:65], v[212:215], v[240:243], v[22:25]
	v_mfma_f32_16x16x32_bf16 v[22:25], v[216:219], v[236:239], v[144:147]
	v_mfma_f32_16x16x32_bf16 v[126:129], v[212:215], v[30:33], v[66:69]
	v_mfma_f32_16x16x32_bf16 v[54:57], v[220:223], v[240:243], v[22:25]
	s_add_i32 s50, s89, s43
	s_nop 3
	v_lshl_add_u64 v[22:23], v[246:247], 0, s[30:31]
	s_mov_b32 m0, s50
	s_add_i32 s51, s50, 0x2000
	ds_read_b128 v[34:37], v153 offset:49152
	ds_read_b128 v[42:45], v153 offset:50176
	ds_read_b128 v[140:143], v153 offset:51200
	ds_read_b128 v[144:147], v153 offset:52224
	ds_read_b128 v[224:227], v153 offset:53248
	ds_read_b128 v[228:231], v153 offset:54272
	ds_read_b128 v[232:235], v153 offset:55296
	ds_read_b128 v[236:239], v153 offset:56320
	global_load_lds_dwordx4 v[22:23], off
	v_lshl_add_u64 v[22:23], v[246:247], 0, s[34:35]
	s_mov_b32 m0, s51
	s_mov_b64 s[56:57], 0x80180
	s_add_i32 s33, s90, s43
	global_load_lds_dwordx4 v[22:23], off
	v_lshl_add_u64 v[22:23], v[246:247], 0, s[56:57]
	s_mov_b32 m0, s33
	s_mov_b64 s[56:57], 0xc0180
	global_load_lds_dwordx4 v[22:23], off
	v_lshl_add_u64 v[22:23], v[246:247], 0, s[56:57]
	s_add_i32 s56, s33, 0x2000
	s_mov_b32 m0, s56
	s_nop 0
	global_load_lds_dwordx4 v[22:23], off
	v_lshl_add_u64 v[22:23], v[244:245], 0, s[30:31]
	s_mov_b32 m0, s53
	s_nop 0
	global_load_lds_dwordx4 v[22:23], off
	v_lshl_add_u64 v[22:23], v[244:245], 0, s[34:35]
	s_mov_b32 m0, s54
	s_nop 0
	global_load_lds_dwordx4 v[22:23], off
	s_waitcnt vmcnt(8)
	s_waitcnt lgkmcnt(0)
	s_barrier
	s_waitcnt lgkmcnt(0)
	v_mfma_f32_16x16x32_bf16 v[22:25], v[10:13], v[34:37], v[148:151]
	v_mfma_f32_16x16x32_bf16 v[78:81], v[14:17], v[42:45], v[22:25]
	v_mfma_f32_16x16x32_bf16 v[22:25], v[18:21], v[34:37], v[156:159]
	v_mfma_f32_16x16x32_bf16 v[70:73], v[26:29], v[42:45], v[22:25]
	v_mfma_f32_16x16x32_bf16 v[22:25], v[10:13], v[140:143], v[160:163]
	v_mfma_f32_16x16x32_bf16 v[46:49], v[14:17], v[144:147], v[22:25]
	v_mfma_f32_16x16x32_bf16 v[22:25], v[18:21], v[140:143], v[164:167]
	v_mfma_f32_16x16x32_bf16 v[38:41], v[26:29], v[144:147], v[22:25]
	v_mfma_f32_16x16x32_bf16 v[22:25], v[10:13], v[224:227], v[168:171]
	v_mfma_f32_16x16x32_bf16 v[2:5], v[10:13], v[232:235], v[2:5]
	v_mfma_f32_16x16x32_bf16 v[30:33], v[14:17], v[228:231], v[22:25]
	v_mfma_f32_16x16x32_bf16 v[22:25], v[18:21], v[224:227], v[172:175]
	v_mfma_f32_16x16x32_bf16 v[14:17], v[14:17], v[236:239], v[2:5]
	v_mfma_f32_16x16x32_bf16 v[2:5], v[18:21], v[232:235], v[6:9]
	v_mfma_f32_16x16x32_bf16 v[22:25], v[26:29], v[228:231], v[22:25]
	v_mfma_f32_16x16x32_bf16 v[10:13], v[26:29], v[236:239], v[2:5]
	v_mfma_f32_16x16x32_bf16 v[2:5], v[208:211], v[34:37], v[176:179]
	v_mfma_f32_16x16x32_bf16 v[74:77], v[212:215], v[42:45], v[2:5]
	v_mfma_f32_16x16x32_bf16 v[2:5], v[216:219], v[34:37], v[180:183]
	v_mfma_f32_16x16x32_bf16 v[66:69], v[220:223], v[42:45], v[2:5]
	v_mfma_f32_16x16x32_bf16 v[2:5], v[208:211], v[140:143], v[184:187]
	v_mfma_f32_16x16x32_bf16 v[42:45], v[212:215], v[144:147], v[2:5]
	v_mfma_f32_16x16x32_bf16 v[2:5], v[216:219], v[140:143], v[188:191]
	v_mfma_f32_16x16x32_bf16 v[34:37], v[220:223], v[144:147], v[2:5]
	v_mfma_f32_16x16x32_bf16 v[2:5], v[208:211], v[224:227], v[192:195]
	v_mfma_f32_16x16x32_bf16 v[26:29], v[212:215], v[228:231], v[2:5]
	v_mfma_f32_16x16x32_bf16 v[2:5], v[216:219], v[224:227], v[196:199]
	v_mfma_f32_16x16x32_bf16 v[18:21], v[220:223], v[228:231], v[2:5]
	s_barrier
	v_mfma_f32_16x16x32_bf16 v[2:5], v[208:211], v[232:235], v[200:203]
	v_mfma_f32_16x16x32_bf16 v[6:9], v[212:215], v[236:239], v[2:5]
	v_mfma_f32_16x16x32_bf16 v[2:5], v[216:219], v[232:235], v[204:207]
	v_mfma_f32_16x16x32_bf16 v[2:5], v[220:223], v[236:239], v[2:5]
	s_add_u32 s82, s82, 0x80180
	s_addc_u32 s83, s83, 0
	s_add_u32 s57, s80, 0x200
	s_addc_u32 s80, s81, 0
	s_mov_b32 s81, 0
.LBB0_1025:
	ds_read_b128 v[140:143], v1
	ds_read_b128 v[144:147], v1 offset:1024
	ds_read_b128 v[148:151], v1 offset:2048
	ds_read_b128 v[156:159], v1 offset:3072
	ds_read_b128 v[160:163], v152
	ds_read_b128 v[164:167], v152 offset:1024
	ds_read_b128 v[168:171], v152 offset:2048
	ds_read_b128 v[172:175], v152 offset:3072
	s_add_u32 s0, s82, 0xfff80080
	s_addc_u32 s1, s83, -1
	s_cmp_eq_u32 s81, 28
	s_cselect_b32 s1, s73, s1
	s_cselect_b32 s0, s75, s0
	s_cselect_b32 s65, s96, s80
	s_cselect_b32 s64, s97, s57
	s_mov_b32 m0, s87
	v_lshl_add_u64 v[208:209], s[82:83], 0, v[134:135]
	ds_read_b128 v[176:179], v153
	ds_read_b128 v[180:183], v153 offset:1024
	ds_read_b128 v[184:187], v153 offset:2048
	ds_read_b128 v[188:191], v153 offset:3072
	ds_read_b128 v[192:195], v153 offset:4096
	ds_read_b128 v[196:199], v153 offset:5120
	ds_read_b128 v[200:203], v153 offset:6144
	ds_read_b128 v[204:207], v153 offset:7168
	global_load_lds_dwordx4 v[208:209], off
	v_lshl_add_u64 v[208:209], v[208:209], 0, s[36:37]
	s_mov_b32 m0, s88
	s_nop 0
	global_load_lds_dwordx4 v[208:209], off
	s_waitcnt vmcnt(8)
	s_waitcnt lgkmcnt(0)
	s_barrier
	s_waitcnt lgkmcnt(0)
	v_mfma_f32_16x16x32_bf16 v[122:125], v[140:143], v[176:179], v[122:125]
	v_mfma_f32_16x16x32_bf16 v[114:117], v[148:151], v[176:179], v[114:117]
	v_mfma_f32_16x16x32_bf16 v[106:109], v[140:143], v[184:187], v[106:109]
	v_mfma_f32_16x16x32_bf16 v[98:101], v[148:151], v[184:187], v[98:101]
	v_mfma_f32_16x16x32_bf16 v[90:93], v[140:143], v[192:195], v[90:93]
	v_mfma_f32_16x16x32_bf16 v[82:85], v[148:151], v[192:195], v[82:85]
	v_mfma_f32_16x16x32_bf16 v[58:61], v[140:143], v[200:203], v[58:61]
	v_mfma_f32_16x16x32_bf16 v[50:53], v[148:151], v[200:203], v[50:53]
	v_mfma_f32_16x16x32_bf16 v[122:125], v[144:147], v[180:183], v[122:125]
	v_mfma_f32_16x16x32_bf16 v[114:117], v[156:159], v[180:183], v[114:117]
	v_mfma_f32_16x16x32_bf16 v[106:109], v[144:147], v[188:191], v[106:109]
	v_mfma_f32_16x16x32_bf16 v[98:101], v[156:159], v[188:191], v[98:101]
	v_mfma_f32_16x16x32_bf16 v[90:93], v[144:147], v[196:199], v[90:93]
	v_mfma_f32_16x16x32_bf16 v[82:85], v[156:159], v[196:199], v[82:85]
	v_mfma_f32_16x16x32_bf16 v[58:61], v[144:147], v[204:207], v[58:61]
	v_mfma_f32_16x16x32_bf16 v[50:53], v[156:159], v[204:207], v[50:53]
	v_mfma_f32_16x16x32_bf16 v[126:129], v[160:163], v[176:179], v[126:129]
	v_mfma_f32_16x16x32_bf16 v[118:121], v[168:171], v[176:179], v[118:121]
	v_mfma_f32_16x16x32_bf16 v[110:113], v[160:163], v[184:187], v[110:113]
	v_mfma_f32_16x16x32_bf16 v[102:105], v[168:171], v[184:187], v[102:105]
	v_mfma_f32_16x16x32_bf16 v[94:97], v[160:163], v[192:195], v[94:97]
	v_mfma_f32_16x16x32_bf16 v[86:89], v[168:171], v[192:195], v[86:89]
	v_mfma_f32_16x16x32_bf16 v[62:65], v[160:163], v[200:203], v[62:65]
	v_mfma_f32_16x16x32_bf16 v[54:57], v[168:171], v[200:203], v[54:57]
	v_mfma_f32_16x16x32_bf16 v[126:129], v[164:167], v[180:183], v[126:129]
	v_mfma_f32_16x16x32_bf16 v[118:121], v[172:175], v[180:183], v[118:121]
	v_mfma_f32_16x16x32_bf16 v[110:113], v[164:167], v[188:191], v[110:113]
	v_mfma_f32_16x16x32_bf16 v[102:105], v[172:175], v[188:191], v[102:105]
	s_barrier
	v_mfma_f32_16x16x32_bf16 v[94:97], v[164:167], v[196:199], v[94:97]
	v_mfma_f32_16x16x32_bf16 v[86:89], v[172:175], v[196:199], v[86:89]
	v_mfma_f32_16x16x32_bf16 v[62:65], v[164:167], v[204:207], v[62:65]
	v_mfma_f32_16x16x32_bf16 v[54:57], v[172:175], v[204:207], v[54:57]
	s_mov_b32 m0, vcc_lo
	v_lshl_add_u64 v[208:209], s[64:65], 0, v[130:131]
	ds_read_b128 v[176:179], v153 offset:16384
	ds_read_b128 v[180:183], v153 offset:17408
	ds_read_b128 v[184:187], v153 offset:18432
	ds_read_b128 v[188:191], v153 offset:19456
	ds_read_b128 v[192:195], v153 offset:20480
	ds_read_b128 v[196:199], v153 offset:21504
	ds_read_b128 v[200:203], v153 offset:22528
	ds_read_b128 v[204:207], v153 offset:23552
	global_load_lds_dwordx4 v[208:209], off
	v_lshl_add_u64 v[210:211], v[208:209], 0, s[36:37]
	s_mov_b32 m0, vcc_hi
	s_nop 0
	global_load_lds_dwordx4 v[210:211], off
	v_lshl_add_u64 v[210:211], v[208:209], 0, s[38:39]
	s_mov_b32 m0, s40
	s_nop 0
	global_load_lds_dwordx4 v[210:211], off
	v_lshl_add_u64 v[210:211], v[208:209], 0, s[66:67]
	s_mov_b32 m0, s41
	s_nop 0
	global_load_lds_dwordx4 v[210:211], off
	v_lshl_add_u64 v[210:211], s[0:1], 0, v[132:133]
	s_mov_b32 m0, s45
	v_lshl_add_u64 v[212:213], v[210:211], 0, s[36:37]
	global_load_lds_dwordx4 v[210:211], off
	s_mov_b32 m0, s46
	s_nop 0
	global_load_lds_dwordx4 v[212:213], off
	s_waitcnt vmcnt(8)
	s_waitcnt lgkmcnt(0)
	s_barrier
	s_waitcnt lgkmcnt(0)
	v_mfma_f32_16x16x32_bf16 v[78:81], v[140:143], v[176:179], v[78:81]
	v_mfma_f32_16x16x32_bf16 v[70:73], v[148:151], v[176:179], v[70:73]
	v_mfma_f32_16x16x32_bf16 v[46:49], v[140:143], v[184:187], v[46:49]
	v_mfma_f32_16x16x32_bf16 v[38:41], v[148:151], v[184:187], v[38:41]
	v_mfma_f32_16x16x32_bf16 v[30:33], v[140:143], v[192:195], v[30:33]
	v_mfma_f32_16x16x32_bf16 v[22:25], v[148:151], v[192:195], v[22:25]
	v_mfma_f32_16x16x32_bf16 v[14:17], v[140:143], v[200:203], v[14:17]
	v_mfma_f32_16x16x32_bf16 v[10:13], v[148:151], v[200:203], v[10:13]
	v_mfma_f32_16x16x32_bf16 v[78:81], v[144:147], v[180:183], v[78:81]
	v_mfma_f32_16x16x32_bf16 v[70:73], v[156:159], v[180:183], v[70:73]
	v_mfma_f32_16x16x32_bf16 v[46:49], v[144:147], v[188:191], v[46:49]
	v_mfma_f32_16x16x32_bf16 v[38:41], v[156:159], v[188:191], v[38:41]
	v_mfma_f32_16x16x32_bf16 v[30:33], v[144:147], v[196:199], v[30:33]
	v_mfma_f32_16x16x32_bf16 v[22:25], v[156:159], v[196:199], v[22:25]
	v_mfma_f32_16x16x32_bf16 v[14:17], v[144:147], v[204:207], v[14:17]
	v_mfma_f32_16x16x32_bf16 v[10:13], v[156:159], v[204:207], v[10:13]
	v_mfma_f32_16x16x32_bf16 v[74:77], v[160:163], v[176:179], v[74:77]
	v_mfma_f32_16x16x32_bf16 v[66:69], v[168:171], v[176:179], v[66:69]
	v_mfma_f32_16x16x32_bf16 v[42:45], v[160:163], v[184:187], v[42:45]
	v_mfma_f32_16x16x32_bf16 v[34:37], v[168:171], v[184:187], v[34:37]
	v_mfma_f32_16x16x32_bf16 v[26:29], v[160:163], v[192:195], v[26:29]
	v_mfma_f32_16x16x32_bf16 v[18:21], v[168:171], v[192:195], v[18:21]
	v_mfma_f32_16x16x32_bf16 v[6:9], v[160:163], v[200:203], v[6:9]
	v_mfma_f32_16x16x32_bf16 v[2:5], v[168:171], v[200:203], v[2:5]
	v_mfma_f32_16x16x32_bf16 v[74:77], v[164:167], v[180:183], v[74:77]
	v_mfma_f32_16x16x32_bf16 v[66:69], v[172:175], v[180:183], v[66:69]
	v_mfma_f32_16x16x32_bf16 v[42:45], v[164:167], v[188:191], v[42:45]
	v_mfma_f32_16x16x32_bf16 v[34:37], v[172:175], v[188:191], v[34:37]
	s_barrier
	v_mfma_f32_16x16x32_bf16 v[26:29], v[164:167], v[196:199], v[26:29]
	v_mfma_f32_16x16x32_bf16 v[18:21], v[172:175], v[196:199], v[18:21]
	v_mfma_f32_16x16x32_bf16 v[6:9], v[164:167], v[204:207], v[6:9]
	v_mfma_f32_16x16x32_bf16 v[2:5], v[172:175], v[204:207], v[2:5]
	ds_read_b128 v[140:143], v154
	ds_read_b128 v[144:147], v154 offset:1024
	ds_read_b128 v[148:151], v154 offset:2048
	ds_read_b128 v[156:159], v154 offset:3072
	ds_read_b128 v[160:163], v155
	ds_read_b128 v[164:167], v155 offset:1024
	ds_read_b128 v[168:171], v155 offset:2048
	ds_read_b128 v[172:175], v155 offset:3072
	s_mov_b32 m0, s47
	v_lshl_add_u64 v[212:213], v[210:211], 0, s[38:39]
	ds_read_b128 v[176:179], v153 offset:32768
	ds_read_b128 v[180:183], v153 offset:33792
	ds_read_b128 v[184:187], v153 offset:34816
	ds_read_b128 v[188:191], v153 offset:35840
	ds_read_b128 v[192:195], v153 offset:36864
	ds_read_b128 v[196:199], v153 offset:37888
	ds_read_b128 v[200:203], v153 offset:38912
	ds_read_b128 v[204:207], v153 offset:39936
	global_load_lds_dwordx4 v[212:213], off
	v_lshl_add_u64 v[212:213], v[210:211], 0, s[66:67]
	s_mov_b32 m0, s52
	s_nop 0
	global_load_lds_dwordx4 v[212:213], off
	s_waitcnt vmcnt(8)
	s_waitcnt lgkmcnt(0)
	s_barrier
	s_waitcnt lgkmcnt(0)
	v_mfma_f32_16x16x32_bf16 v[122:125], v[140:143], v[176:179], v[122:125]
	v_mfma_f32_16x16x32_bf16 v[114:117], v[148:151], v[176:179], v[114:117]
	v_mfma_f32_16x16x32_bf16 v[106:109], v[140:143], v[184:187], v[106:109]
	v_mfma_f32_16x16x32_bf16 v[98:101], v[148:151], v[184:187], v[98:101]
	v_mfma_f32_16x16x32_bf16 v[90:93], v[140:143], v[192:195], v[90:93]
	v_mfma_f32_16x16x32_bf16 v[82:85], v[148:151], v[192:195], v[82:85]
	v_mfma_f32_16x16x32_bf16 v[58:61], v[140:143], v[200:203], v[58:61]
	v_mfma_f32_16x16x32_bf16 v[50:53], v[148:151], v[200:203], v[50:53]
	v_mfma_f32_16x16x32_bf16 v[122:125], v[144:147], v[180:183], v[122:125]
	v_mfma_f32_16x16x32_bf16 v[114:117], v[156:159], v[180:183], v[114:117]
	v_mfma_f32_16x16x32_bf16 v[106:109], v[144:147], v[188:191], v[106:109]
	v_mfma_f32_16x16x32_bf16 v[98:101], v[156:159], v[188:191], v[98:101]
	v_mfma_f32_16x16x32_bf16 v[90:93], v[144:147], v[196:199], v[90:93]
	v_mfma_f32_16x16x32_bf16 v[82:85], v[156:159], v[196:199], v[82:85]
	v_mfma_f32_16x16x32_bf16 v[58:61], v[144:147], v[204:207], v[58:61]
	v_mfma_f32_16x16x32_bf16 v[50:53], v[156:159], v[204:207], v[50:53]
	v_mfma_f32_16x16x32_bf16 v[126:129], v[160:163], v[176:179], v[126:129]
	v_mfma_f32_16x16x32_bf16 v[118:121], v[168:171], v[176:179], v[118:121]
	v_mfma_f32_16x16x32_bf16 v[110:113], v[160:163], v[184:187], v[110:113]
	v_mfma_f32_16x16x32_bf16 v[102:105], v[168:171], v[184:187], v[102:105]
	v_mfma_f32_16x16x32_bf16 v[94:97], v[160:163], v[192:195], v[94:97]
	v_mfma_f32_16x16x32_bf16 v[86:89], v[168:171], v[192:195], v[86:89]
	v_mfma_f32_16x16x32_bf16 v[62:65], v[160:163], v[200:203], v[62:65]
	v_mfma_f32_16x16x32_bf16 v[54:57], v[168:171], v[200:203], v[54:57]
	v_mfma_f32_16x16x32_bf16 v[126:129], v[164:167], v[180:183], v[126:129]
	v_mfma_f32_16x16x32_bf16 v[118:121], v[172:175], v[180:183], v[118:121]
	v_mfma_f32_16x16x32_bf16 v[110:113], v[164:167], v[188:191], v[110:113]
	v_mfma_f32_16x16x32_bf16 v[102:105], v[172:175], v[188:191], v[102:105]
	s_barrier
; #define PG8_WAIT_V(n) asm volatile("s_waitcnt vmcnt(" #n ")" ::: "memory")
; template <class Epi, class Sched, bool ALIGN_EPI = true, bool SP2 = true, bool FULLLINE = false, bool NOSTAGE = false, bool FP8 = false>
; __device__ __forceinline__ void gemm_phase(PG8_LAS unsigned char* lds, const Gemm g, const Sched& S, const Epi& E) {
;     ...
;         static_assert(SP2, "only the SP2 loop is kept");
;         { const int t = 0; if constexpr (Epi::NST == 16) PG8_ITER(PG8_WAIT_V(24)); else if constexpr (Epi::NST == 8) PG8_ITER(PG8_WAIT_V(16)); else PG8_ITER(PG8_WAIT_V(8)); }
;         for (int t = 2; t < nt; t += 2) PG8_ITER(PG8_WAIT_V(8));
	v_mfma_f32_16x16x32_bf16 v[94:97], v[164:167], v[196:199], v[94:97]
	v_mfma_f32_16x16x32_bf16 v[86:89], v[172:175], v[196:199], v[86:89]
	v_mfma_f32_16x16x32_bf16 v[62:65], v[164:167], v[204:207], v[62:65]
	v_mfma_f32_16x16x32_bf16 v[54:57], v[172:175], v[204:207], v[54:57]
	s_mov_b32 m0, s50
	v_lshl_add_u64 v[212:213], v[208:209], 0, s[68:69]
	ds_read_b128 v[176:179], v153 offset:49152
	ds_read_b128 v[180:183], v153 offset:50176
	ds_read_b128 v[184:187], v153 offset:51200
	ds_read_b128 v[188:191], v153 offset:52224
	ds_read_b128 v[192:195], v153 offset:53248
	ds_read_b128 v[196:199], v153 offset:54272
	ds_read_b128 v[200:203], v153 offset:55296
	ds_read_b128 v[204:207], v153 offset:56320
	global_load_lds_dwordx4 v[212:213], off
	v_lshl_add_u64 v[212:213], v[208:209], 0, s[70:71]
	s_mov_b32 m0, s51
	s_nop 0
	global_load_lds_dwordx4 v[212:213], off
	v_lshl_add_u64 v[212:213], v[208:209], 0, s[18:19]
	s_mov_b32 m0, s33
	v_lshl_add_u64 v[208:209], v[208:209], 0, s[20:21]
	global_load_lds_dwordx4 v[212:213], off
	s_mov_b32 m0, s56
	s_nop 0
	global_load_lds_dwordx4 v[208:209], off
	v_lshl_add_u64 v[208:209], v[210:211], 0, s[68:69]
	s_mov_b32 m0, s53
	s_nop 0
	global_load_lds_dwordx4 v[208:209], off
	v_lshl_add_u64 v[208:209], v[210:211], 0, s[70:71]
	s_mov_b32 m0, s54
	s_nop 0
	global_load_lds_dwordx4 v[208:209], off
	s_waitcnt vmcnt(8)
	s_waitcnt lgkmcnt(0)
	s_barrier
	s_waitcnt lgkmcnt(0)
	v_mfma_f32_16x16x32_bf16 v[78:81], v[140:143], v[176:179], v[78:81]
	v_mfma_f32_16x16x32_bf16 v[70:73], v[148:151], v[176:179], v[70:73]
	v_mfma_f32_16x16x32_bf16 v[46:49], v[140:143], v[184:187], v[46:49]
	v_mfma_f32_16x16x32_bf16 v[38:41], v[148:151], v[184:187], v[38:41]
	v_mfma_f32_16x16x32_bf16 v[30:33], v[140:143], v[192:195], v[30:33]
	v_mfma_f32_16x16x32_bf16 v[22:25], v[148:151], v[192:195], v[22:25]
	v_mfma_f32_16x16x32_bf16 v[14:17], v[140:143], v[200:203], v[14:17]
	v_mfma_f32_16x16x32_bf16 v[10:13], v[148:151], v[200:203], v[10:13]
	v_mfma_f32_16x16x32_bf16 v[78:81], v[144:147], v[180:183], v[78:81]
	v_mfma_f32_16x16x32_bf16 v[70:73], v[156:159], v[180:183], v[70:73]
	v_mfma_f32_16x16x32_bf16 v[46:49], v[144:147], v[188:191], v[46:49]
	v_mfma_f32_16x16x32_bf16 v[38:41], v[156:159], v[188:191], v[38:41]
	v_mfma_f32_16x16x32_bf16 v[30:33], v[144:147], v[196:199], v[30:33]
	v_mfma_f32_16x16x32_bf16 v[22:25], v[156:159], v[196:199], v[22:25]
	v_mfma_f32_16x16x32_bf16 v[14:17], v[144:147], v[204:207], v[14:17]
	v_mfma_f32_16x16x32_bf16 v[10:13], v[156:159], v[204:207], v[10:13]
	v_mfma_f32_16x16x32_bf16 v[74:77], v[160:163], v[176:179], v[74:77]
	v_mfma_f32_16x16x32_bf16 v[66:69], v[168:171], v[176:179], v[66:69]
	v_mfma_f32_16x16x32_bf16 v[42:45], v[160:163], v[184:187], v[42:45]
	v_mfma_f32_16x16x32_bf16 v[34:37], v[168:171], v[184:187], v[34:37]
	v_mfma_f32_16x16x32_bf16 v[26:29], v[160:163], v[192:195], v[26:29]
	v_mfma_f32_16x16x32_bf16 v[18:21], v[168:171], v[192:195], v[18:21]
	v_mfma_f32_16x16x32_bf16 v[6:9], v[160:163], v[200:203], v[6:9]
	v_mfma_f32_16x16x32_bf16 v[2:5], v[168:171], v[200:203], v[2:5]
	v_mfma_f32_16x16x32_bf16 v[74:77], v[164:167], v[180:183], v[74:77]
	v_mfma_f32_16x16x32_bf16 v[66:69], v[172:175], v[180:183], v[66:69]
	v_mfma_f32_16x16x32_bf16 v[42:45], v[164:167], v[188:191], v[42:45]
	v_mfma_f32_16x16x32_bf16 v[34:37], v[172:175], v[188:191], v[34:37]
	s_barrier
	v_mfma_f32_16x16x32_bf16 v[26:29], v[164:167], v[196:199], v[26:29]
	v_mfma_f32_16x16x32_bf16 v[18:21], v[172:175], v[196:199], v[18:21]
	v_mfma_f32_16x16x32_bf16 v[6:9], v[164:167], v[204:207], v[6:9]
	v_mfma_f32_16x16x32_bf16 v[2:5], v[172:175], v[204:207], v[2:5]
	s_add_i32 s81, s81, 2
	s_add_u32 s82, s82, 0x100
	s_addc_u32 s83, s83, 0
	s_add_u32 s57, s57, 0x100
	s_addc_u32 s80, s80, 0
	s_cmp_gt_u32 s81, 29
	s_cbranch_scc0 .LBB0_1025
	s_and_b64 vcc, exec, s[14:15]
	s_cbranch_vccz .LBB0_1028
	s_barrier

; #define PG8_WAIT_V(n) asm volatile("s_waitcnt vmcnt(" #n ")" ::: "memory")
; template <class Epi, class Sched, bool ALIGN_EPI = true, bool SP2 = true, bool FULLLINE = false, bool NOSTAGE = false, bool FP8 = false>
; __device__ __forceinline__ void gemm_phase(PG8_LAS unsigned char* lds, const Gemm g, const Sched& S, const Epi& E) {
;     ...
;         { const int t = 0; if constexpr (Epi::NST == 16) PG8_ITER(PG8_WAIT_V(24)); else if constexpr (Epi::NST == 8) PG8_ITER(PG8_WAIT_V(16)); else PG8_ITER(PG8_WAIT_V(8)); }
.LBB0_1207:
	s_ashr_i32 s69, s68, 31
	ds_read_b128 v[2:5], v1
	ds_read_b128 v[6:9], v1 offset:1024
	ds_read_b128 v[10:13], v1 offset:2048
	ds_read_b128 v[14:17], v1 offset:3072
	ds_read_b128 v[18:21], v192
	ds_read_b128 v[22:25], v192 offset:1024
	ds_read_b128 v[26:29], v192 offset:2048
	ds_read_b128 v[30:33], v192 offset:3072
	s_lshl_b64 s[0:1], s[68:69], 20
	s_add_u32 s70, s42, s0
	s_addc_u32 s71, s43, s1
	s_and_b64 s[0:1], s[8:9], exec
	s_cselect_b32 s69, s71, s77
	s_cselect_b32 s92, s70, s76
	s_ashr_i32 s67, s66, 31
	s_lshl_b64 s[0:1], s[66:67], 20
	s_add_u32 s72, s44, s0
	s_addc_u32 s73, s45, s1
	s_and_b64 s[0:1], s[8:9], exec
	s_cselect_b32 s67, s73, s79
	s_cselect_b32 s93, s72, s78
	v_lshl_add_u64 v[248:249], s[76:77], 0, v[170:171]
	s_mov_b32 m0, s88
	v_lshl_add_u64 v[66:67], v[248:249], 0, s[12:13]
	ds_read_b128 v[34:37], v193
	ds_read_b128 v[38:41], v193 offset:1024
	ds_read_b128 v[42:45], v193 offset:2048
	ds_read_b128 v[46:49], v193 offset:3072
	ds_read_b128 v[50:53], v193 offset:4096
	ds_read_b128 v[54:57], v193 offset:5120
	ds_read_b128 v[58:61], v193 offset:6144
	ds_read_b128 v[62:65], v193 offset:7168
	global_load_lds_dwordx4 v[66:67], off
	v_lshl_add_u64 v[66:67], v[248:249], 0, s[14:15]
	s_mov_b32 m0, s89
	s_nop 0
	global_load_lds_dwordx4 v[66:67], off
	s_waitcnt vmcnt(24)
	s_waitcnt lgkmcnt(0)
	s_barrier
	s_waitcnt lgkmcnt(0)
	v_mfma_f32_16x16x32_bf16 v[66:69], v[2:5], v[34:37], 0
	v_mfma_f32_16x16x32_bf16 v[70:73], v[10:13], v[34:37], 0
	v_mfma_f32_16x16x32_bf16 v[78:81], v[10:13], v[42:45], 0
	v_mfma_f32_16x16x32_bf16 v[86:89], v[10:13], v[50:53], 0
	v_mfma_f32_16x16x32_bf16 v[66:69], v[6:9], v[38:41], v[66:69]
	v_mfma_f32_16x16x32_bf16 v[70:73], v[14:17], v[38:41], v[70:73]
	v_mfma_f32_16x16x32_bf16 v[74:77], v[2:5], v[42:45], 0
	v_mfma_f32_16x16x32_bf16 v[78:81], v[14:17], v[46:49], v[78:81]
	v_mfma_f32_16x16x32_bf16 v[82:85], v[2:5], v[50:53], 0
	v_mfma_f32_16x16x32_bf16 v[86:89], v[14:17], v[54:57], v[86:89]
	v_mfma_f32_16x16x32_bf16 v[90:93], v[2:5], v[58:61], 0
	v_mfma_f32_16x16x32_bf16 v[94:97], v[10:13], v[58:61], 0
	v_mfma_f32_16x16x32_bf16 v[74:77], v[6:9], v[46:49], v[74:77]
	v_mfma_f32_16x16x32_bf16 v[82:85], v[6:9], v[54:57], v[82:85]
	v_mfma_f32_16x16x32_bf16 v[90:93], v[6:9], v[62:65], v[90:93]
	v_mfma_f32_16x16x32_bf16 v[94:97], v[14:17], v[62:65], v[94:97]
	v_mfma_f32_16x16x32_bf16 v[98:101], v[18:21], v[34:37], 0
	v_mfma_f32_16x16x32_bf16 v[34:37], v[26:29], v[34:37], 0
	v_mfma_f32_16x16x32_bf16 v[98:101], v[22:25], v[38:41], v[98:101]
	v_mfma_f32_16x16x32_bf16 v[34:37], v[30:33], v[38:41], v[34:37]
	v_mfma_f32_16x16x32_bf16 v[38:41], v[18:21], v[42:45], 0
	v_mfma_f32_16x16x32_bf16 v[42:45], v[26:29], v[42:45], 0
	v_mfma_f32_16x16x32_bf16 v[38:41], v[22:25], v[46:49], v[38:41]
	v_mfma_f32_16x16x32_bf16 v[42:45], v[30:33], v[46:49], v[42:45]
	v_mfma_f32_16x16x32_bf16 v[46:49], v[18:21], v[50:53], 0
	v_mfma_f32_16x16x32_bf16 v[50:53], v[26:29], v[50:53], 0
	v_mfma_f32_16x16x32_bf16 v[46:49], v[22:25], v[54:57], v[46:49]
	v_mfma_f32_16x16x32_bf16 v[50:53], v[30:33], v[54:57], v[50:53]
	s_barrier
	v_mfma_f32_16x16x32_bf16 v[54:57], v[18:21], v[58:61], 0
	v_mfma_f32_16x16x32_bf16 v[58:61], v[26:29], v[58:61], 0
	v_mfma_f32_16x16x32_bf16 v[54:57], v[22:25], v[62:65], v[54:57]
	v_mfma_f32_16x16x32_bf16 v[58:61], v[30:33], v[62:65], v[58:61]
	v_lshl_add_u64 v[250:251], s[78:79], 0, v[172:173]
	s_add_i32 s94, s85, s46
	v_lshl_add_u64 v[130:131], v[250:251], 0, s[16:17]
	s_mov_b32 m0, s94
	s_add_i32 s95, s94, 0x2000
	ds_read_b128 v[62:65], v193 offset:16384
	ds_read_b128 v[102:105], v193 offset:17408
	ds_read_b128 v[106:109], v193 offset:18432
	ds_read_b128 v[110:113], v193 offset:19456
	ds_read_b128 v[114:117], v193 offset:20480
	ds_read_b128 v[118:121], v193 offset:21504
	ds_read_b128 v[122:125], v193 offset:22528
	ds_read_b128 v[126:129], v193 offset:23552
	global_load_lds_dwordx4 v[130:131], off
	v_lshl_add_u64 v[130:131], v[250:251], 0, s[18:19]
	s_mov_b32 m0, s95
	s_add_i32 s40, s87, s46
	global_load_lds_dwordx4 v[130:131], off
	v_lshl_add_u64 v[130:131], v[250:251], 0, s[20:21]
	s_mov_b32 m0, s40
	s_add_i32 s41, s40, 0x2000
	global_load_lds_dwordx4 v[130:131], off
	v_lshl_add_u64 v[130:131], v[250:251], 0, s[22:23]
	s_mov_b32 m0, s41
	s_nop 0
	global_load_lds_dwordx4 v[130:131], off
	v_lshl_add_u64 v[130:131], v[248:249], 0, s[16:17]
	s_mov_b32 m0, s47
	s_nop 0
	global_load_lds_dwordx4 v[130:131], off
	v_lshl_add_u64 v[130:131], v[248:249], 0, s[18:19]
	s_mov_b32 m0, s52
	s_nop 0
	global_load_lds_dwordx4 v[130:131], off
	s_waitcnt vmcnt(24)
	s_waitcnt lgkmcnt(0)
	s_barrier
	s_waitcnt lgkmcnt(0)
	v_mfma_f32_16x16x32_bf16 v[130:133], v[2:5], v[62:65], 0
	v_mfma_f32_16x16x32_bf16 v[138:141], v[6:9], v[102:105], v[130:133]
	v_mfma_f32_16x16x32_bf16 v[130:133], v[10:13], v[62:65], 0
	v_mfma_f32_16x16x32_bf16 v[150:153], v[14:17], v[102:105], v[130:133]
	v_mfma_f32_16x16x32_bf16 v[130:133], v[2:5], v[106:109], 0
	v_mfma_f32_16x16x32_bf16 v[154:157], v[6:9], v[110:113], v[130:133]
	v_mfma_f32_16x16x32_bf16 v[130:133], v[10:13], v[106:109], 0
	v_mfma_f32_16x16x32_bf16 v[158:161], v[14:17], v[110:113], v[130:133]
	v_mfma_f32_16x16x32_bf16 v[130:133], v[2:5], v[114:117], 0
	v_mfma_f32_16x16x32_bf16 v[2:5], v[2:5], v[122:125], 0
	v_mfma_f32_16x16x32_bf16 v[162:165], v[6:9], v[118:121], v[130:133]
	v_mfma_f32_16x16x32_bf16 v[2:5], v[6:9], v[126:129], v[2:5]
	v_mfma_f32_16x16x32_bf16 v[6:9], v[10:13], v[122:125], 0
	v_mfma_f32_16x16x32_bf16 v[130:133], v[10:13], v[114:117], 0
	v_mfma_f32_16x16x32_bf16 v[6:9], v[14:17], v[126:129], v[6:9]
	v_mfma_f32_16x16x32_bf16 v[166:169], v[14:17], v[118:121], v[130:133]
	v_mfma_f32_16x16x32_bf16 v[10:13], v[18:21], v[62:65], 0
	v_mfma_f32_16x16x32_bf16 v[180:183], v[22:25], v[102:105], v[10:13]
	v_mfma_f32_16x16x32_bf16 v[10:13], v[26:29], v[62:65], 0
	v_mfma_f32_16x16x32_bf16 v[184:187], v[30:33], v[102:105], v[10:13]
	v_mfma_f32_16x16x32_bf16 v[10:13], v[18:21], v[106:109], 0
	v_mfma_f32_16x16x32_bf16 v[188:191], v[22:25], v[110:113], v[10:13]
	v_mfma_f32_16x16x32_bf16 v[10:13], v[26:29], v[106:109], 0
	v_mfma_f32_16x16x32_bf16 v[196:199], v[30:33], v[110:113], v[10:13]
	v_mfma_f32_16x16x32_bf16 v[10:13], v[18:21], v[114:117], 0
	v_mfma_f32_16x16x32_bf16 v[200:203], v[22:25], v[118:121], v[10:13]
	v_mfma_f32_16x16x32_bf16 v[10:13], v[26:29], v[114:117], 0
	v_mfma_f32_16x16x32_bf16 v[204:207], v[30:33], v[118:121], v[10:13]
	s_barrier
	v_mfma_f32_16x16x32_bf16 v[10:13], v[18:21], v[122:125], 0
	v_mfma_f32_16x16x32_bf16 v[208:211], v[22:25], v[126:129], v[10:13]
	v_mfma_f32_16x16x32_bf16 v[10:13], v[26:29], v[122:125], 0
	v_mfma_f32_16x16x32_bf16 v[212:215], v[30:33], v[126:129], v[10:13]
	s_nop 5
	ds_read_b128 v[10:13], v194
	ds_read_b128 v[14:17], v194 offset:1024
	ds_read_b128 v[18:21], v194 offset:2048
	ds_read_b128 v[22:25], v194 offset:3072
	ds_read_b128 v[216:219], v195
	ds_read_b128 v[220:223], v195 offset:1024
	ds_read_b128 v[224:227], v195 offset:2048
	ds_read_b128 v[228:231], v195 offset:3072
	s_mov_b32 m0, s53
	v_lshl_add_u64 v[106:107], v[248:249], 0, s[20:21]
	ds_read_b128 v[26:29], v193 offset:32768
	ds_read_b128 v[30:33], v193 offset:33792
	ds_read_b128 v[62:65], v193 offset:34816
	ds_read_b128 v[102:105], v193 offset:35840
	ds_read_b128 v[232:235], v193 offset:36864
	ds_read_b128 v[236:239], v193 offset:37888
	ds_read_b128 v[240:243], v193 offset:38912
	ds_read_b128 v[244:247], v193 offset:39936
	global_load_lds_dwordx4 v[106:107], off
	v_lshl_add_u64 v[106:107], v[248:249], 0, s[22:23]
	s_mov_b32 m0, s54
	s_nop 0
	global_load_lds_dwordx4 v[106:107], off
	s_waitcnt vmcnt(8)
	s_waitcnt lgkmcnt(0)
	s_barrier
	s_waitcnt lgkmcnt(0)
	v_mfma_f32_16x16x32_bf16 v[66:69], v[10:13], v[26:29], v[66:69]
	v_mfma_f32_16x16x32_bf16 v[146:149], v[14:17], v[30:33], v[66:69]
	v_mfma_f32_16x16x32_bf16 v[66:69], v[18:21], v[26:29], v[70:73]
	v_mfma_f32_16x16x32_bf16 v[142:145], v[22:25], v[30:33], v[66:69]
	v_mfma_f32_16x16x32_bf16 v[66:69], v[10:13], v[62:65], v[74:77]
	v_mfma_f32_16x16x32_bf16 v[126:129], v[14:17], v[102:105], v[66:69]
	v_mfma_f32_16x16x32_bf16 v[66:69], v[18:21], v[62:65], v[78:81]
	v_mfma_f32_16x16x32_bf16 v[122:125], v[22:25], v[102:105], v[66:69]
	v_mfma_f32_16x16x32_bf16 v[66:69], v[10:13], v[232:235], v[82:85]
	v_mfma_f32_16x16x32_bf16 v[110:113], v[14:17], v[236:239], v[66:69]
	v_mfma_f32_16x16x32_bf16 v[66:69], v[18:21], v[232:235], v[86:89]
	v_mfma_f32_16x16x32_bf16 v[106:109], v[22:25], v[236:239], v[66:69]
	v_mfma_f32_16x16x32_bf16 v[66:69], v[10:13], v[240:243], v[90:93]
	v_mfma_f32_16x16x32_bf16 v[86:89], v[14:17], v[244:247], v[66:69]
	v_mfma_f32_16x16x32_bf16 v[66:69], v[18:21], v[240:243], v[94:97]
	v_mfma_f32_16x16x32_bf16 v[78:81], v[22:25], v[244:247], v[66:69]
	v_mfma_f32_16x16x32_bf16 v[66:69], v[216:219], v[26:29], v[98:101]
	v_mfma_f32_16x16x32_bf16 v[26:29], v[224:227], v[26:29], v[34:37]
	v_mfma_f32_16x16x32_bf16 v[130:133], v[228:231], v[30:33], v[26:29]
	v_mfma_f32_16x16x32_bf16 v[26:29], v[216:219], v[62:65], v[38:41]
	v_mfma_f32_16x16x32_bf16 v[118:121], v[220:223], v[102:105], v[26:29]
	v_mfma_f32_16x16x32_bf16 v[26:29], v[224:227], v[62:65], v[42:45]
	v_mfma_f32_16x16x32_bf16 v[114:117], v[228:231], v[102:105], v[26:29]
	v_mfma_f32_16x16x32_bf16 v[26:29], v[216:219], v[232:235], v[46:49]
	v_mfma_f32_16x16x32_bf16 v[102:105], v[220:223], v[236:239], v[26:29]
	v_mfma_f32_16x16x32_bf16 v[26:29], v[224:227], v[232:235], v[50:53]
	v_mfma_f32_16x16x32_bf16 v[98:101], v[228:231], v[236:239], v[26:29]
	v_mfma_f32_16x16x32_bf16 v[26:29], v[216:219], v[240:243], v[54:57]
	s_barrier
	v_mfma_f32_16x16x32_bf16 v[70:73], v[220:223], v[244:247], v[26:29]
	v_mfma_f32_16x16x32_bf16 v[26:29], v[224:227], v[240:243], v[58:61]
	v_mfma_f32_16x16x32_bf16 v[134:137], v[220:223], v[30:33], v[66:69]
	v_mfma_f32_16x16x32_bf16 v[66:69], v[228:231], v[244:247], v[26:29]
	s_add_i32 s50, s90, s46
	s_nop 3
	v_lshl_add_u64 v[26:27], v[250:251], 0, s[24:25]
	s_mov_b32 m0, s50
	s_add_i32 s51, s50, 0x2000
	ds_read_b128 v[34:37], v193 offset:49152
	ds_read_b128 v[38:41], v193 offset:50176
	ds_read_b128 v[74:77], v193 offset:51200
	ds_read_b128 v[82:85], v193 offset:52224
	ds_read_b128 v[90:93], v193 offset:53248
	ds_read_b128 v[94:97], v193 offset:54272
	ds_read_b128 v[232:235], v193 offset:55296
	ds_read_b128 v[236:239], v193 offset:56320
	global_load_lds_dwordx4 v[26:27], off
	v_lshl_add_u64 v[26:27], v[250:251], 0, s[26:27]
	s_mov_b32 m0, s51
	s_mov_b64 s[0:1], 0x80180
	s_add_i32 s33, s91, s46
	global_load_lds_dwordx4 v[26:27], off
	v_lshl_add_u64 v[26:27], v[250:251], 0, s[0:1]
	s_mov_b32 m0, s33
	s_mov_b64 s[0:1], 0xc0180
	s_add_i32 s56, s33, 0x2000
	global_load_lds_dwordx4 v[26:27], off
	v_lshl_add_u64 v[26:27], v[250:251], 0, s[0:1]
	s_mov_b32 m0, s56
	s_nop 0
	global_load_lds_dwordx4 v[26:27], off
	v_lshl_add_u64 v[26:27], v[248:249], 0, s[24:25]
	s_mov_b32 m0, s55
	s_nop 0
	global_load_lds_dwordx4 v[26:27], off
	v_lshl_add_u64 v[26:27], v[248:249], 0, s[26:27]
	s_mov_b32 m0, s62
	s_nop 0
	global_load_lds_dwordx4 v[26:27], off
	s_waitcnt vmcnt(8)
	s_waitcnt lgkmcnt(0)
	s_barrier
	s_waitcnt lgkmcnt(0)
	v_mfma_f32_16x16x32_bf16 v[26:29], v[10:13], v[34:37], v[138:141]
	v_mfma_f32_16x16x32_bf16 v[62:65], v[14:17], v[38:41], v[26:29]
	v_mfma_f32_16x16x32_bf16 v[26:29], v[18:21], v[34:37], v[150:153]
	v_mfma_f32_16x16x32_bf16 v[58:61], v[22:25], v[38:41], v[26:29]
	v_mfma_f32_16x16x32_bf16 v[26:29], v[10:13], v[74:77], v[154:157]
	v_mfma_f32_16x16x32_bf16 v[46:49], v[14:17], v[82:85], v[26:29]
	v_mfma_f32_16x16x32_bf16 v[26:29], v[18:21], v[74:77], v[158:161]
	v_mfma_f32_16x16x32_bf16 v[42:45], v[22:25], v[82:85], v[26:29]
	v_mfma_f32_16x16x32_bf16 v[26:29], v[10:13], v[90:93], v[162:165]
	v_mfma_f32_16x16x32_bf16 v[2:5], v[10:13], v[232:235], v[2:5]
	v_mfma_f32_16x16x32_bf16 v[30:33], v[14:17], v[94:97], v[26:29]
	v_mfma_f32_16x16x32_bf16 v[26:29], v[18:21], v[90:93], v[166:169]
	v_mfma_f32_16x16x32_bf16 v[14:17], v[14:17], v[236:239], v[2:5]
	v_mfma_f32_16x16x32_bf16 v[2:5], v[18:21], v[232:235], v[6:9]
	v_mfma_f32_16x16x32_bf16 v[26:29], v[22:25], v[94:97], v[26:29]
	v_mfma_f32_16x16x32_bf16 v[10:13], v[22:25], v[236:239], v[2:5]
	v_mfma_f32_16x16x32_bf16 v[2:5], v[216:219], v[34:37], v[180:183]
	v_mfma_f32_16x16x32_bf16 v[54:57], v[220:223], v[38:41], v[2:5]
	v_mfma_f32_16x16x32_bf16 v[2:5], v[224:227], v[34:37], v[184:187]
	v_mfma_f32_16x16x32_bf16 v[50:53], v[228:231], v[38:41], v[2:5]
	v_mfma_f32_16x16x32_bf16 v[2:5], v[216:219], v[74:77], v[188:191]
	v_mfma_f32_16x16x32_bf16 v[38:41], v[220:223], v[82:85], v[2:5]
	v_mfma_f32_16x16x32_bf16 v[2:5], v[224:227], v[74:77], v[196:199]
	v_mfma_f32_16x16x32_bf16 v[34:37], v[228:231], v[82:85], v[2:5]
	v_mfma_f32_16x16x32_bf16 v[2:5], v[216:219], v[90:93], v[200:203]
	v_mfma_f32_16x16x32_bf16 v[22:25], v[220:223], v[94:97], v[2:5]
	v_mfma_f32_16x16x32_bf16 v[2:5], v[224:227], v[90:93], v[204:207]
	v_mfma_f32_16x16x32_bf16 v[18:21], v[228:231], v[94:97], v[2:5]
	s_barrier
	v_mfma_f32_16x16x32_bf16 v[2:5], v[216:219], v[232:235], v[208:211]
	v_mfma_f32_16x16x32_bf16 v[6:9], v[220:223], v[236:239], v[2:5]
	v_mfma_f32_16x16x32_bf16 v[2:5], v[224:227], v[232:235], v[212:215]
	v_mfma_f32_16x16x32_bf16 v[2:5], v[228:231], v[236:239], v[2:5]
	s_add_u32 s76, s76, 0x80180
	s_addc_u32 s77, s77, 0
	s_add_u32 s57, s78, 0x200
	s_addc_u32 s78, s79, 0
	s_mov_b32 s79, 0
.LBB0_1208:
	ds_read_b128 v[74:77], v1
	ds_read_b128 v[82:85], v1 offset:1024
	ds_read_b128 v[90:93], v1 offset:2048
	ds_read_b128 v[94:97], v1 offset:3072
	ds_read_b128 v[138:141], v192
	ds_read_b128 v[150:153], v192 offset:1024
	ds_read_b128 v[154:157], v192 offset:2048
	ds_read_b128 v[158:161], v192 offset:3072
	s_add_u32 s0, s76, 0xfff80080
	s_addc_u32 s1, s77, -1
	s_cmp_eq_u32 s79, 28
	s_cselect_b32 s1, s69, s1
	s_cselect_b32 s0, s92, s0
	s_cselect_b32 s65, s67, s78
	s_cselect_b32 s64, s93, s57
	s_mov_b32 m0, s88
	v_lshl_add_u64 v[208:209], s[76:77], 0, v[174:175]
	ds_read_b128 v[162:165], v193
	ds_read_b128 v[166:169], v193 offset:1024
	ds_read_b128 v[180:183], v193 offset:2048
	ds_read_b128 v[184:187], v193 offset:3072
	ds_read_b128 v[188:191], v193 offset:4096
	ds_read_b128 v[196:199], v193 offset:5120
	ds_read_b128 v[200:203], v193 offset:6144
	ds_read_b128 v[204:207], v193 offset:7168
	global_load_lds_dwordx4 v[208:209], off
	v_lshl_add_u64 v[208:209], v[208:209], 0, s[28:29]
	s_mov_b32 m0, s89
	s_nop 0
	global_load_lds_dwordx4 v[208:209], off
	s_waitcnt vmcnt(8)
	s_waitcnt lgkmcnt(0)
	s_barrier
	s_waitcnt lgkmcnt(0)
	v_mfma_f32_16x16x32_bf16 v[146:149], v[74:77], v[162:165], v[146:149]
	v_mfma_f32_16x16x32_bf16 v[142:145], v[90:93], v[162:165], v[142:145]
	v_mfma_f32_16x16x32_bf16 v[126:129], v[74:77], v[180:183], v[126:129]
	v_mfma_f32_16x16x32_bf16 v[122:125], v[90:93], v[180:183], v[122:125]
	v_mfma_f32_16x16x32_bf16 v[110:113], v[74:77], v[188:191], v[110:113]
	v_mfma_f32_16x16x32_bf16 v[106:109], v[90:93], v[188:191], v[106:109]
	v_mfma_f32_16x16x32_bf16 v[86:89], v[74:77], v[200:203], v[86:89]
	v_mfma_f32_16x16x32_bf16 v[78:81], v[90:93], v[200:203], v[78:81]
	v_mfma_f32_16x16x32_bf16 v[146:149], v[82:85], v[166:169], v[146:149]
	v_mfma_f32_16x16x32_bf16 v[142:145], v[94:97], v[166:169], v[142:145]
	v_mfma_f32_16x16x32_bf16 v[126:129], v[82:85], v[184:187], v[126:129]
	v_mfma_f32_16x16x32_bf16 v[122:125], v[94:97], v[184:187], v[122:125]
	v_mfma_f32_16x16x32_bf16 v[110:113], v[82:85], v[196:199], v[110:113]
	v_mfma_f32_16x16x32_bf16 v[106:109], v[94:97], v[196:199], v[106:109]
	v_mfma_f32_16x16x32_bf16 v[86:89], v[82:85], v[204:207], v[86:89]
	v_mfma_f32_16x16x32_bf16 v[78:81], v[94:97], v[204:207], v[78:81]
	v_mfma_f32_16x16x32_bf16 v[134:137], v[138:141], v[162:165], v[134:137]
	v_mfma_f32_16x16x32_bf16 v[130:133], v[154:157], v[162:165], v[130:133]
	v_mfma_f32_16x16x32_bf16 v[118:121], v[138:141], v[180:183], v[118:121]
	v_mfma_f32_16x16x32_bf16 v[114:117], v[154:157], v[180:183], v[114:117]
	v_mfma_f32_16x16x32_bf16 v[102:105], v[138:141], v[188:191], v[102:105]
	v_mfma_f32_16x16x32_bf16 v[98:101], v[154:157], v[188:191], v[98:101]
	v_mfma_f32_16x16x32_bf16 v[70:73], v[138:141], v[200:203], v[70:73]
	v_mfma_f32_16x16x32_bf16 v[66:69], v[154:157], v[200:203], v[66:69]
	v_mfma_f32_16x16x32_bf16 v[134:137], v[150:153], v[166:169], v[134:137]
	v_mfma_f32_16x16x32_bf16 v[130:133], v[158:161], v[166:169], v[130:133]
	v_mfma_f32_16x16x32_bf16 v[118:121], v[150:153], v[184:187], v[118:121]
	v_mfma_f32_16x16x32_bf16 v[114:117], v[158:161], v[184:187], v[114:117]
	s_barrier
	v_mfma_f32_16x16x32_bf16 v[102:105], v[150:153], v[196:199], v[102:105]
	v_mfma_f32_16x16x32_bf16 v[98:101], v[158:161], v[196:199], v[98:101]
	v_mfma_f32_16x16x32_bf16 v[70:73], v[150:153], v[204:207], v[70:73]
	v_mfma_f32_16x16x32_bf16 v[66:69], v[158:161], v[204:207], v[66:69]
	s_mov_b32 m0, s94
	v_lshl_add_u64 v[208:209], s[64:65], 0, v[172:173]
	ds_read_b128 v[162:165], v193 offset:16384
	ds_read_b128 v[166:169], v193 offset:17408
	ds_read_b128 v[180:183], v193 offset:18432
	ds_read_b128 v[184:187], v193 offset:19456
	ds_read_b128 v[188:191], v193 offset:20480
	ds_read_b128 v[196:199], v193 offset:21504
	ds_read_b128 v[200:203], v193 offset:22528
	ds_read_b128 v[204:207], v193 offset:23552
	global_load_lds_dwordx4 v[208:209], off
	v_lshl_add_u64 v[210:211], v[208:209], 0, s[28:29]
	s_mov_b32 m0, s95
	s_nop 0
	global_load_lds_dwordx4 v[210:211], off
	v_lshl_add_u64 v[210:211], v[208:209], 0, s[30:31]
	s_mov_b32 m0, s40
	s_nop 0
	global_load_lds_dwordx4 v[210:211], off
	v_lshl_add_u64 v[210:211], v[208:209], 0, s[34:35]
	s_mov_b32 m0, s41
	s_nop 0
	global_load_lds_dwordx4 v[210:211], off
	v_lshl_add_u64 v[210:211], s[0:1], 0, v[170:171]
	s_mov_b32 m0, s47
	v_lshl_add_u64 v[212:213], v[210:211], 0, s[28:29]
	global_load_lds_dwordx4 v[210:211], off
	s_mov_b32 m0, s52
	s_nop 0
	global_load_lds_dwordx4 v[212:213], off
	s_waitcnt vmcnt(8)
	s_waitcnt lgkmcnt(0)
	s_barrier
	s_waitcnt lgkmcnt(0)
	v_mfma_f32_16x16x32_bf16 v[62:65], v[74:77], v[162:165], v[62:65]
	v_mfma_f32_16x16x32_bf16 v[58:61], v[90:93], v[162:165], v[58:61]
	v_mfma_f32_16x16x32_bf16 v[46:49], v[74:77], v[180:183], v[46:49]
	v_mfma_f32_16x16x32_bf16 v[42:45], v[90:93], v[180:183], v[42:45]
	v_mfma_f32_16x16x32_bf16 v[30:33], v[74:77], v[188:191], v[30:33]
	v_mfma_f32_16x16x32_bf16 v[26:29], v[90:93], v[188:191], v[26:29]
	v_mfma_f32_16x16x32_bf16 v[14:17], v[74:77], v[200:203], v[14:17]
	v_mfma_f32_16x16x32_bf16 v[10:13], v[90:93], v[200:203], v[10:13]
	v_mfma_f32_16x16x32_bf16 v[62:65], v[82:85], v[166:169], v[62:65]
	v_mfma_f32_16x16x32_bf16 v[58:61], v[94:97], v[166:169], v[58:61]
	v_mfma_f32_16x16x32_bf16 v[46:49], v[82:85], v[184:187], v[46:49]
	v_mfma_f32_16x16x32_bf16 v[42:45], v[94:97], v[184:187], v[42:45]
	v_mfma_f32_16x16x32_bf16 v[30:33], v[82:85], v[196:199], v[30:33]
	v_mfma_f32_16x16x32_bf16 v[26:29], v[94:97], v[196:199], v[26:29]
	v_mfma_f32_16x16x32_bf16 v[14:17], v[82:85], v[204:207], v[14:17]
	v_mfma_f32_16x16x32_bf16 v[10:13], v[94:97], v[204:207], v[10:13]
	v_mfma_f32_16x16x32_bf16 v[54:57], v[138:141], v[162:165], v[54:57]
	v_mfma_f32_16x16x32_bf16 v[50:53], v[154:157], v[162:165], v[50:53]
	v_mfma_f32_16x16x32_bf16 v[38:41], v[138:141], v[180:183], v[38:41]
	v_mfma_f32_16x16x32_bf16 v[34:37], v[154:157], v[180:183], v[34:37]
	v_mfma_f32_16x16x32_bf16 v[22:25], v[138:141], v[188:191], v[22:25]
	v_mfma_f32_16x16x32_bf16 v[18:21], v[154:157], v[188:191], v[18:21]
	v_mfma_f32_16x16x32_bf16 v[6:9], v[138:141], v[200:203], v[6:9]
	v_mfma_f32_16x16x32_bf16 v[2:5], v[154:157], v[200:203], v[2:5]
	v_mfma_f32_16x16x32_bf16 v[54:57], v[150:153], v[166:169], v[54:57]
	v_mfma_f32_16x16x32_bf16 v[50:53], v[158:161], v[166:169], v[50:53]
	v_mfma_f32_16x16x32_bf16 v[38:41], v[150:153], v[184:187], v[38:41]
	v_mfma_f32_16x16x32_bf16 v[34:37], v[158:161], v[184:187], v[34:37]
	s_barrier
	v_mfma_f32_16x16x32_bf16 v[22:25], v[150:153], v[196:199], v[22:25]
	v_mfma_f32_16x16x32_bf16 v[18:21], v[158:161], v[196:199], v[18:21]
	v_mfma_f32_16x16x32_bf16 v[6:9], v[150:153], v[204:207], v[6:9]
	v_mfma_f32_16x16x32_bf16 v[2:5], v[158:161], v[204:207], v[2:5]
	ds_read_b128 v[74:77], v194
	ds_read_b128 v[82:85], v194 offset:1024
	ds_read_b128 v[90:93], v194 offset:2048
	ds_read_b128 v[94:97], v194 offset:3072
	ds_read_b128 v[138:141], v195
	ds_read_b128 v[150:153], v195 offset:1024
	ds_read_b128 v[154:157], v195 offset:2048
	ds_read_b128 v[158:161], v195 offset:3072
	s_mov_b32 m0, s53
	v_lshl_add_u64 v[212:213], v[210:211], 0, s[30:31]
	ds_read_b128 v[162:165], v193 offset:32768
	ds_read_b128 v[166:169], v193 offset:33792
	ds_read_b128 v[180:183], v193 offset:34816
	ds_read_b128 v[184:187], v193 offset:35840
	ds_read_b128 v[188:191], v193 offset:36864
	ds_read_b128 v[196:199], v193 offset:37888
	ds_read_b128 v[200:203], v193 offset:38912
	ds_read_b128 v[204:207], v193 offset:39936
	global_load_lds_dwordx4 v[212:213], off
	v_lshl_add_u64 v[212:213], v[210:211], 0, s[34:35]
	s_mov_b32 m0, s54
	s_nop 0
	global_load_lds_dwordx4 v[212:213], off
	s_waitcnt vmcnt(8)
	s_waitcnt lgkmcnt(0)
	s_barrier
	s_waitcnt lgkmcnt(0)
	v_mfma_f32_16x16x32_bf16 v[146:149], v[74:77], v[162:165], v[146:149]
	v_mfma_f32_16x16x32_bf16 v[142:145], v[90:93], v[162:165], v[142:145]
	v_mfma_f32_16x16x32_bf16 v[126:129], v[74:77], v[180:183], v[126:129]
	v_mfma_f32_16x16x32_bf16 v[122:125], v[90:93], v[180:183], v[122:125]
	v_mfma_f32_16x16x32_bf16 v[110:113], v[74:77], v[188:191], v[110:113]
	v_mfma_f32_16x16x32_bf16 v[106:109], v[90:93], v[188:191], v[106:109]
	v_mfma_f32_16x16x32_bf16 v[86:89], v[74:77], v[200:203], v[86:89]
	v_mfma_f32_16x16x32_bf16 v[78:81], v[90:93], v[200:203], v[78:81]
	v_mfma_f32_16x16x32_bf16 v[146:149], v[82:85], v[166:169], v[146:149]
	v_mfma_f32_16x16x32_bf16 v[142:145], v[94:97], v[166:169], v[142:145]
	v_mfma_f32_16x16x32_bf16 v[126:129], v[82:85], v[184:187], v[126:129]
	v_mfma_f32_16x16x32_bf16 v[122:125], v[94:97], v[184:187], v[122:125]
	v_mfma_f32_16x16x32_bf16 v[110:113], v[82:85], v[196:199], v[110:113]
	v_mfma_f32_16x16x32_bf16 v[106:109], v[94:97], v[196:199], v[106:109]
	v_mfma_f32_16x16x32_bf16 v[86:89], v[82:85], v[204:207], v[86:89]
	v_mfma_f32_16x16x32_bf16 v[78:81], v[94:97], v[204:207], v[78:81]
	v_mfma_f32_16x16x32_bf16 v[134:137], v[138:141], v[162:165], v[134:137]
	v_mfma_f32_16x16x32_bf16 v[130:133], v[154:157], v[162:165], v[130:133]
	v_mfma_f32_16x16x32_bf16 v[118:121], v[138:141], v[180:183], v[118:121]
	v_mfma_f32_16x16x32_bf16 v[114:117], v[154:157], v[180:183], v[114:117]
	v_mfma_f32_16x16x32_bf16 v[102:105], v[138:141], v[188:191], v[102:105]
	v_mfma_f32_16x16x32_bf16 v[98:101], v[154:157], v[188:191], v[98:101]
	v_mfma_f32_16x16x32_bf16 v[70:73], v[138:141], v[200:203], v[70:73]
	v_mfma_f32_16x16x32_bf16 v[66:69], v[154:157], v[200:203], v[66:69]
	v_mfma_f32_16x16x32_bf16 v[134:137], v[150:153], v[166:169], v[134:137]
	v_mfma_f32_16x16x32_bf16 v[130:133], v[158:161], v[166:169], v[130:133]
	v_mfma_f32_16x16x32_bf16 v[118:121], v[150:153], v[184:187], v[118:121]
	v_mfma_f32_16x16x32_bf16 v[114:117], v[158:161], v[184:187], v[114:117]
	s_barrier
; #define PG8_WAIT_V(n) asm volatile("s_waitcnt vmcnt(" #n ")" ::: "memory")
; template <class Epi, class Sched, bool ALIGN_EPI = true, bool SP2 = true, bool FULLLINE = false, bool NOSTAGE = false, bool FP8 = false>
; __device__ __forceinline__ void gemm_phase(PG8_LAS unsigned char* lds, const Gemm g, const Sched& S, const Epi& E) {
;     ...
;         static_assert(SP2, "only the SP2 loop is kept");
;         { const int t = 0; if constexpr (Epi::NST == 16) PG8_ITER(PG8_WAIT_V(24)); else if constexpr (Epi::NST == 8) PG8_ITER(PG8_WAIT_V(16)); else PG8_ITER(PG8_WAIT_V(8)); }
;         for (int t = 2; t < nt; t += 2) PG8_ITER(PG8_WAIT_V(8));
	v_mfma_f32_16x16x32_bf16 v[102:105], v[150:153], v[196:199], v[102:105]
	v_mfma_f32_16x16x32_bf16 v[98:101], v[158:161], v[196:199], v[98:101]
	v_mfma_f32_16x16x32_bf16 v[70:73], v[150:153], v[204:207], v[70:73]
	v_mfma_f32_16x16x32_bf16 v[66:69], v[158:161], v[204:207], v[66:69]
	s_mov_b32 m0, s50
	v_lshl_add_u64 v[212:213], v[208:209], 0, s[36:37]
	ds_read_b128 v[162:165], v193 offset:49152
	ds_read_b128 v[166:169], v193 offset:50176
	ds_read_b128 v[180:183], v193 offset:51200
	ds_read_b128 v[184:187], v193 offset:52224
	ds_read_b128 v[188:191], v193 offset:53248
	ds_read_b128 v[196:199], v193 offset:54272
	ds_read_b128 v[200:203], v193 offset:55296
	ds_read_b128 v[204:207], v193 offset:56320
	global_load_lds_dwordx4 v[212:213], off
	v_lshl_add_u64 v[212:213], v[208:209], 0, s[38:39]
	s_mov_b32 m0, s51
	s_nop 0
	global_load_lds_dwordx4 v[212:213], off
	v_lshl_add_u64 v[212:213], v[208:209], 0, s[12:13]
	s_mov_b32 m0, s33
	v_lshl_add_u64 v[208:209], v[208:209], 0, s[14:15]
	global_load_lds_dwordx4 v[212:213], off
	s_mov_b32 m0, s56
	s_nop 0
	global_load_lds_dwordx4 v[208:209], off
	v_lshl_add_u64 v[208:209], v[210:211], 0, s[36:37]
	s_mov_b32 m0, s55
	s_nop 0
	global_load_lds_dwordx4 v[208:209], off
	v_lshl_add_u64 v[208:209], v[210:211], 0, s[38:39]
	s_mov_b32 m0, s62
	s_nop 0
	global_load_lds_dwordx4 v[208:209], off
	s_waitcnt vmcnt(8)
	s_waitcnt lgkmcnt(0)
	s_barrier
	s_waitcnt lgkmcnt(0)
	v_mfma_f32_16x16x32_bf16 v[62:65], v[74:77], v[162:165], v[62:65]
	v_mfma_f32_16x16x32_bf16 v[58:61], v[90:93], v[162:165], v[58:61]
	v_mfma_f32_16x16x32_bf16 v[46:49], v[74:77], v[180:183], v[46:49]
	v_mfma_f32_16x16x32_bf16 v[42:45], v[90:93], v[180:183], v[42:45]
	v_mfma_f32_16x16x32_bf16 v[30:33], v[74:77], v[188:191], v[30:33]
	v_mfma_f32_16x16x32_bf16 v[26:29], v[90:93], v[188:191], v[26:29]
	v_mfma_f32_16x16x32_bf16 v[14:17], v[74:77], v[200:203], v[14:17]
	v_mfma_f32_16x16x32_bf16 v[10:13], v[90:93], v[200:203], v[10:13]
	v_mfma_f32_16x16x32_bf16 v[62:65], v[82:85], v[166:169], v[62:65]
	v_mfma_f32_16x16x32_bf16 v[58:61], v[94:97], v[166:169], v[58:61]
	v_mfma_f32_16x16x32_bf16 v[46:49], v[82:85], v[184:187], v[46:49]
	v_mfma_f32_16x16x32_bf16 v[42:45], v[94:97], v[184:187], v[42:45]
	v_mfma_f32_16x16x32_bf16 v[30:33], v[82:85], v[196:199], v[30:33]
	v_mfma_f32_16x16x32_bf16 v[26:29], v[94:97], v[196:199], v[26:29]
	v_mfma_f32_16x16x32_bf16 v[14:17], v[82:85], v[204:207], v[14:17]
	v_mfma_f32_16x16x32_bf16 v[10:13], v[94:97], v[204:207], v[10:13]
	v_mfma_f32_16x16x32_bf16 v[54:57], v[138:141], v[162:165], v[54:57]
	v_mfma_f32_16x16x32_bf16 v[50:53], v[154:157], v[162:165], v[50:53]
	v_mfma_f32_16x16x32_bf16 v[38:41], v[138:141], v[180:183], v[38:41]
	v_mfma_f32_16x16x32_bf16 v[34:37], v[154:157], v[180:183], v[34:37]
	v_mfma_f32_16x16x32_bf16 v[22:25], v[138:141], v[188:191], v[22:25]
	v_mfma_f32_16x16x32_bf16 v[18:21], v[154:157], v[188:191], v[18:21]
	v_mfma_f32_16x16x32_bf16 v[6:9], v[138:141], v[200:203], v[6:9]
	v_mfma_f32_16x16x32_bf16 v[2:5], v[154:157], v[200:203], v[2:5]
	v_mfma_f32_16x16x32_bf16 v[54:57], v[150:153], v[166:169], v[54:57]
	v_mfma_f32_16x16x32_bf16 v[50:53], v[158:161], v[166:169], v[50:53]
	v_mfma_f32_16x16x32_bf16 v[38:41], v[150:153], v[184:187], v[38:41]
	v_mfma_f32_16x16x32_bf16 v[34:37], v[158:161], v[184:187], v[34:37]
	s_barrier
	v_mfma_f32_16x16x32_bf16 v[22:25], v[150:153], v[196:199], v[22:25]
	v_mfma_f32_16x16x32_bf16 v[18:21], v[158:161], v[196:199], v[18:21]
	v_mfma_f32_16x16x32_bf16 v[6:9], v[150:153], v[204:207], v[6:9]
	v_mfma_f32_16x16x32_bf16 v[2:5], v[158:161], v[204:207], v[2:5]
	s_add_i32 s79, s79, 2
	s_add_u32 s76, s76, 0x100
	s_addc_u32 s77, s77, 0
	s_add_u32 s57, s57, 0x100
	s_addc_u32 s78, s78, 0
	s_cmp_gt_u32 s79, 29
	s_cbranch_scc0 .LBB0_1208
	s_and_b64 vcc, exec, s[10:11]
	s_cbranch_vccz .LBB0_1211
	s_barrier

; #define PG8_WAIT_V(n) asm volatile("s_waitcnt vmcnt(" #n ")" ::: "memory")
; template <class Epi, class Sched, bool ALIGN_EPI = true, bool SP2 = true, bool FULLLINE = false, bool NOSTAGE = false, bool FP8 = false>
; __device__ __forceinline__ void gemm_phase(PG8_LAS unsigned char* lds, const Gemm g, const Sched& S, const Epi& E) {
;     ...
;         { const int t = 0; if constexpr (Epi::NST == 16) PG8_ITER(PG8_WAIT_V(24)); else if constexpr (Epi::NST == 8) PG8_ITER(PG8_WAIT_V(16)); else PG8_ITER(PG8_WAIT_V(8)); }
.LBB0_1380:
	s_ashr_i32 s69, s68, 31
	s_lshl_b64 s[0:1], s[68:69], 20
	s_add_u32 s70, s58, s0
	ds_read_b128 v[2:5], v1
	ds_read_b128 v[6:9], v1 offset:1024
	ds_read_b128 v[10:13], v1 offset:2048
	ds_read_b128 v[14:17], v1 offset:3072
	ds_read_b128 v[18:21], v142
	ds_read_b128 v[22:25], v142 offset:1024
	ds_read_b128 v[26:29], v142 offset:2048
	ds_read_b128 v[30:33], v142 offset:3072
	s_addc_u32 s71, s59, s1
	s_ashr_i32 s67, s66, 31
	s_lshl_b64 s[0:1], s[66:67], 20
	s_add_u32 s72, s3, s0
	s_addc_u32 s73, s42, s1
	s_and_b64 s[0:1], s[8:9], exec
	s_cselect_b32 s67, s71, s79
	s_cselect_b32 s69, s70, s78
	s_cselect_b32 s89, s73, s77
	s_cselect_b32 s90, s72, s76
	v_lshl_add_u64 v[140:141], s[78:79], 0, v[132:133]
	s_mov_b32 m0, s81
	v_lshl_add_u64 v[66:67], v[140:141], 0, s[12:13]
	ds_read_b128 v[34:37], v143
	ds_read_b128 v[38:41], v143 offset:1024
	ds_read_b128 v[42:45], v143 offset:2048
	ds_read_b128 v[46:49], v143 offset:3072
	ds_read_b128 v[50:53], v143 offset:4096
	ds_read_b128 v[54:57], v143 offset:5120
	ds_read_b128 v[58:61], v143 offset:6144
	ds_read_b128 v[62:65], v143 offset:7168
	global_load_lds_dwordx4 v[66:67], off
	v_lshl_add_u64 v[66:67], v[140:141], 0, s[14:15]
	s_mov_b32 m0, s82
	s_nop 0
	global_load_lds_dwordx4 v[66:67], off
	s_waitcnt vmcnt(16)
	s_waitcnt lgkmcnt(0)
	s_barrier
	s_waitcnt lgkmcnt(0)
	v_mfma_f32_16x16x32_bf16 v[86:89], v[10:13], v[50:53], 0
	v_mfma_f32_16x16x32_bf16 v[90:93], v[14:17], v[54:57], v[86:89]
	v_mfma_f32_16x16x32_bf16 v[86:89], v[2:5], v[58:61], 0
	v_mfma_f32_16x16x32_bf16 v[66:69], v[2:5], v[34:37], 0
	v_mfma_f32_16x16x32_bf16 v[70:73], v[10:13], v[34:37], 0
	v_mfma_f32_16x16x32_bf16 v[74:77], v[2:5], v[42:45], 0
	v_mfma_f32_16x16x32_bf16 v[78:81], v[10:13], v[42:45], 0
	v_mfma_f32_16x16x32_bf16 v[82:85], v[2:5], v[50:53], 0
	v_mfma_f32_16x16x32_bf16 v[94:97], v[6:9], v[62:65], v[86:89]
	v_mfma_f32_16x16x32_bf16 v[86:89], v[10:13], v[58:61], 0
	v_mfma_f32_16x16x32_bf16 v[66:69], v[6:9], v[38:41], v[66:69]
	v_mfma_f32_16x16x32_bf16 v[70:73], v[14:17], v[38:41], v[70:73]
	v_mfma_f32_16x16x32_bf16 v[74:77], v[6:9], v[46:49], v[74:77]
	v_mfma_f32_16x16x32_bf16 v[78:81], v[14:17], v[46:49], v[78:81]
	v_mfma_f32_16x16x32_bf16 v[82:85], v[6:9], v[54:57], v[82:85]
	v_mfma_f32_16x16x32_bf16 v[106:109], v[14:17], v[62:65], v[86:89]
	v_mfma_f32_16x16x32_bf16 v[86:89], v[18:21], v[34:37], 0
	v_mfma_f32_16x16x32_bf16 v[34:37], v[26:29], v[34:37], 0
	v_mfma_f32_16x16x32_bf16 v[110:113], v[22:25], v[38:41], v[86:89]
	v_mfma_f32_16x16x32_bf16 v[34:37], v[30:33], v[38:41], v[34:37]
	v_mfma_f32_16x16x32_bf16 v[38:41], v[18:21], v[42:45], 0
	v_mfma_f32_16x16x32_bf16 v[42:45], v[26:29], v[42:45], 0
	v_mfma_f32_16x16x32_bf16 v[38:41], v[22:25], v[46:49], v[38:41]
	v_mfma_f32_16x16x32_bf16 v[42:45], v[30:33], v[46:49], v[42:45]
	v_mfma_f32_16x16x32_bf16 v[46:49], v[18:21], v[50:53], 0
	v_mfma_f32_16x16x32_bf16 v[50:53], v[26:29], v[50:53], 0
	v_mfma_f32_16x16x32_bf16 v[46:49], v[22:25], v[54:57], v[46:49]
	v_mfma_f32_16x16x32_bf16 v[50:53], v[30:33], v[54:57], v[50:53]
	s_barrier
	v_mfma_f32_16x16x32_bf16 v[54:57], v[18:21], v[58:61], 0
	v_mfma_f32_16x16x32_bf16 v[58:61], v[26:29], v[58:61], 0
	v_mfma_f32_16x16x32_bf16 v[54:57], v[22:25], v[62:65], v[54:57]
	v_mfma_f32_16x16x32_bf16 v[58:61], v[30:33], v[62:65], v[58:61]
	v_lshl_add_u64 v[238:239], s[76:77], 0, v[130:131]
	s_mov_b32 m0, s83
	v_lshl_add_u64 v[146:147], v[238:239], 0, s[16:17]
	s_add_i32 s91, s83, 0x2000
	ds_read_b128 v[62:65], v143 offset:16384
	ds_read_b128 v[86:89], v143 offset:17408
	ds_read_b128 v[98:101], v143 offset:18432
	ds_read_b128 v[102:105], v143 offset:19456
	ds_read_b128 v[114:117], v143 offset:20480
	ds_read_b128 v[118:121], v143 offset:21504
	ds_read_b128 v[122:125], v143 offset:22528
	ds_read_b128 v[126:129], v143 offset:23552
	global_load_lds_dwordx4 v[146:147], off
	v_lshl_add_u64 v[146:147], v[238:239], 0, s[18:19]
	s_mov_b32 m0, s91
	s_add_i32 s40, s80, s43
	global_load_lds_dwordx4 v[146:147], off
	v_lshl_add_u64 v[146:147], v[238:239], 0, s[20:21]
	s_mov_b32 m0, s40
	s_add_i32 s41, s40, 0x2000
	global_load_lds_dwordx4 v[146:147], off
	v_lshl_add_u64 v[146:147], v[238:239], 0, s[22:23]
	s_mov_b32 m0, s41
	s_nop 0
	global_load_lds_dwordx4 v[146:147], off
	v_lshl_add_u64 v[146:147], v[140:141], 0, s[16:17]
	s_mov_b32 m0, s45
	s_nop 0
	global_load_lds_dwordx4 v[146:147], off
	v_lshl_add_u64 v[146:147], v[140:141], 0, s[18:19]
	s_mov_b32 m0, s46
	s_nop 0
	global_load_lds_dwordx4 v[146:147], off
	s_waitcnt vmcnt(16)
	s_waitcnt lgkmcnt(0)
	s_barrier
	s_waitcnt lgkmcnt(0)
	v_mfma_f32_16x16x32_bf16 v[146:149], v[2:5], v[62:65], 0
	v_mfma_f32_16x16x32_bf16 v[154:157], v[2:5], v[98:101], 0
	v_mfma_f32_16x16x32_bf16 v[162:165], v[2:5], v[114:117], 0
	v_mfma_f32_16x16x32_bf16 v[2:5], v[2:5], v[122:125], 0
	v_mfma_f32_16x16x32_bf16 v[146:149], v[6:9], v[86:89], v[146:149]
	v_mfma_f32_16x16x32_bf16 v[154:157], v[6:9], v[102:105], v[154:157]
	v_mfma_f32_16x16x32_bf16 v[162:165], v[6:9], v[118:121], v[162:165]
	v_mfma_f32_16x16x32_bf16 v[2:5], v[6:9], v[126:129], v[2:5]
	v_mfma_f32_16x16x32_bf16 v[6:9], v[10:13], v[122:125], 0
	v_mfma_f32_16x16x32_bf16 v[150:153], v[10:13], v[62:65], 0
	v_mfma_f32_16x16x32_bf16 v[158:161], v[10:13], v[98:101], 0
	v_mfma_f32_16x16x32_bf16 v[166:169], v[10:13], v[114:117], 0
	v_mfma_f32_16x16x32_bf16 v[10:13], v[14:17], v[126:129], v[6:9]
	v_mfma_f32_16x16x32_bf16 v[150:153], v[14:17], v[86:89], v[150:153]
	v_mfma_f32_16x16x32_bf16 v[158:161], v[14:17], v[102:105], v[158:161]
	v_mfma_f32_16x16x32_bf16 v[166:169], v[14:17], v[118:121], v[166:169]
	v_mfma_f32_16x16x32_bf16 v[6:9], v[18:21], v[62:65], 0
	v_mfma_f32_16x16x32_bf16 v[14:17], v[22:25], v[86:89], v[6:9]
	v_mfma_f32_16x16x32_bf16 v[6:9], v[26:29], v[62:65], 0
	v_mfma_f32_16x16x32_bf16 v[170:173], v[30:33], v[86:89], v[6:9]
	v_mfma_f32_16x16x32_bf16 v[6:9], v[18:21], v[98:101], 0
	v_mfma_f32_16x16x32_bf16 v[174:177], v[22:25], v[102:105], v[6:9]
	v_mfma_f32_16x16x32_bf16 v[6:9], v[26:29], v[98:101], 0
	v_mfma_f32_16x16x32_bf16 v[178:181], v[30:33], v[102:105], v[6:9]
	v_mfma_f32_16x16x32_bf16 v[6:9], v[18:21], v[114:117], 0
	v_mfma_f32_16x16x32_bf16 v[182:185], v[22:25], v[118:121], v[6:9]
	v_mfma_f32_16x16x32_bf16 v[6:9], v[26:29], v[114:117], 0
	v_mfma_f32_16x16x32_bf16 v[186:189], v[30:33], v[118:121], v[6:9]
	s_barrier
	v_mfma_f32_16x16x32_bf16 v[6:9], v[18:21], v[122:125], 0
	v_mfma_f32_16x16x32_bf16 v[190:193], v[22:25], v[126:129], v[6:9]
	v_mfma_f32_16x16x32_bf16 v[6:9], v[26:29], v[122:125], 0
	v_mfma_f32_16x16x32_bf16 v[194:197], v[30:33], v[126:129], v[6:9]
	s_nop 5
	ds_read_b128 v[6:9], v144
	ds_read_b128 v[26:29], v144 offset:1024
	ds_read_b128 v[30:33], v144 offset:2048
	ds_read_b128 v[62:65], v144 offset:3072
	ds_read_b128 v[198:201], v145
	ds_read_b128 v[202:205], v145 offset:1024
	ds_read_b128 v[206:209], v145 offset:2048
	ds_read_b128 v[210:213], v145 offset:3072
	s_mov_b32 m0, s47
	v_lshl_add_u64 v[86:87], v[140:141], 0, s[20:21]
	ds_read_b128 v[18:21], v143 offset:32768
	ds_read_b128 v[22:25], v143 offset:33792
	ds_read_b128 v[214:217], v143 offset:34816
	ds_read_b128 v[218:221], v143 offset:35840
	ds_read_b128 v[222:225], v143 offset:36864
	ds_read_b128 v[226:229], v143 offset:37888
	ds_read_b128 v[230:233], v143 offset:38912
	ds_read_b128 v[234:237], v143 offset:39936
	global_load_lds_dwordx4 v[86:87], off
	v_lshl_add_u64 v[86:87], v[140:141], 0, s[22:23]
	s_mov_b32 m0, s52
	s_nop 0
	global_load_lds_dwordx4 v[86:87], off
	s_waitcnt vmcnt(8)
	s_waitcnt lgkmcnt(0)
	s_barrier
	s_waitcnt lgkmcnt(0)
	v_mfma_f32_16x16x32_bf16 v[66:69], v[6:9], v[18:21], v[66:69]
	v_mfma_f32_16x16x32_bf16 v[118:121], v[26:29], v[22:25], v[66:69]
	v_mfma_f32_16x16x32_bf16 v[66:69], v[30:33], v[18:21], v[70:73]
	v_mfma_f32_16x16x32_bf16 v[114:117], v[62:65], v[22:25], v[66:69]
	v_mfma_f32_16x16x32_bf16 v[66:69], v[6:9], v[214:217], v[74:77]
	v_mfma_f32_16x16x32_bf16 v[102:105], v[26:29], v[218:221], v[66:69]
	v_mfma_f32_16x16x32_bf16 v[66:69], v[30:33], v[214:217], v[78:81]
	v_mfma_f32_16x16x32_bf16 v[98:101], v[62:65], v[218:221], v[66:69]
	v_mfma_f32_16x16x32_bf16 v[66:69], v[6:9], v[222:225], v[82:85]
	v_mfma_f32_16x16x32_bf16 v[86:89], v[26:29], v[226:229], v[66:69]
	v_mfma_f32_16x16x32_bf16 v[66:69], v[30:33], v[222:225], v[90:93]
	v_mfma_f32_16x16x32_bf16 v[82:85], v[62:65], v[226:229], v[66:69]
	v_mfma_f32_16x16x32_bf16 v[66:69], v[6:9], v[230:233], v[94:97]
	v_mfma_f32_16x16x32_bf16 v[70:73], v[26:29], v[234:237], v[66:69]
	v_mfma_f32_16x16x32_bf16 v[66:69], v[30:33], v[230:233], v[106:109]
	v_mfma_f32_16x16x32_bf16 v[66:69], v[62:65], v[234:237], v[66:69]
	v_mfma_f32_16x16x32_bf16 v[74:77], v[198:201], v[18:21], v[110:113]
	v_mfma_f32_16x16x32_bf16 v[18:21], v[206:209], v[18:21], v[34:37]
	v_mfma_f32_16x16x32_bf16 v[122:125], v[210:213], v[22:25], v[18:21]
	v_mfma_f32_16x16x32_bf16 v[18:21], v[198:201], v[214:217], v[38:41]
	v_mfma_f32_16x16x32_bf16 v[110:113], v[202:205], v[218:221], v[18:21]
	v_mfma_f32_16x16x32_bf16 v[18:21], v[206:209], v[214:217], v[42:45]
	v_mfma_f32_16x16x32_bf16 v[106:109], v[210:213], v[218:221], v[18:21]
	v_mfma_f32_16x16x32_bf16 v[18:21], v[198:201], v[222:225], v[46:49]
	v_mfma_f32_16x16x32_bf16 v[94:97], v[202:205], v[226:229], v[18:21]
	v_mfma_f32_16x16x32_bf16 v[18:21], v[206:209], v[222:225], v[50:53]
	v_mfma_f32_16x16x32_bf16 v[90:93], v[210:213], v[226:229], v[18:21]
	v_mfma_f32_16x16x32_bf16 v[18:21], v[198:201], v[230:233], v[54:57]
	s_barrier
	v_mfma_f32_16x16x32_bf16 v[78:81], v[202:205], v[234:237], v[18:21]
	v_mfma_f32_16x16x32_bf16 v[18:21], v[206:209], v[230:233], v[58:61]
	v_mfma_f32_16x16x32_bf16 v[126:129], v[202:205], v[22:25], v[74:77]
	v_mfma_f32_16x16x32_bf16 v[74:77], v[210:213], v[234:237], v[18:21]
	s_add_i32 s50, s84, s43
	s_nop 3
	v_lshl_add_u64 v[18:19], v[238:239], 0, s[24:25]
	s_mov_b32 m0, s50
	s_add_i32 s51, s50, 0x2000
	ds_read_b128 v[42:45], v143 offset:49152
	ds_read_b128 v[46:49], v143 offset:50176
	ds_read_b128 v[214:217], v143 offset:51200
	ds_read_b128 v[218:221], v143 offset:52224
	ds_read_b128 v[222:225], v143 offset:53248
	ds_read_b128 v[226:229], v143 offset:54272
	ds_read_b128 v[230:233], v143 offset:55296
	ds_read_b128 v[234:237], v143 offset:56320
	global_load_lds_dwordx4 v[18:19], off
	v_lshl_add_u64 v[18:19], v[238:239], 0, s[26:27]
	s_mov_b32 m0, s51
	s_mov_b64 s[0:1], 0x80180
	s_add_i32 s33, s85, s43
	global_load_lds_dwordx4 v[18:19], off
	v_lshl_add_u64 v[18:19], v[238:239], 0, s[0:1]
	s_mov_b32 m0, s33
	s_mov_b64 s[0:1], 0xc0180
	s_add_i32 s56, s33, 0x2000
	global_load_lds_dwordx4 v[18:19], off
	v_lshl_add_u64 v[18:19], v[238:239], 0, s[0:1]
	s_mov_b32 m0, s56
	s_nop 0
	global_load_lds_dwordx4 v[18:19], off
	v_lshl_add_u64 v[18:19], v[140:141], 0, s[24:25]
	s_mov_b32 m0, s53
	s_nop 0
	global_load_lds_dwordx4 v[18:19], off
	v_lshl_add_u64 v[18:19], v[140:141], 0, s[26:27]
	s_mov_b32 m0, s54
	s_nop 0
	global_load_lds_dwordx4 v[18:19], off
	s_waitcnt vmcnt(8)
	s_waitcnt lgkmcnt(0)
	s_barrier
	s_waitcnt lgkmcnt(0)
	v_mfma_f32_16x16x32_bf16 v[18:21], v[6:9], v[42:45], v[146:149]
	v_mfma_f32_16x16x32_bf16 v[54:57], v[26:29], v[46:49], v[18:21]
	v_mfma_f32_16x16x32_bf16 v[18:21], v[30:33], v[42:45], v[150:153]
	v_mfma_f32_16x16x32_bf16 v[50:53], v[62:65], v[46:49], v[18:21]
	v_mfma_f32_16x16x32_bf16 v[18:21], v[6:9], v[214:217], v[154:157]
	v_mfma_f32_16x16x32_bf16 v[38:41], v[26:29], v[218:221], v[18:21]
	v_mfma_f32_16x16x32_bf16 v[18:21], v[30:33], v[214:217], v[158:161]
	v_mfma_f32_16x16x32_bf16 v[34:37], v[62:65], v[218:221], v[18:21]
	v_mfma_f32_16x16x32_bf16 v[18:21], v[6:9], v[222:225], v[162:165]
	v_mfma_f32_16x16x32_bf16 v[2:5], v[6:9], v[230:233], v[2:5]
	v_mfma_f32_16x16x32_bf16 v[22:25], v[26:29], v[226:229], v[18:21]
	v_mfma_f32_16x16x32_bf16 v[18:21], v[30:33], v[222:225], v[166:169]
	v_mfma_f32_16x16x32_bf16 v[6:9], v[26:29], v[234:237], v[2:5]
	v_mfma_f32_16x16x32_bf16 v[2:5], v[30:33], v[230:233], v[10:13]
	v_mfma_f32_16x16x32_bf16 v[18:21], v[62:65], v[226:229], v[18:21]
	v_mfma_f32_16x16x32_bf16 v[2:5], v[62:65], v[234:237], v[2:5]
	v_mfma_f32_16x16x32_bf16 v[10:13], v[198:201], v[42:45], v[14:17]
	v_mfma_f32_16x16x32_bf16 v[62:65], v[202:205], v[46:49], v[10:13]
	v_mfma_f32_16x16x32_bf16 v[10:13], v[206:209], v[42:45], v[170:173]
	v_mfma_f32_16x16x32_bf16 v[58:61], v[210:213], v[46:49], v[10:13]
	v_mfma_f32_16x16x32_bf16 v[10:13], v[198:201], v[214:217], v[174:177]
	v_mfma_f32_16x16x32_bf16 v[46:49], v[202:205], v[218:221], v[10:13]
	v_mfma_f32_16x16x32_bf16 v[10:13], v[206:209], v[214:217], v[178:181]
	v_mfma_f32_16x16x32_bf16 v[42:45], v[210:213], v[218:221], v[10:13]
	v_mfma_f32_16x16x32_bf16 v[10:13], v[198:201], v[222:225], v[182:185]
	v_mfma_f32_16x16x32_bf16 v[30:33], v[202:205], v[226:229], v[10:13]
	v_mfma_f32_16x16x32_bf16 v[10:13], v[206:209], v[222:225], v[186:189]
	v_mfma_f32_16x16x32_bf16 v[26:29], v[210:213], v[226:229], v[10:13]
	s_barrier
	v_mfma_f32_16x16x32_bf16 v[10:13], v[198:201], v[230:233], v[190:193]
	v_mfma_f32_16x16x32_bf16 v[14:17], v[202:205], v[234:237], v[10:13]
	v_mfma_f32_16x16x32_bf16 v[10:13], v[206:209], v[230:233], v[194:197]
	v_mfma_f32_16x16x32_bf16 v[10:13], v[210:213], v[234:237], v[10:13]
	s_add_u32 s78, s78, 0x80180
	s_addc_u32 s79, s79, 0
	s_add_u32 s57, s76, 0x200
	s_addc_u32 s76, s77, 0
	s_mov_b32 s77, 0
.LBB0_1381:
	ds_read_b128 v[146:149], v1
	ds_read_b128 v[150:153], v1 offset:1024
	ds_read_b128 v[154:157], v1 offset:2048
	ds_read_b128 v[158:161], v1 offset:3072
	ds_read_b128 v[162:165], v142
	ds_read_b128 v[166:169], v142 offset:1024
	ds_read_b128 v[170:173], v142 offset:2048
	ds_read_b128 v[174:177], v142 offset:3072
	s_add_u32 s0, s78, 0xfff80080
	s_addc_u32 s1, s79, -1
	s_cmp_eq_u32 s77, 28
	s_cselect_b32 s1, s67, s1
	s_cselect_b32 s0, s69, s0
	s_cselect_b32 s65, s89, s76
	s_cselect_b32 s64, s90, s57
	s_mov_b32 m0, s81
	v_lshl_add_u64 v[140:141], s[78:79], 0, v[134:135]
	ds_read_b128 v[178:181], v143
	ds_read_b128 v[182:185], v143 offset:1024
	ds_read_b128 v[186:189], v143 offset:2048
	ds_read_b128 v[190:193], v143 offset:3072
	ds_read_b128 v[194:197], v143 offset:4096
	ds_read_b128 v[198:201], v143 offset:5120
	ds_read_b128 v[202:205], v143 offset:6144
	ds_read_b128 v[206:209], v143 offset:7168
	global_load_lds_dwordx4 v[140:141], off
	v_lshl_add_u64 v[140:141], v[140:141], 0, s[28:29]
	s_mov_b32 m0, s82
	s_nop 0
	global_load_lds_dwordx4 v[140:141], off
	s_waitcnt vmcnt(8)
	s_waitcnt lgkmcnt(0)
	s_barrier
	s_waitcnt lgkmcnt(0)
	v_mfma_f32_16x16x32_bf16 v[118:121], v[146:149], v[178:181], v[118:121]
	v_mfma_f32_16x16x32_bf16 v[114:117], v[154:157], v[178:181], v[114:117]
	v_mfma_f32_16x16x32_bf16 v[102:105], v[146:149], v[186:189], v[102:105]
	v_mfma_f32_16x16x32_bf16 v[98:101], v[154:157], v[186:189], v[98:101]
	v_mfma_f32_16x16x32_bf16 v[86:89], v[146:149], v[194:197], v[86:89]
	v_mfma_f32_16x16x32_bf16 v[82:85], v[154:157], v[194:197], v[82:85]
	v_mfma_f32_16x16x32_bf16 v[70:73], v[146:149], v[202:205], v[70:73]
	v_mfma_f32_16x16x32_bf16 v[66:69], v[154:157], v[202:205], v[66:69]
	v_mfma_f32_16x16x32_bf16 v[118:121], v[150:153], v[182:185], v[118:121]
	v_mfma_f32_16x16x32_bf16 v[114:117], v[158:161], v[182:185], v[114:117]
	v_mfma_f32_16x16x32_bf16 v[102:105], v[150:153], v[190:193], v[102:105]
	v_mfma_f32_16x16x32_bf16 v[98:101], v[158:161], v[190:193], v[98:101]
	v_mfma_f32_16x16x32_bf16 v[86:89], v[150:153], v[198:201], v[86:89]
	v_mfma_f32_16x16x32_bf16 v[82:85], v[158:161], v[198:201], v[82:85]
	v_mfma_f32_16x16x32_bf16 v[70:73], v[150:153], v[206:209], v[70:73]
	v_mfma_f32_16x16x32_bf16 v[66:69], v[158:161], v[206:209], v[66:69]
	v_mfma_f32_16x16x32_bf16 v[126:129], v[162:165], v[178:181], v[126:129]
	v_mfma_f32_16x16x32_bf16 v[122:125], v[170:173], v[178:181], v[122:125]
	v_mfma_f32_16x16x32_bf16 v[110:113], v[162:165], v[186:189], v[110:113]
	v_mfma_f32_16x16x32_bf16 v[106:109], v[170:173], v[186:189], v[106:109]
	v_mfma_f32_16x16x32_bf16 v[94:97], v[162:165], v[194:197], v[94:97]
	v_mfma_f32_16x16x32_bf16 v[90:93], v[170:173], v[194:197], v[90:93]
	v_mfma_f32_16x16x32_bf16 v[78:81], v[162:165], v[202:205], v[78:81]
	v_mfma_f32_16x16x32_bf16 v[74:77], v[170:173], v[202:205], v[74:77]
	v_mfma_f32_16x16x32_bf16 v[126:129], v[166:169], v[182:185], v[126:129]
	v_mfma_f32_16x16x32_bf16 v[122:125], v[174:177], v[182:185], v[122:125]
	v_mfma_f32_16x16x32_bf16 v[110:113], v[166:169], v[190:193], v[110:113]
	v_mfma_f32_16x16x32_bf16 v[106:109], v[174:177], v[190:193], v[106:109]
	s_barrier
	v_mfma_f32_16x16x32_bf16 v[94:97], v[166:169], v[198:201], v[94:97]
	v_mfma_f32_16x16x32_bf16 v[90:93], v[174:177], v[198:201], v[90:93]
	v_mfma_f32_16x16x32_bf16 v[78:81], v[166:169], v[206:209], v[78:81]
	v_mfma_f32_16x16x32_bf16 v[74:77], v[174:177], v[206:209], v[74:77]
	s_mov_b32 m0, s83
	v_lshl_add_u64 v[140:141], s[64:65], 0, v[130:131]
	ds_read_b128 v[178:181], v143 offset:16384
	ds_read_b128 v[182:185], v143 offset:17408
	ds_read_b128 v[186:189], v143 offset:18432
	ds_read_b128 v[190:193], v143 offset:19456
	ds_read_b128 v[194:197], v143 offset:20480
	ds_read_b128 v[198:201], v143 offset:21504
	ds_read_b128 v[202:205], v143 offset:22528
	ds_read_b128 v[206:209], v143 offset:23552
	global_load_lds_dwordx4 v[140:141], off
	v_lshl_add_u64 v[210:211], v[140:141], 0, s[28:29]
	s_mov_b32 m0, s91
	s_nop 0
	global_load_lds_dwordx4 v[210:211], off
	v_lshl_add_u64 v[210:211], v[140:141], 0, s[30:31]
	s_mov_b32 m0, s40
	s_nop 0
	global_load_lds_dwordx4 v[210:211], off
	v_lshl_add_u64 v[210:211], v[140:141], 0, s[34:35]
	s_mov_b32 m0, s41
	s_nop 0
	global_load_lds_dwordx4 v[210:211], off
	v_lshl_add_u64 v[210:211], s[0:1], 0, v[132:133]
	s_mov_b32 m0, s45
	v_lshl_add_u64 v[212:213], v[210:211], 0, s[28:29]
	global_load_lds_dwordx4 v[210:211], off
	s_mov_b32 m0, s46
	s_nop 0
	global_load_lds_dwordx4 v[212:213], off
	s_waitcnt vmcnt(8)
	s_waitcnt lgkmcnt(0)
	s_barrier
	s_waitcnt lgkmcnt(0)
	v_mfma_f32_16x16x32_bf16 v[54:57], v[146:149], v[178:181], v[54:57]
	v_mfma_f32_16x16x32_bf16 v[50:53], v[154:157], v[178:181], v[50:53]
	v_mfma_f32_16x16x32_bf16 v[38:41], v[146:149], v[186:189], v[38:41]
	v_mfma_f32_16x16x32_bf16 v[34:37], v[154:157], v[186:189], v[34:37]
	v_mfma_f32_16x16x32_bf16 v[22:25], v[146:149], v[194:197], v[22:25]
	v_mfma_f32_16x16x32_bf16 v[18:21], v[154:157], v[194:197], v[18:21]
	v_mfma_f32_16x16x32_bf16 v[6:9], v[146:149], v[202:205], v[6:9]
	v_mfma_f32_16x16x32_bf16 v[2:5], v[154:157], v[202:205], v[2:5]
	v_mfma_f32_16x16x32_bf16 v[54:57], v[150:153], v[182:185], v[54:57]
	v_mfma_f32_16x16x32_bf16 v[50:53], v[158:161], v[182:185], v[50:53]
	v_mfma_f32_16x16x32_bf16 v[38:41], v[150:153], v[190:193], v[38:41]
	v_mfma_f32_16x16x32_bf16 v[34:37], v[158:161], v[190:193], v[34:37]
	v_mfma_f32_16x16x32_bf16 v[22:25], v[150:153], v[198:201], v[22:25]
	v_mfma_f32_16x16x32_bf16 v[18:21], v[158:161], v[198:201], v[18:21]
	v_mfma_f32_16x16x32_bf16 v[6:9], v[150:153], v[206:209], v[6:9]
	v_mfma_f32_16x16x32_bf16 v[2:5], v[158:161], v[206:209], v[2:5]
	v_mfma_f32_16x16x32_bf16 v[62:65], v[162:165], v[178:181], v[62:65]
	v_mfma_f32_16x16x32_bf16 v[58:61], v[170:173], v[178:181], v[58:61]
	v_mfma_f32_16x16x32_bf16 v[46:49], v[162:165], v[186:189], v[46:49]
	v_mfma_f32_16x16x32_bf16 v[42:45], v[170:173], v[186:189], v[42:45]
	v_mfma_f32_16x16x32_bf16 v[30:33], v[162:165], v[194:197], v[30:33]
	v_mfma_f32_16x16x32_bf16 v[26:29], v[170:173], v[194:197], v[26:29]
	v_mfma_f32_16x16x32_bf16 v[14:17], v[162:165], v[202:205], v[14:17]
	v_mfma_f32_16x16x32_bf16 v[10:13], v[170:173], v[202:205], v[10:13]
	v_mfma_f32_16x16x32_bf16 v[62:65], v[166:169], v[182:185], v[62:65]
	v_mfma_f32_16x16x32_bf16 v[58:61], v[174:177], v[182:185], v[58:61]
	v_mfma_f32_16x16x32_bf16 v[46:49], v[166:169], v[190:193], v[46:49]
	v_mfma_f32_16x16x32_bf16 v[42:45], v[174:177], v[190:193], v[42:45]
	s_barrier
	v_mfma_f32_16x16x32_bf16 v[30:33], v[166:169], v[198:201], v[30:33]
	v_mfma_f32_16x16x32_bf16 v[26:29], v[174:177], v[198:201], v[26:29]
	v_mfma_f32_16x16x32_bf16 v[14:17], v[166:169], v[206:209], v[14:17]
	v_mfma_f32_16x16x32_bf16 v[10:13], v[174:177], v[206:209], v[10:13]
	ds_read_b128 v[146:149], v144
	ds_read_b128 v[150:153], v144 offset:1024
	ds_read_b128 v[154:157], v144 offset:2048
	ds_read_b128 v[158:161], v144 offset:3072
	ds_read_b128 v[162:165], v145
	ds_read_b128 v[166:169], v145 offset:1024
	ds_read_b128 v[170:173], v145 offset:2048
	ds_read_b128 v[174:177], v145 offset:3072
	s_mov_b32 m0, s47
	v_lshl_add_u64 v[212:213], v[210:211], 0, s[30:31]
	ds_read_b128 v[178:181], v143 offset:32768
	ds_read_b128 v[182:185], v143 offset:33792
	ds_read_b128 v[186:189], v143 offset:34816
	ds_read_b128 v[190:193], v143 offset:35840
	ds_read_b128 v[194:197], v143 offset:36864
	ds_read_b128 v[198:201], v143 offset:37888
	ds_read_b128 v[202:205], v143 offset:38912
	ds_read_b128 v[206:209], v143 offset:39936
	global_load_lds_dwordx4 v[212:213], off
	v_lshl_add_u64 v[212:213], v[210:211], 0, s[34:35]
	s_mov_b32 m0, s52
	s_nop 0
	global_load_lds_dwordx4 v[212:213], off
	s_waitcnt vmcnt(8)
	s_waitcnt lgkmcnt(0)
	s_barrier
	s_waitcnt lgkmcnt(0)
	v_mfma_f32_16x16x32_bf16 v[118:121], v[146:149], v[178:181], v[118:121]
	v_mfma_f32_16x16x32_bf16 v[114:117], v[154:157], v[178:181], v[114:117]
	v_mfma_f32_16x16x32_bf16 v[102:105], v[146:149], v[186:189], v[102:105]
	v_mfma_f32_16x16x32_bf16 v[98:101], v[154:157], v[186:189], v[98:101]
	v_mfma_f32_16x16x32_bf16 v[86:89], v[146:149], v[194:197], v[86:89]
	v_mfma_f32_16x16x32_bf16 v[82:85], v[154:157], v[194:197], v[82:85]
	v_mfma_f32_16x16x32_bf16 v[70:73], v[146:149], v[202:205], v[70:73]
	v_mfma_f32_16x16x32_bf16 v[66:69], v[154:157], v[202:205], v[66:69]
	v_mfma_f32_16x16x32_bf16 v[118:121], v[150:153], v[182:185], v[118:121]
	v_mfma_f32_16x16x32_bf16 v[114:117], v[158:161], v[182:185], v[114:117]
	v_mfma_f32_16x16x32_bf16 v[102:105], v[150:153], v[190:193], v[102:105]
	v_mfma_f32_16x16x32_bf16 v[98:101], v[158:161], v[190:193], v[98:101]
	v_mfma_f32_16x16x32_bf16 v[86:89], v[150:153], v[198:201], v[86:89]
	v_mfma_f32_16x16x32_bf16 v[82:85], v[158:161], v[198:201], v[82:85]
	v_mfma_f32_16x16x32_bf16 v[70:73], v[150:153], v[206:209], v[70:73]
	v_mfma_f32_16x16x32_bf16 v[66:69], v[158:161], v[206:209], v[66:69]
	v_mfma_f32_16x16x32_bf16 v[126:129], v[162:165], v[178:181], v[126:129]
	v_mfma_f32_16x16x32_bf16 v[122:125], v[170:173], v[178:181], v[122:125]
	v_mfma_f32_16x16x32_bf16 v[110:113], v[162:165], v[186:189], v[110:113]
	v_mfma_f32_16x16x32_bf16 v[106:109], v[170:173], v[186:189], v[106:109]
	v_mfma_f32_16x16x32_bf16 v[94:97], v[162:165], v[194:197], v[94:97]
	v_mfma_f32_16x16x32_bf16 v[90:93], v[170:173], v[194:197], v[90:93]
	v_mfma_f32_16x16x32_bf16 v[78:81], v[162:165], v[202:205], v[78:81]
	v_mfma_f32_16x16x32_bf16 v[74:77], v[170:173], v[202:205], v[74:77]
	v_mfma_f32_16x16x32_bf16 v[126:129], v[166:169], v[182:185], v[126:129]
	v_mfma_f32_16x16x32_bf16 v[122:125], v[174:177], v[182:185], v[122:125]
	v_mfma_f32_16x16x32_bf16 v[110:113], v[166:169], v[190:193], v[110:113]
	v_mfma_f32_16x16x32_bf16 v[106:109], v[174:177], v[190:193], v[106:109]
	s_barrier
; #define PG8_WAIT_V(n) asm volatile("s_waitcnt vmcnt(" #n ")" ::: "memory")
; template <class Epi, class Sched, bool ALIGN_EPI = true, bool SP2 = true, bool FULLLINE = false, bool NOSTAGE = false, bool FP8 = false>
; __device__ __forceinline__ void gemm_phase(PG8_LAS unsigned char* lds, const Gemm g, const Sched& S, const Epi& E) {
;     ...
;         static_assert(SP2, "only the SP2 loop is kept");
;         { const int t = 0; if constexpr (Epi::NST == 16) PG8_ITER(PG8_WAIT_V(24)); else if constexpr (Epi::NST == 8) PG8_ITER(PG8_WAIT_V(16)); else PG8_ITER(PG8_WAIT_V(8)); }
;         for (int t = 2; t < nt; t += 2) PG8_ITER(PG8_WAIT_V(8));
	v_mfma_f32_16x16x32_bf16 v[94:97], v[166:169], v[198:201], v[94:97]
	v_mfma_f32_16x16x32_bf16 v[90:93], v[174:177], v[198:201], v[90:93]
	v_mfma_f32_16x16x32_bf16 v[78:81], v[166:169], v[206:209], v[78:81]
	v_mfma_f32_16x16x32_bf16 v[74:77], v[174:177], v[206:209], v[74:77]
	s_mov_b32 m0, s50
	v_lshl_add_u64 v[212:213], v[140:141], 0, s[36:37]
	ds_read_b128 v[178:181], v143 offset:49152
	ds_read_b128 v[182:185], v143 offset:50176
	ds_read_b128 v[186:189], v143 offset:51200
	ds_read_b128 v[190:193], v143 offset:52224
	ds_read_b128 v[194:197], v143 offset:53248
	ds_read_b128 v[198:201], v143 offset:54272
	ds_read_b128 v[202:205], v143 offset:55296
	ds_read_b128 v[206:209], v143 offset:56320
	global_load_lds_dwordx4 v[212:213], off
	v_lshl_add_u64 v[212:213], v[140:141], 0, s[38:39]
	s_mov_b32 m0, s51
	s_nop 0
	global_load_lds_dwordx4 v[212:213], off
	v_lshl_add_u64 v[212:213], v[140:141], 0, s[12:13]
	s_mov_b32 m0, s33
	v_lshl_add_u64 v[140:141], v[140:141], 0, s[14:15]
	global_load_lds_dwordx4 v[212:213], off
	s_mov_b32 m0, s56
	s_nop 0
	global_load_lds_dwordx4 v[140:141], off
	v_lshl_add_u64 v[140:141], v[210:211], 0, s[36:37]
	s_mov_b32 m0, s53
	s_nop 0
	global_load_lds_dwordx4 v[140:141], off
	v_lshl_add_u64 v[140:141], v[210:211], 0, s[38:39]
	s_mov_b32 m0, s54
	s_nop 0
	global_load_lds_dwordx4 v[140:141], off
	s_waitcnt vmcnt(8)
	s_waitcnt lgkmcnt(0)
	s_barrier
	s_waitcnt lgkmcnt(0)
	v_mfma_f32_16x16x32_bf16 v[54:57], v[146:149], v[178:181], v[54:57]
	v_mfma_f32_16x16x32_bf16 v[50:53], v[154:157], v[178:181], v[50:53]
	v_mfma_f32_16x16x32_bf16 v[38:41], v[146:149], v[186:189], v[38:41]
	v_mfma_f32_16x16x32_bf16 v[34:37], v[154:157], v[186:189], v[34:37]
	v_mfma_f32_16x16x32_bf16 v[22:25], v[146:149], v[194:197], v[22:25]
	v_mfma_f32_16x16x32_bf16 v[18:21], v[154:157], v[194:197], v[18:21]
	v_mfma_f32_16x16x32_bf16 v[6:9], v[146:149], v[202:205], v[6:9]
	v_mfma_f32_16x16x32_bf16 v[2:5], v[154:157], v[202:205], v[2:5]
	v_mfma_f32_16x16x32_bf16 v[54:57], v[150:153], v[182:185], v[54:57]
	v_mfma_f32_16x16x32_bf16 v[50:53], v[158:161], v[182:185], v[50:53]
	v_mfma_f32_16x16x32_bf16 v[38:41], v[150:153], v[190:193], v[38:41]
	v_mfma_f32_16x16x32_bf16 v[34:37], v[158:161], v[190:193], v[34:37]
	v_mfma_f32_16x16x32_bf16 v[22:25], v[150:153], v[198:201], v[22:25]
	v_mfma_f32_16x16x32_bf16 v[18:21], v[158:161], v[198:201], v[18:21]
	v_mfma_f32_16x16x32_bf16 v[6:9], v[150:153], v[206:209], v[6:9]
	v_mfma_f32_16x16x32_bf16 v[2:5], v[158:161], v[206:209], v[2:5]
	v_mfma_f32_16x16x32_bf16 v[62:65], v[162:165], v[178:181], v[62:65]
	v_mfma_f32_16x16x32_bf16 v[58:61], v[170:173], v[178:181], v[58:61]
	v_mfma_f32_16x16x32_bf16 v[46:49], v[162:165], v[186:189], v[46:49]
	v_mfma_f32_16x16x32_bf16 v[42:45], v[170:173], v[186:189], v[42:45]
	v_mfma_f32_16x16x32_bf16 v[30:33], v[162:165], v[194:197], v[30:33]
	v_mfma_f32_16x16x32_bf16 v[26:29], v[170:173], v[194:197], v[26:29]
	v_mfma_f32_16x16x32_bf16 v[14:17], v[162:165], v[202:205], v[14:17]
	v_mfma_f32_16x16x32_bf16 v[10:13], v[170:173], v[202:205], v[10:13]
	v_mfma_f32_16x16x32_bf16 v[62:65], v[166:169], v[182:185], v[62:65]
	v_mfma_f32_16x16x32_bf16 v[58:61], v[174:177], v[182:185], v[58:61]
	v_mfma_f32_16x16x32_bf16 v[46:49], v[166:169], v[190:193], v[46:49]
	v_mfma_f32_16x16x32_bf16 v[42:45], v[174:177], v[190:193], v[42:45]
	s_barrier
	v_mfma_f32_16x16x32_bf16 v[30:33], v[166:169], v[198:201], v[30:33]
	v_mfma_f32_16x16x32_bf16 v[26:29], v[174:177], v[198:201], v[26:29]
	v_mfma_f32_16x16x32_bf16 v[14:17], v[166:169], v[206:209], v[14:17]
	v_mfma_f32_16x16x32_bf16 v[10:13], v[174:177], v[206:209], v[10:13]
	s_add_i32 s77, s77, 2
	s_add_u32 s78, s78, 0x100
	s_addc_u32 s79, s79, 0
	s_add_u32 s57, s57, 0x100
	s_addc_u32 s76, s76, 0
	s_cmp_gt_u32 s77, 29
	s_cbranch_scc0 .LBB0_1381
	s_and_b64 vcc, exec, s[10:11]
	s_cbranch_vccz .LBB0_1384
	s_barrier

; #define PG8_WAIT_V(n) asm volatile("s_waitcnt vmcnt(" #n ")" ::: "memory")
; template <class Epi, class Sched, bool ALIGN_EPI = true, bool SP2 = true, bool FULLLINE = false, bool NOSTAGE = false, bool FP8 = false>
; __device__ __forceinline__ void gemm_phase(PG8_LAS unsigned char* lds, const Gemm g, const Sched& S, const Epi& E) {
;     ...
;         { const int t = 0; if constexpr (Epi::NST == 16) PG8_ITER(PG8_WAIT_V(24)); else if constexpr (Epi::NST == 8) PG8_ITER(PG8_WAIT_V(16)); else PG8_ITER(PG8_WAIT_V(8)); }
.LBB0_1483:
	ds_read_b128 v[2:5], v1
	ds_read_b128 v[6:9], v1 offset:1024
	ds_read_b128 v[10:13], v1 offset:2048
	ds_read_b128 v[14:17], v1 offset:3072
	ds_read_b128 v[18:21], v192
	ds_read_b128 v[22:25], v192 offset:1024
	ds_read_b128 v[26:29], v192 offset:2048
	ds_read_b128 v[30:33], v192 offset:3072
	v_lshl_add_u64 v[248:249], s[70:71], 0, v[170:171]
	s_add_i32 s85, s45, 0xc000
	v_lshl_add_u64 v[66:67], v[248:249], 0, s[14:15]
	s_mov_b32 m0, s85
	s_add_i32 s87, s45, 0xe000
	ds_read_b128 v[34:37], v193
	ds_read_b128 v[38:41], v193 offset:1024
	ds_read_b128 v[42:45], v193 offset:2048
	ds_read_b128 v[46:49], v193 offset:3072
	ds_read_b128 v[50:53], v193 offset:4096
	ds_read_b128 v[54:57], v193 offset:5120
	ds_read_b128 v[58:61], v193 offset:6144
	ds_read_b128 v[62:65], v193 offset:7168
	global_load_lds_dwordx4 v[66:67], off
	v_lshl_add_u64 v[66:67], v[248:249], 0, s[16:17]
	s_mov_b32 m0, s87
	s_nop 0
	global_load_lds_dwordx4 v[66:67], off
	s_waitcnt vmcnt(24)
	s_waitcnt lgkmcnt(0)
	s_barrier
	s_waitcnt lgkmcnt(0)
	v_mfma_f32_16x16x32_bf16 v[66:69], v[2:5], v[34:37], 0
	v_mfma_f32_16x16x32_bf16 v[70:73], v[10:13], v[34:37], 0
	v_mfma_f32_16x16x32_bf16 v[78:81], v[10:13], v[42:45], 0
	v_mfma_f32_16x16x32_bf16 v[86:89], v[10:13], v[50:53], 0
	v_mfma_f32_16x16x32_bf16 v[66:69], v[6:9], v[38:41], v[66:69]
	v_mfma_f32_16x16x32_bf16 v[70:73], v[14:17], v[38:41], v[70:73]
	v_mfma_f32_16x16x32_bf16 v[74:77], v[2:5], v[42:45], 0
	v_mfma_f32_16x16x32_bf16 v[78:81], v[14:17], v[46:49], v[78:81]
	v_mfma_f32_16x16x32_bf16 v[82:85], v[2:5], v[50:53], 0
	v_mfma_f32_16x16x32_bf16 v[86:89], v[14:17], v[54:57], v[86:89]
	v_mfma_f32_16x16x32_bf16 v[90:93], v[2:5], v[58:61], 0
	v_mfma_f32_16x16x32_bf16 v[94:97], v[10:13], v[58:61], 0
	v_mfma_f32_16x16x32_bf16 v[74:77], v[6:9], v[46:49], v[74:77]
	v_mfma_f32_16x16x32_bf16 v[82:85], v[6:9], v[54:57], v[82:85]
	v_mfma_f32_16x16x32_bf16 v[90:93], v[6:9], v[62:65], v[90:93]
	v_mfma_f32_16x16x32_bf16 v[94:97], v[14:17], v[62:65], v[94:97]
	v_mfma_f32_16x16x32_bf16 v[98:101], v[18:21], v[34:37], 0
	v_mfma_f32_16x16x32_bf16 v[34:37], v[26:29], v[34:37], 0
	v_mfma_f32_16x16x32_bf16 v[98:101], v[22:25], v[38:41], v[98:101]
	v_mfma_f32_16x16x32_bf16 v[34:37], v[30:33], v[38:41], v[34:37]
	v_mfma_f32_16x16x32_bf16 v[38:41], v[18:21], v[42:45], 0
	v_mfma_f32_16x16x32_bf16 v[42:45], v[26:29], v[42:45], 0
	v_mfma_f32_16x16x32_bf16 v[38:41], v[22:25], v[46:49], v[38:41]
	v_mfma_f32_16x16x32_bf16 v[42:45], v[30:33], v[46:49], v[42:45]
	v_mfma_f32_16x16x32_bf16 v[46:49], v[18:21], v[50:53], 0
	v_mfma_f32_16x16x32_bf16 v[50:53], v[26:29], v[50:53], 0
	v_mfma_f32_16x16x32_bf16 v[46:49], v[22:25], v[54:57], v[46:49]
	v_mfma_f32_16x16x32_bf16 v[50:53], v[30:33], v[54:57], v[50:53]
	s_barrier
	v_mfma_f32_16x16x32_bf16 v[54:57], v[18:21], v[58:61], 0
	v_mfma_f32_16x16x32_bf16 v[58:61], v[26:29], v[58:61], 0
	v_mfma_f32_16x16x32_bf16 v[54:57], v[22:25], v[62:65], v[54:57]
	v_mfma_f32_16x16x32_bf16 v[58:61], v[30:33], v[62:65], v[58:61]
	v_lshl_add_u64 v[250:251], s[72:73], 0, v[172:173]
	s_add_i32 s88, s77, s44
	v_lshl_add_u64 v[130:131], v[250:251], 0, s[18:19]
	s_mov_b32 m0, s88
	s_add_i32 s89, s88, 0x2000
	ds_read_b128 v[62:65], v193 offset:16384
	ds_read_b128 v[102:105], v193 offset:17408
	ds_read_b128 v[106:109], v193 offset:18432
	ds_read_b128 v[110:113], v193 offset:19456
	ds_read_b128 v[114:117], v193 offset:20480
	ds_read_b128 v[118:121], v193 offset:21504
	ds_read_b128 v[122:125], v193 offset:22528
	ds_read_b128 v[126:129], v193 offset:23552
	global_load_lds_dwordx4 v[130:131], off
	v_lshl_add_u64 v[130:131], v[250:251], 0, s[20:21]
	s_mov_b32 m0, s89
	s_add_i32 s40, s78, s44
	global_load_lds_dwordx4 v[130:131], off
	v_lshl_add_u64 v[130:131], v[250:251], 0, s[22:23]
	s_mov_b32 m0, s40
	s_add_i32 s41, s40, 0x2000
	global_load_lds_dwordx4 v[130:131], off
	v_lshl_add_u64 v[130:131], v[250:251], 0, s[24:25]
	s_mov_b32 m0, s41
	s_nop 0
	global_load_lds_dwordx4 v[130:131], off
	v_lshl_add_u64 v[130:131], v[248:249], 0, s[18:19]
	s_mov_b32 m0, s45
	s_nop 0
	global_load_lds_dwordx4 v[130:131], off
	v_lshl_add_u64 v[130:131], v[248:249], 0, s[20:21]
	s_mov_b32 m0, s46
	s_nop 0
	global_load_lds_dwordx4 v[130:131], off
	s_waitcnt vmcnt(24)
	s_waitcnt lgkmcnt(0)
	s_barrier
	s_waitcnt lgkmcnt(0)
	v_mfma_f32_16x16x32_bf16 v[130:133], v[2:5], v[62:65], 0
	v_mfma_f32_16x16x32_bf16 v[138:141], v[6:9], v[102:105], v[130:133]
	v_mfma_f32_16x16x32_bf16 v[130:133], v[10:13], v[62:65], 0
	v_mfma_f32_16x16x32_bf16 v[150:153], v[14:17], v[102:105], v[130:133]
	v_mfma_f32_16x16x32_bf16 v[130:133], v[2:5], v[106:109], 0
	v_mfma_f32_16x16x32_bf16 v[154:157], v[6:9], v[110:113], v[130:133]
	v_mfma_f32_16x16x32_bf16 v[130:133], v[10:13], v[106:109], 0
	v_mfma_f32_16x16x32_bf16 v[158:161], v[14:17], v[110:113], v[130:133]
	v_mfma_f32_16x16x32_bf16 v[130:133], v[2:5], v[114:117], 0
	v_mfma_f32_16x16x32_bf16 v[2:5], v[2:5], v[122:125], 0
	v_mfma_f32_16x16x32_bf16 v[162:165], v[6:9], v[118:121], v[130:133]
	v_mfma_f32_16x16x32_bf16 v[2:5], v[6:9], v[126:129], v[2:5]
	v_mfma_f32_16x16x32_bf16 v[6:9], v[10:13], v[122:125], 0
	v_mfma_f32_16x16x32_bf16 v[130:133], v[10:13], v[114:117], 0
	v_mfma_f32_16x16x32_bf16 v[6:9], v[14:17], v[126:129], v[6:9]
	v_mfma_f32_16x16x32_bf16 v[166:169], v[14:17], v[118:121], v[130:133]
	v_mfma_f32_16x16x32_bf16 v[10:13], v[18:21], v[62:65], 0
	v_mfma_f32_16x16x32_bf16 v[180:183], v[22:25], v[102:105], v[10:13]
	v_mfma_f32_16x16x32_bf16 v[10:13], v[26:29], v[62:65], 0
	v_mfma_f32_16x16x32_bf16 v[184:187], v[30:33], v[102:105], v[10:13]
	v_mfma_f32_16x16x32_bf16 v[10:13], v[18:21], v[106:109], 0
	v_mfma_f32_16x16x32_bf16 v[188:191], v[22:25], v[110:113], v[10:13]
	v_mfma_f32_16x16x32_bf16 v[10:13], v[26:29], v[106:109], 0
	v_mfma_f32_16x16x32_bf16 v[196:199], v[30:33], v[110:113], v[10:13]
	v_mfma_f32_16x16x32_bf16 v[10:13], v[18:21], v[114:117], 0
	v_mfma_f32_16x16x32_bf16 v[200:203], v[22:25], v[118:121], v[10:13]
	v_mfma_f32_16x16x32_bf16 v[10:13], v[26:29], v[114:117], 0
	v_mfma_f32_16x16x32_bf16 v[204:207], v[30:33], v[118:121], v[10:13]
	s_barrier
	v_mfma_f32_16x16x32_bf16 v[10:13], v[18:21], v[122:125], 0
	v_mfma_f32_16x16x32_bf16 v[208:211], v[22:25], v[126:129], v[10:13]
	v_mfma_f32_16x16x32_bf16 v[10:13], v[26:29], v[122:125], 0
	v_mfma_f32_16x16x32_bf16 v[212:215], v[30:33], v[126:129], v[10:13]
	s_nop 5
	ds_read_b128 v[10:13], v194
	ds_read_b128 v[14:17], v194 offset:1024
	ds_read_b128 v[18:21], v194 offset:2048
	ds_read_b128 v[22:25], v194 offset:3072
	ds_read_b128 v[216:219], v195
	ds_read_b128 v[220:223], v195 offset:1024
	ds_read_b128 v[224:227], v195 offset:2048
	ds_read_b128 v[228:231], v195 offset:3072
	s_mov_b32 m0, s47
	v_lshl_add_u64 v[106:107], v[248:249], 0, s[22:23]
	ds_read_b128 v[26:29], v193 offset:32768
	ds_read_b128 v[30:33], v193 offset:33792
	ds_read_b128 v[62:65], v193 offset:34816
	ds_read_b128 v[102:105], v193 offset:35840
	ds_read_b128 v[232:235], v193 offset:36864
	ds_read_b128 v[236:239], v193 offset:37888
	ds_read_b128 v[240:243], v193 offset:38912
	ds_read_b128 v[244:247], v193 offset:39936
	global_load_lds_dwordx4 v[106:107], off
	v_lshl_add_u64 v[106:107], v[248:249], 0, s[24:25]
	s_mov_b32 m0, s52
	s_nop 0
	global_load_lds_dwordx4 v[106:107], off
	s_waitcnt vmcnt(8)
	s_waitcnt lgkmcnt(0)
	s_barrier
	s_waitcnt lgkmcnt(0)
	v_mfma_f32_16x16x32_bf16 v[66:69], v[10:13], v[26:29], v[66:69]
	v_mfma_f32_16x16x32_bf16 v[146:149], v[14:17], v[30:33], v[66:69]
	v_mfma_f32_16x16x32_bf16 v[66:69], v[18:21], v[26:29], v[70:73]
	v_mfma_f32_16x16x32_bf16 v[142:145], v[22:25], v[30:33], v[66:69]
	v_mfma_f32_16x16x32_bf16 v[66:69], v[10:13], v[62:65], v[74:77]
	v_mfma_f32_16x16x32_bf16 v[126:129], v[14:17], v[102:105], v[66:69]
	v_mfma_f32_16x16x32_bf16 v[66:69], v[18:21], v[62:65], v[78:81]
	v_mfma_f32_16x16x32_bf16 v[122:125], v[22:25], v[102:105], v[66:69]
	v_mfma_f32_16x16x32_bf16 v[66:69], v[10:13], v[232:235], v[82:85]
	v_mfma_f32_16x16x32_bf16 v[110:113], v[14:17], v[236:239], v[66:69]
	v_mfma_f32_16x16x32_bf16 v[66:69], v[18:21], v[232:235], v[86:89]
	v_mfma_f32_16x16x32_bf16 v[106:109], v[22:25], v[236:239], v[66:69]
	v_mfma_f32_16x16x32_bf16 v[66:69], v[10:13], v[240:243], v[90:93]
	v_mfma_f32_16x16x32_bf16 v[86:89], v[14:17], v[244:247], v[66:69]
	v_mfma_f32_16x16x32_bf16 v[66:69], v[18:21], v[240:243], v[94:97]
	v_mfma_f32_16x16x32_bf16 v[78:81], v[22:25], v[244:247], v[66:69]
	v_mfma_f32_16x16x32_bf16 v[66:69], v[216:219], v[26:29], v[98:101]
	v_mfma_f32_16x16x32_bf16 v[26:29], v[224:227], v[26:29], v[34:37]
	v_mfma_f32_16x16x32_bf16 v[130:133], v[228:231], v[30:33], v[26:29]
	v_mfma_f32_16x16x32_bf16 v[26:29], v[216:219], v[62:65], v[38:41]
	v_mfma_f32_16x16x32_bf16 v[118:121], v[220:223], v[102:105], v[26:29]
	v_mfma_f32_16x16x32_bf16 v[26:29], v[224:227], v[62:65], v[42:45]
	v_mfma_f32_16x16x32_bf16 v[114:117], v[228:231], v[102:105], v[26:29]
	v_mfma_f32_16x16x32_bf16 v[26:29], v[216:219], v[232:235], v[46:49]
	v_mfma_f32_16x16x32_bf16 v[102:105], v[220:223], v[236:239], v[26:29]
	v_mfma_f32_16x16x32_bf16 v[26:29], v[224:227], v[232:235], v[50:53]
	v_mfma_f32_16x16x32_bf16 v[98:101], v[228:231], v[236:239], v[26:29]
	v_mfma_f32_16x16x32_bf16 v[26:29], v[216:219], v[240:243], v[54:57]
	s_barrier
	v_mfma_f32_16x16x32_bf16 v[70:73], v[220:223], v[244:247], v[26:29]
	v_mfma_f32_16x16x32_bf16 v[26:29], v[224:227], v[240:243], v[58:61]
	v_mfma_f32_16x16x32_bf16 v[134:137], v[220:223], v[30:33], v[66:69]
	v_mfma_f32_16x16x32_bf16 v[66:69], v[228:231], v[244:247], v[26:29]
	s_add_i32 s50, s79, s44
	s_nop 3
	v_lshl_add_u64 v[26:27], v[250:251], 0, s[26:27]
	s_mov_b32 m0, s50
	s_add_i32 s51, s50, 0x2000
	ds_read_b128 v[34:37], v193 offset:49152
	ds_read_b128 v[38:41], v193 offset:50176
	ds_read_b128 v[74:77], v193 offset:51200
	ds_read_b128 v[82:85], v193 offset:52224
	ds_read_b128 v[90:93], v193 offset:53248
	ds_read_b128 v[94:97], v193 offset:54272
	ds_read_b128 v[232:235], v193 offset:55296
	ds_read_b128 v[236:239], v193 offset:56320
	global_load_lds_dwordx4 v[26:27], off
	v_lshl_add_u64 v[26:27], v[250:251], 0, s[28:29]
	s_mov_b32 m0, s51
	s_mov_b64 s[0:1], 0x160180
	s_add_i32 s33, s80, s44
	global_load_lds_dwordx4 v[26:27], off
	v_lshl_add_u64 v[26:27], v[250:251], 0, s[0:1]
	s_mov_b32 m0, s33
	s_mov_b64 s[0:1], 0x210180
	s_add_i32 s56, s33, 0x2000
	global_load_lds_dwordx4 v[26:27], off
	v_lshl_add_u64 v[26:27], v[250:251], 0, s[0:1]
	s_mov_b32 m0, s56
	s_nop 0
	global_load_lds_dwordx4 v[26:27], off
	v_lshl_add_u64 v[26:27], v[248:249], 0, s[26:27]
	s_mov_b32 m0, s53
	s_nop 0
	global_load_lds_dwordx4 v[26:27], off
	v_lshl_add_u64 v[26:27], v[248:249], 0, s[28:29]
	s_mov_b32 m0, s54
	s_nop 0
	global_load_lds_dwordx4 v[26:27], off
	s_waitcnt vmcnt(8)
	s_waitcnt lgkmcnt(0)
	s_barrier
	s_waitcnt lgkmcnt(0)
	v_mfma_f32_16x16x32_bf16 v[26:29], v[10:13], v[34:37], v[138:141]
	v_mfma_f32_16x16x32_bf16 v[62:65], v[14:17], v[38:41], v[26:29]
	v_mfma_f32_16x16x32_bf16 v[26:29], v[18:21], v[34:37], v[150:153]
	v_mfma_f32_16x16x32_bf16 v[58:61], v[22:25], v[38:41], v[26:29]
	v_mfma_f32_16x16x32_bf16 v[26:29], v[10:13], v[74:77], v[154:157]
	v_mfma_f32_16x16x32_bf16 v[46:49], v[14:17], v[82:85], v[26:29]
	v_mfma_f32_16x16x32_bf16 v[26:29], v[18:21], v[74:77], v[158:161]
	v_mfma_f32_16x16x32_bf16 v[42:45], v[22:25], v[82:85], v[26:29]
	v_mfma_f32_16x16x32_bf16 v[26:29], v[10:13], v[90:93], v[162:165]
	v_mfma_f32_16x16x32_bf16 v[2:5], v[10:13], v[232:235], v[2:5]
	v_mfma_f32_16x16x32_bf16 v[30:33], v[14:17], v[94:97], v[26:29]
	v_mfma_f32_16x16x32_bf16 v[26:29], v[18:21], v[90:93], v[166:169]
	v_mfma_f32_16x16x32_bf16 v[14:17], v[14:17], v[236:239], v[2:5]
	v_mfma_f32_16x16x32_bf16 v[2:5], v[18:21], v[232:235], v[6:9]
	v_mfma_f32_16x16x32_bf16 v[26:29], v[22:25], v[94:97], v[26:29]
	v_mfma_f32_16x16x32_bf16 v[10:13], v[22:25], v[236:239], v[2:5]
	v_mfma_f32_16x16x32_bf16 v[2:5], v[216:219], v[34:37], v[180:183]
	v_mfma_f32_16x16x32_bf16 v[54:57], v[220:223], v[38:41], v[2:5]
	v_mfma_f32_16x16x32_bf16 v[2:5], v[224:227], v[34:37], v[184:187]
	v_mfma_f32_16x16x32_bf16 v[50:53], v[228:231], v[38:41], v[2:5]
	v_mfma_f32_16x16x32_bf16 v[2:5], v[216:219], v[74:77], v[188:191]
	v_mfma_f32_16x16x32_bf16 v[38:41], v[220:223], v[82:85], v[2:5]
	v_mfma_f32_16x16x32_bf16 v[2:5], v[224:227], v[74:77], v[196:199]
	v_mfma_f32_16x16x32_bf16 v[34:37], v[228:231], v[82:85], v[2:5]
	v_mfma_f32_16x16x32_bf16 v[2:5], v[216:219], v[90:93], v[200:203]
	v_mfma_f32_16x16x32_bf16 v[22:25], v[220:223], v[94:97], v[2:5]
	v_mfma_f32_16x16x32_bf16 v[2:5], v[224:227], v[90:93], v[204:207]
	v_mfma_f32_16x16x32_bf16 v[18:21], v[228:231], v[94:97], v[2:5]
	s_barrier
	v_mfma_f32_16x16x32_bf16 v[2:5], v[216:219], v[232:235], v[208:211]
	v_mfma_f32_16x16x32_bf16 v[6:9], v[220:223], v[236:239], v[2:5]
	v_mfma_f32_16x16x32_bf16 v[2:5], v[224:227], v[232:235], v[212:215]
	v_mfma_f32_16x16x32_bf16 v[2:5], v[228:231], v[236:239], v[2:5]
	s_add_u32 s70, s70, 0x160180
	s_addc_u32 s71, s71, 0
	s_add_u32 s57, s72, 0x200
	s_addc_u32 s72, s73, 0
	s_mov_b32 s73, 0
.LBB0_1484:
	ds_read_b128 v[74:77], v1
	ds_read_b128 v[82:85], v1 offset:1024
	ds_read_b128 v[90:93], v1 offset:2048
	ds_read_b128 v[94:97], v1 offset:3072
	ds_read_b128 v[138:141], v192
	ds_read_b128 v[150:153], v192 offset:1024
	ds_read_b128 v[154:157], v192 offset:2048
	ds_read_b128 v[158:161], v192 offset:3072
	s_add_u32 s0, s70, 0xffea0080
	s_addc_u32 s1, s71, -1
	s_cmpk_eq_i32 s73, 0x54
	s_cselect_b32 s1, s11, s1
	s_cselect_b32 s0, s10, s0
	s_cselect_b32 s65, s69, s72
	s_cselect_b32 s64, s68, s57
	s_mov_b32 m0, s85
	v_lshl_add_u64 v[208:209], s[70:71], 0, v[174:175]
	ds_read_b128 v[162:165], v193
	ds_read_b128 v[166:169], v193 offset:1024
	ds_read_b128 v[180:183], v193 offset:2048
	ds_read_b128 v[184:187], v193 offset:3072
	ds_read_b128 v[188:191], v193 offset:4096
	ds_read_b128 v[196:199], v193 offset:5120
	ds_read_b128 v[200:203], v193 offset:6144
	ds_read_b128 v[204:207], v193 offset:7168
	global_load_lds_dwordx4 v[208:209], off
	v_lshl_add_u64 v[208:209], v[208:209], 0, s[30:31]
	s_mov_b32 m0, s87
	s_nop 0
	global_load_lds_dwordx4 v[208:209], off
	s_waitcnt vmcnt(8)
	s_waitcnt lgkmcnt(0)
	s_barrier
	s_waitcnt lgkmcnt(0)
	v_mfma_f32_16x16x32_bf16 v[146:149], v[74:77], v[162:165], v[146:149]
	v_mfma_f32_16x16x32_bf16 v[142:145], v[90:93], v[162:165], v[142:145]
	v_mfma_f32_16x16x32_bf16 v[126:129], v[74:77], v[180:183], v[126:129]
	v_mfma_f32_16x16x32_bf16 v[122:125], v[90:93], v[180:183], v[122:125]
	v_mfma_f32_16x16x32_bf16 v[110:113], v[74:77], v[188:191], v[110:113]
	v_mfma_f32_16x16x32_bf16 v[106:109], v[90:93], v[188:191], v[106:109]
	v_mfma_f32_16x16x32_bf16 v[86:89], v[74:77], v[200:203], v[86:89]
	v_mfma_f32_16x16x32_bf16 v[78:81], v[90:93], v[200:203], v[78:81]
	v_mfma_f32_16x16x32_bf16 v[146:149], v[82:85], v[166:169], v[146:149]
	v_mfma_f32_16x16x32_bf16 v[142:145], v[94:97], v[166:169], v[142:145]
	v_mfma_f32_16x16x32_bf16 v[126:129], v[82:85], v[184:187], v[126:129]
	v_mfma_f32_16x16x32_bf16 v[122:125], v[94:97], v[184:187], v[122:125]
	v_mfma_f32_16x16x32_bf16 v[110:113], v[82:85], v[196:199], v[110:113]
	v_mfma_f32_16x16x32_bf16 v[106:109], v[94:97], v[196:199], v[106:109]
	v_mfma_f32_16x16x32_bf16 v[86:89], v[82:85], v[204:207], v[86:89]
	v_mfma_f32_16x16x32_bf16 v[78:81], v[94:97], v[204:207], v[78:81]
	v_mfma_f32_16x16x32_bf16 v[134:137], v[138:141], v[162:165], v[134:137]
	v_mfma_f32_16x16x32_bf16 v[130:133], v[154:157], v[162:165], v[130:133]
	v_mfma_f32_16x16x32_bf16 v[118:121], v[138:141], v[180:183], v[118:121]
	v_mfma_f32_16x16x32_bf16 v[114:117], v[154:157], v[180:183], v[114:117]
	v_mfma_f32_16x16x32_bf16 v[102:105], v[138:141], v[188:191], v[102:105]
	v_mfma_f32_16x16x32_bf16 v[98:101], v[154:157], v[188:191], v[98:101]
	v_mfma_f32_16x16x32_bf16 v[70:73], v[138:141], v[200:203], v[70:73]
	v_mfma_f32_16x16x32_bf16 v[66:69], v[154:157], v[200:203], v[66:69]
	v_mfma_f32_16x16x32_bf16 v[134:137], v[150:153], v[166:169], v[134:137]
	v_mfma_f32_16x16x32_bf16 v[130:133], v[158:161], v[166:169], v[130:133]
	v_mfma_f32_16x16x32_bf16 v[118:121], v[150:153], v[184:187], v[118:121]
	v_mfma_f32_16x16x32_bf16 v[114:117], v[158:161], v[184:187], v[114:117]
	s_barrier
	v_mfma_f32_16x16x32_bf16 v[102:105], v[150:153], v[196:199], v[102:105]
	v_mfma_f32_16x16x32_bf16 v[98:101], v[158:161], v[196:199], v[98:101]
	v_mfma_f32_16x16x32_bf16 v[70:73], v[150:153], v[204:207], v[70:73]
	v_mfma_f32_16x16x32_bf16 v[66:69], v[158:161], v[204:207], v[66:69]
	s_mov_b32 m0, s88
	v_lshl_add_u64 v[208:209], s[64:65], 0, v[172:173]
	ds_read_b128 v[162:165], v193 offset:16384
	ds_read_b128 v[166:169], v193 offset:17408
	ds_read_b128 v[180:183], v193 offset:18432
	ds_read_b128 v[184:187], v193 offset:19456
	ds_read_b128 v[188:191], v193 offset:20480
	ds_read_b128 v[196:199], v193 offset:21504
	ds_read_b128 v[200:203], v193 offset:22528
	ds_read_b128 v[204:207], v193 offset:23552
	global_load_lds_dwordx4 v[208:209], off
	v_lshl_add_u64 v[210:211], v[208:209], 0, s[30:31]
	s_mov_b32 m0, s89
	s_nop 0
	global_load_lds_dwordx4 v[210:211], off
	v_lshl_add_u64 v[210:211], v[208:209], 0, s[34:35]
	s_mov_b32 m0, s40
	s_nop 0
	global_load_lds_dwordx4 v[210:211], off
	v_lshl_add_u64 v[210:211], v[208:209], 0, s[36:37]
	s_mov_b32 m0, s41
	s_nop 0
	global_load_lds_dwordx4 v[210:211], off
	v_lshl_add_u64 v[210:211], s[0:1], 0, v[170:171]
	s_mov_b32 m0, s45
	v_lshl_add_u64 v[212:213], v[210:211], 0, s[30:31]
	global_load_lds_dwordx4 v[210:211], off
	s_mov_b32 m0, s46
	s_nop 0
	global_load_lds_dwordx4 v[212:213], off
	s_waitcnt vmcnt(8)
	s_waitcnt lgkmcnt(0)
	s_barrier
	s_waitcnt lgkmcnt(0)
	v_mfma_f32_16x16x32_bf16 v[62:65], v[74:77], v[162:165], v[62:65]
	v_mfma_f32_16x16x32_bf16 v[58:61], v[90:93], v[162:165], v[58:61]
	v_mfma_f32_16x16x32_bf16 v[46:49], v[74:77], v[180:183], v[46:49]
	v_mfma_f32_16x16x32_bf16 v[42:45], v[90:93], v[180:183], v[42:45]
	v_mfma_f32_16x16x32_bf16 v[30:33], v[74:77], v[188:191], v[30:33]
	v_mfma_f32_16x16x32_bf16 v[26:29], v[90:93], v[188:191], v[26:29]
	v_mfma_f32_16x16x32_bf16 v[14:17], v[74:77], v[200:203], v[14:17]
	v_mfma_f32_16x16x32_bf16 v[10:13], v[90:93], v[200:203], v[10:13]
	v_mfma_f32_16x16x32_bf16 v[62:65], v[82:85], v[166:169], v[62:65]
	v_mfma_f32_16x16x32_bf16 v[58:61], v[94:97], v[166:169], v[58:61]
	v_mfma_f32_16x16x32_bf16 v[46:49], v[82:85], v[184:187], v[46:49]
	v_mfma_f32_16x16x32_bf16 v[42:45], v[94:97], v[184:187], v[42:45]
	v_mfma_f32_16x16x32_bf16 v[30:33], v[82:85], v[196:199], v[30:33]
	v_mfma_f32_16x16x32_bf16 v[26:29], v[94:97], v[196:199], v[26:29]
	v_mfma_f32_16x16x32_bf16 v[14:17], v[82:85], v[204:207], v[14:17]
	v_mfma_f32_16x16x32_bf16 v[10:13], v[94:97], v[204:207], v[10:13]
	v_mfma_f32_16x16x32_bf16 v[54:57], v[138:141], v[162:165], v[54:57]
	v_mfma_f32_16x16x32_bf16 v[50:53], v[154:157], v[162:165], v[50:53]
	v_mfma_f32_16x16x32_bf16 v[38:41], v[138:141], v[180:183], v[38:41]
	v_mfma_f32_16x16x32_bf16 v[34:37], v[154:157], v[180:183], v[34:37]
	v_mfma_f32_16x16x32_bf16 v[22:25], v[138:141], v[188:191], v[22:25]
	v_mfma_f32_16x16x32_bf16 v[18:21], v[154:157], v[188:191], v[18:21]
	v_mfma_f32_16x16x32_bf16 v[6:9], v[138:141], v[200:203], v[6:9]
	v_mfma_f32_16x16x32_bf16 v[2:5], v[154:157], v[200:203], v[2:5]
	v_mfma_f32_16x16x32_bf16 v[54:57], v[150:153], v[166:169], v[54:57]
	v_mfma_f32_16x16x32_bf16 v[50:53], v[158:161], v[166:169], v[50:53]
	v_mfma_f32_16x16x32_bf16 v[38:41], v[150:153], v[184:187], v[38:41]
	v_mfma_f32_16x16x32_bf16 v[34:37], v[158:161], v[184:187], v[34:37]
	s_barrier
	v_mfma_f32_16x16x32_bf16 v[22:25], v[150:153], v[196:199], v[22:25]
	v_mfma_f32_16x16x32_bf16 v[18:21], v[158:161], v[196:199], v[18:21]
	v_mfma_f32_16x16x32_bf16 v[6:9], v[150:153], v[204:207], v[6:9]
	v_mfma_f32_16x16x32_bf16 v[2:5], v[158:161], v[204:207], v[2:5]
	ds_read_b128 v[74:77], v194
	ds_read_b128 v[82:85], v194 offset:1024
	ds_read_b128 v[90:93], v194 offset:2048
	ds_read_b128 v[94:97], v194 offset:3072
	ds_read_b128 v[138:141], v195
	ds_read_b128 v[150:153], v195 offset:1024
	ds_read_b128 v[154:157], v195 offset:2048
	ds_read_b128 v[158:161], v195 offset:3072
	s_mov_b32 m0, s47
	v_lshl_add_u64 v[212:213], v[210:211], 0, s[34:35]
	ds_read_b128 v[162:165], v193 offset:32768
	ds_read_b128 v[166:169], v193 offset:33792
	ds_read_b128 v[180:183], v193 offset:34816
	ds_read_b128 v[184:187], v193 offset:35840
	ds_read_b128 v[188:191], v193 offset:36864
	ds_read_b128 v[196:199], v193 offset:37888
	ds_read_b128 v[200:203], v193 offset:38912
	ds_read_b128 v[204:207], v193 offset:39936
	global_load_lds_dwordx4 v[212:213], off
	v_lshl_add_u64 v[212:213], v[210:211], 0, s[36:37]
	s_mov_b32 m0, s52
	s_nop 0
	global_load_lds_dwordx4 v[212:213], off
	s_waitcnt vmcnt(8)
	s_waitcnt lgkmcnt(0)
	s_barrier
	s_waitcnt lgkmcnt(0)
	v_mfma_f32_16x16x32_bf16 v[146:149], v[74:77], v[162:165], v[146:149]
	v_mfma_f32_16x16x32_bf16 v[142:145], v[90:93], v[162:165], v[142:145]
	v_mfma_f32_16x16x32_bf16 v[126:129], v[74:77], v[180:183], v[126:129]
	v_mfma_f32_16x16x32_bf16 v[122:125], v[90:93], v[180:183], v[122:125]
	v_mfma_f32_16x16x32_bf16 v[110:113], v[74:77], v[188:191], v[110:113]
	v_mfma_f32_16x16x32_bf16 v[106:109], v[90:93], v[188:191], v[106:109]
	v_mfma_f32_16x16x32_bf16 v[86:89], v[74:77], v[200:203], v[86:89]
	v_mfma_f32_16x16x32_bf16 v[78:81], v[90:93], v[200:203], v[78:81]
	v_mfma_f32_16x16x32_bf16 v[146:149], v[82:85], v[166:169], v[146:149]
	v_mfma_f32_16x16x32_bf16 v[142:145], v[94:97], v[166:169], v[142:145]
	v_mfma_f32_16x16x32_bf16 v[126:129], v[82:85], v[184:187], v[126:129]
	v_mfma_f32_16x16x32_bf16 v[122:125], v[94:97], v[184:187], v[122:125]
	v_mfma_f32_16x16x32_bf16 v[110:113], v[82:85], v[196:199], v[110:113]
	v_mfma_f32_16x16x32_bf16 v[106:109], v[94:97], v[196:199], v[106:109]
	v_mfma_f32_16x16x32_bf16 v[86:89], v[82:85], v[204:207], v[86:89]
	v_mfma_f32_16x16x32_bf16 v[78:81], v[94:97], v[204:207], v[78:81]
	v_mfma_f32_16x16x32_bf16 v[134:137], v[138:141], v[162:165], v[134:137]
	v_mfma_f32_16x16x32_bf16 v[130:133], v[154:157], v[162:165], v[130:133]
	v_mfma_f32_16x16x32_bf16 v[118:121], v[138:141], v[180:183], v[118:121]
	v_mfma_f32_16x16x32_bf16 v[114:117], v[154:157], v[180:183], v[114:117]
	v_mfma_f32_16x16x32_bf16 v[102:105], v[138:141], v[188:191], v[102:105]
	v_mfma_f32_16x16x32_bf16 v[98:101], v[154:157], v[188:191], v[98:101]
	v_mfma_f32_16x16x32_bf16 v[70:73], v[138:141], v[200:203], v[70:73]
	v_mfma_f32_16x16x32_bf16 v[66:69], v[154:157], v[200:203], v[66:69]
	v_mfma_f32_16x16x32_bf16 v[134:137], v[150:153], v[166:169], v[134:137]
	v_mfma_f32_16x16x32_bf16 v[130:133], v[158:161], v[166:169], v[130:133]
	v_mfma_f32_16x16x32_bf16 v[118:121], v[150:153], v[184:187], v[118:121]
	v_mfma_f32_16x16x32_bf16 v[114:117], v[158:161], v[184:187], v[114:117]
	s_barrier
; #define PG8_WAIT_V(n) asm volatile("s_waitcnt vmcnt(" #n ")" ::: "memory")
; #define PG8_BAR __builtin_amdgcn_s_barrier()
; template <class Epi, class Sched, bool ALIGN_EPI = true, bool SP2 = true, bool FULLLINE = false, bool NOSTAGE = false, bool FP8 = false>
; __device__ __forceinline__ void gemm_phase(PG8_LAS unsigned char* lds, const Gemm g, const Sched& S, const Epi& E) {
;     ...
;         static_assert(SP2, "only the SP2 loop is kept");
;         { const int t = 0; if constexpr (Epi::NST == 16) PG8_ITER(PG8_WAIT_V(24)); else if constexpr (Epi::NST == 8) PG8_ITER(PG8_WAIT_V(16)); else PG8_ITER(PG8_WAIT_V(8)); }
;         for (int t = 2; t < nt; t += 2) PG8_ITER(PG8_WAIT_V(8));
;     ...
;         if constexpr (ALIGN_EPI) { if (wr == 0) PG8_BAR; }
	v_mfma_f32_16x16x32_bf16 v[102:105], v[150:153], v[196:199], v[102:105]
	v_mfma_f32_16x16x32_bf16 v[98:101], v[158:161], v[196:199], v[98:101]
	v_mfma_f32_16x16x32_bf16 v[70:73], v[150:153], v[204:207], v[70:73]
	v_mfma_f32_16x16x32_bf16 v[66:69], v[158:161], v[204:207], v[66:69]
	s_mov_b32 m0, s50
	v_lshl_add_u64 v[212:213], v[208:209], 0, s[38:39]
	ds_read_b128 v[162:165], v193 offset:49152
	ds_read_b128 v[166:169], v193 offset:50176
	ds_read_b128 v[180:183], v193 offset:51200
	ds_read_b128 v[184:187], v193 offset:52224
	ds_read_b128 v[188:191], v193 offset:53248
	ds_read_b128 v[196:199], v193 offset:54272
	ds_read_b128 v[200:203], v193 offset:55296
	ds_read_b128 v[204:207], v193 offset:56320
	global_load_lds_dwordx4 v[212:213], off
	v_lshl_add_u64 v[212:213], v[208:209], 0, s[66:67]
	s_mov_b32 m0, s51
	s_nop 0
	global_load_lds_dwordx4 v[212:213], off
	v_lshl_add_u64 v[212:213], v[208:209], 0, s[14:15]
	s_mov_b32 m0, s33
	v_lshl_add_u64 v[208:209], v[208:209], 0, s[16:17]
	global_load_lds_dwordx4 v[212:213], off
	s_mov_b32 m0, s56
	s_nop 0
	global_load_lds_dwordx4 v[208:209], off
	v_lshl_add_u64 v[208:209], v[210:211], 0, s[38:39]
	s_mov_b32 m0, s53
	s_nop 0
	global_load_lds_dwordx4 v[208:209], off
	v_lshl_add_u64 v[208:209], v[210:211], 0, s[66:67]
	s_mov_b32 m0, s54
	s_nop 0
	global_load_lds_dwordx4 v[208:209], off
	s_waitcnt vmcnt(8)
	s_waitcnt lgkmcnt(0)
	s_barrier
	s_waitcnt lgkmcnt(0)
	v_mfma_f32_16x16x32_bf16 v[62:65], v[74:77], v[162:165], v[62:65]
	v_mfma_f32_16x16x32_bf16 v[58:61], v[90:93], v[162:165], v[58:61]
	v_mfma_f32_16x16x32_bf16 v[46:49], v[74:77], v[180:183], v[46:49]
	v_mfma_f32_16x16x32_bf16 v[42:45], v[90:93], v[180:183], v[42:45]
	v_mfma_f32_16x16x32_bf16 v[30:33], v[74:77], v[188:191], v[30:33]
	v_mfma_f32_16x16x32_bf16 v[26:29], v[90:93], v[188:191], v[26:29]
	v_mfma_f32_16x16x32_bf16 v[14:17], v[74:77], v[200:203], v[14:17]
	v_mfma_f32_16x16x32_bf16 v[10:13], v[90:93], v[200:203], v[10:13]
	v_mfma_f32_16x16x32_bf16 v[62:65], v[82:85], v[166:169], v[62:65]
	v_mfma_f32_16x16x32_bf16 v[58:61], v[94:97], v[166:169], v[58:61]
	v_mfma_f32_16x16x32_bf16 v[46:49], v[82:85], v[184:187], v[46:49]
	v_mfma_f32_16x16x32_bf16 v[42:45], v[94:97], v[184:187], v[42:45]
	v_mfma_f32_16x16x32_bf16 v[30:33], v[82:85], v[196:199], v[30:33]
	v_mfma_f32_16x16x32_bf16 v[26:29], v[94:97], v[196:199], v[26:29]
	v_mfma_f32_16x16x32_bf16 v[14:17], v[82:85], v[204:207], v[14:17]
	v_mfma_f32_16x16x32_bf16 v[10:13], v[94:97], v[204:207], v[10:13]
	v_mfma_f32_16x16x32_bf16 v[54:57], v[138:141], v[162:165], v[54:57]
	v_mfma_f32_16x16x32_bf16 v[50:53], v[154:157], v[162:165], v[50:53]
	v_mfma_f32_16x16x32_bf16 v[38:41], v[138:141], v[180:183], v[38:41]
	v_mfma_f32_16x16x32_bf16 v[34:37], v[154:157], v[180:183], v[34:37]
	v_mfma_f32_16x16x32_bf16 v[22:25], v[138:141], v[188:191], v[22:25]
	v_mfma_f32_16x16x32_bf16 v[18:21], v[154:157], v[188:191], v[18:21]
	v_mfma_f32_16x16x32_bf16 v[6:9], v[138:141], v[200:203], v[6:9]
	v_mfma_f32_16x16x32_bf16 v[2:5], v[154:157], v[200:203], v[2:5]
	v_mfma_f32_16x16x32_bf16 v[54:57], v[150:153], v[166:169], v[54:57]
	v_mfma_f32_16x16x32_bf16 v[50:53], v[158:161], v[166:169], v[50:53]
	v_mfma_f32_16x16x32_bf16 v[38:41], v[150:153], v[184:187], v[38:41]
	v_mfma_f32_16x16x32_bf16 v[34:37], v[158:161], v[184:187], v[34:37]
	s_barrier
	v_mfma_f32_16x16x32_bf16 v[22:25], v[150:153], v[196:199], v[22:25]
	v_mfma_f32_16x16x32_bf16 v[18:21], v[158:161], v[196:199], v[18:21]
	v_mfma_f32_16x16x32_bf16 v[6:9], v[150:153], v[204:207], v[6:9]
	v_mfma_f32_16x16x32_bf16 v[2:5], v[158:161], v[204:207], v[2:5]
	s_add_i32 s73, s73, 2
	s_add_u32 s70, s70, 0x100
	s_addc_u32 s71, s71, 0
	s_add_u32 s57, s57, 0x100
	s_addc_u32 s72, s72, 0
	s_cmpk_gt_u32 s73, 0x55
	s_cbranch_scc0 .LBB0_1484
	s_and_b64 vcc, exec, s[12:13]
	s_cbranch_vccz .LBB0_1487
	s_barrier

; template <class Epi, class Sched, bool ALIGN_EPI = true, bool SP2 = true, bool FULLLINE = false, bool NOSTAGE = false, bool FP8 = false>
; __device__ __forceinline__ void gemm_phase(PG8_LAS unsigned char* lds, const Gemm g, const Sched& S, const Epi& E) {
;     ...
;         const bool has_next = S.next(ui + 1, nxt);
;         const char* nA = has_next ? PG8_ABASE(nxt) : cA; const char* nB = has_next ? PG8_BBASE(nxt) : cB;
.LBB0_1645:
	s_ashr_i32 s71, s70, 31
	s_lshl_b64 s[0:1], s[70:71], 20
	s_add_u32 s72, s58, s0
	ds_read_b128 v[2:5], v144
	ds_read_b128 v[6:9], v144 offset:1024
	ds_read_b128 v[10:13], v144 offset:2048
	ds_read_b128 v[14:17], v144 offset:3072
	ds_read_b128 v[18:21], v145
	ds_read_b128 v[22:25], v145 offset:1024
	ds_read_b128 v[26:29], v145 offset:2048
	ds_read_b128 v[30:33], v145 offset:3072
	s_addc_u32 s73, s59, s1
	s_ashr_i32 s69, s68, 31
	s_lshl_b64 s[0:1], s[68:69], 20
	s_add_u32 s74, s44, s0
	s_addc_u32 s75, s45, s1
	s_and_b64 s[0:1], s[8:9], exec
	s_cselect_b32 s11, s73, s79
	s_cselect_b32 s14, s72, s78
	s_cselect_b32 s69, s75, s77
	s_cselect_b32 s71, s74, s76
	v_lshl_add_u64 v[242:243], s[78:79], 0, v[130:131]
	s_mov_b32 m0, s97
	v_lshl_add_u64 v[66:67], v[242:243], 0, s[16:17]
	ds_read_b128 v[34:37], v146
	ds_read_b128 v[38:41], v146 offset:1024
	ds_read_b128 v[42:45], v146 offset:2048
	ds_read_b128 v[46:49], v146 offset:3072
	ds_read_b128 v[50:53], v146 offset:4096
	ds_read_b128 v[54:57], v146 offset:5120
	ds_read_b128 v[58:61], v146 offset:6144
	ds_read_b128 v[62:65], v146 offset:7168
	global_load_lds_dwordx4 v[66:67], off
	v_lshl_add_u64 v[66:67], v[242:243], 0, s[18:19]
	s_mov_b32 m0, s47
	s_nop 0
	global_load_lds_dwordx4 v[66:67], off
	s_waitcnt vmcnt(24)
	s_waitcnt lgkmcnt(0)
	s_barrier
	s_waitcnt lgkmcnt(0)
	v_mfma_f32_16x16x32_bf16 v[90:93], v[2:5], v[58:61], 0
	v_mfma_f32_16x16x32_bf16 v[66:69], v[2:5], v[34:37], 0
	v_mfma_f32_16x16x32_bf16 v[70:73], v[10:13], v[34:37], 0
	v_mfma_f32_16x16x32_bf16 v[74:77], v[2:5], v[42:45], 0
	v_mfma_f32_16x16x32_bf16 v[78:81], v[10:13], v[42:45], 0
	v_mfma_f32_16x16x32_bf16 v[82:85], v[2:5], v[50:53], 0
	v_mfma_f32_16x16x32_bf16 v[86:89], v[10:13], v[50:53], 0
	v_mfma_f32_16x16x32_bf16 v[98:101], v[6:9], v[62:65], v[90:93]
	v_mfma_f32_16x16x32_bf16 v[90:93], v[10:13], v[58:61], 0
	v_mfma_f32_16x16x32_bf16 v[66:69], v[6:9], v[38:41], v[66:69]
	v_mfma_f32_16x16x32_bf16 v[70:73], v[14:17], v[38:41], v[70:73]
	v_mfma_f32_16x16x32_bf16 v[74:77], v[6:9], v[46:49], v[74:77]
	v_mfma_f32_16x16x32_bf16 v[78:81], v[14:17], v[46:49], v[78:81]
	v_mfma_f32_16x16x32_bf16 v[82:85], v[6:9], v[54:57], v[82:85]
	v_mfma_f32_16x16x32_bf16 v[86:89], v[14:17], v[54:57], v[86:89]
	v_mfma_f32_16x16x32_bf16 v[102:105], v[14:17], v[62:65], v[90:93]
	v_mfma_f32_16x16x32_bf16 v[90:93], v[18:21], v[34:37], 0
	v_mfma_f32_16x16x32_bf16 v[34:37], v[26:29], v[34:37], 0
	v_mfma_f32_16x16x32_bf16 v[114:117], v[22:25], v[38:41], v[90:93]
	v_mfma_f32_16x16x32_bf16 v[34:37], v[30:33], v[38:41], v[34:37]
	v_mfma_f32_16x16x32_bf16 v[38:41], v[18:21], v[42:45], 0
	v_mfma_f32_16x16x32_bf16 v[42:45], v[26:29], v[42:45], 0
	v_mfma_f32_16x16x32_bf16 v[38:41], v[22:25], v[46:49], v[38:41]
	v_mfma_f32_16x16x32_bf16 v[42:45], v[30:33], v[46:49], v[42:45]
	v_mfma_f32_16x16x32_bf16 v[46:49], v[18:21], v[50:53], 0
	v_mfma_f32_16x16x32_bf16 v[50:53], v[26:29], v[50:53], 0
	v_mfma_f32_16x16x32_bf16 v[46:49], v[22:25], v[54:57], v[46:49]
	v_mfma_f32_16x16x32_bf16 v[50:53], v[30:33], v[54:57], v[50:53]
	s_barrier
	v_mfma_f32_16x16x32_bf16 v[54:57], v[18:21], v[58:61], 0
	v_mfma_f32_16x16x32_bf16 v[58:61], v[26:29], v[58:61], 0
	v_mfma_f32_16x16x32_bf16 v[54:57], v[22:25], v[62:65], v[54:57]
	v_mfma_f32_16x16x32_bf16 v[58:61], v[30:33], v[62:65], v[58:61]
	v_lshl_add_u64 v[244:245], s[76:77], 0, v[132:133]
	s_add_i32 s81, s95, s46
	v_lshl_add_u64 v[140:141], v[244:245], 0, s[20:21]
	s_mov_b32 m0, s81
	s_add_i32 s82, s81, 0x2000
	ds_read_b128 v[62:65], v146 offset:16384
	ds_read_b128 v[90:93], v146 offset:17408
	ds_read_b128 v[94:97], v146 offset:18432
	ds_read_b128 v[106:109], v146 offset:19456
	ds_read_b128 v[110:113], v146 offset:20480
	ds_read_b128 v[118:121], v146 offset:21504
	ds_read_b128 v[122:125], v146 offset:22528
	ds_read_b128 v[126:129], v146 offset:23552
	global_load_lds_dwordx4 v[140:141], off
	v_lshl_add_u64 v[140:141], v[244:245], 0, s[22:23]
	s_mov_b32 m0, s82
	s_add_i32 s83, s96, s46
	global_load_lds_dwordx4 v[140:141], off
	v_lshl_add_u64 v[140:141], v[244:245], 0, s[24:25]
	s_mov_b32 m0, s83
	s_add_i32 s84, s83, 0x2000
	global_load_lds_dwordx4 v[140:141], off
	v_lshl_add_u64 v[140:141], v[244:245], 0, s[26:27]
	s_mov_b32 m0, s84
	s_nop 0
	global_load_lds_dwordx4 v[140:141], off
	v_lshl_add_u64 v[140:141], v[242:243], 0, s[20:21]
	s_mov_b32 m0, s87
	s_nop 0
	global_load_lds_dwordx4 v[140:141], off
	v_lshl_add_u64 v[140:141], v[242:243], 0, s[22:23]
	s_mov_b32 m0, s52
	s_nop 0
	global_load_lds_dwordx4 v[140:141], off
	s_waitcnt vmcnt(24)
	s_waitcnt lgkmcnt(0)
	s_barrier
	s_waitcnt lgkmcnt(0)
	v_mfma_f32_16x16x32_bf16 v[140:143], v[2:5], v[62:65], 0
	v_mfma_f32_16x16x32_bf16 v[154:157], v[2:5], v[94:97], 0
	v_mfma_f32_16x16x32_bf16 v[162:165], v[2:5], v[110:113], 0
	v_mfma_f32_16x16x32_bf16 v[2:5], v[2:5], v[122:125], 0
	v_mfma_f32_16x16x32_bf16 v[140:143], v[6:9], v[90:93], v[140:143]
	v_mfma_f32_16x16x32_bf16 v[154:157], v[6:9], v[106:109], v[154:157]
	v_mfma_f32_16x16x32_bf16 v[162:165], v[6:9], v[118:121], v[162:165]
	v_mfma_f32_16x16x32_bf16 v[2:5], v[6:9], v[126:129], v[2:5]
	v_mfma_f32_16x16x32_bf16 v[6:9], v[10:13], v[122:125], 0
	v_mfma_f32_16x16x32_bf16 v[150:153], v[10:13], v[62:65], 0
	v_mfma_f32_16x16x32_bf16 v[158:161], v[10:13], v[94:97], 0
	v_mfma_f32_16x16x32_bf16 v[166:169], v[10:13], v[110:113], 0
	v_mfma_f32_16x16x32_bf16 v[6:9], v[14:17], v[126:129], v[6:9]
	v_mfma_f32_16x16x32_bf16 v[150:153], v[14:17], v[90:93], v[150:153]
	v_mfma_f32_16x16x32_bf16 v[158:161], v[14:17], v[106:109], v[158:161]
	v_mfma_f32_16x16x32_bf16 v[166:169], v[14:17], v[118:121], v[166:169]
	v_mfma_f32_16x16x32_bf16 v[10:13], v[18:21], v[62:65], 0
	v_mfma_f32_16x16x32_bf16 v[170:173], v[22:25], v[90:93], v[10:13]
	v_mfma_f32_16x16x32_bf16 v[10:13], v[26:29], v[62:65], 0
	v_mfma_f32_16x16x32_bf16 v[174:177], v[30:33], v[90:93], v[10:13]
	v_mfma_f32_16x16x32_bf16 v[10:13], v[18:21], v[94:97], 0
	v_mfma_f32_16x16x32_bf16 v[178:181], v[22:25], v[106:109], v[10:13]
	v_mfma_f32_16x16x32_bf16 v[10:13], v[26:29], v[94:97], 0
	v_mfma_f32_16x16x32_bf16 v[182:185], v[30:33], v[106:109], v[10:13]
	v_mfma_f32_16x16x32_bf16 v[10:13], v[18:21], v[110:113], 0
	v_mfma_f32_16x16x32_bf16 v[186:189], v[22:25], v[118:121], v[10:13]
	v_mfma_f32_16x16x32_bf16 v[10:13], v[26:29], v[110:113], 0
	v_mfma_f32_16x16x32_bf16 v[190:193], v[30:33], v[118:121], v[10:13]
	s_barrier
	v_mfma_f32_16x16x32_bf16 v[10:13], v[18:21], v[122:125], 0
	v_mfma_f32_16x16x32_bf16 v[194:197], v[22:25], v[126:129], v[10:13]
	v_mfma_f32_16x16x32_bf16 v[10:13], v[26:29], v[122:125], 0
	v_mfma_f32_16x16x32_bf16 v[198:201], v[30:33], v[126:129], v[10:13]
	s_nop 5
	ds_read_b128 v[10:13], v147
	ds_read_b128 v[14:17], v147 offset:1024
	ds_read_b128 v[18:21], v147 offset:2048
	ds_read_b128 v[22:25], v147 offset:3072
	ds_read_b128 v[202:205], v148
	ds_read_b128 v[206:209], v148 offset:1024
	ds_read_b128 v[210:213], v148 offset:2048
	ds_read_b128 v[214:217], v148 offset:3072
	s_mov_b32 m0, s53
	v_lshl_add_u64 v[90:91], v[242:243], 0, s[24:25]
	ds_read_b128 v[26:29], v146 offset:32768
	ds_read_b128 v[30:33], v146 offset:33792
	ds_read_b128 v[62:65], v146 offset:34816
	ds_read_b128 v[218:221], v146 offset:35840
	ds_read_b128 v[222:225], v146 offset:36864
	ds_read_b128 v[226:229], v146 offset:37888
	ds_read_b128 v[230:233], v146 offset:38912
	ds_read_b128 v[234:237], v146 offset:39936
	global_load_lds_dwordx4 v[90:91], off
	v_lshl_add_u64 v[90:91], v[242:243], 0, s[26:27]
	s_mov_b32 m0, s54
	s_nop 0
	global_load_lds_dwordx4 v[90:91], off
	s_waitcnt vmcnt(8)
	s_waitcnt lgkmcnt(0)
	s_barrier
	s_waitcnt lgkmcnt(0)
	v_mfma_f32_16x16x32_bf16 v[66:69], v[10:13], v[26:29], v[66:69]
	v_mfma_f32_16x16x32_bf16 v[126:129], v[14:17], v[30:33], v[66:69]
	v_mfma_f32_16x16x32_bf16 v[66:69], v[18:21], v[26:29], v[70:73]
	v_mfma_f32_16x16x32_bf16 v[122:125], v[22:25], v[30:33], v[66:69]
	v_mfma_f32_16x16x32_bf16 v[66:69], v[10:13], v[62:65], v[74:77]
	v_mfma_f32_16x16x32_bf16 v[110:113], v[14:17], v[218:221], v[66:69]
	v_mfma_f32_16x16x32_bf16 v[66:69], v[18:21], v[62:65], v[78:81]
	v_mfma_f32_16x16x32_bf16 v[106:109], v[22:25], v[218:221], v[66:69]
	v_mfma_f32_16x16x32_bf16 v[66:69], v[10:13], v[222:225], v[82:85]
	v_mfma_f32_16x16x32_bf16 v[94:97], v[14:17], v[226:229], v[66:69]
	v_mfma_f32_16x16x32_bf16 v[66:69], v[18:21], v[222:225], v[86:89]
	v_mfma_f32_16x16x32_bf16 v[90:93], v[22:25], v[226:229], v[66:69]
	v_mfma_f32_16x16x32_bf16 v[66:69], v[10:13], v[230:233], v[98:101]
	v_mfma_f32_16x16x32_bf16 v[78:81], v[14:17], v[234:237], v[66:69]
	v_mfma_f32_16x16x32_bf16 v[66:69], v[18:21], v[230:233], v[102:105]
	v_mfma_f32_16x16x32_bf16 v[74:77], v[22:25], v[234:237], v[66:69]
	v_mfma_f32_16x16x32_bf16 v[66:69], v[202:205], v[26:29], v[114:117]
	v_mfma_f32_16x16x32_bf16 v[26:29], v[210:213], v[26:29], v[34:37]
	v_mfma_f32_16x16x32_bf16 v[114:117], v[214:217], v[30:33], v[26:29]
	v_mfma_f32_16x16x32_bf16 v[26:29], v[202:205], v[62:65], v[38:41]
	v_mfma_f32_16x16x32_bf16 v[102:105], v[206:209], v[218:221], v[26:29]
	v_mfma_f32_16x16x32_bf16 v[26:29], v[210:213], v[62:65], v[42:45]
	v_mfma_f32_16x16x32_bf16 v[98:101], v[214:217], v[218:221], v[26:29]
	v_mfma_f32_16x16x32_bf16 v[26:29], v[202:205], v[222:225], v[46:49]
	v_mfma_f32_16x16x32_bf16 v[86:89], v[206:209], v[226:229], v[26:29]
	v_mfma_f32_16x16x32_bf16 v[26:29], v[210:213], v[222:225], v[50:53]
	v_mfma_f32_16x16x32_bf16 v[82:85], v[214:217], v[226:229], v[26:29]
	v_mfma_f32_16x16x32_bf16 v[26:29], v[202:205], v[230:233], v[54:57]
	s_barrier
	v_mfma_f32_16x16x32_bf16 v[70:73], v[206:209], v[234:237], v[26:29]
	v_mfma_f32_16x16x32_bf16 v[26:29], v[210:213], v[230:233], v[58:61]
	v_mfma_f32_16x16x32_bf16 v[118:121], v[206:209], v[30:33], v[66:69]
	v_mfma_f32_16x16x32_bf16 v[66:69], v[214:217], v[234:237], v[26:29]
	s_add_i32 s50, s3, s46
	s_nop 3
	v_lshl_add_u64 v[26:27], v[244:245], 0, s[28:29]
	s_mov_b32 m0, s50
	s_add_i32 s51, s50, 0x2000
	ds_read_b128 v[34:37], v146 offset:49152
	ds_read_b128 v[38:41], v146 offset:50176
	ds_read_b128 v[218:221], v146 offset:51200
	ds_read_b128 v[222:225], v146 offset:52224
	ds_read_b128 v[226:229], v146 offset:53248
	ds_read_b128 v[230:233], v146 offset:54272
	ds_read_b128 v[234:237], v146 offset:55296
	ds_read_b128 v[238:241], v146 offset:56320
	global_load_lds_dwordx4 v[26:27], off
	v_lshl_add_u64 v[26:27], v[244:245], 0, s[30:31]
	s_mov_b32 m0, s51
	s_mov_b64 s[0:1], 0x80180
	s_add_i32 s33, s42, s46
	global_load_lds_dwordx4 v[26:27], off
	v_lshl_add_u64 v[26:27], v[244:245], 0, s[0:1]
	s_mov_b32 m0, s33
	s_mov_b64 s[0:1], 0xc0180
	s_add_i32 s56, s33, 0x2000
	global_load_lds_dwordx4 v[26:27], off
	v_lshl_add_u64 v[26:27], v[244:245], 0, s[0:1]
	s_mov_b32 m0, s56
	s_nop 0
	global_load_lds_dwordx4 v[26:27], off
	v_lshl_add_u64 v[26:27], v[242:243], 0, s[28:29]
	s_mov_b32 m0, s55
	s_nop 0
	global_load_lds_dwordx4 v[26:27], off
	v_lshl_add_u64 v[26:27], v[242:243], 0, s[30:31]
	s_mov_b32 m0, s62
	s_nop 0
	global_load_lds_dwordx4 v[26:27], off
	s_waitcnt vmcnt(8)
	s_waitcnt lgkmcnt(0)
	s_barrier
	s_waitcnt lgkmcnt(0)
	v_mfma_f32_16x16x32_bf16 v[26:29], v[10:13], v[34:37], v[140:143]
	v_mfma_f32_16x16x32_bf16 v[62:65], v[14:17], v[38:41], v[26:29]
	v_mfma_f32_16x16x32_bf16 v[26:29], v[18:21], v[34:37], v[150:153]
	v_mfma_f32_16x16x32_bf16 v[58:61], v[22:25], v[38:41], v[26:29]
	v_mfma_f32_16x16x32_bf16 v[26:29], v[10:13], v[218:221], v[154:157]
	v_mfma_f32_16x16x32_bf16 v[46:49], v[14:17], v[222:225], v[26:29]
	v_mfma_f32_16x16x32_bf16 v[26:29], v[18:21], v[218:221], v[158:161]
	v_mfma_f32_16x16x32_bf16 v[42:45], v[22:25], v[222:225], v[26:29]
	v_mfma_f32_16x16x32_bf16 v[26:29], v[10:13], v[226:229], v[162:165]
	v_mfma_f32_16x16x32_bf16 v[2:5], v[10:13], v[234:237], v[2:5]
	v_mfma_f32_16x16x32_bf16 v[30:33], v[14:17], v[230:233], v[26:29]
	v_mfma_f32_16x16x32_bf16 v[26:29], v[18:21], v[226:229], v[166:169]
	v_mfma_f32_16x16x32_bf16 v[14:17], v[14:17], v[238:241], v[2:5]
	v_mfma_f32_16x16x32_bf16 v[2:5], v[18:21], v[234:237], v[6:9]
	v_mfma_f32_16x16x32_bf16 v[26:29], v[22:25], v[230:233], v[26:29]
	v_mfma_f32_16x16x32_bf16 v[10:13], v[22:25], v[238:241], v[2:5]
	v_mfma_f32_16x16x32_bf16 v[2:5], v[202:205], v[34:37], v[170:173]
	v_mfma_f32_16x16x32_bf16 v[54:57], v[206:209], v[38:41], v[2:5]
	v_mfma_f32_16x16x32_bf16 v[2:5], v[210:213], v[34:37], v[174:177]
	v_mfma_f32_16x16x32_bf16 v[50:53], v[214:217], v[38:41], v[2:5]
	v_mfma_f32_16x16x32_bf16 v[2:5], v[202:205], v[218:221], v[178:181]
	v_mfma_f32_16x16x32_bf16 v[38:41], v[206:209], v[222:225], v[2:5]
	v_mfma_f32_16x16x32_bf16 v[2:5], v[210:213], v[218:221], v[182:185]
	v_mfma_f32_16x16x32_bf16 v[34:37], v[214:217], v[222:225], v[2:5]
	v_mfma_f32_16x16x32_bf16 v[2:5], v[202:205], v[226:229], v[186:189]
	v_mfma_f32_16x16x32_bf16 v[22:25], v[206:209], v[230:233], v[2:5]
	v_mfma_f32_16x16x32_bf16 v[2:5], v[210:213], v[226:229], v[190:193]
	v_mfma_f32_16x16x32_bf16 v[18:21], v[214:217], v[230:233], v[2:5]
	s_barrier
	v_mfma_f32_16x16x32_bf16 v[2:5], v[202:205], v[234:237], v[194:197]
	v_mfma_f32_16x16x32_bf16 v[6:9], v[206:209], v[238:241], v[2:5]
	v_mfma_f32_16x16x32_bf16 v[2:5], v[210:213], v[234:237], v[198:201]
	v_mfma_f32_16x16x32_bf16 v[2:5], v[214:217], v[238:241], v[2:5]
	s_add_u32 s78, s78, 0x80180
	s_addc_u32 s79, s79, 0
	s_add_u32 s57, s76, 0x200
	s_addc_u32 s76, s77, 0
	s_mov_b32 s77, 0
; #define PG8_WAIT_V(n) asm volatile("s_waitcnt vmcnt(" #n ")" ::: "memory")
; template <class Epi, class Sched, bool ALIGN_EPI = true, bool SP2 = true, bool FULLLINE = false, bool NOSTAGE = false, bool FP8 = false>
; __device__ __forceinline__ void gemm_phase(PG8_LAS unsigned char* lds, const Gemm g, const Sched& S, const Epi& E) {
;     ...
;         for (int t = 2; t < nt; t += 2) PG8_ITER(PG8_WAIT_V(8));
.LBB0_1646:
	ds_read_b128 v[140:143], v144
	ds_read_b128 v[150:153], v144 offset:1024
	ds_read_b128 v[154:157], v144 offset:2048
	ds_read_b128 v[158:161], v144 offset:3072
	ds_read_b128 v[162:165], v145
	ds_read_b128 v[166:169], v145 offset:1024
	ds_read_b128 v[170:173], v145 offset:2048
	ds_read_b128 v[174:177], v145 offset:3072
	s_add_u32 s0, s78, 0xfff80080
	s_addc_u32 s1, s79, -1
	s_cmp_eq_u32 s77, 28
	s_cselect_b32 s1, s11, s1
	s_cselect_b32 s0, s14, s0
	s_cselect_b32 s65, s69, s76
	s_cselect_b32 s64, s71, s57
	s_mov_b32 m0, s97
	v_lshl_add_u64 v[210:211], s[78:79], 0, v[134:135]
	ds_read_b128 v[178:181], v146
	ds_read_b128 v[182:185], v146 offset:1024
	ds_read_b128 v[186:189], v146 offset:2048
	ds_read_b128 v[190:193], v146 offset:3072
	ds_read_b128 v[194:197], v146 offset:4096
	ds_read_b128 v[198:201], v146 offset:5120
	ds_read_b128 v[202:205], v146 offset:6144
	ds_read_b128 v[206:209], v146 offset:7168
	global_load_lds_dwordx4 v[210:211], off
	v_lshl_add_u64 v[210:211], v[210:211], 0, s[34:35]
	s_mov_b32 m0, s47
	s_nop 0
	global_load_lds_dwordx4 v[210:211], off
	s_waitcnt vmcnt(8)
	s_waitcnt lgkmcnt(0)
	s_barrier
	s_waitcnt lgkmcnt(0)
	v_mfma_f32_16x16x32_bf16 v[126:129], v[140:143], v[178:181], v[126:129]
	v_mfma_f32_16x16x32_bf16 v[122:125], v[154:157], v[178:181], v[122:125]
	v_mfma_f32_16x16x32_bf16 v[110:113], v[140:143], v[186:189], v[110:113]
	v_mfma_f32_16x16x32_bf16 v[106:109], v[154:157], v[186:189], v[106:109]
	v_mfma_f32_16x16x32_bf16 v[94:97], v[140:143], v[194:197], v[94:97]
	v_mfma_f32_16x16x32_bf16 v[90:93], v[154:157], v[194:197], v[90:93]
	v_mfma_f32_16x16x32_bf16 v[78:81], v[140:143], v[202:205], v[78:81]
	v_mfma_f32_16x16x32_bf16 v[74:77], v[154:157], v[202:205], v[74:77]
	v_mfma_f32_16x16x32_bf16 v[126:129], v[150:153], v[182:185], v[126:129]
	v_mfma_f32_16x16x32_bf16 v[122:125], v[158:161], v[182:185], v[122:125]
	v_mfma_f32_16x16x32_bf16 v[110:113], v[150:153], v[190:193], v[110:113]
	v_mfma_f32_16x16x32_bf16 v[106:109], v[158:161], v[190:193], v[106:109]
	v_mfma_f32_16x16x32_bf16 v[94:97], v[150:153], v[198:201], v[94:97]
	v_mfma_f32_16x16x32_bf16 v[90:93], v[158:161], v[198:201], v[90:93]
	v_mfma_f32_16x16x32_bf16 v[78:81], v[150:153], v[206:209], v[78:81]
	v_mfma_f32_16x16x32_bf16 v[74:77], v[158:161], v[206:209], v[74:77]
	v_mfma_f32_16x16x32_bf16 v[118:121], v[162:165], v[178:181], v[118:121]
	v_mfma_f32_16x16x32_bf16 v[114:117], v[170:173], v[178:181], v[114:117]
	v_mfma_f32_16x16x32_bf16 v[102:105], v[162:165], v[186:189], v[102:105]
	v_mfma_f32_16x16x32_bf16 v[98:101], v[170:173], v[186:189], v[98:101]
	v_mfma_f32_16x16x32_bf16 v[86:89], v[162:165], v[194:197], v[86:89]
	v_mfma_f32_16x16x32_bf16 v[82:85], v[170:173], v[194:197], v[82:85]
	v_mfma_f32_16x16x32_bf16 v[70:73], v[162:165], v[202:205], v[70:73]
	v_mfma_f32_16x16x32_bf16 v[66:69], v[170:173], v[202:205], v[66:69]
	v_mfma_f32_16x16x32_bf16 v[118:121], v[166:169], v[182:185], v[118:121]
	v_mfma_f32_16x16x32_bf16 v[114:117], v[174:177], v[182:185], v[114:117]
	v_mfma_f32_16x16x32_bf16 v[102:105], v[166:169], v[190:193], v[102:105]
	v_mfma_f32_16x16x32_bf16 v[98:101], v[174:177], v[190:193], v[98:101]
	s_barrier
	v_mfma_f32_16x16x32_bf16 v[86:89], v[166:169], v[198:201], v[86:89]
	v_mfma_f32_16x16x32_bf16 v[82:85], v[174:177], v[198:201], v[82:85]
	v_mfma_f32_16x16x32_bf16 v[70:73], v[166:169], v[206:209], v[70:73]
	v_mfma_f32_16x16x32_bf16 v[66:69], v[174:177], v[206:209], v[66:69]
	s_mov_b32 m0, s81
	v_lshl_add_u64 v[210:211], s[64:65], 0, v[132:133]
	ds_read_b128 v[178:181], v146 offset:16384
	ds_read_b128 v[182:185], v146 offset:17408
	ds_read_b128 v[186:189], v146 offset:18432
	ds_read_b128 v[190:193], v146 offset:19456
	ds_read_b128 v[194:197], v146 offset:20480
	ds_read_b128 v[198:201], v146 offset:21504
	ds_read_b128 v[202:205], v146 offset:22528
	ds_read_b128 v[206:209], v146 offset:23552
	global_load_lds_dwordx4 v[210:211], off
	v_lshl_add_u64 v[212:213], v[210:211], 0, s[34:35]
	s_mov_b32 m0, s82
	s_nop 0
	global_load_lds_dwordx4 v[212:213], off
	v_lshl_add_u64 v[212:213], v[210:211], 0, s[36:37]
	s_mov_b32 m0, s83
	s_nop 0
	global_load_lds_dwordx4 v[212:213], off
	v_lshl_add_u64 v[212:213], v[210:211], 0, s[38:39]
	s_mov_b32 m0, s84
	s_nop 0
	global_load_lds_dwordx4 v[212:213], off
	v_lshl_add_u64 v[212:213], s[0:1], 0, v[130:131]
	s_mov_b32 m0, s87
	v_lshl_add_u64 v[214:215], v[212:213], 0, s[34:35]
	global_load_lds_dwordx4 v[212:213], off
	s_mov_b32 m0, s52
	s_nop 0
	global_load_lds_dwordx4 v[214:215], off
	s_waitcnt vmcnt(8)
	s_waitcnt lgkmcnt(0)
	s_barrier
	s_waitcnt lgkmcnt(0)
	v_mfma_f32_16x16x32_bf16 v[62:65], v[140:143], v[178:181], v[62:65]
	v_mfma_f32_16x16x32_bf16 v[58:61], v[154:157], v[178:181], v[58:61]
	v_mfma_f32_16x16x32_bf16 v[46:49], v[140:143], v[186:189], v[46:49]
	v_mfma_f32_16x16x32_bf16 v[42:45], v[154:157], v[186:189], v[42:45]
	v_mfma_f32_16x16x32_bf16 v[30:33], v[140:143], v[194:197], v[30:33]
	v_mfma_f32_16x16x32_bf16 v[26:29], v[154:157], v[194:197], v[26:29]
	v_mfma_f32_16x16x32_bf16 v[14:17], v[140:143], v[202:205], v[14:17]
	v_mfma_f32_16x16x32_bf16 v[10:13], v[154:157], v[202:205], v[10:13]
	v_mfma_f32_16x16x32_bf16 v[62:65], v[150:153], v[182:185], v[62:65]
	v_mfma_f32_16x16x32_bf16 v[58:61], v[158:161], v[182:185], v[58:61]
	v_mfma_f32_16x16x32_bf16 v[46:49], v[150:153], v[190:193], v[46:49]
	v_mfma_f32_16x16x32_bf16 v[42:45], v[158:161], v[190:193], v[42:45]
	v_mfma_f32_16x16x32_bf16 v[30:33], v[150:153], v[198:201], v[30:33]
	v_mfma_f32_16x16x32_bf16 v[26:29], v[158:161], v[198:201], v[26:29]
	v_mfma_f32_16x16x32_bf16 v[14:17], v[150:153], v[206:209], v[14:17]
	v_mfma_f32_16x16x32_bf16 v[10:13], v[158:161], v[206:209], v[10:13]
	v_mfma_f32_16x16x32_bf16 v[54:57], v[162:165], v[178:181], v[54:57]
	v_mfma_f32_16x16x32_bf16 v[50:53], v[170:173], v[178:181], v[50:53]
	v_mfma_f32_16x16x32_bf16 v[38:41], v[162:165], v[186:189], v[38:41]
	v_mfma_f32_16x16x32_bf16 v[34:37], v[170:173], v[186:189], v[34:37]
	v_mfma_f32_16x16x32_bf16 v[22:25], v[162:165], v[194:197], v[22:25]
	v_mfma_f32_16x16x32_bf16 v[18:21], v[170:173], v[194:197], v[18:21]
	v_mfma_f32_16x16x32_bf16 v[6:9], v[162:165], v[202:205], v[6:9]
	v_mfma_f32_16x16x32_bf16 v[2:5], v[170:173], v[202:205], v[2:5]
	v_mfma_f32_16x16x32_bf16 v[54:57], v[166:169], v[182:185], v[54:57]
	v_mfma_f32_16x16x32_bf16 v[50:53], v[174:177], v[182:185], v[50:53]
	v_mfma_f32_16x16x32_bf16 v[38:41], v[166:169], v[190:193], v[38:41]
	v_mfma_f32_16x16x32_bf16 v[34:37], v[174:177], v[190:193], v[34:37]
	s_barrier
	v_mfma_f32_16x16x32_bf16 v[22:25], v[166:169], v[198:201], v[22:25]
	v_mfma_f32_16x16x32_bf16 v[18:21], v[174:177], v[198:201], v[18:21]
	v_mfma_f32_16x16x32_bf16 v[6:9], v[166:169], v[206:209], v[6:9]
	v_mfma_f32_16x16x32_bf16 v[2:5], v[174:177], v[206:209], v[2:5]
	ds_read_b128 v[140:143], v147
	ds_read_b128 v[150:153], v147 offset:1024
	ds_read_b128 v[154:157], v147 offset:2048
	ds_read_b128 v[158:161], v147 offset:3072
	ds_read_b128 v[162:165], v148
	ds_read_b128 v[166:169], v148 offset:1024
	ds_read_b128 v[170:173], v148 offset:2048
	ds_read_b128 v[174:177], v148 offset:3072
	s_mov_b32 m0, s53
	v_lshl_add_u64 v[214:215], v[212:213], 0, s[36:37]
	ds_read_b128 v[178:181], v146 offset:32768
	ds_read_b128 v[182:185], v146 offset:33792
	ds_read_b128 v[186:189], v146 offset:34816
	ds_read_b128 v[190:193], v146 offset:35840
	ds_read_b128 v[194:197], v146 offset:36864
	ds_read_b128 v[198:201], v146 offset:37888
	ds_read_b128 v[202:205], v146 offset:38912
	ds_read_b128 v[206:209], v146 offset:39936
	global_load_lds_dwordx4 v[214:215], off
	v_lshl_add_u64 v[214:215], v[212:213], 0, s[38:39]
	s_mov_b32 m0, s54
	s_nop 0
	global_load_lds_dwordx4 v[214:215], off
	s_waitcnt vmcnt(8)
	s_waitcnt lgkmcnt(0)
	s_barrier
	s_waitcnt lgkmcnt(0)
	v_mfma_f32_16x16x32_bf16 v[126:129], v[140:143], v[178:181], v[126:129]
	v_mfma_f32_16x16x32_bf16 v[122:125], v[154:157], v[178:181], v[122:125]
	v_mfma_f32_16x16x32_bf16 v[110:113], v[140:143], v[186:189], v[110:113]
	v_mfma_f32_16x16x32_bf16 v[106:109], v[154:157], v[186:189], v[106:109]
	v_mfma_f32_16x16x32_bf16 v[94:97], v[140:143], v[194:197], v[94:97]
	v_mfma_f32_16x16x32_bf16 v[90:93], v[154:157], v[194:197], v[90:93]
	v_mfma_f32_16x16x32_bf16 v[78:81], v[140:143], v[202:205], v[78:81]
	v_mfma_f32_16x16x32_bf16 v[74:77], v[154:157], v[202:205], v[74:77]
	v_mfma_f32_16x16x32_bf16 v[126:129], v[150:153], v[182:185], v[126:129]
	v_mfma_f32_16x16x32_bf16 v[122:125], v[158:161], v[182:185], v[122:125]
	v_mfma_f32_16x16x32_bf16 v[110:113], v[150:153], v[190:193], v[110:113]
	v_mfma_f32_16x16x32_bf16 v[106:109], v[158:161], v[190:193], v[106:109]
	v_mfma_f32_16x16x32_bf16 v[94:97], v[150:153], v[198:201], v[94:97]
	v_mfma_f32_16x16x32_bf16 v[90:93], v[158:161], v[198:201], v[90:93]
	v_mfma_f32_16x16x32_bf16 v[78:81], v[150:153], v[206:209], v[78:81]
	v_mfma_f32_16x16x32_bf16 v[74:77], v[158:161], v[206:209], v[74:77]
	v_mfma_f32_16x16x32_bf16 v[118:121], v[162:165], v[178:181], v[118:121]
	v_mfma_f32_16x16x32_bf16 v[114:117], v[170:173], v[178:181], v[114:117]
	v_mfma_f32_16x16x32_bf16 v[102:105], v[162:165], v[186:189], v[102:105]
	v_mfma_f32_16x16x32_bf16 v[98:101], v[170:173], v[186:189], v[98:101]
	v_mfma_f32_16x16x32_bf16 v[86:89], v[162:165], v[194:197], v[86:89]
	v_mfma_f32_16x16x32_bf16 v[82:85], v[170:173], v[194:197], v[82:85]
	v_mfma_f32_16x16x32_bf16 v[70:73], v[162:165], v[202:205], v[70:73]
	v_mfma_f32_16x16x32_bf16 v[66:69], v[170:173], v[202:205], v[66:69]
	v_mfma_f32_16x16x32_bf16 v[118:121], v[166:169], v[182:185], v[118:121]
	v_mfma_f32_16x16x32_bf16 v[114:117], v[174:177], v[182:185], v[114:117]
	v_mfma_f32_16x16x32_bf16 v[102:105], v[166:169], v[190:193], v[102:105]
	v_mfma_f32_16x16x32_bf16 v[98:101], v[174:177], v[190:193], v[98:101]
	s_barrier
; #define PG8_WAIT_V(n) asm volatile("s_waitcnt vmcnt(" #n ")" ::: "memory")
; #define PG8_BAR __builtin_amdgcn_s_barrier()
; template <class Epi, class Sched, bool ALIGN_EPI = true, bool SP2 = true, bool FULLLINE = false, bool NOSTAGE = false, bool FP8 = false>
; __device__ __forceinline__ void gemm_phase(PG8_LAS unsigned char* lds, const Gemm g, const Sched& S, const Epi& E) {
;     ...
;         static_assert(SP2, "only the SP2 loop is kept");
;         { const int t = 0; if constexpr (Epi::NST == 16) PG8_ITER(PG8_WAIT_V(24)); else if constexpr (Epi::NST == 8) PG8_ITER(PG8_WAIT_V(16)); else PG8_ITER(PG8_WAIT_V(8)); }
;         for (int t = 2; t < nt; t += 2) PG8_ITER(PG8_WAIT_V(8));
;     ...
;         if constexpr (ALIGN_EPI) { if (wr == 0) PG8_BAR; }
	v_mfma_f32_16x16x32_bf16 v[86:89], v[166:169], v[198:201], v[86:89]
	v_mfma_f32_16x16x32_bf16 v[82:85], v[174:177], v[198:201], v[82:85]
	v_mfma_f32_16x16x32_bf16 v[70:73], v[166:169], v[206:209], v[70:73]
	v_mfma_f32_16x16x32_bf16 v[66:69], v[174:177], v[206:209], v[66:69]
	s_mov_b32 m0, s50
	v_lshl_add_u64 v[214:215], v[210:211], 0, s[40:41]
	ds_read_b128 v[178:181], v146 offset:49152
	ds_read_b128 v[182:185], v146 offset:50176
	ds_read_b128 v[186:189], v146 offset:51200
	ds_read_b128 v[190:193], v146 offset:52224
	ds_read_b128 v[194:197], v146 offset:53248
	ds_read_b128 v[198:201], v146 offset:54272
	ds_read_b128 v[202:205], v146 offset:55296
	ds_read_b128 v[206:209], v146 offset:56320
	global_load_lds_dwordx4 v[214:215], off
	v_lshl_add_u64 v[214:215], v[210:211], 0, s[66:67]
	s_mov_b32 m0, s51
	s_nop 0
	global_load_lds_dwordx4 v[214:215], off
	v_lshl_add_u64 v[214:215], v[210:211], 0, s[16:17]
	s_mov_b32 m0, s33
	v_lshl_add_u64 v[210:211], v[210:211], 0, s[18:19]
	global_load_lds_dwordx4 v[214:215], off
	s_mov_b32 m0, s56
	s_nop 0
	global_load_lds_dwordx4 v[210:211], off
	v_lshl_add_u64 v[210:211], v[212:213], 0, s[40:41]
	s_mov_b32 m0, s55
	s_nop 0
	global_load_lds_dwordx4 v[210:211], off
	v_lshl_add_u64 v[210:211], v[212:213], 0, s[66:67]
	s_mov_b32 m0, s62
	s_nop 0
	global_load_lds_dwordx4 v[210:211], off
	s_waitcnt vmcnt(8)
	s_waitcnt lgkmcnt(0)
	s_barrier
	s_waitcnt lgkmcnt(0)
	v_mfma_f32_16x16x32_bf16 v[62:65], v[140:143], v[178:181], v[62:65]
	v_mfma_f32_16x16x32_bf16 v[58:61], v[154:157], v[178:181], v[58:61]
	v_mfma_f32_16x16x32_bf16 v[46:49], v[140:143], v[186:189], v[46:49]
	v_mfma_f32_16x16x32_bf16 v[42:45], v[154:157], v[186:189], v[42:45]
	v_mfma_f32_16x16x32_bf16 v[30:33], v[140:143], v[194:197], v[30:33]
	v_mfma_f32_16x16x32_bf16 v[26:29], v[154:157], v[194:197], v[26:29]
	v_mfma_f32_16x16x32_bf16 v[14:17], v[140:143], v[202:205], v[14:17]
	v_mfma_f32_16x16x32_bf16 v[10:13], v[154:157], v[202:205], v[10:13]
	v_mfma_f32_16x16x32_bf16 v[62:65], v[150:153], v[182:185], v[62:65]
	v_mfma_f32_16x16x32_bf16 v[58:61], v[158:161], v[182:185], v[58:61]
	v_mfma_f32_16x16x32_bf16 v[46:49], v[150:153], v[190:193], v[46:49]
	v_mfma_f32_16x16x32_bf16 v[42:45], v[158:161], v[190:193], v[42:45]
	v_mfma_f32_16x16x32_bf16 v[30:33], v[150:153], v[198:201], v[30:33]
	v_mfma_f32_16x16x32_bf16 v[26:29], v[158:161], v[198:201], v[26:29]
	v_mfma_f32_16x16x32_bf16 v[14:17], v[150:153], v[206:209], v[14:17]
	v_mfma_f32_16x16x32_bf16 v[10:13], v[158:161], v[206:209], v[10:13]
	v_mfma_f32_16x16x32_bf16 v[54:57], v[162:165], v[178:181], v[54:57]
	v_mfma_f32_16x16x32_bf16 v[50:53], v[170:173], v[178:181], v[50:53]
	v_mfma_f32_16x16x32_bf16 v[38:41], v[162:165], v[186:189], v[38:41]
	v_mfma_f32_16x16x32_bf16 v[34:37], v[170:173], v[186:189], v[34:37]
	v_mfma_f32_16x16x32_bf16 v[22:25], v[162:165], v[194:197], v[22:25]
	v_mfma_f32_16x16x32_bf16 v[18:21], v[170:173], v[194:197], v[18:21]
	v_mfma_f32_16x16x32_bf16 v[6:9], v[162:165], v[202:205], v[6:9]
	v_mfma_f32_16x16x32_bf16 v[2:5], v[170:173], v[202:205], v[2:5]
	v_mfma_f32_16x16x32_bf16 v[54:57], v[166:169], v[182:185], v[54:57]
	v_mfma_f32_16x16x32_bf16 v[50:53], v[174:177], v[182:185], v[50:53]
	v_mfma_f32_16x16x32_bf16 v[38:41], v[166:169], v[190:193], v[38:41]
	v_mfma_f32_16x16x32_bf16 v[34:37], v[174:177], v[190:193], v[34:37]
	s_barrier
	v_mfma_f32_16x16x32_bf16 v[22:25], v[166:169], v[198:201], v[22:25]
	v_mfma_f32_16x16x32_bf16 v[18:21], v[174:177], v[198:201], v[18:21]
	v_mfma_f32_16x16x32_bf16 v[6:9], v[166:169], v[206:209], v[6:9]
	v_mfma_f32_16x16x32_bf16 v[2:5], v[174:177], v[206:209], v[2:5]
	s_add_i32 s77, s77, 2
	s_add_u32 s78, s78, 0x100
	s_addc_u32 s79, s79, 0
	s_add_u32 s57, s57, 0x100
	s_addc_u32 s76, s76, 0
	s_cmp_gt_u32 s77, 29
	s_cbranch_scc0 .LBB0_1646
	s_and_b64 vcc, exec, s[12:13]
	s_cbranch_vccz .LBB0_1649
	s_barrier

; template <class Epi, class Sched, bool ALIGN_EPI = true, bool SP2 = true, bool FULLLINE = false, bool NOSTAGE = false, bool FP8 = false>
; __device__ __forceinline__ void gemm_phase(PG8_LAS unsigned char* lds, const Gemm g, const Sched& S, const Epi& E) {
;     ...
;         const bool has_next = S.next(ui + 1, nxt);
;         const char* nA = has_next ? PG8_ABASE(nxt) : cA; const char* nB = has_next ? PG8_BBASE(nxt) : cB;
.LBB0_2096:
	s_ashr_i32 s67, s66, 31
	ds_read_b128 v[2:5], v1
	ds_read_b128 v[6:9], v1 offset:1024
	ds_read_b128 v[10:13], v1 offset:2048
	ds_read_b128 v[14:17], v1 offset:3072
	ds_read_b128 v[18:21], v192
	ds_read_b128 v[22:25], v192 offset:1024
	ds_read_b128 v[26:29], v192 offset:2048
	ds_read_b128 v[30:33], v192 offset:3072
	s_lshl_b64 s[0:1], s[66:67], 20
	s_add_u32 s68, s42, s0
	s_addc_u32 s69, s43, s1
	s_and_b64 s[0:1], s[8:9], exec
	s_cselect_b32 s67, s69, s75
	s_cselect_b32 s90, s68, s74
	s_ashr_i32 s41, s40, 31
	s_lshl_b64 s[0:1], s[40:41], 20
	s_add_u32 s70, s44, s0
	s_addc_u32 s71, s45, s1
	s_and_b64 s[0:1], s[8:9], exec
	s_cselect_b32 s41, s71, s77
	s_cselect_b32 s91, s70, s76
	v_lshl_add_u64 v[248:249], s[74:75], 0, v[170:171]
	s_mov_b32 m0, s85
	v_lshl_add_u64 v[66:67], v[248:249], 0, s[12:13]
	ds_read_b128 v[34:37], v193
	ds_read_b128 v[38:41], v193 offset:1024
	ds_read_b128 v[42:45], v193 offset:2048
	ds_read_b128 v[46:49], v193 offset:3072
	ds_read_b128 v[50:53], v193 offset:4096
	ds_read_b128 v[54:57], v193 offset:5120
	ds_read_b128 v[58:61], v193 offset:6144
	ds_read_b128 v[62:65], v193 offset:7168
	global_load_lds_dwordx4 v[66:67], off
	v_lshl_add_u64 v[66:67], v[248:249], 0, s[14:15]
	s_mov_b32 m0, s87
	s_nop 0
	global_load_lds_dwordx4 v[66:67], off
	s_waitcnt vmcnt(24)
	s_waitcnt lgkmcnt(0)
	s_barrier
	s_waitcnt lgkmcnt(0)
	v_mfma_f32_16x16x32_bf16 v[66:69], v[2:5], v[34:37], 0
	v_mfma_f32_16x16x32_bf16 v[70:73], v[10:13], v[34:37], 0
	v_mfma_f32_16x16x32_bf16 v[78:81], v[10:13], v[42:45], 0
	v_mfma_f32_16x16x32_bf16 v[86:89], v[10:13], v[50:53], 0
	v_mfma_f32_16x16x32_bf16 v[66:69], v[6:9], v[38:41], v[66:69]
	v_mfma_f32_16x16x32_bf16 v[70:73], v[14:17], v[38:41], v[70:73]
	v_mfma_f32_16x16x32_bf16 v[74:77], v[2:5], v[42:45], 0
	v_mfma_f32_16x16x32_bf16 v[78:81], v[14:17], v[46:49], v[78:81]
	v_mfma_f32_16x16x32_bf16 v[82:85], v[2:5], v[50:53], 0
	v_mfma_f32_16x16x32_bf16 v[86:89], v[14:17], v[54:57], v[86:89]
	v_mfma_f32_16x16x32_bf16 v[90:93], v[2:5], v[58:61], 0
	v_mfma_f32_16x16x32_bf16 v[94:97], v[10:13], v[58:61], 0
	v_mfma_f32_16x16x32_bf16 v[74:77], v[6:9], v[46:49], v[74:77]
	v_mfma_f32_16x16x32_bf16 v[82:85], v[6:9], v[54:57], v[82:85]
	v_mfma_f32_16x16x32_bf16 v[90:93], v[6:9], v[62:65], v[90:93]
	v_mfma_f32_16x16x32_bf16 v[94:97], v[14:17], v[62:65], v[94:97]
	v_mfma_f32_16x16x32_bf16 v[98:101], v[18:21], v[34:37], 0
	v_mfma_f32_16x16x32_bf16 v[34:37], v[26:29], v[34:37], 0
	v_mfma_f32_16x16x32_bf16 v[98:101], v[22:25], v[38:41], v[98:101]
	v_mfma_f32_16x16x32_bf16 v[34:37], v[30:33], v[38:41], v[34:37]
	v_mfma_f32_16x16x32_bf16 v[38:41], v[18:21], v[42:45], 0
	v_mfma_f32_16x16x32_bf16 v[42:45], v[26:29], v[42:45], 0
	v_mfma_f32_16x16x32_bf16 v[38:41], v[22:25], v[46:49], v[38:41]
	v_mfma_f32_16x16x32_bf16 v[42:45], v[30:33], v[46:49], v[42:45]
	v_mfma_f32_16x16x32_bf16 v[46:49], v[18:21], v[50:53], 0
	v_mfma_f32_16x16x32_bf16 v[50:53], v[26:29], v[50:53], 0
	v_mfma_f32_16x16x32_bf16 v[46:49], v[22:25], v[54:57], v[46:49]
	v_mfma_f32_16x16x32_bf16 v[50:53], v[30:33], v[54:57], v[50:53]
	s_barrier
	v_mfma_f32_16x16x32_bf16 v[54:57], v[18:21], v[58:61], 0
	v_mfma_f32_16x16x32_bf16 v[58:61], v[26:29], v[58:61], 0
	v_mfma_f32_16x16x32_bf16 v[54:57], v[22:25], v[62:65], v[54:57]
	v_mfma_f32_16x16x32_bf16 v[58:61], v[30:33], v[62:65], v[58:61]
	v_lshl_add_u64 v[250:251], s[76:77], 0, v[172:173]
	s_add_i32 s92, s83, s46
	v_lshl_add_u64 v[130:131], v[250:251], 0, s[16:17]
	s_mov_b32 m0, s92
	s_add_i32 s93, s92, 0x2000
	ds_read_b128 v[62:65], v193 offset:16384
	ds_read_b128 v[102:105], v193 offset:17408
	ds_read_b128 v[106:109], v193 offset:18432
	ds_read_b128 v[110:113], v193 offset:19456
	ds_read_b128 v[114:117], v193 offset:20480
	ds_read_b128 v[118:121], v193 offset:21504
	ds_read_b128 v[122:125], v193 offset:22528
	ds_read_b128 v[126:129], v193 offset:23552
	global_load_lds_dwordx4 v[130:131], off
	v_lshl_add_u64 v[130:131], v[250:251], 0, s[18:19]
	s_mov_b32 m0, s93
	s_add_i32 s94, s84, s46
	global_load_lds_dwordx4 v[130:131], off
	v_lshl_add_u64 v[130:131], v[250:251], 0, s[20:21]
	s_mov_b32 m0, s94
	s_add_i32 s95, s94, 0x2000
	global_load_lds_dwordx4 v[130:131], off
	v_lshl_add_u64 v[130:131], v[250:251], 0, s[22:23]
	s_mov_b32 m0, s95
	s_nop 0
	global_load_lds_dwordx4 v[130:131], off
	v_lshl_add_u64 v[130:131], v[248:249], 0, s[16:17]
	s_mov_b32 m0, s47
	s_nop 0
	global_load_lds_dwordx4 v[130:131], off
	v_lshl_add_u64 v[130:131], v[248:249], 0, s[18:19]
	s_mov_b32 m0, s52
	s_nop 0
	global_load_lds_dwordx4 v[130:131], off
	s_waitcnt vmcnt(24)
	s_waitcnt lgkmcnt(0)
	s_barrier
	s_waitcnt lgkmcnt(0)
	v_mfma_f32_16x16x32_bf16 v[130:133], v[2:5], v[62:65], 0
	v_mfma_f32_16x16x32_bf16 v[138:141], v[6:9], v[102:105], v[130:133]
	v_mfma_f32_16x16x32_bf16 v[130:133], v[10:13], v[62:65], 0
	v_mfma_f32_16x16x32_bf16 v[150:153], v[14:17], v[102:105], v[130:133]
	v_mfma_f32_16x16x32_bf16 v[130:133], v[2:5], v[106:109], 0
	v_mfma_f32_16x16x32_bf16 v[154:157], v[6:9], v[110:113], v[130:133]
	v_mfma_f32_16x16x32_bf16 v[130:133], v[10:13], v[106:109], 0
	v_mfma_f32_16x16x32_bf16 v[158:161], v[14:17], v[110:113], v[130:133]
	v_mfma_f32_16x16x32_bf16 v[130:133], v[2:5], v[114:117], 0
	v_mfma_f32_16x16x32_bf16 v[2:5], v[2:5], v[122:125], 0
	v_mfma_f32_16x16x32_bf16 v[162:165], v[6:9], v[118:121], v[130:133]
	v_mfma_f32_16x16x32_bf16 v[2:5], v[6:9], v[126:129], v[2:5]
	v_mfma_f32_16x16x32_bf16 v[6:9], v[10:13], v[122:125], 0
	v_mfma_f32_16x16x32_bf16 v[130:133], v[10:13], v[114:117], 0
	v_mfma_f32_16x16x32_bf16 v[6:9], v[14:17], v[126:129], v[6:9]
	v_mfma_f32_16x16x32_bf16 v[166:169], v[14:17], v[118:121], v[130:133]
	v_mfma_f32_16x16x32_bf16 v[10:13], v[18:21], v[62:65], 0
	v_mfma_f32_16x16x32_bf16 v[180:183], v[22:25], v[102:105], v[10:13]
	v_mfma_f32_16x16x32_bf16 v[10:13], v[26:29], v[62:65], 0
	v_mfma_f32_16x16x32_bf16 v[184:187], v[30:33], v[102:105], v[10:13]
	v_mfma_f32_16x16x32_bf16 v[10:13], v[18:21], v[106:109], 0
	v_mfma_f32_16x16x32_bf16 v[188:191], v[22:25], v[110:113], v[10:13]
	v_mfma_f32_16x16x32_bf16 v[10:13], v[26:29], v[106:109], 0
	v_mfma_f32_16x16x32_bf16 v[196:199], v[30:33], v[110:113], v[10:13]
	v_mfma_f32_16x16x32_bf16 v[10:13], v[18:21], v[114:117], 0
	v_mfma_f32_16x16x32_bf16 v[200:203], v[22:25], v[118:121], v[10:13]
	v_mfma_f32_16x16x32_bf16 v[10:13], v[26:29], v[114:117], 0
	v_mfma_f32_16x16x32_bf16 v[204:207], v[30:33], v[118:121], v[10:13]
	s_barrier
	v_mfma_f32_16x16x32_bf16 v[10:13], v[18:21], v[122:125], 0
	v_mfma_f32_16x16x32_bf16 v[208:211], v[22:25], v[126:129], v[10:13]
	v_mfma_f32_16x16x32_bf16 v[10:13], v[26:29], v[122:125], 0
	v_mfma_f32_16x16x32_bf16 v[212:215], v[30:33], v[126:129], v[10:13]
	s_nop 5
	ds_read_b128 v[10:13], v194
	ds_read_b128 v[14:17], v194 offset:1024
	ds_read_b128 v[18:21], v194 offset:2048
	ds_read_b128 v[22:25], v194 offset:3072
	ds_read_b128 v[216:219], v195
	ds_read_b128 v[220:223], v195 offset:1024
	ds_read_b128 v[224:227], v195 offset:2048
	ds_read_b128 v[228:231], v195 offset:3072
	s_mov_b32 m0, s53
	v_lshl_add_u64 v[106:107], v[248:249], 0, s[20:21]
	ds_read_b128 v[26:29], v193 offset:32768
	ds_read_b128 v[30:33], v193 offset:33792
	ds_read_b128 v[62:65], v193 offset:34816
	ds_read_b128 v[102:105], v193 offset:35840
	ds_read_b128 v[232:235], v193 offset:36864
	ds_read_b128 v[236:239], v193 offset:37888
	ds_read_b128 v[240:243], v193 offset:38912
	ds_read_b128 v[244:247], v193 offset:39936
	global_load_lds_dwordx4 v[106:107], off
	v_lshl_add_u64 v[106:107], v[248:249], 0, s[22:23]
	s_mov_b32 m0, s54
	s_nop 0
	global_load_lds_dwordx4 v[106:107], off
	s_waitcnt vmcnt(8)
	s_waitcnt lgkmcnt(0)
	s_barrier
	s_waitcnt lgkmcnt(0)
	v_mfma_f32_16x16x32_bf16 v[66:69], v[10:13], v[26:29], v[66:69]
	v_mfma_f32_16x16x32_bf16 v[146:149], v[14:17], v[30:33], v[66:69]
	v_mfma_f32_16x16x32_bf16 v[66:69], v[18:21], v[26:29], v[70:73]
	v_mfma_f32_16x16x32_bf16 v[142:145], v[22:25], v[30:33], v[66:69]
	v_mfma_f32_16x16x32_bf16 v[66:69], v[10:13], v[62:65], v[74:77]
	v_mfma_f32_16x16x32_bf16 v[126:129], v[14:17], v[102:105], v[66:69]
	v_mfma_f32_16x16x32_bf16 v[66:69], v[18:21], v[62:65], v[78:81]
	v_mfma_f32_16x16x32_bf16 v[122:125], v[22:25], v[102:105], v[66:69]
	v_mfma_f32_16x16x32_bf16 v[66:69], v[10:13], v[232:235], v[82:85]
	v_mfma_f32_16x16x32_bf16 v[110:113], v[14:17], v[236:239], v[66:69]
	v_mfma_f32_16x16x32_bf16 v[66:69], v[18:21], v[232:235], v[86:89]
	v_mfma_f32_16x16x32_bf16 v[106:109], v[22:25], v[236:239], v[66:69]
	v_mfma_f32_16x16x32_bf16 v[66:69], v[10:13], v[240:243], v[90:93]
	v_mfma_f32_16x16x32_bf16 v[86:89], v[14:17], v[244:247], v[66:69]
	v_mfma_f32_16x16x32_bf16 v[66:69], v[18:21], v[240:243], v[94:97]
	v_mfma_f32_16x16x32_bf16 v[78:81], v[22:25], v[244:247], v[66:69]
	v_mfma_f32_16x16x32_bf16 v[66:69], v[216:219], v[26:29], v[98:101]
	v_mfma_f32_16x16x32_bf16 v[26:29], v[224:227], v[26:29], v[34:37]
	v_mfma_f32_16x16x32_bf16 v[130:133], v[228:231], v[30:33], v[26:29]
	v_mfma_f32_16x16x32_bf16 v[26:29], v[216:219], v[62:65], v[38:41]
	v_mfma_f32_16x16x32_bf16 v[118:121], v[220:223], v[102:105], v[26:29]
	v_mfma_f32_16x16x32_bf16 v[26:29], v[224:227], v[62:65], v[42:45]
	v_mfma_f32_16x16x32_bf16 v[114:117], v[228:231], v[102:105], v[26:29]
	v_mfma_f32_16x16x32_bf16 v[26:29], v[216:219], v[232:235], v[46:49]
	v_mfma_f32_16x16x32_bf16 v[102:105], v[220:223], v[236:239], v[26:29]
	v_mfma_f32_16x16x32_bf16 v[26:29], v[224:227], v[232:235], v[50:53]
	v_mfma_f32_16x16x32_bf16 v[98:101], v[228:231], v[236:239], v[26:29]
	v_mfma_f32_16x16x32_bf16 v[26:29], v[216:219], v[240:243], v[54:57]
	s_barrier
	v_mfma_f32_16x16x32_bf16 v[70:73], v[220:223], v[244:247], v[26:29]
	v_mfma_f32_16x16x32_bf16 v[26:29], v[224:227], v[240:243], v[58:61]
	v_mfma_f32_16x16x32_bf16 v[134:137], v[220:223], v[30:33], v[66:69]
	v_mfma_f32_16x16x32_bf16 v[66:69], v[228:231], v[244:247], v[26:29]
	s_add_i32 s50, s88, s46
	s_nop 3
	v_lshl_add_u64 v[26:27], v[250:251], 0, s[24:25]
	s_mov_b32 m0, s50
	s_add_i32 s51, s50, 0x2000
	ds_read_b128 v[34:37], v193 offset:49152
	ds_read_b128 v[38:41], v193 offset:50176
	ds_read_b128 v[74:77], v193 offset:51200
	ds_read_b128 v[82:85], v193 offset:52224
	ds_read_b128 v[90:93], v193 offset:53248
	ds_read_b128 v[94:97], v193 offset:54272
	ds_read_b128 v[232:235], v193 offset:55296
	ds_read_b128 v[236:239], v193 offset:56320
	global_load_lds_dwordx4 v[26:27], off
	v_lshl_add_u64 v[26:27], v[250:251], 0, s[26:27]
	s_mov_b32 m0, s51
	s_mov_b64 s[0:1], 0x80180
	s_add_i32 s33, s89, s46
	global_load_lds_dwordx4 v[26:27], off
	v_lshl_add_u64 v[26:27], v[250:251], 0, s[0:1]
	s_mov_b32 m0, s33
	s_mov_b64 s[0:1], 0xc0180
	s_add_i32 s56, s33, 0x2000
	global_load_lds_dwordx4 v[26:27], off
	v_lshl_add_u64 v[26:27], v[250:251], 0, s[0:1]
	s_mov_b32 m0, s56
	s_nop 0
	global_load_lds_dwordx4 v[26:27], off
	v_lshl_add_u64 v[26:27], v[248:249], 0, s[24:25]
	s_mov_b32 m0, s55
	s_nop 0
	global_load_lds_dwordx4 v[26:27], off
	v_lshl_add_u64 v[26:27], v[248:249], 0, s[26:27]
	s_mov_b32 m0, s62
	s_nop 0
	global_load_lds_dwordx4 v[26:27], off
	s_waitcnt vmcnt(8)
	s_waitcnt lgkmcnt(0)
	s_barrier
	s_waitcnt lgkmcnt(0)
	v_mfma_f32_16x16x32_bf16 v[26:29], v[10:13], v[34:37], v[138:141]
	v_mfma_f32_16x16x32_bf16 v[62:65], v[14:17], v[38:41], v[26:29]
	v_mfma_f32_16x16x32_bf16 v[26:29], v[18:21], v[34:37], v[150:153]
	v_mfma_f32_16x16x32_bf16 v[58:61], v[22:25], v[38:41], v[26:29]
	v_mfma_f32_16x16x32_bf16 v[26:29], v[10:13], v[74:77], v[154:157]
	v_mfma_f32_16x16x32_bf16 v[46:49], v[14:17], v[82:85], v[26:29]
	v_mfma_f32_16x16x32_bf16 v[26:29], v[18:21], v[74:77], v[158:161]
	v_mfma_f32_16x16x32_bf16 v[42:45], v[22:25], v[82:85], v[26:29]
	v_mfma_f32_16x16x32_bf16 v[26:29], v[10:13], v[90:93], v[162:165]
	v_mfma_f32_16x16x32_bf16 v[2:5], v[10:13], v[232:235], v[2:5]
	v_mfma_f32_16x16x32_bf16 v[30:33], v[14:17], v[94:97], v[26:29]
	v_mfma_f32_16x16x32_bf16 v[26:29], v[18:21], v[90:93], v[166:169]
	v_mfma_f32_16x16x32_bf16 v[14:17], v[14:17], v[236:239], v[2:5]
	v_mfma_f32_16x16x32_bf16 v[2:5], v[18:21], v[232:235], v[6:9]
	v_mfma_f32_16x16x32_bf16 v[26:29], v[22:25], v[94:97], v[26:29]
	v_mfma_f32_16x16x32_bf16 v[10:13], v[22:25], v[236:239], v[2:5]
	v_mfma_f32_16x16x32_bf16 v[2:5], v[216:219], v[34:37], v[180:183]
	v_mfma_f32_16x16x32_bf16 v[54:57], v[220:223], v[38:41], v[2:5]
	v_mfma_f32_16x16x32_bf16 v[2:5], v[224:227], v[34:37], v[184:187]
	v_mfma_f32_16x16x32_bf16 v[50:53], v[228:231], v[38:41], v[2:5]
	v_mfma_f32_16x16x32_bf16 v[2:5], v[216:219], v[74:77], v[188:191]
	v_mfma_f32_16x16x32_bf16 v[38:41], v[220:223], v[82:85], v[2:5]
	v_mfma_f32_16x16x32_bf16 v[2:5], v[224:227], v[74:77], v[196:199]
	v_mfma_f32_16x16x32_bf16 v[34:37], v[228:231], v[82:85], v[2:5]
	v_mfma_f32_16x16x32_bf16 v[2:5], v[216:219], v[90:93], v[200:203]
	v_mfma_f32_16x16x32_bf16 v[22:25], v[220:223], v[94:97], v[2:5]
	v_mfma_f32_16x16x32_bf16 v[2:5], v[224:227], v[90:93], v[204:207]
	v_mfma_f32_16x16x32_bf16 v[18:21], v[228:231], v[94:97], v[2:5]
	s_barrier
	v_mfma_f32_16x16x32_bf16 v[2:5], v[216:219], v[232:235], v[208:211]
	v_mfma_f32_16x16x32_bf16 v[6:9], v[220:223], v[236:239], v[2:5]
	v_mfma_f32_16x16x32_bf16 v[2:5], v[224:227], v[232:235], v[212:215]
	v_mfma_f32_16x16x32_bf16 v[2:5], v[228:231], v[236:239], v[2:5]
	s_add_u32 s74, s74, 0x80180
	s_addc_u32 s75, s75, 0
	s_add_u32 s57, s76, 0x200
	s_addc_u32 s76, s77, 0
	s_mov_b32 s77, 0
; #define PG8_WAIT_V(n) asm volatile("s_waitcnt vmcnt(" #n ")" ::: "memory")
; template <class Epi, class Sched, bool ALIGN_EPI = true, bool SP2 = true, bool FULLLINE = false, bool NOSTAGE = false, bool FP8 = false>
; __device__ __forceinline__ void gemm_phase(PG8_LAS unsigned char* lds, const Gemm g, const Sched& S, const Epi& E) {
;     ...
;         for (int t = 2; t < nt; t += 2) PG8_ITER(PG8_WAIT_V(8));
.LBB0_2097:
	ds_read_b128 v[74:77], v1
	ds_read_b128 v[82:85], v1 offset:1024
	ds_read_b128 v[90:93], v1 offset:2048
	ds_read_b128 v[94:97], v1 offset:3072
	ds_read_b128 v[138:141], v192
	ds_read_b128 v[150:153], v192 offset:1024
	ds_read_b128 v[154:157], v192 offset:2048
	ds_read_b128 v[158:161], v192 offset:3072
	s_add_u32 s0, s74, 0xfff80080
	s_addc_u32 s1, s75, -1
	s_cmp_eq_u32 s77, 28
	s_cselect_b32 s1, s67, s1
	s_cselect_b32 s0, s90, s0
	s_cselect_b32 s65, s41, s76
	s_cselect_b32 s64, s91, s57
	s_mov_b32 m0, s85
	v_lshl_add_u64 v[208:209], s[74:75], 0, v[174:175]
	ds_read_b128 v[162:165], v193
	ds_read_b128 v[166:169], v193 offset:1024
	ds_read_b128 v[180:183], v193 offset:2048
	ds_read_b128 v[184:187], v193 offset:3072
	ds_read_b128 v[188:191], v193 offset:4096
	ds_read_b128 v[196:199], v193 offset:5120
	ds_read_b128 v[200:203], v193 offset:6144
	ds_read_b128 v[204:207], v193 offset:7168
	global_load_lds_dwordx4 v[208:209], off
	v_lshl_add_u64 v[208:209], v[208:209], 0, s[28:29]
	s_mov_b32 m0, s87
	s_nop 0
	global_load_lds_dwordx4 v[208:209], off
	s_waitcnt vmcnt(8)
	s_waitcnt lgkmcnt(0)
	s_barrier
	s_waitcnt lgkmcnt(0)
	v_mfma_f32_16x16x32_bf16 v[146:149], v[74:77], v[162:165], v[146:149]
	v_mfma_f32_16x16x32_bf16 v[142:145], v[90:93], v[162:165], v[142:145]
	v_mfma_f32_16x16x32_bf16 v[126:129], v[74:77], v[180:183], v[126:129]
	v_mfma_f32_16x16x32_bf16 v[122:125], v[90:93], v[180:183], v[122:125]
	v_mfma_f32_16x16x32_bf16 v[110:113], v[74:77], v[188:191], v[110:113]
	v_mfma_f32_16x16x32_bf16 v[106:109], v[90:93], v[188:191], v[106:109]
	v_mfma_f32_16x16x32_bf16 v[86:89], v[74:77], v[200:203], v[86:89]
	v_mfma_f32_16x16x32_bf16 v[78:81], v[90:93], v[200:203], v[78:81]
	v_mfma_f32_16x16x32_bf16 v[146:149], v[82:85], v[166:169], v[146:149]
	v_mfma_f32_16x16x32_bf16 v[142:145], v[94:97], v[166:169], v[142:145]
	v_mfma_f32_16x16x32_bf16 v[126:129], v[82:85], v[184:187], v[126:129]
	v_mfma_f32_16x16x32_bf16 v[122:125], v[94:97], v[184:187], v[122:125]
	v_mfma_f32_16x16x32_bf16 v[110:113], v[82:85], v[196:199], v[110:113]
	v_mfma_f32_16x16x32_bf16 v[106:109], v[94:97], v[196:199], v[106:109]
	v_mfma_f32_16x16x32_bf16 v[86:89], v[82:85], v[204:207], v[86:89]
	v_mfma_f32_16x16x32_bf16 v[78:81], v[94:97], v[204:207], v[78:81]
	v_mfma_f32_16x16x32_bf16 v[134:137], v[138:141], v[162:165], v[134:137]
	v_mfma_f32_16x16x32_bf16 v[130:133], v[154:157], v[162:165], v[130:133]
	v_mfma_f32_16x16x32_bf16 v[118:121], v[138:141], v[180:183], v[118:121]
	v_mfma_f32_16x16x32_bf16 v[114:117], v[154:157], v[180:183], v[114:117]
	v_mfma_f32_16x16x32_bf16 v[102:105], v[138:141], v[188:191], v[102:105]
	v_mfma_f32_16x16x32_bf16 v[98:101], v[154:157], v[188:191], v[98:101]
	v_mfma_f32_16x16x32_bf16 v[70:73], v[138:141], v[200:203], v[70:73]
	v_mfma_f32_16x16x32_bf16 v[66:69], v[154:157], v[200:203], v[66:69]
	v_mfma_f32_16x16x32_bf16 v[134:137], v[150:153], v[166:169], v[134:137]
	v_mfma_f32_16x16x32_bf16 v[130:133], v[158:161], v[166:169], v[130:133]
	v_mfma_f32_16x16x32_bf16 v[118:121], v[150:153], v[184:187], v[118:121]
	v_mfma_f32_16x16x32_bf16 v[114:117], v[158:161], v[184:187], v[114:117]
	s_barrier
	v_mfma_f32_16x16x32_bf16 v[102:105], v[150:153], v[196:199], v[102:105]
	v_mfma_f32_16x16x32_bf16 v[98:101], v[158:161], v[196:199], v[98:101]
	v_mfma_f32_16x16x32_bf16 v[70:73], v[150:153], v[204:207], v[70:73]
	v_mfma_f32_16x16x32_bf16 v[66:69], v[158:161], v[204:207], v[66:69]
	s_mov_b32 m0, s92
	v_lshl_add_u64 v[208:209], s[64:65], 0, v[172:173]
	ds_read_b128 v[162:165], v193 offset:16384
	ds_read_b128 v[166:169], v193 offset:17408
	ds_read_b128 v[180:183], v193 offset:18432
	ds_read_b128 v[184:187], v193 offset:19456
	ds_read_b128 v[188:191], v193 offset:20480
	ds_read_b128 v[196:199], v193 offset:21504
	ds_read_b128 v[200:203], v193 offset:22528
	ds_read_b128 v[204:207], v193 offset:23552
	global_load_lds_dwordx4 v[208:209], off
	v_lshl_add_u64 v[210:211], v[208:209], 0, s[28:29]
	s_mov_b32 m0, s93
	s_nop 0
	global_load_lds_dwordx4 v[210:211], off
	v_lshl_add_u64 v[210:211], v[208:209], 0, s[30:31]
	s_mov_b32 m0, s94
	s_nop 0
	global_load_lds_dwordx4 v[210:211], off
	v_lshl_add_u64 v[210:211], v[208:209], 0, s[34:35]
	s_mov_b32 m0, s95
	s_nop 0
	global_load_lds_dwordx4 v[210:211], off
	v_lshl_add_u64 v[210:211], s[0:1], 0, v[170:171]
	s_mov_b32 m0, s47
	v_lshl_add_u64 v[212:213], v[210:211], 0, s[28:29]
	global_load_lds_dwordx4 v[210:211], off
	s_mov_b32 m0, s52
	s_nop 0
	global_load_lds_dwordx4 v[212:213], off
	s_waitcnt vmcnt(8)
	s_waitcnt lgkmcnt(0)
	s_barrier
	s_waitcnt lgkmcnt(0)
	v_mfma_f32_16x16x32_bf16 v[62:65], v[74:77], v[162:165], v[62:65]
	v_mfma_f32_16x16x32_bf16 v[58:61], v[90:93], v[162:165], v[58:61]
	v_mfma_f32_16x16x32_bf16 v[46:49], v[74:77], v[180:183], v[46:49]
	v_mfma_f32_16x16x32_bf16 v[42:45], v[90:93], v[180:183], v[42:45]
	v_mfma_f32_16x16x32_bf16 v[30:33], v[74:77], v[188:191], v[30:33]
	v_mfma_f32_16x16x32_bf16 v[26:29], v[90:93], v[188:191], v[26:29]
	v_mfma_f32_16x16x32_bf16 v[14:17], v[74:77], v[200:203], v[14:17]
	v_mfma_f32_16x16x32_bf16 v[10:13], v[90:93], v[200:203], v[10:13]
	v_mfma_f32_16x16x32_bf16 v[62:65], v[82:85], v[166:169], v[62:65]
	v_mfma_f32_16x16x32_bf16 v[58:61], v[94:97], v[166:169], v[58:61]
	v_mfma_f32_16x16x32_bf16 v[46:49], v[82:85], v[184:187], v[46:49]
	v_mfma_f32_16x16x32_bf16 v[42:45], v[94:97], v[184:187], v[42:45]
	v_mfma_f32_16x16x32_bf16 v[30:33], v[82:85], v[196:199], v[30:33]
	v_mfma_f32_16x16x32_bf16 v[26:29], v[94:97], v[196:199], v[26:29]
	v_mfma_f32_16x16x32_bf16 v[14:17], v[82:85], v[204:207], v[14:17]
	v_mfma_f32_16x16x32_bf16 v[10:13], v[94:97], v[204:207], v[10:13]
	v_mfma_f32_16x16x32_bf16 v[54:57], v[138:141], v[162:165], v[54:57]
	v_mfma_f32_16x16x32_bf16 v[50:53], v[154:157], v[162:165], v[50:53]
	v_mfma_f32_16x16x32_bf16 v[38:41], v[138:141], v[180:183], v[38:41]
	v_mfma_f32_16x16x32_bf16 v[34:37], v[154:157], v[180:183], v[34:37]
	v_mfma_f32_16x16x32_bf16 v[22:25], v[138:141], v[188:191], v[22:25]
	v_mfma_f32_16x16x32_bf16 v[18:21], v[154:157], v[188:191], v[18:21]
	v_mfma_f32_16x16x32_bf16 v[6:9], v[138:141], v[200:203], v[6:9]
	v_mfma_f32_16x16x32_bf16 v[2:5], v[154:157], v[200:203], v[2:5]
	v_mfma_f32_16x16x32_bf16 v[54:57], v[150:153], v[166:169], v[54:57]
	v_mfma_f32_16x16x32_bf16 v[50:53], v[158:161], v[166:169], v[50:53]
	v_mfma_f32_16x16x32_bf16 v[38:41], v[150:153], v[184:187], v[38:41]
	v_mfma_f32_16x16x32_bf16 v[34:37], v[158:161], v[184:187], v[34:37]
	s_barrier
	v_mfma_f32_16x16x32_bf16 v[22:25], v[150:153], v[196:199], v[22:25]
	v_mfma_f32_16x16x32_bf16 v[18:21], v[158:161], v[196:199], v[18:21]
	v_mfma_f32_16x16x32_bf16 v[6:9], v[150:153], v[204:207], v[6:9]
	v_mfma_f32_16x16x32_bf16 v[2:5], v[158:161], v[204:207], v[2:5]
	ds_read_b128 v[74:77], v194
	ds_read_b128 v[82:85], v194 offset:1024
	ds_read_b128 v[90:93], v194 offset:2048
	ds_read_b128 v[94:97], v194 offset:3072
	ds_read_b128 v[138:141], v195
	ds_read_b128 v[150:153], v195 offset:1024
	ds_read_b128 v[154:157], v195 offset:2048
	ds_read_b128 v[158:161], v195 offset:3072
	s_mov_b32 m0, s53
	v_lshl_add_u64 v[212:213], v[210:211], 0, s[30:31]
	ds_read_b128 v[162:165], v193 offset:32768
	ds_read_b128 v[166:169], v193 offset:33792
	ds_read_b128 v[180:183], v193 offset:34816
	ds_read_b128 v[184:187], v193 offset:35840
	ds_read_b128 v[188:191], v193 offset:36864
	ds_read_b128 v[196:199], v193 offset:37888
	ds_read_b128 v[200:203], v193 offset:38912
	ds_read_b128 v[204:207], v193 offset:39936
	global_load_lds_dwordx4 v[212:213], off
	v_lshl_add_u64 v[212:213], v[210:211], 0, s[34:35]
	s_mov_b32 m0, s54
	s_nop 0
	global_load_lds_dwordx4 v[212:213], off
	s_waitcnt vmcnt(8)
	s_waitcnt lgkmcnt(0)
	s_barrier
	s_waitcnt lgkmcnt(0)
	v_mfma_f32_16x16x32_bf16 v[146:149], v[74:77], v[162:165], v[146:149]
	v_mfma_f32_16x16x32_bf16 v[142:145], v[90:93], v[162:165], v[142:145]
	v_mfma_f32_16x16x32_bf16 v[126:129], v[74:77], v[180:183], v[126:129]
	v_mfma_f32_16x16x32_bf16 v[122:125], v[90:93], v[180:183], v[122:125]
	v_mfma_f32_16x16x32_bf16 v[110:113], v[74:77], v[188:191], v[110:113]
	v_mfma_f32_16x16x32_bf16 v[106:109], v[90:93], v[188:191], v[106:109]
	v_mfma_f32_16x16x32_bf16 v[86:89], v[74:77], v[200:203], v[86:89]
	v_mfma_f32_16x16x32_bf16 v[78:81], v[90:93], v[200:203], v[78:81]
	v_mfma_f32_16x16x32_bf16 v[146:149], v[82:85], v[166:169], v[146:149]
	v_mfma_f32_16x16x32_bf16 v[142:145], v[94:97], v[166:169], v[142:145]
	v_mfma_f32_16x16x32_bf16 v[126:129], v[82:85], v[184:187], v[126:129]
	v_mfma_f32_16x16x32_bf16 v[122:125], v[94:97], v[184:187], v[122:125]
	v_mfma_f32_16x16x32_bf16 v[110:113], v[82:85], v[196:199], v[110:113]
	v_mfma_f32_16x16x32_bf16 v[106:109], v[94:97], v[196:199], v[106:109]
	v_mfma_f32_16x16x32_bf16 v[86:89], v[82:85], v[204:207], v[86:89]
	v_mfma_f32_16x16x32_bf16 v[78:81], v[94:97], v[204:207], v[78:81]
	v_mfma_f32_16x16x32_bf16 v[134:137], v[138:141], v[162:165], v[134:137]
	v_mfma_f32_16x16x32_bf16 v[130:133], v[154:157], v[162:165], v[130:133]
	v_mfma_f32_16x16x32_bf16 v[118:121], v[138:141], v[180:183], v[118:121]
	v_mfma_f32_16x16x32_bf16 v[114:117], v[154:157], v[180:183], v[114:117]
	v_mfma_f32_16x16x32_bf16 v[102:105], v[138:141], v[188:191], v[102:105]
	v_mfma_f32_16x16x32_bf16 v[98:101], v[154:157], v[188:191], v[98:101]
	v_mfma_f32_16x16x32_bf16 v[70:73], v[138:141], v[200:203], v[70:73]
	v_mfma_f32_16x16x32_bf16 v[66:69], v[154:157], v[200:203], v[66:69]
	v_mfma_f32_16x16x32_bf16 v[134:137], v[150:153], v[166:169], v[134:137]
	v_mfma_f32_16x16x32_bf16 v[130:133], v[158:161], v[166:169], v[130:133]
	v_mfma_f32_16x16x32_bf16 v[118:121], v[150:153], v[184:187], v[118:121]
	v_mfma_f32_16x16x32_bf16 v[114:117], v[158:161], v[184:187], v[114:117]
	s_barrier
; #define PG8_WAIT_V(n) asm volatile("s_waitcnt vmcnt(" #n ")" ::: "memory")
; #define PG8_BAR __builtin_amdgcn_s_barrier()
; template <class Epi, class Sched, bool ALIGN_EPI = true, bool SP2 = true, bool FULLLINE = false, bool NOSTAGE = false, bool FP8 = false>
; __device__ __forceinline__ void gemm_phase(PG8_LAS unsigned char* lds, const Gemm g, const Sched& S, const Epi& E) {
;     ...
;         static_assert(SP2, "only the SP2 loop is kept");
;         { const int t = 0; if constexpr (Epi::NST == 16) PG8_ITER(PG8_WAIT_V(24)); else if constexpr (Epi::NST == 8) PG8_ITER(PG8_WAIT_V(16)); else PG8_ITER(PG8_WAIT_V(8)); }
;         for (int t = 2; t < nt; t += 2) PG8_ITER(PG8_WAIT_V(8));
;     ...
;         if constexpr (ALIGN_EPI) { if (wr == 0) PG8_BAR; }
	v_mfma_f32_16x16x32_bf16 v[102:105], v[150:153], v[196:199], v[102:105]
	v_mfma_f32_16x16x32_bf16 v[98:101], v[158:161], v[196:199], v[98:101]
	v_mfma_f32_16x16x32_bf16 v[70:73], v[150:153], v[204:207], v[70:73]
	v_mfma_f32_16x16x32_bf16 v[66:69], v[158:161], v[204:207], v[66:69]
	s_mov_b32 m0, s50
	v_lshl_add_u64 v[212:213], v[208:209], 0, s[36:37]
	ds_read_b128 v[162:165], v193 offset:49152
	ds_read_b128 v[166:169], v193 offset:50176
	ds_read_b128 v[180:183], v193 offset:51200
	ds_read_b128 v[184:187], v193 offset:52224
	ds_read_b128 v[188:191], v193 offset:53248
	ds_read_b128 v[196:199], v193 offset:54272
	ds_read_b128 v[200:203], v193 offset:55296
	ds_read_b128 v[204:207], v193 offset:56320
	global_load_lds_dwordx4 v[212:213], off
	v_lshl_add_u64 v[212:213], v[208:209], 0, s[38:39]
	s_mov_b32 m0, s51
	s_nop 0
	global_load_lds_dwordx4 v[212:213], off
	v_lshl_add_u64 v[212:213], v[208:209], 0, s[12:13]
	s_mov_b32 m0, s33
	v_lshl_add_u64 v[208:209], v[208:209], 0, s[14:15]
	global_load_lds_dwordx4 v[212:213], off
	s_mov_b32 m0, s56
	s_nop 0
	global_load_lds_dwordx4 v[208:209], off
	v_lshl_add_u64 v[208:209], v[210:211], 0, s[36:37]
	s_mov_b32 m0, s55
	s_nop 0
	global_load_lds_dwordx4 v[208:209], off
	v_lshl_add_u64 v[208:209], v[210:211], 0, s[38:39]
	s_mov_b32 m0, s62
	s_nop 0
	global_load_lds_dwordx4 v[208:209], off
	s_waitcnt vmcnt(8)
	s_waitcnt lgkmcnt(0)
	s_barrier
	s_waitcnt lgkmcnt(0)
	v_mfma_f32_16x16x32_bf16 v[62:65], v[74:77], v[162:165], v[62:65]
	v_mfma_f32_16x16x32_bf16 v[58:61], v[90:93], v[162:165], v[58:61]
	v_mfma_f32_16x16x32_bf16 v[46:49], v[74:77], v[180:183], v[46:49]
	v_mfma_f32_16x16x32_bf16 v[42:45], v[90:93], v[180:183], v[42:45]
	v_mfma_f32_16x16x32_bf16 v[30:33], v[74:77], v[188:191], v[30:33]
	v_mfma_f32_16x16x32_bf16 v[26:29], v[90:93], v[188:191], v[26:29]
	v_mfma_f32_16x16x32_bf16 v[14:17], v[74:77], v[200:203], v[14:17]
	v_mfma_f32_16x16x32_bf16 v[10:13], v[90:93], v[200:203], v[10:13]
	v_mfma_f32_16x16x32_bf16 v[62:65], v[82:85], v[166:169], v[62:65]
	v_mfma_f32_16x16x32_bf16 v[58:61], v[94:97], v[166:169], v[58:61]
	v_mfma_f32_16x16x32_bf16 v[46:49], v[82:85], v[184:187], v[46:49]
	v_mfma_f32_16x16x32_bf16 v[42:45], v[94:97], v[184:187], v[42:45]
	v_mfma_f32_16x16x32_bf16 v[30:33], v[82:85], v[196:199], v[30:33]
	v_mfma_f32_16x16x32_bf16 v[26:29], v[94:97], v[196:199], v[26:29]
	v_mfma_f32_16x16x32_bf16 v[14:17], v[82:85], v[204:207], v[14:17]
	v_mfma_f32_16x16x32_bf16 v[10:13], v[94:97], v[204:207], v[10:13]
	v_mfma_f32_16x16x32_bf16 v[54:57], v[138:141], v[162:165], v[54:57]
	v_mfma_f32_16x16x32_bf16 v[50:53], v[154:157], v[162:165], v[50:53]
	v_mfma_f32_16x16x32_bf16 v[38:41], v[138:141], v[180:183], v[38:41]
	v_mfma_f32_16x16x32_bf16 v[34:37], v[154:157], v[180:183], v[34:37]
	v_mfma_f32_16x16x32_bf16 v[22:25], v[138:141], v[188:191], v[22:25]
	v_mfma_f32_16x16x32_bf16 v[18:21], v[154:157], v[188:191], v[18:21]
	v_mfma_f32_16x16x32_bf16 v[6:9], v[138:141], v[200:203], v[6:9]
	v_mfma_f32_16x16x32_bf16 v[2:5], v[154:157], v[200:203], v[2:5]
	v_mfma_f32_16x16x32_bf16 v[54:57], v[150:153], v[166:169], v[54:57]
	v_mfma_f32_16x16x32_bf16 v[50:53], v[158:161], v[166:169], v[50:53]
	v_mfma_f32_16x16x32_bf16 v[38:41], v[150:153], v[184:187], v[38:41]
	v_mfma_f32_16x16x32_bf16 v[34:37], v[158:161], v[184:187], v[34:37]
	s_barrier
	v_mfma_f32_16x16x32_bf16 v[22:25], v[150:153], v[196:199], v[22:25]
	v_mfma_f32_16x16x32_bf16 v[18:21], v[158:161], v[196:199], v[18:21]
	v_mfma_f32_16x16x32_bf16 v[6:9], v[150:153], v[204:207], v[6:9]
	v_mfma_f32_16x16x32_bf16 v[2:5], v[158:161], v[204:207], v[2:5]
	s_add_i32 s77, s77, 2
	s_add_u32 s74, s74, 0x100
	s_addc_u32 s75, s75, 0
	s_add_u32 s57, s57, 0x100
	s_addc_u32 s76, s76, 0
	s_cmp_gt_u32 s77, 29
	s_cbranch_scc0 .LBB0_2097
	s_and_b64 vcc, exec, s[10:11]
	s_cbranch_vccz .LBB0_2100
	s_barrier

; template <class Epi, class Sched, bool ALIGN_EPI = true, bool SP2 = true, bool FULLLINE = false, bool NOSTAGE = false, bool FP8 = false>
; __device__ __forceinline__ void gemm_phase(PG8_LAS unsigned char* lds, const Gemm g, const Sched& S, const Epi& E) {
;     ...
;         const bool has_next = S.next(ui + 1, nxt);
;         const char* nA = has_next ? PG8_ABASE(nxt) : cA; const char* nB = has_next ? PG8_BBASE(nxt) : cB;
.LBB0_2286:
	s_ashr_i32 s63, s62, 31
	s_lshl_b64 s[0:1], s[62:63], 20
	s_add_u32 s66, s58, s0
	ds_read_b128 v[2:5], v1
	ds_read_b128 v[6:9], v1 offset:1024
	ds_read_b128 v[10:13], v1 offset:2048
	ds_read_b128 v[14:17], v1 offset:3072
	ds_read_b128 v[18:21], v142
	ds_read_b128 v[22:25], v142 offset:1024
	ds_read_b128 v[26:29], v142 offset:2048
	ds_read_b128 v[30:33], v142 offset:3072
	s_addc_u32 s67, s59, s1
	s_ashr_i32 s41, s40, 31
	s_lshl_b64 s[0:1], s[40:41], 20
	s_add_u32 s68, s3, s0
	s_addc_u32 s69, s42, s1
	s_and_b64 s[0:1], s[8:9], exec
	s_cselect_b32 s41, s67, s75
	s_cselect_b32 s63, s66, s74
	s_cselect_b32 s87, s69, s73
	s_cselect_b32 s88, s68, s72
	v_lshl_add_u64 v[140:141], s[74:75], 0, v[132:133]
	s_mov_b32 m0, s79
	v_lshl_add_u64 v[66:67], v[140:141], 0, s[12:13]
	ds_read_b128 v[34:37], v143
	ds_read_b128 v[38:41], v143 offset:1024
	ds_read_b128 v[42:45], v143 offset:2048
	ds_read_b128 v[46:49], v143 offset:3072
	ds_read_b128 v[50:53], v143 offset:4096
	ds_read_b128 v[54:57], v143 offset:5120
	ds_read_b128 v[58:61], v143 offset:6144
	ds_read_b128 v[62:65], v143 offset:7168
	global_load_lds_dwordx4 v[66:67], off
	v_lshl_add_u64 v[66:67], v[140:141], 0, s[14:15]
	s_mov_b32 m0, s80
	s_nop 0
	global_load_lds_dwordx4 v[66:67], off
	s_waitcnt vmcnt(16)
	s_waitcnt lgkmcnt(0)
	s_barrier
	s_waitcnt lgkmcnt(0)
	v_mfma_f32_16x16x32_bf16 v[86:89], v[10:13], v[50:53], 0
	v_mfma_f32_16x16x32_bf16 v[90:93], v[14:17], v[54:57], v[86:89]
	v_mfma_f32_16x16x32_bf16 v[86:89], v[2:5], v[58:61], 0
	v_mfma_f32_16x16x32_bf16 v[66:69], v[2:5], v[34:37], 0
	v_mfma_f32_16x16x32_bf16 v[70:73], v[10:13], v[34:37], 0
	v_mfma_f32_16x16x32_bf16 v[74:77], v[2:5], v[42:45], 0
	v_mfma_f32_16x16x32_bf16 v[78:81], v[10:13], v[42:45], 0
	v_mfma_f32_16x16x32_bf16 v[82:85], v[2:5], v[50:53], 0
	v_mfma_f32_16x16x32_bf16 v[94:97], v[6:9], v[62:65], v[86:89]
	v_mfma_f32_16x16x32_bf16 v[86:89], v[10:13], v[58:61], 0
	v_mfma_f32_16x16x32_bf16 v[66:69], v[6:9], v[38:41], v[66:69]
	v_mfma_f32_16x16x32_bf16 v[70:73], v[14:17], v[38:41], v[70:73]
	v_mfma_f32_16x16x32_bf16 v[74:77], v[6:9], v[46:49], v[74:77]
	v_mfma_f32_16x16x32_bf16 v[78:81], v[14:17], v[46:49], v[78:81]
	v_mfma_f32_16x16x32_bf16 v[82:85], v[6:9], v[54:57], v[82:85]
	v_mfma_f32_16x16x32_bf16 v[106:109], v[14:17], v[62:65], v[86:89]
	v_mfma_f32_16x16x32_bf16 v[86:89], v[18:21], v[34:37], 0
	v_mfma_f32_16x16x32_bf16 v[34:37], v[26:29], v[34:37], 0
	v_mfma_f32_16x16x32_bf16 v[110:113], v[22:25], v[38:41], v[86:89]
	v_mfma_f32_16x16x32_bf16 v[34:37], v[30:33], v[38:41], v[34:37]
	v_mfma_f32_16x16x32_bf16 v[38:41], v[18:21], v[42:45], 0
	v_mfma_f32_16x16x32_bf16 v[42:45], v[26:29], v[42:45], 0
	v_mfma_f32_16x16x32_bf16 v[38:41], v[22:25], v[46:49], v[38:41]
	v_mfma_f32_16x16x32_bf16 v[42:45], v[30:33], v[46:49], v[42:45]
	v_mfma_f32_16x16x32_bf16 v[46:49], v[18:21], v[50:53], 0
	v_mfma_f32_16x16x32_bf16 v[50:53], v[26:29], v[50:53], 0
	v_mfma_f32_16x16x32_bf16 v[46:49], v[22:25], v[54:57], v[46:49]
	v_mfma_f32_16x16x32_bf16 v[50:53], v[30:33], v[54:57], v[50:53]
	s_barrier
	v_mfma_f32_16x16x32_bf16 v[54:57], v[18:21], v[58:61], 0
	v_mfma_f32_16x16x32_bf16 v[58:61], v[26:29], v[58:61], 0
	v_mfma_f32_16x16x32_bf16 v[54:57], v[22:25], v[62:65], v[54:57]
	v_mfma_f32_16x16x32_bf16 v[58:61], v[30:33], v[62:65], v[58:61]
	v_lshl_add_u64 v[238:239], s[72:73], 0, v[130:131]
	s_mov_b32 m0, s81
	v_lshl_add_u64 v[146:147], v[238:239], 0, s[16:17]
	s_add_i32 s89, s81, 0x2000
	ds_read_b128 v[62:65], v143 offset:16384
	ds_read_b128 v[86:89], v143 offset:17408
	ds_read_b128 v[98:101], v143 offset:18432
	ds_read_b128 v[102:105], v143 offset:19456
	ds_read_b128 v[114:117], v143 offset:20480
	ds_read_b128 v[118:121], v143 offset:21504
	ds_read_b128 v[122:125], v143 offset:22528
	ds_read_b128 v[126:129], v143 offset:23552
	global_load_lds_dwordx4 v[146:147], off
	v_lshl_add_u64 v[146:147], v[238:239], 0, s[18:19]
	s_mov_b32 m0, s89
	s_add_i32 s90, s78, s43
	global_load_lds_dwordx4 v[146:147], off
	v_lshl_add_u64 v[146:147], v[238:239], 0, s[20:21]
	s_mov_b32 m0, s90
	s_add_i32 s91, s90, 0x2000
	global_load_lds_dwordx4 v[146:147], off
	v_lshl_add_u64 v[146:147], v[238:239], 0, s[22:23]
	s_mov_b32 m0, s91
	s_nop 0
	global_load_lds_dwordx4 v[146:147], off
	v_lshl_add_u64 v[146:147], v[140:141], 0, s[16:17]
	s_mov_b32 m0, s45
	s_nop 0
	global_load_lds_dwordx4 v[146:147], off
	v_lshl_add_u64 v[146:147], v[140:141], 0, s[18:19]
	s_mov_b32 m0, s46
	s_nop 0
	global_load_lds_dwordx4 v[146:147], off
	s_waitcnt vmcnt(16)
	s_waitcnt lgkmcnt(0)
	s_barrier
	s_waitcnt lgkmcnt(0)
	v_mfma_f32_16x16x32_bf16 v[146:149], v[2:5], v[62:65], 0
	v_mfma_f32_16x16x32_bf16 v[154:157], v[2:5], v[98:101], 0
	v_mfma_f32_16x16x32_bf16 v[162:165], v[2:5], v[114:117], 0
	v_mfma_f32_16x16x32_bf16 v[2:5], v[2:5], v[122:125], 0
	v_mfma_f32_16x16x32_bf16 v[146:149], v[6:9], v[86:89], v[146:149]
	v_mfma_f32_16x16x32_bf16 v[154:157], v[6:9], v[102:105], v[154:157]
	v_mfma_f32_16x16x32_bf16 v[162:165], v[6:9], v[118:121], v[162:165]
	v_mfma_f32_16x16x32_bf16 v[2:5], v[6:9], v[126:129], v[2:5]
	v_mfma_f32_16x16x32_bf16 v[6:9], v[10:13], v[122:125], 0
	v_mfma_f32_16x16x32_bf16 v[150:153], v[10:13], v[62:65], 0
	v_mfma_f32_16x16x32_bf16 v[158:161], v[10:13], v[98:101], 0
	v_mfma_f32_16x16x32_bf16 v[166:169], v[10:13], v[114:117], 0
	v_mfma_f32_16x16x32_bf16 v[10:13], v[14:17], v[126:129], v[6:9]
	v_mfma_f32_16x16x32_bf16 v[150:153], v[14:17], v[86:89], v[150:153]
	v_mfma_f32_16x16x32_bf16 v[158:161], v[14:17], v[102:105], v[158:161]
	v_mfma_f32_16x16x32_bf16 v[166:169], v[14:17], v[118:121], v[166:169]
	v_mfma_f32_16x16x32_bf16 v[6:9], v[18:21], v[62:65], 0
	v_mfma_f32_16x16x32_bf16 v[14:17], v[22:25], v[86:89], v[6:9]
	v_mfma_f32_16x16x32_bf16 v[6:9], v[26:29], v[62:65], 0
	v_mfma_f32_16x16x32_bf16 v[170:173], v[30:33], v[86:89], v[6:9]
	v_mfma_f32_16x16x32_bf16 v[6:9], v[18:21], v[98:101], 0
	v_mfma_f32_16x16x32_bf16 v[174:177], v[22:25], v[102:105], v[6:9]
	v_mfma_f32_16x16x32_bf16 v[6:9], v[26:29], v[98:101], 0
	v_mfma_f32_16x16x32_bf16 v[178:181], v[30:33], v[102:105], v[6:9]
	v_mfma_f32_16x16x32_bf16 v[6:9], v[18:21], v[114:117], 0
	v_mfma_f32_16x16x32_bf16 v[182:185], v[22:25], v[118:121], v[6:9]
	v_mfma_f32_16x16x32_bf16 v[6:9], v[26:29], v[114:117], 0
	v_mfma_f32_16x16x32_bf16 v[186:189], v[30:33], v[118:121], v[6:9]
	s_barrier
	v_mfma_f32_16x16x32_bf16 v[6:9], v[18:21], v[122:125], 0
	v_mfma_f32_16x16x32_bf16 v[190:193], v[22:25], v[126:129], v[6:9]
	v_mfma_f32_16x16x32_bf16 v[6:9], v[26:29], v[122:125], 0
	v_mfma_f32_16x16x32_bf16 v[194:197], v[30:33], v[126:129], v[6:9]
	s_nop 5
	ds_read_b128 v[6:9], v144
	ds_read_b128 v[26:29], v144 offset:1024
	ds_read_b128 v[30:33], v144 offset:2048
	ds_read_b128 v[62:65], v144 offset:3072
	ds_read_b128 v[198:201], v145
	ds_read_b128 v[202:205], v145 offset:1024
	ds_read_b128 v[206:209], v145 offset:2048
	ds_read_b128 v[210:213], v145 offset:3072
	s_mov_b32 m0, s47
	v_lshl_add_u64 v[86:87], v[140:141], 0, s[20:21]
	ds_read_b128 v[18:21], v143 offset:32768
	ds_read_b128 v[22:25], v143 offset:33792
	ds_read_b128 v[214:217], v143 offset:34816
	ds_read_b128 v[218:221], v143 offset:35840
	ds_read_b128 v[222:225], v143 offset:36864
	ds_read_b128 v[226:229], v143 offset:37888
	ds_read_b128 v[230:233], v143 offset:38912
	ds_read_b128 v[234:237], v143 offset:39936
	global_load_lds_dwordx4 v[86:87], off
	v_lshl_add_u64 v[86:87], v[140:141], 0, s[22:23]
	s_mov_b32 m0, s52
	s_nop 0
	global_load_lds_dwordx4 v[86:87], off
	s_waitcnt vmcnt(8)
	s_waitcnt lgkmcnt(0)
	s_barrier
	s_waitcnt lgkmcnt(0)
	v_mfma_f32_16x16x32_bf16 v[66:69], v[6:9], v[18:21], v[66:69]
	v_mfma_f32_16x16x32_bf16 v[118:121], v[26:29], v[22:25], v[66:69]
	v_mfma_f32_16x16x32_bf16 v[66:69], v[30:33], v[18:21], v[70:73]
	v_mfma_f32_16x16x32_bf16 v[114:117], v[62:65], v[22:25], v[66:69]
	v_mfma_f32_16x16x32_bf16 v[66:69], v[6:9], v[214:217], v[74:77]
	v_mfma_f32_16x16x32_bf16 v[102:105], v[26:29], v[218:221], v[66:69]
	v_mfma_f32_16x16x32_bf16 v[66:69], v[30:33], v[214:217], v[78:81]
	v_mfma_f32_16x16x32_bf16 v[98:101], v[62:65], v[218:221], v[66:69]
	v_mfma_f32_16x16x32_bf16 v[66:69], v[6:9], v[222:225], v[82:85]
	v_mfma_f32_16x16x32_bf16 v[86:89], v[26:29], v[226:229], v[66:69]
	v_mfma_f32_16x16x32_bf16 v[66:69], v[30:33], v[222:225], v[90:93]
	v_mfma_f32_16x16x32_bf16 v[82:85], v[62:65], v[226:229], v[66:69]
	v_mfma_f32_16x16x32_bf16 v[66:69], v[6:9], v[230:233], v[94:97]
	v_mfma_f32_16x16x32_bf16 v[70:73], v[26:29], v[234:237], v[66:69]
	v_mfma_f32_16x16x32_bf16 v[66:69], v[30:33], v[230:233], v[106:109]
	v_mfma_f32_16x16x32_bf16 v[66:69], v[62:65], v[234:237], v[66:69]
	v_mfma_f32_16x16x32_bf16 v[74:77], v[198:201], v[18:21], v[110:113]
	v_mfma_f32_16x16x32_bf16 v[18:21], v[206:209], v[18:21], v[34:37]
	v_mfma_f32_16x16x32_bf16 v[122:125], v[210:213], v[22:25], v[18:21]
	v_mfma_f32_16x16x32_bf16 v[18:21], v[198:201], v[214:217], v[38:41]
	v_mfma_f32_16x16x32_bf16 v[110:113], v[202:205], v[218:221], v[18:21]
	v_mfma_f32_16x16x32_bf16 v[18:21], v[206:209], v[214:217], v[42:45]
	v_mfma_f32_16x16x32_bf16 v[106:109], v[210:213], v[218:221], v[18:21]
	v_mfma_f32_16x16x32_bf16 v[18:21], v[198:201], v[222:225], v[46:49]
	v_mfma_f32_16x16x32_bf16 v[94:97], v[202:205], v[226:229], v[18:21]
	v_mfma_f32_16x16x32_bf16 v[18:21], v[206:209], v[222:225], v[50:53]
	v_mfma_f32_16x16x32_bf16 v[90:93], v[210:213], v[226:229], v[18:21]
	v_mfma_f32_16x16x32_bf16 v[18:21], v[198:201], v[230:233], v[54:57]
	s_barrier
	v_mfma_f32_16x16x32_bf16 v[78:81], v[202:205], v[234:237], v[18:21]
	v_mfma_f32_16x16x32_bf16 v[18:21], v[206:209], v[230:233], v[58:61]
	v_mfma_f32_16x16x32_bf16 v[126:129], v[202:205], v[22:25], v[74:77]
	v_mfma_f32_16x16x32_bf16 v[74:77], v[210:213], v[234:237], v[18:21]
	s_add_i32 s50, s82, s43
	s_nop 3
	v_lshl_add_u64 v[18:19], v[238:239], 0, s[24:25]
	s_mov_b32 m0, s50
	s_add_i32 s51, s50, 0x2000
	ds_read_b128 v[42:45], v143 offset:49152
	ds_read_b128 v[46:49], v143 offset:50176
	ds_read_b128 v[214:217], v143 offset:51200
	ds_read_b128 v[218:221], v143 offset:52224
	ds_read_b128 v[222:225], v143 offset:53248
	ds_read_b128 v[226:229], v143 offset:54272
	ds_read_b128 v[230:233], v143 offset:55296
	ds_read_b128 v[234:237], v143 offset:56320
	global_load_lds_dwordx4 v[18:19], off
	v_lshl_add_u64 v[18:19], v[238:239], 0, s[26:27]
	s_mov_b32 m0, s51
	s_mov_b64 s[0:1], 0x80180
	s_add_i32 s33, s83, s43
	global_load_lds_dwordx4 v[18:19], off
	v_lshl_add_u64 v[18:19], v[238:239], 0, s[0:1]
	s_mov_b32 m0, s33
	s_mov_b64 s[0:1], 0xc0180
	s_add_i32 s56, s33, 0x2000
	global_load_lds_dwordx4 v[18:19], off
	v_lshl_add_u64 v[18:19], v[238:239], 0, s[0:1]
	s_mov_b32 m0, s56
	s_nop 0
	global_load_lds_dwordx4 v[18:19], off
	v_lshl_add_u64 v[18:19], v[140:141], 0, s[24:25]
	s_mov_b32 m0, s53
	s_nop 0
	global_load_lds_dwordx4 v[18:19], off
	v_lshl_add_u64 v[18:19], v[140:141], 0, s[26:27]
	s_mov_b32 m0, s54
	s_nop 0
	global_load_lds_dwordx4 v[18:19], off
	s_waitcnt vmcnt(8)
	s_waitcnt lgkmcnt(0)
	s_barrier
	s_waitcnt lgkmcnt(0)
	v_mfma_f32_16x16x32_bf16 v[18:21], v[6:9], v[42:45], v[146:149]
	v_mfma_f32_16x16x32_bf16 v[54:57], v[26:29], v[46:49], v[18:21]
	v_mfma_f32_16x16x32_bf16 v[18:21], v[30:33], v[42:45], v[150:153]
	v_mfma_f32_16x16x32_bf16 v[50:53], v[62:65], v[46:49], v[18:21]
	v_mfma_f32_16x16x32_bf16 v[18:21], v[6:9], v[214:217], v[154:157]
	v_mfma_f32_16x16x32_bf16 v[38:41], v[26:29], v[218:221], v[18:21]
	v_mfma_f32_16x16x32_bf16 v[18:21], v[30:33], v[214:217], v[158:161]
	v_mfma_f32_16x16x32_bf16 v[34:37], v[62:65], v[218:221], v[18:21]
	v_mfma_f32_16x16x32_bf16 v[18:21], v[6:9], v[222:225], v[162:165]
	v_mfma_f32_16x16x32_bf16 v[2:5], v[6:9], v[230:233], v[2:5]
	v_mfma_f32_16x16x32_bf16 v[22:25], v[26:29], v[226:229], v[18:21]
	v_mfma_f32_16x16x32_bf16 v[18:21], v[30:33], v[222:225], v[166:169]
	v_mfma_f32_16x16x32_bf16 v[6:9], v[26:29], v[234:237], v[2:5]
	v_mfma_f32_16x16x32_bf16 v[2:5], v[30:33], v[230:233], v[10:13]
	v_mfma_f32_16x16x32_bf16 v[18:21], v[62:65], v[226:229], v[18:21]
	v_mfma_f32_16x16x32_bf16 v[2:5], v[62:65], v[234:237], v[2:5]
	v_mfma_f32_16x16x32_bf16 v[10:13], v[198:201], v[42:45], v[14:17]
	v_mfma_f32_16x16x32_bf16 v[62:65], v[202:205], v[46:49], v[10:13]
	v_mfma_f32_16x16x32_bf16 v[10:13], v[206:209], v[42:45], v[170:173]
	v_mfma_f32_16x16x32_bf16 v[58:61], v[210:213], v[46:49], v[10:13]
	v_mfma_f32_16x16x32_bf16 v[10:13], v[198:201], v[214:217], v[174:177]
	v_mfma_f32_16x16x32_bf16 v[46:49], v[202:205], v[218:221], v[10:13]
	v_mfma_f32_16x16x32_bf16 v[10:13], v[206:209], v[214:217], v[178:181]
	v_mfma_f32_16x16x32_bf16 v[42:45], v[210:213], v[218:221], v[10:13]
	v_mfma_f32_16x16x32_bf16 v[10:13], v[198:201], v[222:225], v[182:185]
	v_mfma_f32_16x16x32_bf16 v[30:33], v[202:205], v[226:229], v[10:13]
	v_mfma_f32_16x16x32_bf16 v[10:13], v[206:209], v[222:225], v[186:189]
	v_mfma_f32_16x16x32_bf16 v[26:29], v[210:213], v[226:229], v[10:13]
	s_barrier
	v_mfma_f32_16x16x32_bf16 v[10:13], v[198:201], v[230:233], v[190:193]
	v_mfma_f32_16x16x32_bf16 v[14:17], v[202:205], v[234:237], v[10:13]
	v_mfma_f32_16x16x32_bf16 v[10:13], v[206:209], v[230:233], v[194:197]
	v_mfma_f32_16x16x32_bf16 v[10:13], v[210:213], v[234:237], v[10:13]
	s_add_u32 s74, s74, 0x80180
	s_addc_u32 s75, s75, 0
	s_add_u32 s57, s72, 0x200
	s_addc_u32 s72, s73, 0
	s_mov_b32 s73, 0
; #define PG8_WAIT_V(n) asm volatile("s_waitcnt vmcnt(" #n ")" ::: "memory")
; template <class Epi, class Sched, bool ALIGN_EPI = true, bool SP2 = true, bool FULLLINE = false, bool NOSTAGE = false, bool FP8 = false>
; __device__ __forceinline__ void gemm_phase(PG8_LAS unsigned char* lds, const Gemm g, const Sched& S, const Epi& E) {
;     ...
;         for (int t = 2; t < nt; t += 2) PG8_ITER(PG8_WAIT_V(8));
.LBB0_2287:
	ds_read_b128 v[146:149], v1
	ds_read_b128 v[150:153], v1 offset:1024
	ds_read_b128 v[154:157], v1 offset:2048
	ds_read_b128 v[158:161], v1 offset:3072
	ds_read_b128 v[162:165], v142
	ds_read_b128 v[166:169], v142 offset:1024
	ds_read_b128 v[170:173], v142 offset:2048
	ds_read_b128 v[174:177], v142 offset:3072
	s_add_u32 s0, s74, 0xfff80080
	s_addc_u32 s1, s75, -1
	s_cmp_eq_u32 s73, 28
	s_cselect_b32 s1, s41, s1
	s_cselect_b32 s0, s63, s0
	s_cselect_b32 s65, s87, s72
	s_cselect_b32 s64, s88, s57
	s_mov_b32 m0, s79
	v_lshl_add_u64 v[140:141], s[74:75], 0, v[134:135]
	ds_read_b128 v[178:181], v143
	ds_read_b128 v[182:185], v143 offset:1024
	ds_read_b128 v[186:189], v143 offset:2048
	ds_read_b128 v[190:193], v143 offset:3072
	ds_read_b128 v[194:197], v143 offset:4096
	ds_read_b128 v[198:201], v143 offset:5120
	ds_read_b128 v[202:205], v143 offset:6144
	ds_read_b128 v[206:209], v143 offset:7168
	global_load_lds_dwordx4 v[140:141], off
	v_lshl_add_u64 v[140:141], v[140:141], 0, s[28:29]
	s_mov_b32 m0, s80
	s_nop 0
	global_load_lds_dwordx4 v[140:141], off
	s_waitcnt vmcnt(8)
	s_waitcnt lgkmcnt(0)
	s_barrier
	s_waitcnt lgkmcnt(0)
	v_mfma_f32_16x16x32_bf16 v[118:121], v[146:149], v[178:181], v[118:121]
	v_mfma_f32_16x16x32_bf16 v[114:117], v[154:157], v[178:181], v[114:117]
	v_mfma_f32_16x16x32_bf16 v[102:105], v[146:149], v[186:189], v[102:105]
	v_mfma_f32_16x16x32_bf16 v[98:101], v[154:157], v[186:189], v[98:101]
	v_mfma_f32_16x16x32_bf16 v[86:89], v[146:149], v[194:197], v[86:89]
	v_mfma_f32_16x16x32_bf16 v[82:85], v[154:157], v[194:197], v[82:85]
	v_mfma_f32_16x16x32_bf16 v[70:73], v[146:149], v[202:205], v[70:73]
	v_mfma_f32_16x16x32_bf16 v[66:69], v[154:157], v[202:205], v[66:69]
	v_mfma_f32_16x16x32_bf16 v[118:121], v[150:153], v[182:185], v[118:121]
	v_mfma_f32_16x16x32_bf16 v[114:117], v[158:161], v[182:185], v[114:117]
	v_mfma_f32_16x16x32_bf16 v[102:105], v[150:153], v[190:193], v[102:105]
	v_mfma_f32_16x16x32_bf16 v[98:101], v[158:161], v[190:193], v[98:101]
	v_mfma_f32_16x16x32_bf16 v[86:89], v[150:153], v[198:201], v[86:89]
	v_mfma_f32_16x16x32_bf16 v[82:85], v[158:161], v[198:201], v[82:85]
	v_mfma_f32_16x16x32_bf16 v[70:73], v[150:153], v[206:209], v[70:73]
	v_mfma_f32_16x16x32_bf16 v[66:69], v[158:161], v[206:209], v[66:69]
	v_mfma_f32_16x16x32_bf16 v[126:129], v[162:165], v[178:181], v[126:129]
	v_mfma_f32_16x16x32_bf16 v[122:125], v[170:173], v[178:181], v[122:125]
	v_mfma_f32_16x16x32_bf16 v[110:113], v[162:165], v[186:189], v[110:113]
	v_mfma_f32_16x16x32_bf16 v[106:109], v[170:173], v[186:189], v[106:109]
	v_mfma_f32_16x16x32_bf16 v[94:97], v[162:165], v[194:197], v[94:97]
	v_mfma_f32_16x16x32_bf16 v[90:93], v[170:173], v[194:197], v[90:93]
	v_mfma_f32_16x16x32_bf16 v[78:81], v[162:165], v[202:205], v[78:81]
	v_mfma_f32_16x16x32_bf16 v[74:77], v[170:173], v[202:205], v[74:77]
	v_mfma_f32_16x16x32_bf16 v[126:129], v[166:169], v[182:185], v[126:129]
	v_mfma_f32_16x16x32_bf16 v[122:125], v[174:177], v[182:185], v[122:125]
	v_mfma_f32_16x16x32_bf16 v[110:113], v[166:169], v[190:193], v[110:113]
	v_mfma_f32_16x16x32_bf16 v[106:109], v[174:177], v[190:193], v[106:109]
	s_barrier
	v_mfma_f32_16x16x32_bf16 v[94:97], v[166:169], v[198:201], v[94:97]
	v_mfma_f32_16x16x32_bf16 v[90:93], v[174:177], v[198:201], v[90:93]
	v_mfma_f32_16x16x32_bf16 v[78:81], v[166:169], v[206:209], v[78:81]
	v_mfma_f32_16x16x32_bf16 v[74:77], v[174:177], v[206:209], v[74:77]
	s_mov_b32 m0, s81
	v_lshl_add_u64 v[140:141], s[64:65], 0, v[130:131]
	ds_read_b128 v[178:181], v143 offset:16384
	ds_read_b128 v[182:185], v143 offset:17408
	ds_read_b128 v[186:189], v143 offset:18432
	ds_read_b128 v[190:193], v143 offset:19456
	ds_read_b128 v[194:197], v143 offset:20480
	ds_read_b128 v[198:201], v143 offset:21504
	ds_read_b128 v[202:205], v143 offset:22528
	ds_read_b128 v[206:209], v143 offset:23552
	global_load_lds_dwordx4 v[140:141], off
	v_lshl_add_u64 v[210:211], v[140:141], 0, s[28:29]
	s_mov_b32 m0, s89
	s_nop 0
	global_load_lds_dwordx4 v[210:211], off
	v_lshl_add_u64 v[210:211], v[140:141], 0, s[30:31]
	s_mov_b32 m0, s90
	s_nop 0
	global_load_lds_dwordx4 v[210:211], off
	v_lshl_add_u64 v[210:211], v[140:141], 0, s[34:35]
	s_mov_b32 m0, s91
	s_nop 0
	global_load_lds_dwordx4 v[210:211], off
	v_lshl_add_u64 v[210:211], s[0:1], 0, v[132:133]
	s_mov_b32 m0, s45
	v_lshl_add_u64 v[212:213], v[210:211], 0, s[28:29]
	global_load_lds_dwordx4 v[210:211], off
	s_mov_b32 m0, s46
	s_nop 0
	global_load_lds_dwordx4 v[212:213], off
	s_waitcnt vmcnt(8)
	s_waitcnt lgkmcnt(0)
	s_barrier
	s_waitcnt lgkmcnt(0)
	v_mfma_f32_16x16x32_bf16 v[54:57], v[146:149], v[178:181], v[54:57]
	v_mfma_f32_16x16x32_bf16 v[50:53], v[154:157], v[178:181], v[50:53]
	v_mfma_f32_16x16x32_bf16 v[38:41], v[146:149], v[186:189], v[38:41]
	v_mfma_f32_16x16x32_bf16 v[34:37], v[154:157], v[186:189], v[34:37]
	v_mfma_f32_16x16x32_bf16 v[22:25], v[146:149], v[194:197], v[22:25]
	v_mfma_f32_16x16x32_bf16 v[18:21], v[154:157], v[194:197], v[18:21]
	v_mfma_f32_16x16x32_bf16 v[6:9], v[146:149], v[202:205], v[6:9]
	v_mfma_f32_16x16x32_bf16 v[2:5], v[154:157], v[202:205], v[2:5]
	v_mfma_f32_16x16x32_bf16 v[54:57], v[150:153], v[182:185], v[54:57]
	v_mfma_f32_16x16x32_bf16 v[50:53], v[158:161], v[182:185], v[50:53]
	v_mfma_f32_16x16x32_bf16 v[38:41], v[150:153], v[190:193], v[38:41]
	v_mfma_f32_16x16x32_bf16 v[34:37], v[158:161], v[190:193], v[34:37]
	v_mfma_f32_16x16x32_bf16 v[22:25], v[150:153], v[198:201], v[22:25]
	v_mfma_f32_16x16x32_bf16 v[18:21], v[158:161], v[198:201], v[18:21]
	v_mfma_f32_16x16x32_bf16 v[6:9], v[150:153], v[206:209], v[6:9]
	v_mfma_f32_16x16x32_bf16 v[2:5], v[158:161], v[206:209], v[2:5]
	v_mfma_f32_16x16x32_bf16 v[62:65], v[162:165], v[178:181], v[62:65]
	v_mfma_f32_16x16x32_bf16 v[58:61], v[170:173], v[178:181], v[58:61]
	v_mfma_f32_16x16x32_bf16 v[46:49], v[162:165], v[186:189], v[46:49]
	v_mfma_f32_16x16x32_bf16 v[42:45], v[170:173], v[186:189], v[42:45]
	v_mfma_f32_16x16x32_bf16 v[30:33], v[162:165], v[194:197], v[30:33]
	v_mfma_f32_16x16x32_bf16 v[26:29], v[170:173], v[194:197], v[26:29]
	v_mfma_f32_16x16x32_bf16 v[14:17], v[162:165], v[202:205], v[14:17]
	v_mfma_f32_16x16x32_bf16 v[10:13], v[170:173], v[202:205], v[10:13]
	v_mfma_f32_16x16x32_bf16 v[62:65], v[166:169], v[182:185], v[62:65]
	v_mfma_f32_16x16x32_bf16 v[58:61], v[174:177], v[182:185], v[58:61]
	v_mfma_f32_16x16x32_bf16 v[46:49], v[166:169], v[190:193], v[46:49]
	v_mfma_f32_16x16x32_bf16 v[42:45], v[174:177], v[190:193], v[42:45]
	s_barrier
	v_mfma_f32_16x16x32_bf16 v[30:33], v[166:169], v[198:201], v[30:33]
	v_mfma_f32_16x16x32_bf16 v[26:29], v[174:177], v[198:201], v[26:29]
	v_mfma_f32_16x16x32_bf16 v[14:17], v[166:169], v[206:209], v[14:17]
	v_mfma_f32_16x16x32_bf16 v[10:13], v[174:177], v[206:209], v[10:13]
	ds_read_b128 v[146:149], v144
	ds_read_b128 v[150:153], v144 offset:1024
	ds_read_b128 v[154:157], v144 offset:2048
	ds_read_b128 v[158:161], v144 offset:3072
	ds_read_b128 v[162:165], v145
	ds_read_b128 v[166:169], v145 offset:1024
	ds_read_b128 v[170:173], v145 offset:2048
	ds_read_b128 v[174:177], v145 offset:3072
	s_mov_b32 m0, s47
	v_lshl_add_u64 v[212:213], v[210:211], 0, s[30:31]
	ds_read_b128 v[178:181], v143 offset:32768
	ds_read_b128 v[182:185], v143 offset:33792
	ds_read_b128 v[186:189], v143 offset:34816
	ds_read_b128 v[190:193], v143 offset:35840
	ds_read_b128 v[194:197], v143 offset:36864
	ds_read_b128 v[198:201], v143 offset:37888
	ds_read_b128 v[202:205], v143 offset:38912
	ds_read_b128 v[206:209], v143 offset:39936
	global_load_lds_dwordx4 v[212:213], off
	v_lshl_add_u64 v[212:213], v[210:211], 0, s[34:35]
	s_mov_b32 m0, s52
	s_nop 0
	global_load_lds_dwordx4 v[212:213], off
	s_waitcnt vmcnt(8)
	s_waitcnt lgkmcnt(0)
	s_barrier
	s_waitcnt lgkmcnt(0)
	v_mfma_f32_16x16x32_bf16 v[118:121], v[146:149], v[178:181], v[118:121]
	v_mfma_f32_16x16x32_bf16 v[114:117], v[154:157], v[178:181], v[114:117]
	v_mfma_f32_16x16x32_bf16 v[102:105], v[146:149], v[186:189], v[102:105]
	v_mfma_f32_16x16x32_bf16 v[98:101], v[154:157], v[186:189], v[98:101]
	v_mfma_f32_16x16x32_bf16 v[86:89], v[146:149], v[194:197], v[86:89]
	v_mfma_f32_16x16x32_bf16 v[82:85], v[154:157], v[194:197], v[82:85]
	v_mfma_f32_16x16x32_bf16 v[70:73], v[146:149], v[202:205], v[70:73]
	v_mfma_f32_16x16x32_bf16 v[66:69], v[154:157], v[202:205], v[66:69]
	v_mfma_f32_16x16x32_bf16 v[118:121], v[150:153], v[182:185], v[118:121]
	v_mfma_f32_16x16x32_bf16 v[114:117], v[158:161], v[182:185], v[114:117]
	v_mfma_f32_16x16x32_bf16 v[102:105], v[150:153], v[190:193], v[102:105]
	v_mfma_f32_16x16x32_bf16 v[98:101], v[158:161], v[190:193], v[98:101]
	v_mfma_f32_16x16x32_bf16 v[86:89], v[150:153], v[198:201], v[86:89]
	v_mfma_f32_16x16x32_bf16 v[82:85], v[158:161], v[198:201], v[82:85]
	v_mfma_f32_16x16x32_bf16 v[70:73], v[150:153], v[206:209], v[70:73]
	v_mfma_f32_16x16x32_bf16 v[66:69], v[158:161], v[206:209], v[66:69]
	v_mfma_f32_16x16x32_bf16 v[126:129], v[162:165], v[178:181], v[126:129]
	v_mfma_f32_16x16x32_bf16 v[122:125], v[170:173], v[178:181], v[122:125]
	v_mfma_f32_16x16x32_bf16 v[110:113], v[162:165], v[186:189], v[110:113]
	v_mfma_f32_16x16x32_bf16 v[106:109], v[170:173], v[186:189], v[106:109]
	v_mfma_f32_16x16x32_bf16 v[94:97], v[162:165], v[194:197], v[94:97]
	v_mfma_f32_16x16x32_bf16 v[90:93], v[170:173], v[194:197], v[90:93]
	v_mfma_f32_16x16x32_bf16 v[78:81], v[162:165], v[202:205], v[78:81]
	v_mfma_f32_16x16x32_bf16 v[74:77], v[170:173], v[202:205], v[74:77]
	v_mfma_f32_16x16x32_bf16 v[126:129], v[166:169], v[182:185], v[126:129]
	v_mfma_f32_16x16x32_bf16 v[122:125], v[174:177], v[182:185], v[122:125]
	v_mfma_f32_16x16x32_bf16 v[110:113], v[166:169], v[190:193], v[110:113]
	v_mfma_f32_16x16x32_bf16 v[106:109], v[174:177], v[190:193], v[106:109]
	s_barrier
; #define PG8_WAIT_V(n) asm volatile("s_waitcnt vmcnt(" #n ")" ::: "memory")
; #define PG8_BAR __builtin_amdgcn_s_barrier()
; template <class Epi, class Sched, bool ALIGN_EPI = true, bool SP2 = true, bool FULLLINE = false, bool NOSTAGE = false, bool FP8 = false>
; __device__ __forceinline__ void gemm_phase(PG8_LAS unsigned char* lds, const Gemm g, const Sched& S, const Epi& E) {
;     ...
;         static_assert(SP2, "only the SP2 loop is kept");
;         { const int t = 0; if constexpr (Epi::NST == 16) PG8_ITER(PG8_WAIT_V(24)); else if constexpr (Epi::NST == 8) PG8_ITER(PG8_WAIT_V(16)); else PG8_ITER(PG8_WAIT_V(8)); }
;         for (int t = 2; t < nt; t += 2) PG8_ITER(PG8_WAIT_V(8));
;     ...
;         if constexpr (ALIGN_EPI) { if (wr == 0) PG8_BAR; }
	v_mfma_f32_16x16x32_bf16 v[94:97], v[166:169], v[198:201], v[94:97]
	v_mfma_f32_16x16x32_bf16 v[90:93], v[174:177], v[198:201], v[90:93]
	v_mfma_f32_16x16x32_bf16 v[78:81], v[166:169], v[206:209], v[78:81]
	v_mfma_f32_16x16x32_bf16 v[74:77], v[174:177], v[206:209], v[74:77]
	s_mov_b32 m0, s50
	v_lshl_add_u64 v[212:213], v[140:141], 0, s[36:37]
	ds_read_b128 v[178:181], v143 offset:49152
	ds_read_b128 v[182:185], v143 offset:50176
	ds_read_b128 v[186:189], v143 offset:51200
	ds_read_b128 v[190:193], v143 offset:52224
	ds_read_b128 v[194:197], v143 offset:53248
	ds_read_b128 v[198:201], v143 offset:54272
	ds_read_b128 v[202:205], v143 offset:55296
	ds_read_b128 v[206:209], v143 offset:56320
	global_load_lds_dwordx4 v[212:213], off
	v_lshl_add_u64 v[212:213], v[140:141], 0, s[38:39]
	s_mov_b32 m0, s51
	s_nop 0
	global_load_lds_dwordx4 v[212:213], off
	v_lshl_add_u64 v[212:213], v[140:141], 0, s[12:13]
	s_mov_b32 m0, s33
	v_lshl_add_u64 v[140:141], v[140:141], 0, s[14:15]
	global_load_lds_dwordx4 v[212:213], off
	s_mov_b32 m0, s56
	s_nop 0
	global_load_lds_dwordx4 v[140:141], off
	v_lshl_add_u64 v[140:141], v[210:211], 0, s[36:37]
	s_mov_b32 m0, s53
	s_nop 0
	global_load_lds_dwordx4 v[140:141], off
	v_lshl_add_u64 v[140:141], v[210:211], 0, s[38:39]
	s_mov_b32 m0, s54
	s_nop 0
	global_load_lds_dwordx4 v[140:141], off
	s_waitcnt vmcnt(8)
	s_waitcnt lgkmcnt(0)
	s_barrier
	s_waitcnt lgkmcnt(0)
	v_mfma_f32_16x16x32_bf16 v[54:57], v[146:149], v[178:181], v[54:57]
	v_mfma_f32_16x16x32_bf16 v[50:53], v[154:157], v[178:181], v[50:53]
	v_mfma_f32_16x16x32_bf16 v[38:41], v[146:149], v[186:189], v[38:41]
	v_mfma_f32_16x16x32_bf16 v[34:37], v[154:157], v[186:189], v[34:37]
	v_mfma_f32_16x16x32_bf16 v[22:25], v[146:149], v[194:197], v[22:25]
	v_mfma_f32_16x16x32_bf16 v[18:21], v[154:157], v[194:197], v[18:21]
	v_mfma_f32_16x16x32_bf16 v[6:9], v[146:149], v[202:205], v[6:9]
	v_mfma_f32_16x16x32_bf16 v[2:5], v[154:157], v[202:205], v[2:5]
	v_mfma_f32_16x16x32_bf16 v[54:57], v[150:153], v[182:185], v[54:57]
	v_mfma_f32_16x16x32_bf16 v[50:53], v[158:161], v[182:185], v[50:53]
	v_mfma_f32_16x16x32_bf16 v[38:41], v[150:153], v[190:193], v[38:41]
	v_mfma_f32_16x16x32_bf16 v[34:37], v[158:161], v[190:193], v[34:37]
	v_mfma_f32_16x16x32_bf16 v[22:25], v[150:153], v[198:201], v[22:25]
	v_mfma_f32_16x16x32_bf16 v[18:21], v[158:161], v[198:201], v[18:21]
	v_mfma_f32_16x16x32_bf16 v[6:9], v[150:153], v[206:209], v[6:9]
	v_mfma_f32_16x16x32_bf16 v[2:5], v[158:161], v[206:209], v[2:5]
	v_mfma_f32_16x16x32_bf16 v[62:65], v[162:165], v[178:181], v[62:65]
	v_mfma_f32_16x16x32_bf16 v[58:61], v[170:173], v[178:181], v[58:61]
	v_mfma_f32_16x16x32_bf16 v[46:49], v[162:165], v[186:189], v[46:49]
	v_mfma_f32_16x16x32_bf16 v[42:45], v[170:173], v[186:189], v[42:45]
	v_mfma_f32_16x16x32_bf16 v[30:33], v[162:165], v[194:197], v[30:33]
	v_mfma_f32_16x16x32_bf16 v[26:29], v[170:173], v[194:197], v[26:29]
	v_mfma_f32_16x16x32_bf16 v[14:17], v[162:165], v[202:205], v[14:17]
	v_mfma_f32_16x16x32_bf16 v[10:13], v[170:173], v[202:205], v[10:13]
	v_mfma_f32_16x16x32_bf16 v[62:65], v[166:169], v[182:185], v[62:65]
	v_mfma_f32_16x16x32_bf16 v[58:61], v[174:177], v[182:185], v[58:61]
	v_mfma_f32_16x16x32_bf16 v[46:49], v[166:169], v[190:193], v[46:49]
	v_mfma_f32_16x16x32_bf16 v[42:45], v[174:177], v[190:193], v[42:45]
	s_barrier
	v_mfma_f32_16x16x32_bf16 v[30:33], v[166:169], v[198:201], v[30:33]
	v_mfma_f32_16x16x32_bf16 v[26:29], v[174:177], v[198:201], v[26:29]
	v_mfma_f32_16x16x32_bf16 v[14:17], v[166:169], v[206:209], v[14:17]
	v_mfma_f32_16x16x32_bf16 v[10:13], v[174:177], v[206:209], v[10:13]
	s_add_i32 s73, s73, 2
	s_add_u32 s74, s74, 0x100
	s_addc_u32 s75, s75, 0
	s_add_u32 s57, s57, 0x100
	s_addc_u32 s72, s72, 0
	s_cmp_gt_u32 s73, 29
	s_cbranch_scc0 .LBB0_2287
	s_and_b64 vcc, exec, s[10:11]
	s_cbranch_vccz .LBB0_2290
	s_barrier

; template <class Epi, class Sched, bool ALIGN_EPI = true, bool SP2 = true, bool FULLLINE = false, bool NOSTAGE = false, bool FP8 = false>
; __device__ __forceinline__ void gemm_phase(PG8_LAS unsigned char* lds, const Gemm g, const Sched& S, const Epi& E) {
;     ...
;         const bool has_next = S.next(ui + 1, nxt);
;         const char* nA = has_next ? PG8_ABASE(nxt) : cA; const char* nB = has_next ? PG8_BBASE(nxt) : cB;
.LBB0_2389:
	ds_read_b128 v[2:5], v1
	ds_read_b128 v[6:9], v1 offset:1024
	ds_read_b128 v[10:13], v1 offset:2048
	ds_read_b128 v[14:17], v1 offset:3072
	ds_read_b128 v[18:21], v192
	ds_read_b128 v[22:25], v192 offset:1024
	ds_read_b128 v[26:29], v192 offset:2048
	ds_read_b128 v[30:33], v192 offset:3072
	v_lshl_add_u64 v[244:245], s[66:67], 0, v[170:171]
	s_add_i32 s83, s45, 0xc000
	v_lshl_add_u64 v[66:67], v[244:245], 0, s[14:15]
	s_mov_b32 m0, s83
	s_add_i32 s84, s45, 0xe000
	ds_read_b128 v[34:37], v193
	ds_read_b128 v[38:41], v193 offset:1024
	ds_read_b128 v[42:45], v193 offset:2048
	ds_read_b128 v[46:49], v193 offset:3072
	ds_read_b128 v[50:53], v193 offset:4096
	ds_read_b128 v[54:57], v193 offset:5120
	ds_read_b128 v[58:61], v193 offset:6144
	ds_read_b128 v[62:65], v193 offset:7168
	global_load_lds_dwordx4 v[66:67], off
	v_lshl_add_u64 v[66:67], v[244:245], 0, s[16:17]
	s_mov_b32 m0, s84
	s_nop 0
	global_load_lds_dwordx4 v[66:67], off
	s_waitcnt vmcnt(24)
	s_waitcnt lgkmcnt(0)
	s_barrier
	s_waitcnt lgkmcnt(0)
	v_mfma_f32_16x16x32_bf16 v[66:69], v[2:5], v[34:37], 0
	v_mfma_f32_16x16x32_bf16 v[70:73], v[10:13], v[34:37], 0
	v_mfma_f32_16x16x32_bf16 v[74:77], v[2:5], v[42:45], 0
	v_mfma_f32_16x16x32_bf16 v[78:81], v[10:13], v[42:45], 0
	v_mfma_f32_16x16x32_bf16 v[90:93], v[2:5], v[58:61], 0
	v_mfma_f32_16x16x32_bf16 v[94:97], v[10:13], v[58:61], 0
	v_mfma_f32_16x16x32_bf16 v[66:69], v[6:9], v[38:41], v[66:69]
	v_mfma_f32_16x16x32_bf16 v[70:73], v[14:17], v[38:41], v[70:73]
	v_mfma_f32_16x16x32_bf16 v[74:77], v[6:9], v[46:49], v[74:77]
	v_mfma_f32_16x16x32_bf16 v[78:81], v[14:17], v[46:49], v[78:81]
	v_mfma_f32_16x16x32_bf16 v[82:85], v[2:5], v[50:53], 0
	v_mfma_f32_16x16x32_bf16 v[86:89], v[10:13], v[50:53], 0
	v_mfma_f32_16x16x32_bf16 v[90:93], v[6:9], v[62:65], v[90:93]
	v_mfma_f32_16x16x32_bf16 v[94:97], v[14:17], v[62:65], v[94:97]
	v_mfma_f32_16x16x32_bf16 v[82:85], v[6:9], v[54:57], v[82:85]
	v_mfma_f32_16x16x32_bf16 v[86:89], v[14:17], v[54:57], v[86:89]
	v_mfma_f32_16x16x32_bf16 v[98:101], v[18:21], v[34:37], 0
	v_mfma_f32_16x16x32_bf16 v[34:37], v[26:29], v[34:37], 0
	v_mfma_f32_16x16x32_bf16 v[98:101], v[22:25], v[38:41], v[98:101]
	v_mfma_f32_16x16x32_bf16 v[34:37], v[30:33], v[38:41], v[34:37]
	v_mfma_f32_16x16x32_bf16 v[38:41], v[18:21], v[42:45], 0
	v_mfma_f32_16x16x32_bf16 v[42:45], v[26:29], v[42:45], 0
	v_mfma_f32_16x16x32_bf16 v[38:41], v[22:25], v[46:49], v[38:41]
	v_mfma_f32_16x16x32_bf16 v[42:45], v[30:33], v[46:49], v[42:45]
	v_mfma_f32_16x16x32_bf16 v[46:49], v[18:21], v[50:53], 0
	v_mfma_f32_16x16x32_bf16 v[50:53], v[26:29], v[50:53], 0
	v_mfma_f32_16x16x32_bf16 v[46:49], v[22:25], v[54:57], v[46:49]
	v_mfma_f32_16x16x32_bf16 v[50:53], v[30:33], v[54:57], v[50:53]
	s_barrier
	v_mfma_f32_16x16x32_bf16 v[54:57], v[18:21], v[58:61], 0
	v_mfma_f32_16x16x32_bf16 v[58:61], v[26:29], v[58:61], 0
	v_mfma_f32_16x16x32_bf16 v[54:57], v[22:25], v[62:65], v[54:57]
	v_mfma_f32_16x16x32_bf16 v[58:61], v[30:33], v[62:65], v[58:61]
	v_lshl_add_u64 v[246:247], s[68:69], 0, v[172:173]
	s_add_i32 s85, s75, s44
	v_lshl_add_u64 v[130:131], v[246:247], 0, s[18:19]
	s_mov_b32 m0, s85
	s_add_i32 s87, s85, 0x2000
	ds_read_b128 v[62:65], v193 offset:16384
	ds_read_b128 v[102:105], v193 offset:17408
	ds_read_b128 v[106:109], v193 offset:18432
	ds_read_b128 v[110:113], v193 offset:19456
	ds_read_b128 v[114:117], v193 offset:20480
	ds_read_b128 v[118:121], v193 offset:21504
	ds_read_b128 v[122:125], v193 offset:22528
	ds_read_b128 v[126:129], v193 offset:23552
	global_load_lds_dwordx4 v[130:131], off
	v_lshl_add_u64 v[130:131], v[246:247], 0, s[20:21]
	s_mov_b32 m0, s87
	s_add_i32 s88, s76, s44
	global_load_lds_dwordx4 v[130:131], off
	v_lshl_add_u64 v[130:131], v[246:247], 0, s[22:23]
	s_mov_b32 m0, s88
	s_add_i32 s89, s88, 0x2000
	global_load_lds_dwordx4 v[130:131], off
	v_lshl_add_u64 v[130:131], v[246:247], 0, s[24:25]
	s_mov_b32 m0, s89
	s_nop 0
	global_load_lds_dwordx4 v[130:131], off
	v_lshl_add_u64 v[130:131], v[244:245], 0, s[18:19]
	s_mov_b32 m0, s45
	s_nop 0
	global_load_lds_dwordx4 v[130:131], off
	v_lshl_add_u64 v[130:131], v[244:245], 0, s[20:21]
	s_mov_b32 m0, s46
	s_nop 0
	global_load_lds_dwordx4 v[130:131], off
	s_waitcnt vmcnt(24)
	s_waitcnt lgkmcnt(0)
	s_barrier
	s_waitcnt lgkmcnt(0)
	v_mfma_f32_16x16x32_bf16 v[130:133], v[2:5], v[62:65], 0
	v_mfma_f32_16x16x32_bf16 v[146:149], v[6:9], v[102:105], v[130:133]
	v_mfma_f32_16x16x32_bf16 v[130:133], v[10:13], v[62:65], 0
	v_mfma_f32_16x16x32_bf16 v[150:153], v[14:17], v[102:105], v[130:133]
	v_mfma_f32_16x16x32_bf16 v[130:133], v[2:5], v[106:109], 0
	v_mfma_f32_16x16x32_bf16 v[154:157], v[6:9], v[110:113], v[130:133]
	v_mfma_f32_16x16x32_bf16 v[130:133], v[10:13], v[106:109], 0
	v_mfma_f32_16x16x32_bf16 v[158:161], v[14:17], v[110:113], v[130:133]
	v_mfma_f32_16x16x32_bf16 v[130:133], v[2:5], v[114:117], 0
	v_mfma_f32_16x16x32_bf16 v[2:5], v[2:5], v[122:125], 0
	v_mfma_f32_16x16x32_bf16 v[162:165], v[6:9], v[118:121], v[130:133]
	v_mfma_f32_16x16x32_bf16 v[2:5], v[6:9], v[126:129], v[2:5]
	v_mfma_f32_16x16x32_bf16 v[6:9], v[10:13], v[122:125], 0
	v_mfma_f32_16x16x32_bf16 v[130:133], v[10:13], v[114:117], 0
	v_mfma_f32_16x16x32_bf16 v[6:9], v[14:17], v[126:129], v[6:9]
	v_mfma_f32_16x16x32_bf16 v[166:169], v[14:17], v[118:121], v[130:133]
	v_mfma_f32_16x16x32_bf16 v[10:13], v[18:21], v[62:65], 0
	v_mfma_f32_16x16x32_bf16 v[180:183], v[22:25], v[102:105], v[10:13]
	v_mfma_f32_16x16x32_bf16 v[10:13], v[26:29], v[62:65], 0
	v_mfma_f32_16x16x32_bf16 v[102:105], v[30:33], v[102:105], v[10:13]
	v_mfma_f32_16x16x32_bf16 v[10:13], v[18:21], v[106:109], 0
	v_mfma_f32_16x16x32_bf16 v[184:187], v[22:25], v[110:113], v[10:13]
	v_mfma_f32_16x16x32_bf16 v[10:13], v[26:29], v[106:109], 0
	v_mfma_f32_16x16x32_bf16 v[188:191], v[30:33], v[110:113], v[10:13]
	v_mfma_f32_16x16x32_bf16 v[10:13], v[18:21], v[114:117], 0
	v_mfma_f32_16x16x32_bf16 v[196:199], v[22:25], v[118:121], v[10:13]
	v_mfma_f32_16x16x32_bf16 v[10:13], v[26:29], v[114:117], 0
	v_mfma_f32_16x16x32_bf16 v[200:203], v[30:33], v[118:121], v[10:13]
	s_barrier
	v_mfma_f32_16x16x32_bf16 v[10:13], v[18:21], v[122:125], 0
	v_mfma_f32_16x16x32_bf16 v[204:207], v[22:25], v[126:129], v[10:13]
	v_mfma_f32_16x16x32_bf16 v[10:13], v[26:29], v[122:125], 0
	v_mfma_f32_16x16x32_bf16 v[208:211], v[30:33], v[126:129], v[10:13]
	s_nop 5
	ds_read_b128 v[10:13], v194
	ds_read_b128 v[14:17], v194 offset:1024
	ds_read_b128 v[18:21], v194 offset:2048
	ds_read_b128 v[22:25], v194 offset:3072
	ds_read_b128 v[212:215], v195
	ds_read_b128 v[216:219], v195 offset:1024
	ds_read_b128 v[220:223], v195 offset:2048
	ds_read_b128 v[224:227], v195 offset:3072
	s_mov_b32 m0, s47
	v_lshl_add_u64 v[106:107], v[244:245], 0, s[22:23]
	ds_read_b128 v[26:29], v193 offset:32768
	ds_read_b128 v[30:33], v193 offset:33792
	ds_read_b128 v[62:65], v193 offset:34816
	ds_read_b128 v[114:117], v193 offset:35840
	ds_read_b128 v[228:231], v193 offset:36864
	ds_read_b128 v[232:235], v193 offset:37888
	ds_read_b128 v[236:239], v193 offset:38912
	ds_read_b128 v[240:243], v193 offset:39936
	global_load_lds_dwordx4 v[106:107], off
	v_lshl_add_u64 v[106:107], v[244:245], 0, s[24:25]
	s_mov_b32 m0, s52
	s_nop 0
	global_load_lds_dwordx4 v[106:107], off
	s_waitcnt vmcnt(8)
	s_waitcnt lgkmcnt(0)
	s_barrier
	s_waitcnt lgkmcnt(0)
	v_mfma_f32_16x16x32_bf16 v[66:69], v[10:13], v[26:29], v[66:69]
	v_mfma_f32_16x16x32_bf16 v[142:145], v[14:17], v[30:33], v[66:69]
	v_mfma_f32_16x16x32_bf16 v[66:69], v[18:21], v[26:29], v[70:73]
	v_mfma_f32_16x16x32_bf16 v[138:141], v[22:25], v[30:33], v[66:69]
	v_mfma_f32_16x16x32_bf16 v[66:69], v[10:13], v[62:65], v[74:77]
	v_mfma_f32_16x16x32_bf16 v[126:129], v[14:17], v[114:117], v[66:69]
	v_mfma_f32_16x16x32_bf16 v[66:69], v[18:21], v[62:65], v[78:81]
	v_mfma_f32_16x16x32_bf16 v[122:125], v[22:25], v[114:117], v[66:69]
	v_mfma_f32_16x16x32_bf16 v[66:69], v[10:13], v[228:231], v[82:85]
	v_mfma_f32_16x16x32_bf16 v[110:113], v[14:17], v[232:235], v[66:69]
	v_mfma_f32_16x16x32_bf16 v[66:69], v[18:21], v[228:231], v[86:89]
	v_mfma_f32_16x16x32_bf16 v[106:109], v[22:25], v[232:235], v[66:69]
	v_mfma_f32_16x16x32_bf16 v[66:69], v[10:13], v[236:239], v[90:93]
	v_mfma_f32_16x16x32_bf16 v[78:81], v[14:17], v[240:243], v[66:69]
	v_mfma_f32_16x16x32_bf16 v[66:69], v[18:21], v[236:239], v[94:97]
	v_mfma_f32_16x16x32_bf16 v[74:77], v[22:25], v[240:243], v[66:69]
	v_mfma_f32_16x16x32_bf16 v[66:69], v[212:215], v[26:29], v[98:101]
	v_mfma_f32_16x16x32_bf16 v[26:29], v[220:223], v[26:29], v[34:37]
	v_mfma_f32_16x16x32_bf16 v[130:133], v[224:227], v[30:33], v[26:29]
	v_mfma_f32_16x16x32_bf16 v[26:29], v[212:215], v[62:65], v[38:41]
	v_mfma_f32_16x16x32_bf16 v[118:121], v[216:219], v[114:117], v[26:29]
	v_mfma_f32_16x16x32_bf16 v[26:29], v[220:223], v[62:65], v[42:45]
	v_mfma_f32_16x16x32_bf16 v[114:117], v[224:227], v[114:117], v[26:29]
	v_mfma_f32_16x16x32_bf16 v[26:29], v[212:215], v[228:231], v[46:49]
	v_mfma_f32_16x16x32_bf16 v[94:97], v[216:219], v[232:235], v[26:29]
	v_mfma_f32_16x16x32_bf16 v[26:29], v[220:223], v[228:231], v[50:53]
	v_mfma_f32_16x16x32_bf16 v[90:93], v[224:227], v[232:235], v[26:29]
	v_mfma_f32_16x16x32_bf16 v[26:29], v[212:215], v[236:239], v[54:57]
	s_barrier
	v_mfma_f32_16x16x32_bf16 v[70:73], v[216:219], v[240:243], v[26:29]
	v_mfma_f32_16x16x32_bf16 v[26:29], v[220:223], v[236:239], v[58:61]
	v_mfma_f32_16x16x32_bf16 v[134:137], v[216:219], v[30:33], v[66:69]
	v_mfma_f32_16x16x32_bf16 v[66:69], v[224:227], v[240:243], v[26:29]
	s_add_i32 s50, s77, s44
	s_nop 3
	v_lshl_add_u64 v[26:27], v[246:247], 0, s[26:27]
	s_mov_b32 m0, s50
	s_add_i32 s51, s50, 0x2000
	ds_read_b128 v[34:37], v193 offset:49152
	ds_read_b128 v[38:41], v193 offset:50176
	ds_read_b128 v[82:85], v193 offset:51200
	ds_read_b128 v[86:89], v193 offset:52224
	ds_read_b128 v[98:101], v193 offset:53248
	ds_read_b128 v[228:231], v193 offset:54272
	ds_read_b128 v[232:235], v193 offset:55296
	ds_read_b128 v[236:239], v193 offset:56320
	global_load_lds_dwordx4 v[26:27], off
	v_lshl_add_u64 v[26:27], v[246:247], 0, s[28:29]
	s_mov_b32 m0, s51
	s_mov_b64 s[0:1], 0x160180
	s_add_i32 s33, s78, s44
	global_load_lds_dwordx4 v[26:27], off
	v_lshl_add_u64 v[26:27], v[246:247], 0, s[0:1]
	s_mov_b32 m0, s33
	s_mov_b64 s[0:1], 0x210180
	s_add_i32 s56, s33, 0x2000
	global_load_lds_dwordx4 v[26:27], off
	v_lshl_add_u64 v[26:27], v[246:247], 0, s[0:1]
	s_mov_b32 m0, s56
	s_nop 0
	global_load_lds_dwordx4 v[26:27], off
	v_lshl_add_u64 v[26:27], v[244:245], 0, s[26:27]
	s_mov_b32 m0, s53
	s_nop 0
	global_load_lds_dwordx4 v[26:27], off
	v_lshl_add_u64 v[26:27], v[244:245], 0, s[28:29]
	s_mov_b32 m0, s54
	s_nop 0
	global_load_lds_dwordx4 v[26:27], off
	s_waitcnt vmcnt(8)
	s_waitcnt lgkmcnt(0)
	s_barrier
	s_waitcnt lgkmcnt(0)
	v_mfma_f32_16x16x32_bf16 v[26:29], v[10:13], v[34:37], v[146:149]
	v_mfma_f32_16x16x32_bf16 v[62:65], v[14:17], v[38:41], v[26:29]
	v_mfma_f32_16x16x32_bf16 v[26:29], v[18:21], v[34:37], v[150:153]
	v_mfma_f32_16x16x32_bf16 v[58:61], v[22:25], v[38:41], v[26:29]
	v_mfma_f32_16x16x32_bf16 v[26:29], v[10:13], v[82:85], v[154:157]
	v_mfma_f32_16x16x32_bf16 v[46:49], v[14:17], v[86:89], v[26:29]
	v_mfma_f32_16x16x32_bf16 v[26:29], v[18:21], v[82:85], v[158:161]
	v_mfma_f32_16x16x32_bf16 v[42:45], v[22:25], v[86:89], v[26:29]
	v_mfma_f32_16x16x32_bf16 v[26:29], v[10:13], v[98:101], v[162:165]
	v_mfma_f32_16x16x32_bf16 v[2:5], v[10:13], v[232:235], v[2:5]
	v_mfma_f32_16x16x32_bf16 v[30:33], v[14:17], v[228:231], v[26:29]
	v_mfma_f32_16x16x32_bf16 v[26:29], v[18:21], v[98:101], v[166:169]
	v_mfma_f32_16x16x32_bf16 v[14:17], v[14:17], v[236:239], v[2:5]
	v_mfma_f32_16x16x32_bf16 v[2:5], v[18:21], v[232:235], v[6:9]
	v_mfma_f32_16x16x32_bf16 v[26:29], v[22:25], v[228:231], v[26:29]
	v_mfma_f32_16x16x32_bf16 v[10:13], v[22:25], v[236:239], v[2:5]
	v_mfma_f32_16x16x32_bf16 v[2:5], v[212:215], v[34:37], v[180:183]
	v_mfma_f32_16x16x32_bf16 v[54:57], v[216:219], v[38:41], v[2:5]
	v_mfma_f32_16x16x32_bf16 v[2:5], v[220:223], v[34:37], v[102:105]
	v_mfma_f32_16x16x32_bf16 v[50:53], v[224:227], v[38:41], v[2:5]
	v_mfma_f32_16x16x32_bf16 v[2:5], v[212:215], v[82:85], v[184:187]
	v_mfma_f32_16x16x32_bf16 v[38:41], v[216:219], v[86:89], v[2:5]
	v_mfma_f32_16x16x32_bf16 v[2:5], v[220:223], v[82:85], v[188:191]
	v_mfma_f32_16x16x32_bf16 v[34:37], v[224:227], v[86:89], v[2:5]
	v_mfma_f32_16x16x32_bf16 v[2:5], v[212:215], v[98:101], v[196:199]
	v_mfma_f32_16x16x32_bf16 v[22:25], v[216:219], v[228:231], v[2:5]
	v_mfma_f32_16x16x32_bf16 v[2:5], v[220:223], v[98:101], v[200:203]
	v_mfma_f32_16x16x32_bf16 v[18:21], v[224:227], v[228:231], v[2:5]
	s_barrier
	v_mfma_f32_16x16x32_bf16 v[2:5], v[212:215], v[232:235], v[204:207]
	v_mfma_f32_16x16x32_bf16 v[6:9], v[216:219], v[236:239], v[2:5]
	v_mfma_f32_16x16x32_bf16 v[2:5], v[220:223], v[232:235], v[208:211]
	v_mfma_f32_16x16x32_bf16 v[2:5], v[224:227], v[236:239], v[2:5]
	s_add_u32 s66, s66, 0x160180
	s_addc_u32 s67, s67, 0
	s_add_u32 s57, s68, 0x200
	s_addc_u32 s68, s69, 0
	s_mov_b32 s69, 0
; #define PG8_WAIT_V(n) asm volatile("s_waitcnt vmcnt(" #n ")" ::: "memory")
; template <class Epi, class Sched, bool ALIGN_EPI = true, bool SP2 = true, bool FULLLINE = false, bool NOSTAGE = false, bool FP8 = false>
; __device__ __forceinline__ void gemm_phase(PG8_LAS unsigned char* lds, const Gemm g, const Sched& S, const Epi& E) {
;     ...
;         for (int t = 2; t < nt; t += 2) PG8_ITER(PG8_WAIT_V(8));
.LBB0_2390:
	ds_read_b128 v[82:85], v1
	ds_read_b128 v[86:89], v1 offset:1024
	ds_read_b128 v[98:101], v1 offset:2048
	ds_read_b128 v[102:105], v1 offset:3072
	ds_read_b128 v[146:149], v192
	ds_read_b128 v[150:153], v192 offset:1024
	ds_read_b128 v[154:157], v192 offset:2048
	ds_read_b128 v[158:161], v192 offset:3072
	s_add_u32 s0, s66, 0xffea0080
	s_addc_u32 s1, s67, -1
	s_cmpk_eq_i32 s69, 0x54
	s_cselect_b32 s1, s11, s1
	s_cselect_b32 s0, s10, s0
	s_cselect_b32 s65, s63, s68
	s_cselect_b32 s64, s62, s57
	s_mov_b32 m0, s83
	v_lshl_add_u64 v[208:209], s[66:67], 0, v[174:175]
	ds_read_b128 v[162:165], v193
	ds_read_b128 v[166:169], v193 offset:1024
	ds_read_b128 v[180:183], v193 offset:2048
	ds_read_b128 v[184:187], v193 offset:3072
	ds_read_b128 v[188:191], v193 offset:4096
	ds_read_b128 v[196:199], v193 offset:5120
	ds_read_b128 v[200:203], v193 offset:6144
	ds_read_b128 v[204:207], v193 offset:7168
	global_load_lds_dwordx4 v[208:209], off
	v_lshl_add_u64 v[208:209], v[208:209], 0, s[30:31]
	s_mov_b32 m0, s84
	s_nop 0
	global_load_lds_dwordx4 v[208:209], off
	s_waitcnt vmcnt(8)
	s_waitcnt lgkmcnt(0)
	s_barrier
	s_waitcnt lgkmcnt(0)
	v_mfma_f32_16x16x32_bf16 v[142:145], v[82:85], v[162:165], v[142:145]
	v_mfma_f32_16x16x32_bf16 v[138:141], v[98:101], v[162:165], v[138:141]
	v_mfma_f32_16x16x32_bf16 v[126:129], v[82:85], v[180:183], v[126:129]
	v_mfma_f32_16x16x32_bf16 v[122:125], v[98:101], v[180:183], v[122:125]
	v_mfma_f32_16x16x32_bf16 v[110:113], v[82:85], v[188:191], v[110:113]
	v_mfma_f32_16x16x32_bf16 v[106:109], v[98:101], v[188:191], v[106:109]
	v_mfma_f32_16x16x32_bf16 v[78:81], v[82:85], v[200:203], v[78:81]
	v_mfma_f32_16x16x32_bf16 v[74:77], v[98:101], v[200:203], v[74:77]
	v_mfma_f32_16x16x32_bf16 v[142:145], v[86:89], v[166:169], v[142:145]
	v_mfma_f32_16x16x32_bf16 v[138:141], v[102:105], v[166:169], v[138:141]
	v_mfma_f32_16x16x32_bf16 v[126:129], v[86:89], v[184:187], v[126:129]
	v_mfma_f32_16x16x32_bf16 v[122:125], v[102:105], v[184:187], v[122:125]
	v_mfma_f32_16x16x32_bf16 v[110:113], v[86:89], v[196:199], v[110:113]
	v_mfma_f32_16x16x32_bf16 v[106:109], v[102:105], v[196:199], v[106:109]
	v_mfma_f32_16x16x32_bf16 v[78:81], v[86:89], v[204:207], v[78:81]
	v_mfma_f32_16x16x32_bf16 v[74:77], v[102:105], v[204:207], v[74:77]
	v_mfma_f32_16x16x32_bf16 v[134:137], v[146:149], v[162:165], v[134:137]
	v_mfma_f32_16x16x32_bf16 v[130:133], v[154:157], v[162:165], v[130:133]
	v_mfma_f32_16x16x32_bf16 v[118:121], v[146:149], v[180:183], v[118:121]
	v_mfma_f32_16x16x32_bf16 v[114:117], v[154:157], v[180:183], v[114:117]
	v_mfma_f32_16x16x32_bf16 v[94:97], v[146:149], v[188:191], v[94:97]
	v_mfma_f32_16x16x32_bf16 v[90:93], v[154:157], v[188:191], v[90:93]
	v_mfma_f32_16x16x32_bf16 v[70:73], v[146:149], v[200:203], v[70:73]
	v_mfma_f32_16x16x32_bf16 v[66:69], v[154:157], v[200:203], v[66:69]
	v_mfma_f32_16x16x32_bf16 v[134:137], v[150:153], v[166:169], v[134:137]
	v_mfma_f32_16x16x32_bf16 v[130:133], v[158:161], v[166:169], v[130:133]
	v_mfma_f32_16x16x32_bf16 v[118:121], v[150:153], v[184:187], v[118:121]
	v_mfma_f32_16x16x32_bf16 v[114:117], v[158:161], v[184:187], v[114:117]
	s_barrier
	v_mfma_f32_16x16x32_bf16 v[94:97], v[150:153], v[196:199], v[94:97]
	v_mfma_f32_16x16x32_bf16 v[90:93], v[158:161], v[196:199], v[90:93]
	v_mfma_f32_16x16x32_bf16 v[70:73], v[150:153], v[204:207], v[70:73]
	v_mfma_f32_16x16x32_bf16 v[66:69], v[158:161], v[204:207], v[66:69]
	s_mov_b32 m0, s85
	v_lshl_add_u64 v[208:209], s[64:65], 0, v[172:173]
	ds_read_b128 v[162:165], v193 offset:16384
	ds_read_b128 v[166:169], v193 offset:17408
	ds_read_b128 v[180:183], v193 offset:18432
	ds_read_b128 v[184:187], v193 offset:19456
	ds_read_b128 v[188:191], v193 offset:20480
	ds_read_b128 v[196:199], v193 offset:21504
	ds_read_b128 v[200:203], v193 offset:22528
	ds_read_b128 v[204:207], v193 offset:23552
	global_load_lds_dwordx4 v[208:209], off
	v_lshl_add_u64 v[210:211], v[208:209], 0, s[30:31]
	s_mov_b32 m0, s87
	s_nop 0
	global_load_lds_dwordx4 v[210:211], off
	v_lshl_add_u64 v[210:211], v[208:209], 0, s[34:35]
	s_mov_b32 m0, s88
	s_nop 0
	global_load_lds_dwordx4 v[210:211], off
	v_lshl_add_u64 v[210:211], v[208:209], 0, s[36:37]
	s_mov_b32 m0, s89
	s_nop 0
	global_load_lds_dwordx4 v[210:211], off
	v_lshl_add_u64 v[210:211], s[0:1], 0, v[170:171]
	s_mov_b32 m0, s45
	v_lshl_add_u64 v[212:213], v[210:211], 0, s[30:31]
	global_load_lds_dwordx4 v[210:211], off
	s_mov_b32 m0, s46
	s_nop 0
	global_load_lds_dwordx4 v[212:213], off
	s_waitcnt vmcnt(8)
	s_waitcnt lgkmcnt(0)
	s_barrier
	s_waitcnt lgkmcnt(0)
	v_mfma_f32_16x16x32_bf16 v[62:65], v[82:85], v[162:165], v[62:65]
	v_mfma_f32_16x16x32_bf16 v[58:61], v[98:101], v[162:165], v[58:61]
	v_mfma_f32_16x16x32_bf16 v[46:49], v[82:85], v[180:183], v[46:49]
	v_mfma_f32_16x16x32_bf16 v[42:45], v[98:101], v[180:183], v[42:45]
	v_mfma_f32_16x16x32_bf16 v[30:33], v[82:85], v[188:191], v[30:33]
	v_mfma_f32_16x16x32_bf16 v[26:29], v[98:101], v[188:191], v[26:29]
	v_mfma_f32_16x16x32_bf16 v[14:17], v[82:85], v[200:203], v[14:17]
	v_mfma_f32_16x16x32_bf16 v[10:13], v[98:101], v[200:203], v[10:13]
	v_mfma_f32_16x16x32_bf16 v[62:65], v[86:89], v[166:169], v[62:65]
	v_mfma_f32_16x16x32_bf16 v[58:61], v[102:105], v[166:169], v[58:61]
	v_mfma_f32_16x16x32_bf16 v[46:49], v[86:89], v[184:187], v[46:49]
	v_mfma_f32_16x16x32_bf16 v[42:45], v[102:105], v[184:187], v[42:45]
	v_mfma_f32_16x16x32_bf16 v[30:33], v[86:89], v[196:199], v[30:33]
	v_mfma_f32_16x16x32_bf16 v[26:29], v[102:105], v[196:199], v[26:29]
	v_mfma_f32_16x16x32_bf16 v[14:17], v[86:89], v[204:207], v[14:17]
	v_mfma_f32_16x16x32_bf16 v[10:13], v[102:105], v[204:207], v[10:13]
	v_mfma_f32_16x16x32_bf16 v[54:57], v[146:149], v[162:165], v[54:57]
	v_mfma_f32_16x16x32_bf16 v[50:53], v[154:157], v[162:165], v[50:53]
	v_mfma_f32_16x16x32_bf16 v[38:41], v[146:149], v[180:183], v[38:41]
	v_mfma_f32_16x16x32_bf16 v[34:37], v[154:157], v[180:183], v[34:37]
	v_mfma_f32_16x16x32_bf16 v[22:25], v[146:149], v[188:191], v[22:25]
	v_mfma_f32_16x16x32_bf16 v[18:21], v[154:157], v[188:191], v[18:21]
	v_mfma_f32_16x16x32_bf16 v[6:9], v[146:149], v[200:203], v[6:9]
	v_mfma_f32_16x16x32_bf16 v[2:5], v[154:157], v[200:203], v[2:5]
	v_mfma_f32_16x16x32_bf16 v[54:57], v[150:153], v[166:169], v[54:57]
	v_mfma_f32_16x16x32_bf16 v[50:53], v[158:161], v[166:169], v[50:53]
	v_mfma_f32_16x16x32_bf16 v[38:41], v[150:153], v[184:187], v[38:41]
	v_mfma_f32_16x16x32_bf16 v[34:37], v[158:161], v[184:187], v[34:37]
	s_barrier
	v_mfma_f32_16x16x32_bf16 v[22:25], v[150:153], v[196:199], v[22:25]
	v_mfma_f32_16x16x32_bf16 v[18:21], v[158:161], v[196:199], v[18:21]
	v_mfma_f32_16x16x32_bf16 v[6:9], v[150:153], v[204:207], v[6:9]
	v_mfma_f32_16x16x32_bf16 v[2:5], v[158:161], v[204:207], v[2:5]
	ds_read_b128 v[82:85], v194
	ds_read_b128 v[86:89], v194 offset:1024
	ds_read_b128 v[98:101], v194 offset:2048
	ds_read_b128 v[102:105], v194 offset:3072
	ds_read_b128 v[146:149], v195
	ds_read_b128 v[150:153], v195 offset:1024
	ds_read_b128 v[154:157], v195 offset:2048
	ds_read_b128 v[158:161], v195 offset:3072
	s_mov_b32 m0, s47
	v_lshl_add_u64 v[212:213], v[210:211], 0, s[34:35]
	ds_read_b128 v[162:165], v193 offset:32768
	ds_read_b128 v[166:169], v193 offset:33792
	ds_read_b128 v[180:183], v193 offset:34816
	ds_read_b128 v[184:187], v193 offset:35840
	ds_read_b128 v[188:191], v193 offset:36864
	ds_read_b128 v[196:199], v193 offset:37888
	ds_read_b128 v[200:203], v193 offset:38912
	ds_read_b128 v[204:207], v193 offset:39936
	global_load_lds_dwordx4 v[212:213], off
	v_lshl_add_u64 v[212:213], v[210:211], 0, s[36:37]
	s_mov_b32 m0, s52
	s_nop 0
	global_load_lds_dwordx4 v[212:213], off
	s_waitcnt vmcnt(8)
	s_waitcnt lgkmcnt(0)
	s_barrier
	s_waitcnt lgkmcnt(0)
	v_mfma_f32_16x16x32_bf16 v[142:145], v[82:85], v[162:165], v[142:145]
	v_mfma_f32_16x16x32_bf16 v[138:141], v[98:101], v[162:165], v[138:141]
	v_mfma_f32_16x16x32_bf16 v[126:129], v[82:85], v[180:183], v[126:129]
	v_mfma_f32_16x16x32_bf16 v[122:125], v[98:101], v[180:183], v[122:125]
	v_mfma_f32_16x16x32_bf16 v[110:113], v[82:85], v[188:191], v[110:113]
	v_mfma_f32_16x16x32_bf16 v[106:109], v[98:101], v[188:191], v[106:109]
	v_mfma_f32_16x16x32_bf16 v[78:81], v[82:85], v[200:203], v[78:81]
	v_mfma_f32_16x16x32_bf16 v[74:77], v[98:101], v[200:203], v[74:77]
	v_mfma_f32_16x16x32_bf16 v[142:145], v[86:89], v[166:169], v[142:145]
	v_mfma_f32_16x16x32_bf16 v[138:141], v[102:105], v[166:169], v[138:141]
	v_mfma_f32_16x16x32_bf16 v[126:129], v[86:89], v[184:187], v[126:129]
	v_mfma_f32_16x16x32_bf16 v[122:125], v[102:105], v[184:187], v[122:125]
	v_mfma_f32_16x16x32_bf16 v[110:113], v[86:89], v[196:199], v[110:113]
	v_mfma_f32_16x16x32_bf16 v[106:109], v[102:105], v[196:199], v[106:109]
	v_mfma_f32_16x16x32_bf16 v[78:81], v[86:89], v[204:207], v[78:81]
	v_mfma_f32_16x16x32_bf16 v[74:77], v[102:105], v[204:207], v[74:77]
	v_mfma_f32_16x16x32_bf16 v[134:137], v[146:149], v[162:165], v[134:137]
	v_mfma_f32_16x16x32_bf16 v[130:133], v[154:157], v[162:165], v[130:133]
	v_mfma_f32_16x16x32_bf16 v[118:121], v[146:149], v[180:183], v[118:121]
	v_mfma_f32_16x16x32_bf16 v[114:117], v[154:157], v[180:183], v[114:117]
	v_mfma_f32_16x16x32_bf16 v[94:97], v[146:149], v[188:191], v[94:97]
	v_mfma_f32_16x16x32_bf16 v[90:93], v[154:157], v[188:191], v[90:93]
	v_mfma_f32_16x16x32_bf16 v[70:73], v[146:149], v[200:203], v[70:73]
	v_mfma_f32_16x16x32_bf16 v[66:69], v[154:157], v[200:203], v[66:69]
	v_mfma_f32_16x16x32_bf16 v[134:137], v[150:153], v[166:169], v[134:137]
	v_mfma_f32_16x16x32_bf16 v[130:133], v[158:161], v[166:169], v[130:133]
	v_mfma_f32_16x16x32_bf16 v[118:121], v[150:153], v[184:187], v[118:121]
	v_mfma_f32_16x16x32_bf16 v[114:117], v[158:161], v[184:187], v[114:117]
	s_barrier
; #define PG8_WAIT_V(n) asm volatile("s_waitcnt vmcnt(" #n ")" ::: "memory")
; #define PG8_BAR __builtin_amdgcn_s_barrier()
; template <class Epi, class Sched, bool ALIGN_EPI = true, bool SP2 = true, bool FULLLINE = false, bool NOSTAGE = false, bool FP8 = false>
; __device__ __forceinline__ void gemm_phase(PG8_LAS unsigned char* lds, const Gemm g, const Sched& S, const Epi& E) {
;     ...
;         static_assert(SP2, "only the SP2 loop is kept");
;         { const int t = 0; if constexpr (Epi::NST == 16) PG8_ITER(PG8_WAIT_V(24)); else if constexpr (Epi::NST == 8) PG8_ITER(PG8_WAIT_V(16)); else PG8_ITER(PG8_WAIT_V(8)); }
;         for (int t = 2; t < nt; t += 2) PG8_ITER(PG8_WAIT_V(8));
;     ...
;         if constexpr (ALIGN_EPI) { if (wr == 0) PG8_BAR; }
	v_mfma_f32_16x16x32_bf16 v[94:97], v[150:153], v[196:199], v[94:97]
	v_mfma_f32_16x16x32_bf16 v[90:93], v[158:161], v[196:199], v[90:93]
	v_mfma_f32_16x16x32_bf16 v[70:73], v[150:153], v[204:207], v[70:73]
	v_mfma_f32_16x16x32_bf16 v[66:69], v[158:161], v[204:207], v[66:69]
	s_mov_b32 m0, s50
	v_lshl_add_u64 v[212:213], v[208:209], 0, s[38:39]
	ds_read_b128 v[162:165], v193 offset:49152
	ds_read_b128 v[166:169], v193 offset:50176
	ds_read_b128 v[180:183], v193 offset:51200
	ds_read_b128 v[184:187], v193 offset:52224
	ds_read_b128 v[188:191], v193 offset:53248
	ds_read_b128 v[196:199], v193 offset:54272
	ds_read_b128 v[200:203], v193 offset:55296
	ds_read_b128 v[204:207], v193 offset:56320
	global_load_lds_dwordx4 v[212:213], off
	v_lshl_add_u64 v[212:213], v[208:209], 0, s[40:41]
	s_mov_b32 m0, s51
	s_nop 0
	global_load_lds_dwordx4 v[212:213], off
	v_lshl_add_u64 v[212:213], v[208:209], 0, s[14:15]
	s_mov_b32 m0, s33
	v_lshl_add_u64 v[208:209], v[208:209], 0, s[16:17]
	global_load_lds_dwordx4 v[212:213], off
	s_mov_b32 m0, s56
	s_nop 0
	global_load_lds_dwordx4 v[208:209], off
	v_lshl_add_u64 v[208:209], v[210:211], 0, s[38:39]
	s_mov_b32 m0, s53
	s_nop 0
	global_load_lds_dwordx4 v[208:209], off
	v_lshl_add_u64 v[208:209], v[210:211], 0, s[40:41]
	s_mov_b32 m0, s54
	s_nop 0
	global_load_lds_dwordx4 v[208:209], off
	s_waitcnt vmcnt(8)
	s_waitcnt lgkmcnt(0)
	s_barrier
	s_waitcnt lgkmcnt(0)
	v_mfma_f32_16x16x32_bf16 v[62:65], v[82:85], v[162:165], v[62:65]
	v_mfma_f32_16x16x32_bf16 v[58:61], v[98:101], v[162:165], v[58:61]
	v_mfma_f32_16x16x32_bf16 v[46:49], v[82:85], v[180:183], v[46:49]
	v_mfma_f32_16x16x32_bf16 v[42:45], v[98:101], v[180:183], v[42:45]
	v_mfma_f32_16x16x32_bf16 v[30:33], v[82:85], v[188:191], v[30:33]
	v_mfma_f32_16x16x32_bf16 v[26:29], v[98:101], v[188:191], v[26:29]
	v_mfma_f32_16x16x32_bf16 v[14:17], v[82:85], v[200:203], v[14:17]
	v_mfma_f32_16x16x32_bf16 v[10:13], v[98:101], v[200:203], v[10:13]
	v_mfma_f32_16x16x32_bf16 v[62:65], v[86:89], v[166:169], v[62:65]
	v_mfma_f32_16x16x32_bf16 v[58:61], v[102:105], v[166:169], v[58:61]
	v_mfma_f32_16x16x32_bf16 v[46:49], v[86:89], v[184:187], v[46:49]
	v_mfma_f32_16x16x32_bf16 v[42:45], v[102:105], v[184:187], v[42:45]
	v_mfma_f32_16x16x32_bf16 v[30:33], v[86:89], v[196:199], v[30:33]
	v_mfma_f32_16x16x32_bf16 v[26:29], v[102:105], v[196:199], v[26:29]
	v_mfma_f32_16x16x32_bf16 v[14:17], v[86:89], v[204:207], v[14:17]
	v_mfma_f32_16x16x32_bf16 v[10:13], v[102:105], v[204:207], v[10:13]
	v_mfma_f32_16x16x32_bf16 v[54:57], v[146:149], v[162:165], v[54:57]
	v_mfma_f32_16x16x32_bf16 v[50:53], v[154:157], v[162:165], v[50:53]
	v_mfma_f32_16x16x32_bf16 v[38:41], v[146:149], v[180:183], v[38:41]
	v_mfma_f32_16x16x32_bf16 v[34:37], v[154:157], v[180:183], v[34:37]
	v_mfma_f32_16x16x32_bf16 v[22:25], v[146:149], v[188:191], v[22:25]
	v_mfma_f32_16x16x32_bf16 v[18:21], v[154:157], v[188:191], v[18:21]
	v_mfma_f32_16x16x32_bf16 v[6:9], v[146:149], v[200:203], v[6:9]
	v_mfma_f32_16x16x32_bf16 v[2:5], v[154:157], v[200:203], v[2:5]
	v_mfma_f32_16x16x32_bf16 v[54:57], v[150:153], v[166:169], v[54:57]
	v_mfma_f32_16x16x32_bf16 v[50:53], v[158:161], v[166:169], v[50:53]
	v_mfma_f32_16x16x32_bf16 v[38:41], v[150:153], v[184:187], v[38:41]
	v_mfma_f32_16x16x32_bf16 v[34:37], v[158:161], v[184:187], v[34:37]
	s_barrier
	v_mfma_f32_16x16x32_bf16 v[22:25], v[150:153], v[196:199], v[22:25]
	v_mfma_f32_16x16x32_bf16 v[18:21], v[158:161], v[196:199], v[18:21]
	v_mfma_f32_16x16x32_bf16 v[6:9], v[150:153], v[204:207], v[6:9]
	v_mfma_f32_16x16x32_bf16 v[2:5], v[158:161], v[204:207], v[2:5]
	s_add_i32 s69, s69, 2
	s_add_u32 s66, s66, 0x100
	s_addc_u32 s67, s67, 0
	s_add_u32 s57, s57, 0x100
	s_addc_u32 s68, s68, 0
	s_cmpk_gt_u32 s69, 0x55
	s_cbranch_scc0 .LBB0_2390
	s_and_b64 vcc, exec, s[12:13]
	s_cbranch_vccz .LBB0_2393
	s_barrier

; template <class Epi, class Sched, bool ALIGN_EPI = true, bool SP2 = true, bool FULLLINE = false, bool NOSTAGE = false, bool FP8 = false>
; __device__ __forceinline__ void gemm_phase(PG8_LAS unsigned char* lds, const Gemm g, const Sched& S, const Epi& E) {
;     ...
;         const bool has_next = S.next(ui + 1, nxt);
;         const char* nA = has_next ? PG8_ABASE(nxt) : cA; const char* nB = has_next ? PG8_BBASE(nxt) : cB;
.LBB0_2681:
	ds_read_b128 v[2:5], v1
	ds_read_b128 v[6:9], v1 offset:1024
	ds_read_b128 v[10:13], v1 offset:2048
	ds_read_b128 v[14:17], v1 offset:3072
	ds_read_b128 v[18:21], v200
	ds_read_b128 v[22:25], v200 offset:1024
	ds_read_b128 v[26:29], v200 offset:2048
	ds_read_b128 v[30:33], v200 offset:3072
	s_ashr_i32 s31, s30, 31
	s_lshl_b64 s[0:1], s[30:31], 18
	s_add_u32 s38, s43, s0
	s_addc_u32 s39, s46, s1
	s_and_b64 s[0:1], s[10:11], exec
	s_cselect_b32 s31, s39, s63
	s_cselect_b32 s35, s38, s62
	v_lshl_add_u64 v[244:245], s[66:67], 0, v[178:179]
	s_mov_b64 s[0:1], 0x80080
	s_add_i32 s79, s41, 0xc000
	v_lshl_add_u64 v[66:67], v[244:245], 0, s[0:1]
	s_mov_b32 m0, s79
	s_mov_b64 s[0:1], 0xc0080
	s_add_i32 s80, s41, 0xe000
	ds_read_b128 v[34:37], v201
	ds_read_b128 v[38:41], v201 offset:1024
	ds_read_b128 v[42:45], v201 offset:2048
	ds_read_b128 v[46:49], v201 offset:3072
	ds_read_b128 v[50:53], v201 offset:4096
	ds_read_b128 v[54:57], v201 offset:5120
	ds_read_b128 v[58:61], v201 offset:6144
	ds_read_b128 v[62:65], v201 offset:7168
	global_load_lds_dwordx4 v[66:67], off
	v_lshl_add_u64 v[66:67], v[244:245], 0, s[0:1]
	s_mov_b32 m0, s80
	s_nop 0
	global_load_lds_dwordx4 v[66:67], off
	s_waitcnt vmcnt(24)
	s_waitcnt lgkmcnt(0)
	s_barrier
	s_waitcnt lgkmcnt(0)
	v_mfma_f32_16x16x32_bf16 v[66:69], v[2:5], v[34:37], 0
	v_mfma_f32_16x16x32_bf16 v[70:73], v[10:13], v[34:37], 0
	v_mfma_f32_16x16x32_bf16 v[74:77], v[2:5], v[42:45], 0
	v_mfma_f32_16x16x32_bf16 v[78:81], v[10:13], v[42:45], 0
	v_mfma_f32_16x16x32_bf16 v[82:85], v[2:5], v[50:53], 0
	v_mfma_f32_16x16x32_bf16 v[90:93], v[2:5], v[58:61], 0
	v_mfma_f32_16x16x32_bf16 v[66:69], v[6:9], v[38:41], v[66:69]
	v_mfma_f32_16x16x32_bf16 v[70:73], v[14:17], v[38:41], v[70:73]
	v_mfma_f32_16x16x32_bf16 v[74:77], v[6:9], v[46:49], v[74:77]
	v_mfma_f32_16x16x32_bf16 v[78:81], v[14:17], v[46:49], v[78:81]
	v_mfma_f32_16x16x32_bf16 v[82:85], v[6:9], v[54:57], v[82:85]
	v_mfma_f32_16x16x32_bf16 v[86:89], v[10:13], v[50:53], 0
	v_mfma_f32_16x16x32_bf16 v[90:93], v[6:9], v[62:65], v[90:93]
	v_mfma_f32_16x16x32_bf16 v[94:97], v[10:13], v[58:61], 0
	v_mfma_f32_16x16x32_bf16 v[86:89], v[14:17], v[54:57], v[86:89]
	v_mfma_f32_16x16x32_bf16 v[94:97], v[14:17], v[62:65], v[94:97]
	v_mfma_f32_16x16x32_bf16 v[98:101], v[18:21], v[34:37], 0
	v_mfma_f32_16x16x32_bf16 v[34:37], v[26:29], v[34:37], 0
	v_mfma_f32_16x16x32_bf16 v[102:105], v[22:25], v[38:41], v[98:101]
	v_mfma_f32_16x16x32_bf16 v[34:37], v[30:33], v[38:41], v[34:37]
	v_mfma_f32_16x16x32_bf16 v[38:41], v[18:21], v[42:45], 0
	v_mfma_f32_16x16x32_bf16 v[42:45], v[26:29], v[42:45], 0
	v_mfma_f32_16x16x32_bf16 v[38:41], v[22:25], v[46:49], v[38:41]
	v_mfma_f32_16x16x32_bf16 v[42:45], v[30:33], v[46:49], v[42:45]
	v_mfma_f32_16x16x32_bf16 v[46:49], v[18:21], v[50:53], 0
	v_mfma_f32_16x16x32_bf16 v[50:53], v[26:29], v[50:53], 0
	v_mfma_f32_16x16x32_bf16 v[46:49], v[22:25], v[54:57], v[46:49]
	v_mfma_f32_16x16x32_bf16 v[50:53], v[30:33], v[54:57], v[50:53]
	s_barrier
	v_mfma_f32_16x16x32_bf16 v[54:57], v[18:21], v[58:61], 0
	v_mfma_f32_16x16x32_bf16 v[58:61], v[26:29], v[58:61], 0
	v_mfma_f32_16x16x32_bf16 v[54:57], v[22:25], v[62:65], v[54:57]
	v_mfma_f32_16x16x32_bf16 v[58:61], v[30:33], v[62:65], v[58:61]
	v_lshl_add_u64 v[246:247], s[62:63], 0, v[180:181]
	s_add_i32 s81, s75, s47
	v_lshl_add_u64 v[130:131], v[246:247], 0, s[18:19]
	s_mov_b32 m0, s81
	s_mov_b64 s[0:1], 0x10100
	s_add_i32 s82, s81, 0x2000
	ds_read_b128 v[62:65], v201 offset:16384
	ds_read_b128 v[98:101], v201 offset:17408
	ds_read_b128 v[106:109], v201 offset:18432
	ds_read_b128 v[110:113], v201 offset:19456
	ds_read_b128 v[114:117], v201 offset:20480
	ds_read_b128 v[118:121], v201 offset:21504
	ds_read_b128 v[122:125], v201 offset:22528
	ds_read_b128 v[126:129], v201 offset:23552
	global_load_lds_dwordx4 v[130:131], off
	v_lshl_add_u64 v[130:131], v[246:247], 0, s[0:1]
	s_mov_b32 m0, s82
	s_mov_b64 s[0:1], 0x20100
	s_add_i32 s83, s76, s47
	global_load_lds_dwordx4 v[130:131], off
	v_lshl_add_u64 v[130:131], v[246:247], 0, s[0:1]
	s_mov_b32 m0, s83
	s_mov_b64 s[0:1], 0x30100
	s_add_i32 s84, s83, 0x2000
	global_load_lds_dwordx4 v[130:131], off
	v_lshl_add_u64 v[130:131], v[246:247], 0, s[0:1]
	s_mov_b32 m0, s84
	s_mov_b64 s[0:1], 0x40100
	global_load_lds_dwordx4 v[130:131], off
	v_lshl_add_u64 v[130:131], v[244:245], 0, s[18:19]
	s_mov_b32 m0, s41
	s_nop 0
	global_load_lds_dwordx4 v[130:131], off
	v_lshl_add_u64 v[130:131], v[244:245], 0, s[0:1]
	s_mov_b32 m0, s45
	s_nop 0
	global_load_lds_dwordx4 v[130:131], off
	s_waitcnt vmcnt(24)
	s_waitcnt lgkmcnt(0)
	s_barrier
	s_waitcnt lgkmcnt(0)
	v_mfma_f32_16x16x32_bf16 v[130:133], v[2:5], v[62:65], 0
	v_mfma_f32_16x16x32_bf16 v[146:149], v[6:9], v[98:101], v[130:133]
	v_mfma_f32_16x16x32_bf16 v[130:133], v[10:13], v[62:65], 0
	v_mfma_f32_16x16x32_bf16 v[150:153], v[14:17], v[98:101], v[130:133]
	v_mfma_f32_16x16x32_bf16 v[130:133], v[2:5], v[106:109], 0
	v_mfma_f32_16x16x32_bf16 v[154:157], v[6:9], v[110:113], v[130:133]
	v_mfma_f32_16x16x32_bf16 v[130:133], v[10:13], v[106:109], 0
	v_mfma_f32_16x16x32_bf16 v[158:161], v[14:17], v[110:113], v[130:133]
	v_mfma_f32_16x16x32_bf16 v[130:133], v[2:5], v[114:117], 0
	v_mfma_f32_16x16x32_bf16 v[2:5], v[2:5], v[122:125], 0
	v_mfma_f32_16x16x32_bf16 v[162:165], v[6:9], v[118:121], v[130:133]
	v_mfma_f32_16x16x32_bf16 v[2:5], v[6:9], v[126:129], v[2:5]
	v_mfma_f32_16x16x32_bf16 v[6:9], v[10:13], v[122:125], 0
	v_mfma_f32_16x16x32_bf16 v[130:133], v[10:13], v[114:117], 0
	v_mfma_f32_16x16x32_bf16 v[6:9], v[14:17], v[126:129], v[6:9]
	v_mfma_f32_16x16x32_bf16 v[166:169], v[14:17], v[118:121], v[130:133]
	v_mfma_f32_16x16x32_bf16 v[10:13], v[18:21], v[62:65], 0
	v_mfma_f32_16x16x32_bf16 v[170:173], v[22:25], v[98:101], v[10:13]
	v_mfma_f32_16x16x32_bf16 v[10:13], v[26:29], v[62:65], 0
	v_mfma_f32_16x16x32_bf16 v[174:177], v[30:33], v[98:101], v[10:13]
	v_mfma_f32_16x16x32_bf16 v[10:13], v[18:21], v[106:109], 0
	v_mfma_f32_16x16x32_bf16 v[188:191], v[22:25], v[110:113], v[10:13]
	v_mfma_f32_16x16x32_bf16 v[10:13], v[26:29], v[106:109], 0
	v_mfma_f32_16x16x32_bf16 v[106:109], v[30:33], v[110:113], v[10:13]
	v_mfma_f32_16x16x32_bf16 v[10:13], v[18:21], v[114:117], 0
	v_mfma_f32_16x16x32_bf16 v[192:195], v[22:25], v[118:121], v[10:13]
	v_mfma_f32_16x16x32_bf16 v[10:13], v[26:29], v[114:117], 0
	v_mfma_f32_16x16x32_bf16 v[196:199], v[30:33], v[118:121], v[10:13]
	s_barrier
	v_mfma_f32_16x16x32_bf16 v[10:13], v[18:21], v[122:125], 0
	v_mfma_f32_16x16x32_bf16 v[204:207], v[22:25], v[126:129], v[10:13]
	v_mfma_f32_16x16x32_bf16 v[10:13], v[26:29], v[122:125], 0
	v_mfma_f32_16x16x32_bf16 v[208:211], v[30:33], v[126:129], v[10:13]
	s_nop 5
	ds_read_b128 v[10:13], v202
	ds_read_b128 v[14:17], v202 offset:1024
	ds_read_b128 v[18:21], v202 offset:2048
	ds_read_b128 v[22:25], v202 offset:3072
	ds_read_b128 v[212:215], v203
	ds_read_b128 v[216:219], v203 offset:1024
	ds_read_b128 v[220:223], v203 offset:2048
	ds_read_b128 v[224:227], v203 offset:3072
	s_mov_b64 s[0:1], 0x80100
	s_mov_b32 m0, s52
	v_lshl_add_u64 v[98:99], v[244:245], 0, s[0:1]
	s_mov_b64 s[0:1], 0xc0100
	ds_read_b128 v[26:29], v201 offset:32768
	ds_read_b128 v[30:33], v201 offset:33792
	ds_read_b128 v[62:65], v201 offset:34816
	ds_read_b128 v[114:117], v201 offset:35840
	ds_read_b128 v[228:231], v201 offset:36864
	ds_read_b128 v[232:235], v201 offset:37888
	ds_read_b128 v[236:239], v201 offset:38912
	ds_read_b128 v[240:243], v201 offset:39936
	global_load_lds_dwordx4 v[98:99], off
	v_lshl_add_u64 v[98:99], v[244:245], 0, s[0:1]
	s_mov_b32 m0, s53
	s_nop 0
	global_load_lds_dwordx4 v[98:99], off
	s_waitcnt vmcnt(8)
	s_waitcnt lgkmcnt(0)
	s_barrier
	s_waitcnt lgkmcnt(0)
	v_mfma_f32_16x16x32_bf16 v[66:69], v[10:13], v[26:29], v[66:69]
	v_mfma_f32_16x16x32_bf16 v[134:137], v[14:17], v[30:33], v[66:69]
	v_mfma_f32_16x16x32_bf16 v[66:69], v[18:21], v[26:29], v[70:73]
	v_mfma_f32_16x16x32_bf16 v[130:133], v[22:25], v[30:33], v[66:69]
	v_mfma_f32_16x16x32_bf16 v[66:69], v[10:13], v[62:65], v[74:77]
	v_mfma_f32_16x16x32_bf16 v[126:129], v[14:17], v[114:117], v[66:69]
	v_mfma_f32_16x16x32_bf16 v[66:69], v[18:21], v[62:65], v[78:81]
	v_mfma_f32_16x16x32_bf16 v[122:125], v[22:25], v[114:117], v[66:69]
	v_mfma_f32_16x16x32_bf16 v[66:69], v[10:13], v[228:231], v[82:85]
	v_mfma_f32_16x16x32_bf16 v[110:113], v[14:17], v[232:235], v[66:69]
	v_mfma_f32_16x16x32_bf16 v[66:69], v[18:21], v[228:231], v[86:89]
	v_mfma_f32_16x16x32_bf16 v[98:101], v[22:25], v[232:235], v[66:69]
	v_mfma_f32_16x16x32_bf16 v[66:69], v[10:13], v[236:239], v[90:93]
	v_mfma_f32_16x16x32_bf16 v[78:81], v[14:17], v[240:243], v[66:69]
	v_mfma_f32_16x16x32_bf16 v[66:69], v[18:21], v[236:239], v[94:97]
	v_mfma_f32_16x16x32_bf16 v[74:77], v[22:25], v[240:243], v[66:69]
	v_mfma_f32_16x16x32_bf16 v[66:69], v[212:215], v[26:29], v[102:105]
	v_mfma_f32_16x16x32_bf16 v[26:29], v[220:223], v[26:29], v[34:37]
	v_mfma_f32_16x16x32_bf16 v[138:141], v[224:227], v[30:33], v[26:29]
	v_mfma_f32_16x16x32_bf16 v[26:29], v[212:215], v[62:65], v[38:41]
	v_mfma_f32_16x16x32_bf16 v[118:121], v[216:219], v[114:117], v[26:29]
	v_mfma_f32_16x16x32_bf16 v[26:29], v[220:223], v[62:65], v[42:45]
	v_mfma_f32_16x16x32_bf16 v[114:117], v[224:227], v[114:117], v[26:29]
	v_mfma_f32_16x16x32_bf16 v[26:29], v[212:215], v[228:231], v[46:49]
	v_mfma_f32_16x16x32_bf16 v[90:93], v[216:219], v[232:235], v[26:29]
	v_mfma_f32_16x16x32_bf16 v[26:29], v[220:223], v[228:231], v[50:53]
	v_mfma_f32_16x16x32_bf16 v[82:85], v[224:227], v[232:235], v[26:29]
	v_mfma_f32_16x16x32_bf16 v[26:29], v[212:215], v[236:239], v[54:57]
	s_barrier
	v_mfma_f32_16x16x32_bf16 v[70:73], v[216:219], v[240:243], v[26:29]
	v_mfma_f32_16x16x32_bf16 v[26:29], v[220:223], v[236:239], v[58:61]
	v_mfma_f32_16x16x32_bf16 v[142:145], v[216:219], v[30:33], v[66:69]
	v_mfma_f32_16x16x32_bf16 v[66:69], v[224:227], v[240:243], v[26:29]
	s_add_i32 s85, s77, s47
	s_nop 3
	v_lshl_add_u64 v[26:27], v[246:247], 0, s[20:21]
	s_mov_b32 m0, s85
	s_mov_b64 s[0:1], 0x10180
	s_add_i32 s87, s85, 0x2000
	ds_read_b128 v[34:37], v201 offset:49152
	ds_read_b128 v[38:41], v201 offset:50176
	ds_read_b128 v[86:89], v201 offset:51200
	ds_read_b128 v[94:97], v201 offset:52224
	ds_read_b128 v[102:105], v201 offset:53248
	ds_read_b128 v[228:231], v201 offset:54272
	ds_read_b128 v[232:235], v201 offset:55296
	ds_read_b128 v[236:239], v201 offset:56320
	global_load_lds_dwordx4 v[26:27], off
	v_lshl_add_u64 v[26:27], v[246:247], 0, s[0:1]
	s_mov_b32 m0, s87
	s_mov_b64 s[0:1], 0x20180
	s_add_i32 s50, s78, s47
	global_load_lds_dwordx4 v[26:27], off
	v_lshl_add_u64 v[26:27], v[246:247], 0, s[0:1]
	s_mov_b32 m0, s50
	s_mov_b64 s[0:1], 0x30180
	s_add_i32 s51, s50, 0x2000
	global_load_lds_dwordx4 v[26:27], off
	v_lshl_add_u64 v[26:27], v[246:247], 0, s[0:1]
	s_mov_b32 m0, s51
	s_mov_b64 s[0:1], 0x40180
	global_load_lds_dwordx4 v[26:27], off
	v_lshl_add_u64 v[26:27], v[244:245], 0, s[20:21]
	s_mov_b32 m0, s54
	s_nop 0
	global_load_lds_dwordx4 v[26:27], off
	v_lshl_add_u64 v[26:27], v[244:245], 0, s[0:1]
	s_mov_b32 m0, s55
	s_nop 0
	global_load_lds_dwordx4 v[26:27], off
	s_waitcnt vmcnt(8)
	s_waitcnt lgkmcnt(0)
	s_barrier
	s_waitcnt lgkmcnt(0)
	v_mfma_f32_16x16x32_bf16 v[26:29], v[10:13], v[34:37], v[146:149]
	v_mfma_f32_16x16x32_bf16 v[62:65], v[14:17], v[38:41], v[26:29]
	v_mfma_f32_16x16x32_bf16 v[26:29], v[18:21], v[34:37], v[150:153]
	v_mfma_f32_16x16x32_bf16 v[58:61], v[22:25], v[38:41], v[26:29]
	v_mfma_f32_16x16x32_bf16 v[26:29], v[10:13], v[86:89], v[154:157]
	v_mfma_f32_16x16x32_bf16 v[46:49], v[14:17], v[94:97], v[26:29]
	v_mfma_f32_16x16x32_bf16 v[26:29], v[18:21], v[86:89], v[158:161]
	v_mfma_f32_16x16x32_bf16 v[42:45], v[22:25], v[94:97], v[26:29]
	v_mfma_f32_16x16x32_bf16 v[26:29], v[10:13], v[102:105], v[162:165]
	v_mfma_f32_16x16x32_bf16 v[2:5], v[10:13], v[232:235], v[2:5]
	v_mfma_f32_16x16x32_bf16 v[30:33], v[14:17], v[228:231], v[26:29]
	v_mfma_f32_16x16x32_bf16 v[26:29], v[18:21], v[102:105], v[166:169]
	v_mfma_f32_16x16x32_bf16 v[14:17], v[14:17], v[236:239], v[2:5]
	v_mfma_f32_16x16x32_bf16 v[2:5], v[18:21], v[232:235], v[6:9]
	v_mfma_f32_16x16x32_bf16 v[26:29], v[22:25], v[228:231], v[26:29]
	v_mfma_f32_16x16x32_bf16 v[10:13], v[22:25], v[236:239], v[2:5]
	v_mfma_f32_16x16x32_bf16 v[2:5], v[212:215], v[34:37], v[170:173]
	v_mfma_f32_16x16x32_bf16 v[54:57], v[216:219], v[38:41], v[2:5]
	v_mfma_f32_16x16x32_bf16 v[2:5], v[220:223], v[34:37], v[174:177]
	v_mfma_f32_16x16x32_bf16 v[50:53], v[224:227], v[38:41], v[2:5]
	v_mfma_f32_16x16x32_bf16 v[2:5], v[212:215], v[86:89], v[188:191]
	v_mfma_f32_16x16x32_bf16 v[38:41], v[216:219], v[94:97], v[2:5]
	v_mfma_f32_16x16x32_bf16 v[2:5], v[220:223], v[86:89], v[106:109]
	v_mfma_f32_16x16x32_bf16 v[34:37], v[224:227], v[94:97], v[2:5]
	v_mfma_f32_16x16x32_bf16 v[2:5], v[212:215], v[102:105], v[192:195]
	v_mfma_f32_16x16x32_bf16 v[22:25], v[216:219], v[228:231], v[2:5]
	v_mfma_f32_16x16x32_bf16 v[2:5], v[220:223], v[102:105], v[196:199]
	v_mfma_f32_16x16x32_bf16 v[18:21], v[224:227], v[228:231], v[2:5]
	s_barrier
	v_mfma_f32_16x16x32_bf16 v[2:5], v[212:215], v[232:235], v[204:207]
	v_mfma_f32_16x16x32_bf16 v[6:9], v[216:219], v[236:239], v[2:5]
	v_mfma_f32_16x16x32_bf16 v[2:5], v[220:223], v[232:235], v[208:211]
	v_mfma_f32_16x16x32_bf16 v[2:5], v[224:227], v[236:239], v[2:5]
	s_add_u32 s10, s66, 0x80180
	s_addc_u32 s11, s67, 0
	s_add_u32 s33, s62, 0x200
	s_addc_u32 s56, s63, 0
	s_mov_b32 s57, 0
.LBB0_2682:
	ds_read_b128 v[86:89], v1
	ds_read_b128 v[94:97], v1 offset:1024
	ds_read_b128 v[102:105], v1 offset:2048
	ds_read_b128 v[106:109], v1 offset:3072
	ds_read_b128 v[146:149], v200
	ds_read_b128 v[150:153], v200 offset:1024
	ds_read_b128 v[154:157], v200 offset:2048
	ds_read_b128 v[158:161], v200 offset:3072
	s_add_u32 s0, s10, 0xfff80080
	s_addc_u32 s1, s11, -1
	s_cmp_eq_u32 s57, 4
	s_cselect_b32 s1, s37, s1
	s_cselect_b32 s0, s36, s0
	s_cselect_b32 s63, s31, s56
	s_cselect_b32 s62, s35, s33
	s_mov_b32 m0, s79
	v_lshl_add_u64 v[208:209], s[10:11], 0, v[182:183]
	ds_read_b128 v[162:165], v201
	ds_read_b128 v[166:169], v201 offset:1024
	ds_read_b128 v[170:173], v201 offset:2048
	ds_read_b128 v[174:177], v201 offset:3072
	ds_read_b128 v[188:191], v201 offset:4096
	ds_read_b128 v[192:195], v201 offset:5120
	ds_read_b128 v[196:199], v201 offset:6144
	ds_read_b128 v[204:207], v201 offset:7168
	global_load_lds_dwordx4 v[208:209], off
	v_lshl_add_u64 v[208:209], v[208:209], 0, s[22:23]
	s_mov_b32 m0, s80
	s_nop 0
	global_load_lds_dwordx4 v[208:209], off
	s_waitcnt vmcnt(8)
	s_waitcnt lgkmcnt(0)
	s_barrier
	s_waitcnt lgkmcnt(0)
	v_mfma_f32_16x16x32_bf16 v[134:137], v[86:89], v[162:165], v[134:137]
	v_mfma_f32_16x16x32_bf16 v[130:133], v[102:105], v[162:165], v[130:133]
	v_mfma_f32_16x16x32_bf16 v[126:129], v[86:89], v[170:173], v[126:129]
	v_mfma_f32_16x16x32_bf16 v[122:125], v[102:105], v[170:173], v[122:125]
	v_mfma_f32_16x16x32_bf16 v[110:113], v[86:89], v[188:191], v[110:113]
	v_mfma_f32_16x16x32_bf16 v[98:101], v[102:105], v[188:191], v[98:101]
	v_mfma_f32_16x16x32_bf16 v[78:81], v[86:89], v[196:199], v[78:81]
	v_mfma_f32_16x16x32_bf16 v[74:77], v[102:105], v[196:199], v[74:77]
	v_mfma_f32_16x16x32_bf16 v[134:137], v[94:97], v[166:169], v[134:137]
	v_mfma_f32_16x16x32_bf16 v[130:133], v[106:109], v[166:169], v[130:133]
	v_mfma_f32_16x16x32_bf16 v[126:129], v[94:97], v[174:177], v[126:129]
	v_mfma_f32_16x16x32_bf16 v[122:125], v[106:109], v[174:177], v[122:125]
	v_mfma_f32_16x16x32_bf16 v[110:113], v[94:97], v[192:195], v[110:113]
	v_mfma_f32_16x16x32_bf16 v[98:101], v[106:109], v[192:195], v[98:101]
	v_mfma_f32_16x16x32_bf16 v[78:81], v[94:97], v[204:207], v[78:81]
	v_mfma_f32_16x16x32_bf16 v[74:77], v[106:109], v[204:207], v[74:77]
	v_mfma_f32_16x16x32_bf16 v[142:145], v[146:149], v[162:165], v[142:145]
	v_mfma_f32_16x16x32_bf16 v[138:141], v[154:157], v[162:165], v[138:141]
	v_mfma_f32_16x16x32_bf16 v[118:121], v[146:149], v[170:173], v[118:121]
	v_mfma_f32_16x16x32_bf16 v[114:117], v[154:157], v[170:173], v[114:117]
	v_mfma_f32_16x16x32_bf16 v[90:93], v[146:149], v[188:191], v[90:93]
	v_mfma_f32_16x16x32_bf16 v[82:85], v[154:157], v[188:191], v[82:85]
	v_mfma_f32_16x16x32_bf16 v[70:73], v[146:149], v[196:199], v[70:73]
	v_mfma_f32_16x16x32_bf16 v[66:69], v[154:157], v[196:199], v[66:69]
	v_mfma_f32_16x16x32_bf16 v[142:145], v[150:153], v[166:169], v[142:145]
	v_mfma_f32_16x16x32_bf16 v[138:141], v[158:161], v[166:169], v[138:141]
	v_mfma_f32_16x16x32_bf16 v[118:121], v[150:153], v[174:177], v[118:121]
	v_mfma_f32_16x16x32_bf16 v[114:117], v[158:161], v[174:177], v[114:117]
	s_barrier
	v_mfma_f32_16x16x32_bf16 v[90:93], v[150:153], v[192:195], v[90:93]
	v_mfma_f32_16x16x32_bf16 v[82:85], v[158:161], v[192:195], v[82:85]
	v_mfma_f32_16x16x32_bf16 v[70:73], v[150:153], v[204:207], v[70:73]
	v_mfma_f32_16x16x32_bf16 v[66:69], v[158:161], v[204:207], v[66:69]
	s_mov_b32 m0, s81
	v_lshl_add_u64 v[208:209], s[62:63], 0, v[180:181]
	s_mov_b64 s[62:63], 0x10000
	ds_read_b128 v[162:165], v201 offset:16384
	ds_read_b128 v[166:169], v201 offset:17408
	ds_read_b128 v[170:173], v201 offset:18432
	ds_read_b128 v[174:177], v201 offset:19456
	ds_read_b128 v[188:191], v201 offset:20480
	ds_read_b128 v[192:195], v201 offset:21504
	ds_read_b128 v[196:199], v201 offset:22528
	ds_read_b128 v[204:207], v201 offset:23552
	global_load_lds_dwordx4 v[208:209], off
	v_lshl_add_u64 v[210:211], v[208:209], 0, s[62:63]
	s_mov_b32 m0, s82
	s_mov_b64 s[62:63], 0x20000
	global_load_lds_dwordx4 v[210:211], off
	v_lshl_add_u64 v[210:211], v[208:209], 0, s[62:63]
	s_mov_b32 m0, s83
	s_mov_b64 s[62:63], 0x30000
	global_load_lds_dwordx4 v[210:211], off
	v_lshl_add_u64 v[210:211], v[208:209], 0, s[62:63]
	s_mov_b32 m0, s84
	s_nop 0
	global_load_lds_dwordx4 v[210:211], off
	v_lshl_add_u64 v[210:211], s[0:1], 0, v[178:179]
	s_mov_b32 m0, s41
	v_lshl_add_u64 v[212:213], v[210:211], 0, s[22:23]
	global_load_lds_dwordx4 v[210:211], off
	s_mov_b32 m0, s45
	s_nop 0
	global_load_lds_dwordx4 v[212:213], off
	s_waitcnt vmcnt(8)
	s_waitcnt lgkmcnt(0)
	s_barrier
	s_waitcnt lgkmcnt(0)
	v_mfma_f32_16x16x32_bf16 v[62:65], v[86:89], v[162:165], v[62:65]
	v_mfma_f32_16x16x32_bf16 v[58:61], v[102:105], v[162:165], v[58:61]
	v_mfma_f32_16x16x32_bf16 v[46:49], v[86:89], v[170:173], v[46:49]
	v_mfma_f32_16x16x32_bf16 v[42:45], v[102:105], v[170:173], v[42:45]
	v_mfma_f32_16x16x32_bf16 v[30:33], v[86:89], v[188:191], v[30:33]
	v_mfma_f32_16x16x32_bf16 v[26:29], v[102:105], v[188:191], v[26:29]
	v_mfma_f32_16x16x32_bf16 v[14:17], v[86:89], v[196:199], v[14:17]
	v_mfma_f32_16x16x32_bf16 v[10:13], v[102:105], v[196:199], v[10:13]
	v_mfma_f32_16x16x32_bf16 v[62:65], v[94:97], v[166:169], v[62:65]
	v_mfma_f32_16x16x32_bf16 v[58:61], v[106:109], v[166:169], v[58:61]
	v_mfma_f32_16x16x32_bf16 v[46:49], v[94:97], v[174:177], v[46:49]
	v_mfma_f32_16x16x32_bf16 v[42:45], v[106:109], v[174:177], v[42:45]
	v_mfma_f32_16x16x32_bf16 v[30:33], v[94:97], v[192:195], v[30:33]
	v_mfma_f32_16x16x32_bf16 v[26:29], v[106:109], v[192:195], v[26:29]
	v_mfma_f32_16x16x32_bf16 v[14:17], v[94:97], v[204:207], v[14:17]
	v_mfma_f32_16x16x32_bf16 v[10:13], v[106:109], v[204:207], v[10:13]
	v_mfma_f32_16x16x32_bf16 v[54:57], v[146:149], v[162:165], v[54:57]
	v_mfma_f32_16x16x32_bf16 v[50:53], v[154:157], v[162:165], v[50:53]
	v_mfma_f32_16x16x32_bf16 v[38:41], v[146:149], v[170:173], v[38:41]
	v_mfma_f32_16x16x32_bf16 v[34:37], v[154:157], v[170:173], v[34:37]
	v_mfma_f32_16x16x32_bf16 v[22:25], v[146:149], v[188:191], v[22:25]
	v_mfma_f32_16x16x32_bf16 v[18:21], v[154:157], v[188:191], v[18:21]
	v_mfma_f32_16x16x32_bf16 v[6:9], v[146:149], v[196:199], v[6:9]
	v_mfma_f32_16x16x32_bf16 v[2:5], v[154:157], v[196:199], v[2:5]
	v_mfma_f32_16x16x32_bf16 v[54:57], v[150:153], v[166:169], v[54:57]
	v_mfma_f32_16x16x32_bf16 v[50:53], v[158:161], v[166:169], v[50:53]
	v_mfma_f32_16x16x32_bf16 v[38:41], v[150:153], v[174:177], v[38:41]
	v_mfma_f32_16x16x32_bf16 v[34:37], v[158:161], v[174:177], v[34:37]
	s_barrier
	v_mfma_f32_16x16x32_bf16 v[22:25], v[150:153], v[192:195], v[22:25]
	v_mfma_f32_16x16x32_bf16 v[18:21], v[158:161], v[192:195], v[18:21]
	v_mfma_f32_16x16x32_bf16 v[6:9], v[150:153], v[204:207], v[6:9]
	v_mfma_f32_16x16x32_bf16 v[2:5], v[158:161], v[204:207], v[2:5]
	ds_read_b128 v[86:89], v202
	ds_read_b128 v[94:97], v202 offset:1024
	ds_read_b128 v[102:105], v202 offset:2048
	ds_read_b128 v[106:109], v202 offset:3072
	ds_read_b128 v[146:149], v203
	ds_read_b128 v[150:153], v203 offset:1024
	ds_read_b128 v[154:157], v203 offset:2048
	ds_read_b128 v[158:161], v203 offset:3072
	s_mov_b32 m0, s52
	v_lshl_add_u64 v[212:213], v[210:211], 0, s[24:25]
	s_mov_b64 s[0:1], 0xc0000
	ds_read_b128 v[162:165], v201 offset:32768
	ds_read_b128 v[166:169], v201 offset:33792
	ds_read_b128 v[170:173], v201 offset:34816
	ds_read_b128 v[174:177], v201 offset:35840
	ds_read_b128 v[188:191], v201 offset:36864
	ds_read_b128 v[192:195], v201 offset:37888
	ds_read_b128 v[196:199], v201 offset:38912
	ds_read_b128 v[204:207], v201 offset:39936
	global_load_lds_dwordx4 v[212:213], off
	v_lshl_add_u64 v[212:213], v[210:211], 0, s[0:1]
	s_mov_b32 m0, s53
	s_nop 0
	global_load_lds_dwordx4 v[212:213], off
	s_waitcnt vmcnt(8)
	s_waitcnt lgkmcnt(0)
	s_barrier
	s_waitcnt lgkmcnt(0)
	v_mfma_f32_16x16x32_bf16 v[134:137], v[86:89], v[162:165], v[134:137]
	v_mfma_f32_16x16x32_bf16 v[130:133], v[102:105], v[162:165], v[130:133]
	v_mfma_f32_16x16x32_bf16 v[126:129], v[86:89], v[170:173], v[126:129]
	v_mfma_f32_16x16x32_bf16 v[122:125], v[102:105], v[170:173], v[122:125]
	v_mfma_f32_16x16x32_bf16 v[110:113], v[86:89], v[188:191], v[110:113]
	v_mfma_f32_16x16x32_bf16 v[98:101], v[102:105], v[188:191], v[98:101]
	v_mfma_f32_16x16x32_bf16 v[78:81], v[86:89], v[196:199], v[78:81]
	v_mfma_f32_16x16x32_bf16 v[74:77], v[102:105], v[196:199], v[74:77]
	v_mfma_f32_16x16x32_bf16 v[134:137], v[94:97], v[166:169], v[134:137]
	v_mfma_f32_16x16x32_bf16 v[130:133], v[106:109], v[166:169], v[130:133]
	v_mfma_f32_16x16x32_bf16 v[126:129], v[94:97], v[174:177], v[126:129]
	v_mfma_f32_16x16x32_bf16 v[122:125], v[106:109], v[174:177], v[122:125]
	v_mfma_f32_16x16x32_bf16 v[110:113], v[94:97], v[192:195], v[110:113]
	v_mfma_f32_16x16x32_bf16 v[98:101], v[106:109], v[192:195], v[98:101]
	v_mfma_f32_16x16x32_bf16 v[78:81], v[94:97], v[204:207], v[78:81]
	v_mfma_f32_16x16x32_bf16 v[74:77], v[106:109], v[204:207], v[74:77]
	v_mfma_f32_16x16x32_bf16 v[142:145], v[146:149], v[162:165], v[142:145]
	v_mfma_f32_16x16x32_bf16 v[138:141], v[154:157], v[162:165], v[138:141]
	v_mfma_f32_16x16x32_bf16 v[118:121], v[146:149], v[170:173], v[118:121]
	v_mfma_f32_16x16x32_bf16 v[114:117], v[154:157], v[170:173], v[114:117]
	v_mfma_f32_16x16x32_bf16 v[90:93], v[146:149], v[188:191], v[90:93]
	v_mfma_f32_16x16x32_bf16 v[82:85], v[154:157], v[188:191], v[82:85]
	v_mfma_f32_16x16x32_bf16 v[70:73], v[146:149], v[196:199], v[70:73]
	v_mfma_f32_16x16x32_bf16 v[66:69], v[154:157], v[196:199], v[66:69]
	v_mfma_f32_16x16x32_bf16 v[142:145], v[150:153], v[166:169], v[142:145]
	v_mfma_f32_16x16x32_bf16 v[138:141], v[158:161], v[166:169], v[138:141]
	v_mfma_f32_16x16x32_bf16 v[118:121], v[150:153], v[174:177], v[118:121]
	v_mfma_f32_16x16x32_bf16 v[114:117], v[158:161], v[174:177], v[114:117]
	s_barrier
	v_mfma_f32_16x16x32_bf16 v[90:93], v[150:153], v[192:195], v[90:93]
	v_mfma_f32_16x16x32_bf16 v[82:85], v[158:161], v[192:195], v[82:85]
	v_mfma_f32_16x16x32_bf16 v[70:73], v[150:153], v[204:207], v[70:73]
	v_mfma_f32_16x16x32_bf16 v[66:69], v[158:161], v[204:207], v[66:69]
	s_mov_b32 m0, s85
	v_lshl_add_u64 v[212:213], v[208:209], 0, s[26:27]
	s_mov_b64 s[0:1], 0x10080
	ds_read_b128 v[162:165], v201 offset:49152
	ds_read_b128 v[166:169], v201 offset:50176
	ds_read_b128 v[170:173], v201 offset:51200
	ds_read_b128 v[174:177], v201 offset:52224
	ds_read_b128 v[188:191], v201 offset:53248
	ds_read_b128 v[192:195], v201 offset:54272
	ds_read_b128 v[196:199], v201 offset:55296
	ds_read_b128 v[204:207], v201 offset:56320
	global_load_lds_dwordx4 v[212:213], off
	v_lshl_add_u64 v[212:213], v[208:209], 0, s[0:1]
	s_mov_b32 m0, s87
	s_mov_b64 s[0:1], 0x20080
	global_load_lds_dwordx4 v[212:213], off
	v_lshl_add_u64 v[212:213], v[208:209], 0, s[0:1]
	s_mov_b32 m0, s50
	s_mov_b64 s[0:1], 0x30080
	global_load_lds_dwordx4 v[212:213], off
	v_lshl_add_u64 v[208:209], v[208:209], 0, s[0:1]
	s_mov_b32 m0, s51
	s_mov_b64 s[0:1], 0x40080
	global_load_lds_dwordx4 v[208:209], off
	v_lshl_add_u64 v[208:209], v[210:211], 0, s[26:27]
	s_mov_b32 m0, s54
	s_nop 0
	global_load_lds_dwordx4 v[208:209], off
	v_lshl_add_u64 v[208:209], v[210:211], 0, s[0:1]
	s_mov_b32 m0, s55
	s_nop 0
	global_load_lds_dwordx4 v[208:209], off
	s_waitcnt vmcnt(8)
	s_waitcnt lgkmcnt(0)
	s_barrier
	s_waitcnt lgkmcnt(0)
	v_mfma_f32_16x16x32_bf16 v[62:65], v[86:89], v[162:165], v[62:65]
	v_mfma_f32_16x16x32_bf16 v[58:61], v[102:105], v[162:165], v[58:61]
	v_mfma_f32_16x16x32_bf16 v[46:49], v[86:89], v[170:173], v[46:49]
	v_mfma_f32_16x16x32_bf16 v[42:45], v[102:105], v[170:173], v[42:45]
	v_mfma_f32_16x16x32_bf16 v[30:33], v[86:89], v[188:191], v[30:33]
	v_mfma_f32_16x16x32_bf16 v[26:29], v[102:105], v[188:191], v[26:29]
	v_mfma_f32_16x16x32_bf16 v[14:17], v[86:89], v[196:199], v[14:17]
	v_mfma_f32_16x16x32_bf16 v[10:13], v[102:105], v[196:199], v[10:13]
	v_mfma_f32_16x16x32_bf16 v[62:65], v[94:97], v[166:169], v[62:65]
	v_mfma_f32_16x16x32_bf16 v[58:61], v[106:109], v[166:169], v[58:61]
	v_mfma_f32_16x16x32_bf16 v[46:49], v[94:97], v[174:177], v[46:49]
	v_mfma_f32_16x16x32_bf16 v[42:45], v[106:109], v[174:177], v[42:45]
	v_mfma_f32_16x16x32_bf16 v[30:33], v[94:97], v[192:195], v[30:33]
	v_mfma_f32_16x16x32_bf16 v[26:29], v[106:109], v[192:195], v[26:29]
	v_mfma_f32_16x16x32_bf16 v[14:17], v[94:97], v[204:207], v[14:17]
	v_mfma_f32_16x16x32_bf16 v[10:13], v[106:109], v[204:207], v[10:13]
	v_mfma_f32_16x16x32_bf16 v[54:57], v[146:149], v[162:165], v[54:57]
	v_mfma_f32_16x16x32_bf16 v[50:53], v[154:157], v[162:165], v[50:53]
	v_mfma_f32_16x16x32_bf16 v[38:41], v[146:149], v[170:173], v[38:41]
	v_mfma_f32_16x16x32_bf16 v[34:37], v[154:157], v[170:173], v[34:37]
	v_mfma_f32_16x16x32_bf16 v[22:25], v[146:149], v[188:191], v[22:25]
	v_mfma_f32_16x16x32_bf16 v[18:21], v[154:157], v[188:191], v[18:21]
	v_mfma_f32_16x16x32_bf16 v[6:9], v[146:149], v[196:199], v[6:9]
	v_mfma_f32_16x16x32_bf16 v[2:5], v[154:157], v[196:199], v[2:5]
	v_mfma_f32_16x16x32_bf16 v[54:57], v[150:153], v[166:169], v[54:57]
	v_mfma_f32_16x16x32_bf16 v[50:53], v[158:161], v[166:169], v[50:53]
	v_mfma_f32_16x16x32_bf16 v[38:41], v[150:153], v[174:177], v[38:41]
	v_mfma_f32_16x16x32_bf16 v[34:37], v[158:161], v[174:177], v[34:37]
	s_barrier
	v_mfma_f32_16x16x32_bf16 v[22:25], v[150:153], v[192:195], v[22:25]
	v_mfma_f32_16x16x32_bf16 v[18:21], v[158:161], v[192:195], v[18:21]
	v_mfma_f32_16x16x32_bf16 v[6:9], v[150:153], v[204:207], v[6:9]
	v_mfma_f32_16x16x32_bf16 v[2:5], v[158:161], v[204:207], v[2:5]
	s_add_i32 s57, s57, 2
	s_add_u32 s10, s10, 0x100
	s_addc_u32 s11, s11, 0
	s_add_u32 s33, s33, 0x100
	s_addc_u32 s56, s56, 0
	s_cmp_gt_u32 s57, 5
	s_cbranch_scc0 .LBB0_2682
	s_and_b64 vcc, exec, s[14:15]
	s_cbranch_vccz .LBB0_2685
	s_barrier

.LBB0_2861:
	s_ashr_i32 s45, s44, 31
	s_lshl_b64 s[0:1], s[44:45], 20
	s_add_u32 s46, s58, s0
	ds_read_b128 v[2:5], v1
	ds_read_b128 v[6:9], v1 offset:1024
	ds_read_b128 v[10:13], v1 offset:2048
	ds_read_b128 v[14:17], v1 offset:3072
	ds_read_b128 v[18:21], v142
	ds_read_b128 v[22:25], v142 offset:1024
	ds_read_b128 v[26:29], v142 offset:2048
	ds_read_b128 v[30:33], v142 offset:3072
	s_addc_u32 s47, s59, s1
	s_ashr_i32 s41, s40, 31
	s_lshl_b64 s[0:1], s[40:41], 20
	s_add_u32 s62, s3, s0
	s_addc_u32 s63, s42, s1
	s_and_b64 s[0:1], s[8:9], exec
	s_cselect_b32 s41, s47, s71
	s_cselect_b32 s45, s46, s70
	s_cselect_b32 s87, s63, s69
	s_cselect_b32 s88, s62, s68
	v_lshl_add_u64 v[140:141], s[70:71], 0, v[132:133]
	s_mov_b32 m0, s79
	v_lshl_add_u64 v[66:67], v[140:141], 0, s[12:13]
	ds_read_b128 v[34:37], v143
	ds_read_b128 v[38:41], v143 offset:1024
	ds_read_b128 v[42:45], v143 offset:2048
	ds_read_b128 v[46:49], v143 offset:3072
	ds_read_b128 v[50:53], v143 offset:4096
	ds_read_b128 v[54:57], v143 offset:5120
	ds_read_b128 v[58:61], v143 offset:6144
	ds_read_b128 v[62:65], v143 offset:7168
	global_load_lds_dwordx4 v[66:67], off
	v_lshl_add_u64 v[66:67], v[140:141], 0, s[14:15]
	s_mov_b32 m0, s80
	s_nop 0
	global_load_lds_dwordx4 v[66:67], off
	s_waitcnt vmcnt(16)
	s_waitcnt lgkmcnt(0)
	s_barrier
	s_waitcnt lgkmcnt(0)
	v_mfma_f32_16x16x32_bf16 v[86:89], v[10:13], v[50:53], 0
	v_mfma_f32_16x16x32_bf16 v[90:93], v[14:17], v[54:57], v[86:89]
	v_mfma_f32_16x16x32_bf16 v[86:89], v[2:5], v[58:61], 0
	v_mfma_f32_16x16x32_bf16 v[66:69], v[2:5], v[34:37], 0
	v_mfma_f32_16x16x32_bf16 v[70:73], v[10:13], v[34:37], 0
	v_mfma_f32_16x16x32_bf16 v[74:77], v[2:5], v[42:45], 0
	v_mfma_f32_16x16x32_bf16 v[78:81], v[10:13], v[42:45], 0
	v_mfma_f32_16x16x32_bf16 v[82:85], v[2:5], v[50:53], 0
	v_mfma_f32_16x16x32_bf16 v[94:97], v[6:9], v[62:65], v[86:89]
	v_mfma_f32_16x16x32_bf16 v[86:89], v[10:13], v[58:61], 0
	v_mfma_f32_16x16x32_bf16 v[66:69], v[6:9], v[38:41], v[66:69]
	v_mfma_f32_16x16x32_bf16 v[70:73], v[14:17], v[38:41], v[70:73]
	v_mfma_f32_16x16x32_bf16 v[74:77], v[6:9], v[46:49], v[74:77]
	v_mfma_f32_16x16x32_bf16 v[78:81], v[14:17], v[46:49], v[78:81]
	v_mfma_f32_16x16x32_bf16 v[82:85], v[6:9], v[54:57], v[82:85]
	v_mfma_f32_16x16x32_bf16 v[106:109], v[14:17], v[62:65], v[86:89]
	v_mfma_f32_16x16x32_bf16 v[86:89], v[18:21], v[34:37], 0
	v_mfma_f32_16x16x32_bf16 v[34:37], v[26:29], v[34:37], 0
	v_mfma_f32_16x16x32_bf16 v[110:113], v[22:25], v[38:41], v[86:89]
	v_mfma_f32_16x16x32_bf16 v[34:37], v[30:33], v[38:41], v[34:37]
	v_mfma_f32_16x16x32_bf16 v[38:41], v[18:21], v[42:45], 0
	v_mfma_f32_16x16x32_bf16 v[42:45], v[26:29], v[42:45], 0
	v_mfma_f32_16x16x32_bf16 v[38:41], v[22:25], v[46:49], v[38:41]
	v_mfma_f32_16x16x32_bf16 v[42:45], v[30:33], v[46:49], v[42:45]
	v_mfma_f32_16x16x32_bf16 v[46:49], v[18:21], v[50:53], 0
	v_mfma_f32_16x16x32_bf16 v[50:53], v[26:29], v[50:53], 0
	v_mfma_f32_16x16x32_bf16 v[46:49], v[22:25], v[54:57], v[46:49]
	v_mfma_f32_16x16x32_bf16 v[50:53], v[30:33], v[54:57], v[50:53]
	s_barrier
	v_mfma_f32_16x16x32_bf16 v[54:57], v[18:21], v[58:61], 0
	v_mfma_f32_16x16x32_bf16 v[58:61], v[26:29], v[58:61], 0
	v_mfma_f32_16x16x32_bf16 v[54:57], v[22:25], v[62:65], v[54:57]
	v_mfma_f32_16x16x32_bf16 v[58:61], v[30:33], v[62:65], v[58:61]
	v_lshl_add_u64 v[238:239], s[68:69], 0, v[130:131]
	s_mov_b32 m0, s81
	v_lshl_add_u64 v[146:147], v[238:239], 0, s[16:17]
	s_add_i32 s89, s81, 0x2000
	ds_read_b128 v[62:65], v143 offset:16384
	ds_read_b128 v[86:89], v143 offset:17408
	ds_read_b128 v[98:101], v143 offset:18432
	ds_read_b128 v[102:105], v143 offset:19456
	ds_read_b128 v[114:117], v143 offset:20480
	ds_read_b128 v[118:121], v143 offset:21504
	ds_read_b128 v[122:125], v143 offset:22528
	ds_read_b128 v[126:129], v143 offset:23552
	global_load_lds_dwordx4 v[146:147], off
	v_lshl_add_u64 v[146:147], v[238:239], 0, s[18:19]
	s_mov_b32 m0, s89
	s_add_i32 s90, s78, s43
	global_load_lds_dwordx4 v[146:147], off
	v_lshl_add_u64 v[146:147], v[238:239], 0, s[20:21]
	s_mov_b32 m0, s90
	s_add_i32 s91, s90, 0x2000
	global_load_lds_dwordx4 v[146:147], off
	v_lshl_add_u64 v[146:147], v[238:239], 0, s[22:23]
	s_mov_b32 m0, s91
	s_nop 0
	global_load_lds_dwordx4 v[146:147], off
	v_lshl_add_u64 v[146:147], v[140:141], 0, s[16:17]
	s_mov_b32 m0, s53
	s_nop 0
	global_load_lds_dwordx4 v[146:147], off
	v_lshl_add_u64 v[146:147], v[140:141], 0, s[18:19]
	s_mov_b32 m0, s54
	s_nop 0
	global_load_lds_dwordx4 v[146:147], off
	s_waitcnt vmcnt(16)
	s_waitcnt lgkmcnt(0)
	s_barrier
	s_waitcnt lgkmcnt(0)
	v_mfma_f32_16x16x32_bf16 v[146:149], v[2:5], v[62:65], 0
	v_mfma_f32_16x16x32_bf16 v[154:157], v[2:5], v[98:101], 0
	v_mfma_f32_16x16x32_bf16 v[162:165], v[2:5], v[114:117], 0
	v_mfma_f32_16x16x32_bf16 v[2:5], v[2:5], v[122:125], 0
	v_mfma_f32_16x16x32_bf16 v[146:149], v[6:9], v[86:89], v[146:149]
	v_mfma_f32_16x16x32_bf16 v[154:157], v[6:9], v[102:105], v[154:157]
	v_mfma_f32_16x16x32_bf16 v[162:165], v[6:9], v[118:121], v[162:165]
	v_mfma_f32_16x16x32_bf16 v[2:5], v[6:9], v[126:129], v[2:5]
	v_mfma_f32_16x16x32_bf16 v[6:9], v[10:13], v[122:125], 0
	v_mfma_f32_16x16x32_bf16 v[150:153], v[10:13], v[62:65], 0
	v_mfma_f32_16x16x32_bf16 v[158:161], v[10:13], v[98:101], 0
	v_mfma_f32_16x16x32_bf16 v[166:169], v[10:13], v[114:117], 0
	v_mfma_f32_16x16x32_bf16 v[10:13], v[14:17], v[126:129], v[6:9]
	v_mfma_f32_16x16x32_bf16 v[150:153], v[14:17], v[86:89], v[150:153]
	v_mfma_f32_16x16x32_bf16 v[158:161], v[14:17], v[102:105], v[158:161]
	v_mfma_f32_16x16x32_bf16 v[166:169], v[14:17], v[118:121], v[166:169]
	v_mfma_f32_16x16x32_bf16 v[6:9], v[18:21], v[62:65], 0
	v_mfma_f32_16x16x32_bf16 v[14:17], v[22:25], v[86:89], v[6:9]
	v_mfma_f32_16x16x32_bf16 v[6:9], v[26:29], v[62:65], 0
	v_mfma_f32_16x16x32_bf16 v[170:173], v[30:33], v[86:89], v[6:9]
	v_mfma_f32_16x16x32_bf16 v[6:9], v[18:21], v[98:101], 0
	v_mfma_f32_16x16x32_bf16 v[174:177], v[22:25], v[102:105], v[6:9]
	v_mfma_f32_16x16x32_bf16 v[6:9], v[26:29], v[98:101], 0
	v_mfma_f32_16x16x32_bf16 v[178:181], v[30:33], v[102:105], v[6:9]
	v_mfma_f32_16x16x32_bf16 v[6:9], v[18:21], v[114:117], 0
	v_mfma_f32_16x16x32_bf16 v[182:185], v[22:25], v[118:121], v[6:9]
	v_mfma_f32_16x16x32_bf16 v[6:9], v[26:29], v[114:117], 0
	v_mfma_f32_16x16x32_bf16 v[186:189], v[30:33], v[118:121], v[6:9]
	s_barrier
	v_mfma_f32_16x16x32_bf16 v[6:9], v[18:21], v[122:125], 0
	v_mfma_f32_16x16x32_bf16 v[190:193], v[22:25], v[126:129], v[6:9]
	v_mfma_f32_16x16x32_bf16 v[6:9], v[26:29], v[122:125], 0
	v_mfma_f32_16x16x32_bf16 v[194:197], v[30:33], v[126:129], v[6:9]
	s_nop 5
	ds_read_b128 v[6:9], v144
	ds_read_b128 v[26:29], v144 offset:1024
	ds_read_b128 v[30:33], v144 offset:2048
	ds_read_b128 v[62:65], v144 offset:3072
	ds_read_b128 v[198:201], v145
	ds_read_b128 v[202:205], v145 offset:1024
	ds_read_b128 v[206:209], v145 offset:2048
	ds_read_b128 v[210:213], v145 offset:3072
	s_mov_b32 m0, s55
	v_lshl_add_u64 v[86:87], v[140:141], 0, s[20:21]
	ds_read_b128 v[18:21], v143 offset:32768
	ds_read_b128 v[22:25], v143 offset:33792
	ds_read_b128 v[214:217], v143 offset:34816
	ds_read_b128 v[218:221], v143 offset:35840
	ds_read_b128 v[222:225], v143 offset:36864
	ds_read_b128 v[226:229], v143 offset:37888
	ds_read_b128 v[230:233], v143 offset:38912
	ds_read_b128 v[234:237], v143 offset:39936
	global_load_lds_dwordx4 v[86:87], off
	v_lshl_add_u64 v[86:87], v[140:141], 0, s[22:23]
	s_mov_b32 m0, s67
	s_nop 0
	global_load_lds_dwordx4 v[86:87], off
	s_waitcnt vmcnt(8)
	s_waitcnt lgkmcnt(0)
	s_barrier
	s_waitcnt lgkmcnt(0)
	v_mfma_f32_16x16x32_bf16 v[66:69], v[6:9], v[18:21], v[66:69]
	v_mfma_f32_16x16x32_bf16 v[118:121], v[26:29], v[22:25], v[66:69]
	v_mfma_f32_16x16x32_bf16 v[66:69], v[30:33], v[18:21], v[70:73]
	v_mfma_f32_16x16x32_bf16 v[114:117], v[62:65], v[22:25], v[66:69]
	v_mfma_f32_16x16x32_bf16 v[66:69], v[6:9], v[214:217], v[74:77]
	v_mfma_f32_16x16x32_bf16 v[102:105], v[26:29], v[218:221], v[66:69]
	v_mfma_f32_16x16x32_bf16 v[66:69], v[30:33], v[214:217], v[78:81]
	v_mfma_f32_16x16x32_bf16 v[98:101], v[62:65], v[218:221], v[66:69]
	v_mfma_f32_16x16x32_bf16 v[66:69], v[6:9], v[222:225], v[82:85]
	v_mfma_f32_16x16x32_bf16 v[86:89], v[26:29], v[226:229], v[66:69]
	v_mfma_f32_16x16x32_bf16 v[66:69], v[30:33], v[222:225], v[90:93]
	v_mfma_f32_16x16x32_bf16 v[82:85], v[62:65], v[226:229], v[66:69]
	v_mfma_f32_16x16x32_bf16 v[66:69], v[6:9], v[230:233], v[94:97]
	v_mfma_f32_16x16x32_bf16 v[70:73], v[26:29], v[234:237], v[66:69]
	v_mfma_f32_16x16x32_bf16 v[66:69], v[30:33], v[230:233], v[106:109]
	v_mfma_f32_16x16x32_bf16 v[66:69], v[62:65], v[234:237], v[66:69]
	v_mfma_f32_16x16x32_bf16 v[74:77], v[198:201], v[18:21], v[110:113]
	v_mfma_f32_16x16x32_bf16 v[18:21], v[206:209], v[18:21], v[34:37]
	v_mfma_f32_16x16x32_bf16 v[122:125], v[210:213], v[22:25], v[18:21]
	v_mfma_f32_16x16x32_bf16 v[18:21], v[198:201], v[214:217], v[38:41]
	v_mfma_f32_16x16x32_bf16 v[110:113], v[202:205], v[218:221], v[18:21]
	v_mfma_f32_16x16x32_bf16 v[18:21], v[206:209], v[214:217], v[42:45]
	v_mfma_f32_16x16x32_bf16 v[106:109], v[210:213], v[218:221], v[18:21]
	v_mfma_f32_16x16x32_bf16 v[18:21], v[198:201], v[222:225], v[46:49]
	v_mfma_f32_16x16x32_bf16 v[94:97], v[202:205], v[226:229], v[18:21]
	v_mfma_f32_16x16x32_bf16 v[18:21], v[206:209], v[222:225], v[50:53]
	v_mfma_f32_16x16x32_bf16 v[90:93], v[210:213], v[226:229], v[18:21]
	v_mfma_f32_16x16x32_bf16 v[18:21], v[198:201], v[230:233], v[54:57]
	s_barrier
	v_mfma_f32_16x16x32_bf16 v[78:81], v[202:205], v[234:237], v[18:21]
	v_mfma_f32_16x16x32_bf16 v[18:21], v[206:209], v[230:233], v[58:61]
	v_mfma_f32_16x16x32_bf16 v[126:129], v[202:205], v[22:25], v[74:77]
	v_mfma_f32_16x16x32_bf16 v[74:77], v[210:213], v[234:237], v[18:21]
	s_add_i32 s50, s82, s43
	s_nop 3
	v_lshl_add_u64 v[18:19], v[238:239], 0, s[24:25]
	s_mov_b32 m0, s50
	s_add_i32 s51, s50, 0x2000
	ds_read_b128 v[42:45], v143 offset:49152
	ds_read_b128 v[46:49], v143 offset:50176
	ds_read_b128 v[214:217], v143 offset:51200
	ds_read_b128 v[218:221], v143 offset:52224
	ds_read_b128 v[222:225], v143 offset:53248
	ds_read_b128 v[226:229], v143 offset:54272
	ds_read_b128 v[230:233], v143 offset:55296
	ds_read_b128 v[234:237], v143 offset:56320
	global_load_lds_dwordx4 v[18:19], off
	v_lshl_add_u64 v[18:19], v[238:239], 0, s[26:27]
	s_mov_b32 m0, s51
	s_mov_b64 s[0:1], 0x80180
	s_add_i32 s33, s83, s43
	global_load_lds_dwordx4 v[18:19], off
	v_lshl_add_u64 v[18:19], v[238:239], 0, s[0:1]
	s_mov_b32 m0, s33
	s_mov_b64 s[0:1], 0xc0180
	s_add_i32 s56, s33, 0x2000
	global_load_lds_dwordx4 v[18:19], off
	v_lshl_add_u64 v[18:19], v[238:239], 0, s[0:1]
	s_mov_b32 m0, s56
	s_nop 0
	global_load_lds_dwordx4 v[18:19], off
	v_lshl_add_u64 v[18:19], v[140:141], 0, s[24:25]
	s_mov_b32 m0, s72
	s_nop 0
	global_load_lds_dwordx4 v[18:19], off
	v_lshl_add_u64 v[18:19], v[140:141], 0, s[26:27]
	s_mov_b32 m0, s73
	s_nop 0
	global_load_lds_dwordx4 v[18:19], off
	s_waitcnt vmcnt(8)
	s_waitcnt lgkmcnt(0)
	s_barrier
	s_waitcnt lgkmcnt(0)
	v_mfma_f32_16x16x32_bf16 v[18:21], v[6:9], v[42:45], v[146:149]
	v_mfma_f32_16x16x32_bf16 v[54:57], v[26:29], v[46:49], v[18:21]
	v_mfma_f32_16x16x32_bf16 v[18:21], v[30:33], v[42:45], v[150:153]
	v_mfma_f32_16x16x32_bf16 v[50:53], v[62:65], v[46:49], v[18:21]
	v_mfma_f32_16x16x32_bf16 v[18:21], v[6:9], v[214:217], v[154:157]
	v_mfma_f32_16x16x32_bf16 v[38:41], v[26:29], v[218:221], v[18:21]
	v_mfma_f32_16x16x32_bf16 v[18:21], v[30:33], v[214:217], v[158:161]
	v_mfma_f32_16x16x32_bf16 v[34:37], v[62:65], v[218:221], v[18:21]
	v_mfma_f32_16x16x32_bf16 v[18:21], v[6:9], v[222:225], v[162:165]
	v_mfma_f32_16x16x32_bf16 v[2:5], v[6:9], v[230:233], v[2:5]
	v_mfma_f32_16x16x32_bf16 v[22:25], v[26:29], v[226:229], v[18:21]
	v_mfma_f32_16x16x32_bf16 v[18:21], v[30:33], v[222:225], v[166:169]
	v_mfma_f32_16x16x32_bf16 v[6:9], v[26:29], v[234:237], v[2:5]
	v_mfma_f32_16x16x32_bf16 v[2:5], v[30:33], v[230:233], v[10:13]
	v_mfma_f32_16x16x32_bf16 v[18:21], v[62:65], v[226:229], v[18:21]
	v_mfma_f32_16x16x32_bf16 v[2:5], v[62:65], v[234:237], v[2:5]
	v_mfma_f32_16x16x32_bf16 v[10:13], v[198:201], v[42:45], v[14:17]
	v_mfma_f32_16x16x32_bf16 v[62:65], v[202:205], v[46:49], v[10:13]
	v_mfma_f32_16x16x32_bf16 v[10:13], v[206:209], v[42:45], v[170:173]
	v_mfma_f32_16x16x32_bf16 v[58:61], v[210:213], v[46:49], v[10:13]
	v_mfma_f32_16x16x32_bf16 v[10:13], v[198:201], v[214:217], v[174:177]
	v_mfma_f32_16x16x32_bf16 v[46:49], v[202:205], v[218:221], v[10:13]
	v_mfma_f32_16x16x32_bf16 v[10:13], v[206:209], v[214:217], v[178:181]
	v_mfma_f32_16x16x32_bf16 v[42:45], v[210:213], v[218:221], v[10:13]
	v_mfma_f32_16x16x32_bf16 v[10:13], v[198:201], v[222:225], v[182:185]
	v_mfma_f32_16x16x32_bf16 v[30:33], v[202:205], v[226:229], v[10:13]
	v_mfma_f32_16x16x32_bf16 v[10:13], v[206:209], v[222:225], v[186:189]
	v_mfma_f32_16x16x32_bf16 v[26:29], v[210:213], v[226:229], v[10:13]
	s_barrier
	v_mfma_f32_16x16x32_bf16 v[10:13], v[198:201], v[230:233], v[190:193]
	v_mfma_f32_16x16x32_bf16 v[14:17], v[202:205], v[234:237], v[10:13]
	v_mfma_f32_16x16x32_bf16 v[10:13], v[206:209], v[230:233], v[194:197]
	v_mfma_f32_16x16x32_bf16 v[10:13], v[210:213], v[234:237], v[10:13]
	s_add_u32 s70, s70, 0x80180
	s_addc_u32 s71, s71, 0
	s_add_u32 s57, s68, 0x200
	s_addc_u32 s68, s69, 0
	s_mov_b32 s69, 0
.LBB0_2862:
	ds_read_b128 v[146:149], v1
	ds_read_b128 v[150:153], v1 offset:1024
	ds_read_b128 v[154:157], v1 offset:2048
	ds_read_b128 v[158:161], v1 offset:3072
	ds_read_b128 v[162:165], v142
	ds_read_b128 v[166:169], v142 offset:1024
	ds_read_b128 v[170:173], v142 offset:2048
	ds_read_b128 v[174:177], v142 offset:3072
	s_add_u32 s0, s70, 0xfff80080
	s_addc_u32 s1, s71, -1
	s_cmp_eq_u32 s69, 28
	s_cselect_b32 s1, s41, s1
	s_cselect_b32 s0, s45, s0
	s_cselect_b32 s65, s87, s68
	s_cselect_b32 s64, s88, s57
	s_mov_b32 m0, s79
	v_lshl_add_u64 v[140:141], s[70:71], 0, v[134:135]
	ds_read_b128 v[178:181], v143
	ds_read_b128 v[182:185], v143 offset:1024
	ds_read_b128 v[186:189], v143 offset:2048
	ds_read_b128 v[190:193], v143 offset:3072
	ds_read_b128 v[194:197], v143 offset:4096
	ds_read_b128 v[198:201], v143 offset:5120
	ds_read_b128 v[202:205], v143 offset:6144
	ds_read_b128 v[206:209], v143 offset:7168
	global_load_lds_dwordx4 v[140:141], off
	v_lshl_add_u64 v[140:141], v[140:141], 0, s[28:29]
	s_mov_b32 m0, s80
	s_nop 0
	global_load_lds_dwordx4 v[140:141], off
	s_waitcnt vmcnt(8)
	s_waitcnt lgkmcnt(0)
	s_barrier
	s_waitcnt lgkmcnt(0)
	v_mfma_f32_16x16x32_bf16 v[118:121], v[146:149], v[178:181], v[118:121]
	v_mfma_f32_16x16x32_bf16 v[114:117], v[154:157], v[178:181], v[114:117]
	v_mfma_f32_16x16x32_bf16 v[102:105], v[146:149], v[186:189], v[102:105]
	v_mfma_f32_16x16x32_bf16 v[98:101], v[154:157], v[186:189], v[98:101]
	v_mfma_f32_16x16x32_bf16 v[86:89], v[146:149], v[194:197], v[86:89]
	v_mfma_f32_16x16x32_bf16 v[82:85], v[154:157], v[194:197], v[82:85]
	v_mfma_f32_16x16x32_bf16 v[70:73], v[146:149], v[202:205], v[70:73]
	v_mfma_f32_16x16x32_bf16 v[66:69], v[154:157], v[202:205], v[66:69]
	v_mfma_f32_16x16x32_bf16 v[118:121], v[150:153], v[182:185], v[118:121]
	v_mfma_f32_16x16x32_bf16 v[114:117], v[158:161], v[182:185], v[114:117]
	v_mfma_f32_16x16x32_bf16 v[102:105], v[150:153], v[190:193], v[102:105]
	v_mfma_f32_16x16x32_bf16 v[98:101], v[158:161], v[190:193], v[98:101]
	v_mfma_f32_16x16x32_bf16 v[86:89], v[150:153], v[198:201], v[86:89]
	v_mfma_f32_16x16x32_bf16 v[82:85], v[158:161], v[198:201], v[82:85]
	v_mfma_f32_16x16x32_bf16 v[70:73], v[150:153], v[206:209], v[70:73]
	v_mfma_f32_16x16x32_bf16 v[66:69], v[158:161], v[206:209], v[66:69]
	v_mfma_f32_16x16x32_bf16 v[126:129], v[162:165], v[178:181], v[126:129]
	v_mfma_f32_16x16x32_bf16 v[122:125], v[170:173], v[178:181], v[122:125]
	v_mfma_f32_16x16x32_bf16 v[110:113], v[162:165], v[186:189], v[110:113]
	v_mfma_f32_16x16x32_bf16 v[106:109], v[170:173], v[186:189], v[106:109]
	v_mfma_f32_16x16x32_bf16 v[94:97], v[162:165], v[194:197], v[94:97]
	v_mfma_f32_16x16x32_bf16 v[90:93], v[170:173], v[194:197], v[90:93]
	v_mfma_f32_16x16x32_bf16 v[78:81], v[162:165], v[202:205], v[78:81]
	v_mfma_f32_16x16x32_bf16 v[74:77], v[170:173], v[202:205], v[74:77]
	v_mfma_f32_16x16x32_bf16 v[126:129], v[166:169], v[182:185], v[126:129]
	v_mfma_f32_16x16x32_bf16 v[122:125], v[174:177], v[182:185], v[122:125]
	v_mfma_f32_16x16x32_bf16 v[110:113], v[166:169], v[190:193], v[110:113]
	v_mfma_f32_16x16x32_bf16 v[106:109], v[174:177], v[190:193], v[106:109]
	s_barrier
	v_mfma_f32_16x16x32_bf16 v[94:97], v[166:169], v[198:201], v[94:97]
	v_mfma_f32_16x16x32_bf16 v[90:93], v[174:177], v[198:201], v[90:93]
	v_mfma_f32_16x16x32_bf16 v[78:81], v[166:169], v[206:209], v[78:81]
	v_mfma_f32_16x16x32_bf16 v[74:77], v[174:177], v[206:209], v[74:77]
	s_mov_b32 m0, s81
	v_lshl_add_u64 v[140:141], s[64:65], 0, v[130:131]
	ds_read_b128 v[178:181], v143 offset:16384
	ds_read_b128 v[182:185], v143 offset:17408
	ds_read_b128 v[186:189], v143 offset:18432
	ds_read_b128 v[190:193], v143 offset:19456
	ds_read_b128 v[194:197], v143 offset:20480
	ds_read_b128 v[198:201], v143 offset:21504
	ds_read_b128 v[202:205], v143 offset:22528
	ds_read_b128 v[206:209], v143 offset:23552
	global_load_lds_dwordx4 v[140:141], off
	v_lshl_add_u64 v[210:211], v[140:141], 0, s[28:29]
	s_mov_b32 m0, s89
	s_nop 0
	global_load_lds_dwordx4 v[210:211], off
	v_lshl_add_u64 v[210:211], v[140:141], 0, s[30:31]
	s_mov_b32 m0, s90
	s_nop 0
	global_load_lds_dwordx4 v[210:211], off
	v_lshl_add_u64 v[210:211], v[140:141], 0, s[34:35]
	s_mov_b32 m0, s91
	s_nop 0
	global_load_lds_dwordx4 v[210:211], off
	v_lshl_add_u64 v[210:211], s[0:1], 0, v[132:133]
	s_mov_b32 m0, s53
	v_lshl_add_u64 v[212:213], v[210:211], 0, s[28:29]
	global_load_lds_dwordx4 v[210:211], off
	s_mov_b32 m0, s54
	s_nop 0
	global_load_lds_dwordx4 v[212:213], off
	s_waitcnt vmcnt(8)
	s_waitcnt lgkmcnt(0)
	s_barrier
	s_waitcnt lgkmcnt(0)
	v_mfma_f32_16x16x32_bf16 v[54:57], v[146:149], v[178:181], v[54:57]
	v_mfma_f32_16x16x32_bf16 v[50:53], v[154:157], v[178:181], v[50:53]
	v_mfma_f32_16x16x32_bf16 v[38:41], v[146:149], v[186:189], v[38:41]
	v_mfma_f32_16x16x32_bf16 v[34:37], v[154:157], v[186:189], v[34:37]
	v_mfma_f32_16x16x32_bf16 v[22:25], v[146:149], v[194:197], v[22:25]
	v_mfma_f32_16x16x32_bf16 v[18:21], v[154:157], v[194:197], v[18:21]
	v_mfma_f32_16x16x32_bf16 v[6:9], v[146:149], v[202:205], v[6:9]
	v_mfma_f32_16x16x32_bf16 v[2:5], v[154:157], v[202:205], v[2:5]
	v_mfma_f32_16x16x32_bf16 v[54:57], v[150:153], v[182:185], v[54:57]
	v_mfma_f32_16x16x32_bf16 v[50:53], v[158:161], v[182:185], v[50:53]
	v_mfma_f32_16x16x32_bf16 v[38:41], v[150:153], v[190:193], v[38:41]
	v_mfma_f32_16x16x32_bf16 v[34:37], v[158:161], v[190:193], v[34:37]
	v_mfma_f32_16x16x32_bf16 v[22:25], v[150:153], v[198:201], v[22:25]
	v_mfma_f32_16x16x32_bf16 v[18:21], v[158:161], v[198:201], v[18:21]
	v_mfma_f32_16x16x32_bf16 v[6:9], v[150:153], v[206:209], v[6:9]
	v_mfma_f32_16x16x32_bf16 v[2:5], v[158:161], v[206:209], v[2:5]
	v_mfma_f32_16x16x32_bf16 v[62:65], v[162:165], v[178:181], v[62:65]
	v_mfma_f32_16x16x32_bf16 v[58:61], v[170:173], v[178:181], v[58:61]
	v_mfma_f32_16x16x32_bf16 v[46:49], v[162:165], v[186:189], v[46:49]
	v_mfma_f32_16x16x32_bf16 v[42:45], v[170:173], v[186:189], v[42:45]
	v_mfma_f32_16x16x32_bf16 v[30:33], v[162:165], v[194:197], v[30:33]
	v_mfma_f32_16x16x32_bf16 v[26:29], v[170:173], v[194:197], v[26:29]
	v_mfma_f32_16x16x32_bf16 v[14:17], v[162:165], v[202:205], v[14:17]
	v_mfma_f32_16x16x32_bf16 v[10:13], v[170:173], v[202:205], v[10:13]
	v_mfma_f32_16x16x32_bf16 v[62:65], v[166:169], v[182:185], v[62:65]
	v_mfma_f32_16x16x32_bf16 v[58:61], v[174:177], v[182:185], v[58:61]
	v_mfma_f32_16x16x32_bf16 v[46:49], v[166:169], v[190:193], v[46:49]
	v_mfma_f32_16x16x32_bf16 v[42:45], v[174:177], v[190:193], v[42:45]
	s_barrier
	v_mfma_f32_16x16x32_bf16 v[30:33], v[166:169], v[198:201], v[30:33]
	v_mfma_f32_16x16x32_bf16 v[26:29], v[174:177], v[198:201], v[26:29]
	v_mfma_f32_16x16x32_bf16 v[14:17], v[166:169], v[206:209], v[14:17]
	v_mfma_f32_16x16x32_bf16 v[10:13], v[174:177], v[206:209], v[10:13]
	ds_read_b128 v[146:149], v144
	ds_read_b128 v[150:153], v144 offset:1024
	ds_read_b128 v[154:157], v144 offset:2048
	ds_read_b128 v[158:161], v144 offset:3072
	ds_read_b128 v[162:165], v145
	ds_read_b128 v[166:169], v145 offset:1024
	ds_read_b128 v[170:173], v145 offset:2048
	ds_read_b128 v[174:177], v145 offset:3072
	s_mov_b32 m0, s55
	v_lshl_add_u64 v[212:213], v[210:211], 0, s[30:31]
	ds_read_b128 v[178:181], v143 offset:32768
	ds_read_b128 v[182:185], v143 offset:33792
	ds_read_b128 v[186:189], v143 offset:34816
	ds_read_b128 v[190:193], v143 offset:35840
	ds_read_b128 v[194:197], v143 offset:36864
	ds_read_b128 v[198:201], v143 offset:37888
	ds_read_b128 v[202:205], v143 offset:38912
	ds_read_b128 v[206:209], v143 offset:39936
	global_load_lds_dwordx4 v[212:213], off
	v_lshl_add_u64 v[212:213], v[210:211], 0, s[34:35]
	s_mov_b32 m0, s67
	s_nop 0
	global_load_lds_dwordx4 v[212:213], off
	s_waitcnt vmcnt(8)
	s_waitcnt lgkmcnt(0)
	s_barrier
	s_waitcnt lgkmcnt(0)
	v_mfma_f32_16x16x32_bf16 v[118:121], v[146:149], v[178:181], v[118:121]
	v_mfma_f32_16x16x32_bf16 v[114:117], v[154:157], v[178:181], v[114:117]
	v_mfma_f32_16x16x32_bf16 v[102:105], v[146:149], v[186:189], v[102:105]
	v_mfma_f32_16x16x32_bf16 v[98:101], v[154:157], v[186:189], v[98:101]
	v_mfma_f32_16x16x32_bf16 v[86:89], v[146:149], v[194:197], v[86:89]
	v_mfma_f32_16x16x32_bf16 v[82:85], v[154:157], v[194:197], v[82:85]
	v_mfma_f32_16x16x32_bf16 v[70:73], v[146:149], v[202:205], v[70:73]
	v_mfma_f32_16x16x32_bf16 v[66:69], v[154:157], v[202:205], v[66:69]
	v_mfma_f32_16x16x32_bf16 v[118:121], v[150:153], v[182:185], v[118:121]
	v_mfma_f32_16x16x32_bf16 v[114:117], v[158:161], v[182:185], v[114:117]
	v_mfma_f32_16x16x32_bf16 v[102:105], v[150:153], v[190:193], v[102:105]
	v_mfma_f32_16x16x32_bf16 v[98:101], v[158:161], v[190:193], v[98:101]
	v_mfma_f32_16x16x32_bf16 v[86:89], v[150:153], v[198:201], v[86:89]
	v_mfma_f32_16x16x32_bf16 v[82:85], v[158:161], v[198:201], v[82:85]
	v_mfma_f32_16x16x32_bf16 v[70:73], v[150:153], v[206:209], v[70:73]
	v_mfma_f32_16x16x32_bf16 v[66:69], v[158:161], v[206:209], v[66:69]
	v_mfma_f32_16x16x32_bf16 v[126:129], v[162:165], v[178:181], v[126:129]
	v_mfma_f32_16x16x32_bf16 v[122:125], v[170:173], v[178:181], v[122:125]
	v_mfma_f32_16x16x32_bf16 v[110:113], v[162:165], v[186:189], v[110:113]
	v_mfma_f32_16x16x32_bf16 v[106:109], v[170:173], v[186:189], v[106:109]
	v_mfma_f32_16x16x32_bf16 v[94:97], v[162:165], v[194:197], v[94:97]
	v_mfma_f32_16x16x32_bf16 v[90:93], v[170:173], v[194:197], v[90:93]
	v_mfma_f32_16x16x32_bf16 v[78:81], v[162:165], v[202:205], v[78:81]
	v_mfma_f32_16x16x32_bf16 v[74:77], v[170:173], v[202:205], v[74:77]
	v_mfma_f32_16x16x32_bf16 v[126:129], v[166:169], v[182:185], v[126:129]
	v_mfma_f32_16x16x32_bf16 v[122:125], v[174:177], v[182:185], v[122:125]
	v_mfma_f32_16x16x32_bf16 v[110:113], v[166:169], v[190:193], v[110:113]
	v_mfma_f32_16x16x32_bf16 v[106:109], v[174:177], v[190:193], v[106:109]
	s_barrier
	v_mfma_f32_16x16x32_bf16 v[94:97], v[166:169], v[198:201], v[94:97]
	v_mfma_f32_16x16x32_bf16 v[90:93], v[174:177], v[198:201], v[90:93]
	v_mfma_f32_16x16x32_bf16 v[78:81], v[166:169], v[206:209], v[78:81]
	v_mfma_f32_16x16x32_bf16 v[74:77], v[174:177], v[206:209], v[74:77]
	s_mov_b32 m0, s50
	v_lshl_add_u64 v[212:213], v[140:141], 0, s[36:37]
	ds_read_b128 v[178:181], v143 offset:49152
	ds_read_b128 v[182:185], v143 offset:50176
	ds_read_b128 v[186:189], v143 offset:51200
	ds_read_b128 v[190:193], v143 offset:52224
	ds_read_b128 v[194:197], v143 offset:53248
	ds_read_b128 v[198:201], v143 offset:54272
	ds_read_b128 v[202:205], v143 offset:55296
	ds_read_b128 v[206:209], v143 offset:56320
	global_load_lds_dwordx4 v[212:213], off
	v_lshl_add_u64 v[212:213], v[140:141], 0, s[38:39]
	s_mov_b32 m0, s51
	s_nop 0
	global_load_lds_dwordx4 v[212:213], off
	v_lshl_add_u64 v[212:213], v[140:141], 0, s[12:13]
	s_mov_b32 m0, s33
	v_lshl_add_u64 v[140:141], v[140:141], 0, s[14:15]
	global_load_lds_dwordx4 v[212:213], off
	s_mov_b32 m0, s56
	s_nop 0
	global_load_lds_dwordx4 v[140:141], off
	v_lshl_add_u64 v[140:141], v[210:211], 0, s[36:37]
	s_mov_b32 m0, s72
	s_nop 0
	global_load_lds_dwordx4 v[140:141], off
	v_lshl_add_u64 v[140:141], v[210:211], 0, s[38:39]
	s_mov_b32 m0, s73
	s_nop 0
	global_load_lds_dwordx4 v[140:141], off
	s_waitcnt vmcnt(8)
	s_waitcnt lgkmcnt(0)
	s_barrier
	s_waitcnt lgkmcnt(0)
	v_mfma_f32_16x16x32_bf16 v[54:57], v[146:149], v[178:181], v[54:57]
	v_mfma_f32_16x16x32_bf16 v[50:53], v[154:157], v[178:181], v[50:53]
	v_mfma_f32_16x16x32_bf16 v[38:41], v[146:149], v[186:189], v[38:41]
	v_mfma_f32_16x16x32_bf16 v[34:37], v[154:157], v[186:189], v[34:37]
	v_mfma_f32_16x16x32_bf16 v[22:25], v[146:149], v[194:197], v[22:25]
	v_mfma_f32_16x16x32_bf16 v[18:21], v[154:157], v[194:197], v[18:21]
	v_mfma_f32_16x16x32_bf16 v[6:9], v[146:149], v[202:205], v[6:9]
	v_mfma_f32_16x16x32_bf16 v[2:5], v[154:157], v[202:205], v[2:5]
	v_mfma_f32_16x16x32_bf16 v[54:57], v[150:153], v[182:185], v[54:57]
	v_mfma_f32_16x16x32_bf16 v[50:53], v[158:161], v[182:185], v[50:53]
	v_mfma_f32_16x16x32_bf16 v[38:41], v[150:153], v[190:193], v[38:41]
	v_mfma_f32_16x16x32_bf16 v[34:37], v[158:161], v[190:193], v[34:37]
	v_mfma_f32_16x16x32_bf16 v[22:25], v[150:153], v[198:201], v[22:25]
	v_mfma_f32_16x16x32_bf16 v[18:21], v[158:161], v[198:201], v[18:21]
	v_mfma_f32_16x16x32_bf16 v[6:9], v[150:153], v[206:209], v[6:9]
	v_mfma_f32_16x16x32_bf16 v[2:5], v[158:161], v[206:209], v[2:5]
	v_mfma_f32_16x16x32_bf16 v[62:65], v[162:165], v[178:181], v[62:65]
	v_mfma_f32_16x16x32_bf16 v[58:61], v[170:173], v[178:181], v[58:61]
	v_mfma_f32_16x16x32_bf16 v[46:49], v[162:165], v[186:189], v[46:49]
	v_mfma_f32_16x16x32_bf16 v[42:45], v[170:173], v[186:189], v[42:45]
	v_mfma_f32_16x16x32_bf16 v[30:33], v[162:165], v[194:197], v[30:33]
	v_mfma_f32_16x16x32_bf16 v[26:29], v[170:173], v[194:197], v[26:29]
	v_mfma_f32_16x16x32_bf16 v[14:17], v[162:165], v[202:205], v[14:17]
	v_mfma_f32_16x16x32_bf16 v[10:13], v[170:173], v[202:205], v[10:13]
	v_mfma_f32_16x16x32_bf16 v[62:65], v[166:169], v[182:185], v[62:65]
	v_mfma_f32_16x16x32_bf16 v[58:61], v[174:177], v[182:185], v[58:61]
	v_mfma_f32_16x16x32_bf16 v[46:49], v[166:169], v[190:193], v[46:49]
	v_mfma_f32_16x16x32_bf16 v[42:45], v[174:177], v[190:193], v[42:45]
	s_barrier
	v_mfma_f32_16x16x32_bf16 v[30:33], v[166:169], v[198:201], v[30:33]
	v_mfma_f32_16x16x32_bf16 v[26:29], v[174:177], v[198:201], v[26:29]
	v_mfma_f32_16x16x32_bf16 v[14:17], v[166:169], v[206:209], v[14:17]
	v_mfma_f32_16x16x32_bf16 v[10:13], v[174:177], v[206:209], v[10:13]
	s_add_i32 s69, s69, 2
	s_add_u32 s70, s70, 0x100
	s_addc_u32 s71, s71, 0
	s_add_u32 s57, s57, 0x100
	s_addc_u32 s68, s68, 0
	s_cmp_gt_u32 s69, 29
	s_cbranch_scc0 .LBB0_2862
	s_and_b64 vcc, exec, s[10:11]
	s_cbranch_vccz .LBB0_2865
	s_barrier

.LBB0_2964:
	ds_read_b128 v[2:5], v1
	ds_read_b128 v[6:9], v1 offset:1024
	ds_read_b128 v[10:13], v1 offset:2048
	ds_read_b128 v[14:17], v1 offset:3072
	ds_read_b128 v[18:21], v168
	ds_read_b128 v[22:25], v168 offset:1024
	ds_read_b128 v[26:29], v168 offset:2048
	ds_read_b128 v[30:33], v168 offset:3072
	v_lshl_add_u64 v[244:245], s[46:47], 0, v[150:151]
	s_add_i32 s81, s53, 0xc000
	v_lshl_add_u64 v[66:67], v[244:245], 0, s[14:15]
	s_mov_b32 m0, s81
	s_add_i32 s82, s53, 0xe000
	ds_read_b128 v[34:37], v169
	ds_read_b128 v[38:41], v169 offset:1024
	ds_read_b128 v[42:45], v169 offset:2048
	ds_read_b128 v[46:49], v169 offset:3072
	ds_read_b128 v[50:53], v169 offset:4096
	ds_read_b128 v[54:57], v169 offset:5120
	ds_read_b128 v[58:61], v169 offset:6144
	ds_read_b128 v[62:65], v169 offset:7168
	global_load_lds_dwordx4 v[66:67], off
	v_lshl_add_u64 v[66:67], v[244:245], 0, s[16:17]
	s_mov_b32 m0, s82
	s_nop 0
	global_load_lds_dwordx4 v[66:67], off
	s_waitcnt vmcnt(24)
	s_waitcnt lgkmcnt(0)
	s_barrier
	s_waitcnt lgkmcnt(0)
	v_mfma_f32_16x16x32_bf16 v[66:69], v[2:5], v[34:37], 0
	v_mfma_f32_16x16x32_bf16 v[70:73], v[10:13], v[34:37], 0
	v_mfma_f32_16x16x32_bf16 v[74:77], v[2:5], v[42:45], 0
	v_mfma_f32_16x16x32_bf16 v[78:81], v[10:13], v[42:45], 0
	v_mfma_f32_16x16x32_bf16 v[90:93], v[2:5], v[58:61], 0
	v_mfma_f32_16x16x32_bf16 v[66:69], v[6:9], v[38:41], v[66:69]
	v_mfma_f32_16x16x32_bf16 v[70:73], v[14:17], v[38:41], v[70:73]
	v_mfma_f32_16x16x32_bf16 v[74:77], v[6:9], v[46:49], v[74:77]
	v_mfma_f32_16x16x32_bf16 v[78:81], v[14:17], v[46:49], v[78:81]
	v_mfma_f32_16x16x32_bf16 v[82:85], v[2:5], v[50:53], 0
	v_mfma_f32_16x16x32_bf16 v[86:89], v[10:13], v[50:53], 0
	v_mfma_f32_16x16x32_bf16 v[90:93], v[6:9], v[62:65], v[90:93]
	v_mfma_f32_16x16x32_bf16 v[94:97], v[10:13], v[58:61], 0
	v_mfma_f32_16x16x32_bf16 v[82:85], v[6:9], v[54:57], v[82:85]
	v_mfma_f32_16x16x32_bf16 v[86:89], v[14:17], v[54:57], v[86:89]
	v_mfma_f32_16x16x32_bf16 v[94:97], v[14:17], v[62:65], v[94:97]
	v_mfma_f32_16x16x32_bf16 v[98:101], v[18:21], v[34:37], 0
	v_mfma_f32_16x16x32_bf16 v[34:37], v[26:29], v[34:37], 0
	v_mfma_f32_16x16x32_bf16 v[98:101], v[22:25], v[38:41], v[98:101]
	v_mfma_f32_16x16x32_bf16 v[34:37], v[30:33], v[38:41], v[34:37]
	v_mfma_f32_16x16x32_bf16 v[38:41], v[18:21], v[42:45], 0
	v_mfma_f32_16x16x32_bf16 v[42:45], v[26:29], v[42:45], 0
	v_mfma_f32_16x16x32_bf16 v[38:41], v[22:25], v[46:49], v[38:41]
	v_mfma_f32_16x16x32_bf16 v[42:45], v[30:33], v[46:49], v[42:45]
	v_mfma_f32_16x16x32_bf16 v[46:49], v[18:21], v[50:53], 0
	v_mfma_f32_16x16x32_bf16 v[50:53], v[26:29], v[50:53], 0
	v_mfma_f32_16x16x32_bf16 v[46:49], v[22:25], v[54:57], v[46:49]
	v_mfma_f32_16x16x32_bf16 v[50:53], v[30:33], v[54:57], v[50:53]
	s_barrier
	v_mfma_f32_16x16x32_bf16 v[54:57], v[18:21], v[58:61], 0
	v_mfma_f32_16x16x32_bf16 v[58:61], v[26:29], v[58:61], 0
	v_mfma_f32_16x16x32_bf16 v[54:57], v[22:25], v[62:65], v[54:57]
	v_mfma_f32_16x16x32_bf16 v[58:61], v[30:33], v[62:65], v[58:61]
	v_lshl_add_u64 v[246:247], s[58:59], 0, v[152:153]
	s_add_i32 s83, s73, s52
	v_lshl_add_u64 v[130:131], v[246:247], 0, s[18:19]
	s_mov_b32 m0, s83
	s_add_i32 s84, s83, 0x2000
	ds_read_b128 v[62:65], v169 offset:16384
	ds_read_b128 v[102:105], v169 offset:17408
	ds_read_b128 v[106:109], v169 offset:18432
	ds_read_b128 v[110:113], v169 offset:19456
	ds_read_b128 v[114:117], v169 offset:20480
	ds_read_b128 v[118:121], v169 offset:21504
	ds_read_b128 v[122:125], v169 offset:22528
	ds_read_b128 v[126:129], v169 offset:23552
	global_load_lds_dwordx4 v[130:131], off
	v_lshl_add_u64 v[130:131], v[246:247], 0, s[20:21]
	s_mov_b32 m0, s84
	s_add_i32 s85, s74, s52
	global_load_lds_dwordx4 v[130:131], off
	v_lshl_add_u64 v[130:131], v[246:247], 0, s[22:23]
	s_mov_b32 m0, s85
	s_add_i32 s87, s85, 0x2000
	global_load_lds_dwordx4 v[130:131], off
	v_lshl_add_u64 v[130:131], v[246:247], 0, s[24:25]
	s_mov_b32 m0, s87
	s_nop 0
	global_load_lds_dwordx4 v[130:131], off
	v_lshl_add_u64 v[130:131], v[244:245], 0, s[18:19]
	s_mov_b32 m0, s53
	s_nop 0
	global_load_lds_dwordx4 v[130:131], off
	v_lshl_add_u64 v[130:131], v[244:245], 0, s[20:21]
	s_mov_b32 m0, s54
	s_nop 0
	global_load_lds_dwordx4 v[130:131], off
	s_waitcnt vmcnt(24)
	s_waitcnt lgkmcnt(0)
	s_barrier
	s_waitcnt lgkmcnt(0)
	v_mfma_f32_16x16x32_bf16 v[130:133], v[2:5], v[62:65], 0
	v_mfma_f32_16x16x32_bf16 v[146:149], v[6:9], v[102:105], v[130:133]
	v_mfma_f32_16x16x32_bf16 v[130:133], v[10:13], v[62:65], 0
	v_mfma_f32_16x16x32_bf16 v[160:163], v[14:17], v[102:105], v[130:133]
	v_mfma_f32_16x16x32_bf16 v[130:133], v[2:5], v[106:109], 0
	v_mfma_f32_16x16x32_bf16 v[164:167], v[6:9], v[110:113], v[130:133]
	v_mfma_f32_16x16x32_bf16 v[130:133], v[10:13], v[106:109], 0
	v_mfma_f32_16x16x32_bf16 v[172:175], v[14:17], v[110:113], v[130:133]
	v_mfma_f32_16x16x32_bf16 v[130:133], v[2:5], v[114:117], 0
	v_mfma_f32_16x16x32_bf16 v[2:5], v[2:5], v[122:125], 0
	v_mfma_f32_16x16x32_bf16 v[176:179], v[6:9], v[118:121], v[130:133]
	v_mfma_f32_16x16x32_bf16 v[2:5], v[6:9], v[126:129], v[2:5]
	v_mfma_f32_16x16x32_bf16 v[6:9], v[10:13], v[122:125], 0
	v_mfma_f32_16x16x32_bf16 v[130:133], v[10:13], v[114:117], 0
	v_mfma_f32_16x16x32_bf16 v[6:9], v[14:17], v[126:129], v[6:9]
	v_mfma_f32_16x16x32_bf16 v[180:183], v[14:17], v[118:121], v[130:133]
	v_mfma_f32_16x16x32_bf16 v[10:13], v[18:21], v[62:65], 0
	v_mfma_f32_16x16x32_bf16 v[184:187], v[22:25], v[102:105], v[10:13]
	v_mfma_f32_16x16x32_bf16 v[10:13], v[26:29], v[62:65], 0
	v_mfma_f32_16x16x32_bf16 v[102:105], v[30:33], v[102:105], v[10:13]
	v_mfma_f32_16x16x32_bf16 v[10:13], v[18:21], v[106:109], 0
	v_mfma_f32_16x16x32_bf16 v[188:191], v[22:25], v[110:113], v[10:13]
	v_mfma_f32_16x16x32_bf16 v[10:13], v[26:29], v[106:109], 0
	v_mfma_f32_16x16x32_bf16 v[192:195], v[30:33], v[110:113], v[10:13]
	v_mfma_f32_16x16x32_bf16 v[10:13], v[18:21], v[114:117], 0
	v_mfma_f32_16x16x32_bf16 v[196:199], v[22:25], v[118:121], v[10:13]
	v_mfma_f32_16x16x32_bf16 v[10:13], v[26:29], v[114:117], 0
	v_mfma_f32_16x16x32_bf16 v[200:203], v[30:33], v[118:121], v[10:13]
	s_barrier
	v_mfma_f32_16x16x32_bf16 v[10:13], v[18:21], v[122:125], 0
	v_mfma_f32_16x16x32_bf16 v[204:207], v[22:25], v[126:129], v[10:13]
	v_mfma_f32_16x16x32_bf16 v[10:13], v[26:29], v[122:125], 0
	v_mfma_f32_16x16x32_bf16 v[208:211], v[30:33], v[126:129], v[10:13]
	s_nop 5
	ds_read_b128 v[10:13], v170
	ds_read_b128 v[14:17], v170 offset:1024
	ds_read_b128 v[18:21], v170 offset:2048
	ds_read_b128 v[22:25], v170 offset:3072
	ds_read_b128 v[212:215], v171
	ds_read_b128 v[216:219], v171 offset:1024
	ds_read_b128 v[220:223], v171 offset:2048
	ds_read_b128 v[224:227], v171 offset:3072
	s_mov_b32 m0, s55
	v_lshl_add_u64 v[106:107], v[244:245], 0, s[22:23]
	ds_read_b128 v[26:29], v169 offset:32768
	ds_read_b128 v[30:33], v169 offset:33792
	ds_read_b128 v[62:65], v169 offset:34816
	ds_read_b128 v[114:117], v169 offset:35840
	ds_read_b128 v[228:231], v169 offset:36864
	ds_read_b128 v[232:235], v169 offset:37888
	ds_read_b128 v[236:239], v169 offset:38912
	ds_read_b128 v[240:243], v169 offset:39936
	global_load_lds_dwordx4 v[106:107], off
	v_lshl_add_u64 v[106:107], v[244:245], 0, s[24:25]
	s_mov_b32 m0, s62
	s_nop 0
	global_load_lds_dwordx4 v[106:107], off
	s_waitcnt vmcnt(8)
	s_waitcnt lgkmcnt(0)
	s_barrier
	s_waitcnt lgkmcnt(0)
	v_mfma_f32_16x16x32_bf16 v[66:69], v[10:13], v[26:29], v[66:69]
	v_mfma_f32_16x16x32_bf16 v[138:141], v[14:17], v[30:33], v[66:69]
	v_mfma_f32_16x16x32_bf16 v[66:69], v[18:21], v[26:29], v[70:73]
	v_mfma_f32_16x16x32_bf16 v[134:137], v[22:25], v[30:33], v[66:69]
	v_mfma_f32_16x16x32_bf16 v[66:69], v[10:13], v[62:65], v[74:77]
	v_mfma_f32_16x16x32_bf16 v[126:129], v[14:17], v[114:117], v[66:69]
	v_mfma_f32_16x16x32_bf16 v[66:69], v[18:21], v[62:65], v[78:81]
	v_mfma_f32_16x16x32_bf16 v[122:125], v[22:25], v[114:117], v[66:69]
	v_mfma_f32_16x16x32_bf16 v[66:69], v[10:13], v[228:231], v[82:85]
	v_mfma_f32_16x16x32_bf16 v[110:113], v[14:17], v[232:235], v[66:69]
	v_mfma_f32_16x16x32_bf16 v[66:69], v[18:21], v[228:231], v[86:89]
	v_mfma_f32_16x16x32_bf16 v[106:109], v[22:25], v[232:235], v[66:69]
	v_mfma_f32_16x16x32_bf16 v[66:69], v[10:13], v[236:239], v[90:93]
	v_mfma_f32_16x16x32_bf16 v[78:81], v[14:17], v[240:243], v[66:69]
	v_mfma_f32_16x16x32_bf16 v[66:69], v[18:21], v[236:239], v[94:97]
	v_mfma_f32_16x16x32_bf16 v[74:77], v[22:25], v[240:243], v[66:69]
	v_mfma_f32_16x16x32_bf16 v[66:69], v[212:215], v[26:29], v[98:101]
	v_mfma_f32_16x16x32_bf16 v[26:29], v[220:223], v[26:29], v[34:37]
	v_mfma_f32_16x16x32_bf16 v[130:133], v[224:227], v[30:33], v[26:29]
	v_mfma_f32_16x16x32_bf16 v[26:29], v[212:215], v[62:65], v[38:41]
	v_mfma_f32_16x16x32_bf16 v[118:121], v[216:219], v[114:117], v[26:29]
	v_mfma_f32_16x16x32_bf16 v[26:29], v[220:223], v[62:65], v[42:45]
	v_mfma_f32_16x16x32_bf16 v[114:117], v[224:227], v[114:117], v[26:29]
	v_mfma_f32_16x16x32_bf16 v[26:29], v[212:215], v[228:231], v[46:49]
	v_mfma_f32_16x16x32_bf16 v[98:101], v[216:219], v[232:235], v[26:29]
	v_mfma_f32_16x16x32_bf16 v[26:29], v[220:223], v[228:231], v[50:53]
	v_mfma_f32_16x16x32_bf16 v[90:93], v[224:227], v[232:235], v[26:29]
	v_mfma_f32_16x16x32_bf16 v[26:29], v[212:215], v[236:239], v[54:57]
	s_barrier
	v_mfma_f32_16x16x32_bf16 v[70:73], v[216:219], v[240:243], v[26:29]
	v_mfma_f32_16x16x32_bf16 v[26:29], v[220:223], v[236:239], v[58:61]
	v_mfma_f32_16x16x32_bf16 v[142:145], v[216:219], v[30:33], v[66:69]
	v_mfma_f32_16x16x32_bf16 v[66:69], v[224:227], v[240:243], v[26:29]
	s_add_i32 s50, s75, s52
	s_nop 3
	v_lshl_add_u64 v[26:27], v[246:247], 0, s[26:27]
	s_mov_b32 m0, s50
	s_add_i32 s51, s50, 0x2000
	ds_read_b128 v[34:37], v169 offset:49152
	ds_read_b128 v[38:41], v169 offset:50176
	ds_read_b128 v[82:85], v169 offset:51200
	ds_read_b128 v[86:89], v169 offset:52224
	ds_read_b128 v[94:97], v169 offset:53248
	ds_read_b128 v[228:231], v169 offset:54272
	ds_read_b128 v[232:235], v169 offset:55296
	ds_read_b128 v[236:239], v169 offset:56320
	global_load_lds_dwordx4 v[26:27], off
	v_lshl_add_u64 v[26:27], v[246:247], 0, s[28:29]
	s_mov_b32 m0, s51
	s_mov_b64 s[0:1], 0x160180
	s_add_i32 s33, s76, s52
	global_load_lds_dwordx4 v[26:27], off
	v_lshl_add_u64 v[26:27], v[246:247], 0, s[0:1]
	s_mov_b32 m0, s33
	s_mov_b64 s[0:1], 0x210180
	s_add_i32 s56, s33, 0x2000
	global_load_lds_dwordx4 v[26:27], off
	v_lshl_add_u64 v[26:27], v[246:247], 0, s[0:1]
	s_mov_b32 m0, s56
	s_nop 0
	global_load_lds_dwordx4 v[26:27], off
	v_lshl_add_u64 v[26:27], v[244:245], 0, s[26:27]
	s_mov_b32 m0, s63
	s_nop 0
	global_load_lds_dwordx4 v[26:27], off
	v_lshl_add_u64 v[26:27], v[244:245], 0, s[28:29]
	s_mov_b32 m0, s66
	s_nop 0
	global_load_lds_dwordx4 v[26:27], off
	s_waitcnt vmcnt(8)
	s_waitcnt lgkmcnt(0)
	s_barrier
	s_waitcnt lgkmcnt(0)
	v_mfma_f32_16x16x32_bf16 v[26:29], v[10:13], v[34:37], v[146:149]
	v_mfma_f32_16x16x32_bf16 v[62:65], v[14:17], v[38:41], v[26:29]
	v_mfma_f32_16x16x32_bf16 v[26:29], v[18:21], v[34:37], v[160:163]
	v_mfma_f32_16x16x32_bf16 v[58:61], v[22:25], v[38:41], v[26:29]
	v_mfma_f32_16x16x32_bf16 v[26:29], v[10:13], v[82:85], v[164:167]
	v_mfma_f32_16x16x32_bf16 v[46:49], v[14:17], v[86:89], v[26:29]
	v_mfma_f32_16x16x32_bf16 v[26:29], v[18:21], v[82:85], v[172:175]
	v_mfma_f32_16x16x32_bf16 v[42:45], v[22:25], v[86:89], v[26:29]
	v_mfma_f32_16x16x32_bf16 v[26:29], v[10:13], v[94:97], v[176:179]
	v_mfma_f32_16x16x32_bf16 v[2:5], v[10:13], v[232:235], v[2:5]
	v_mfma_f32_16x16x32_bf16 v[30:33], v[14:17], v[228:231], v[26:29]
	v_mfma_f32_16x16x32_bf16 v[26:29], v[18:21], v[94:97], v[180:183]
	v_mfma_f32_16x16x32_bf16 v[14:17], v[14:17], v[236:239], v[2:5]
	v_mfma_f32_16x16x32_bf16 v[2:5], v[18:21], v[232:235], v[6:9]
	v_mfma_f32_16x16x32_bf16 v[26:29], v[22:25], v[228:231], v[26:29]
	v_mfma_f32_16x16x32_bf16 v[10:13], v[22:25], v[236:239], v[2:5]
	v_mfma_f32_16x16x32_bf16 v[2:5], v[212:215], v[34:37], v[184:187]
	v_mfma_f32_16x16x32_bf16 v[54:57], v[216:219], v[38:41], v[2:5]
	v_mfma_f32_16x16x32_bf16 v[2:5], v[220:223], v[34:37], v[102:105]
	v_mfma_f32_16x16x32_bf16 v[50:53], v[224:227], v[38:41], v[2:5]
	v_mfma_f32_16x16x32_bf16 v[2:5], v[212:215], v[82:85], v[188:191]
	v_mfma_f32_16x16x32_bf16 v[38:41], v[216:219], v[86:89], v[2:5]
	v_mfma_f32_16x16x32_bf16 v[2:5], v[220:223], v[82:85], v[192:195]
	v_mfma_f32_16x16x32_bf16 v[34:37], v[224:227], v[86:89], v[2:5]
	v_mfma_f32_16x16x32_bf16 v[2:5], v[212:215], v[94:97], v[196:199]
	v_mfma_f32_16x16x32_bf16 v[22:25], v[216:219], v[228:231], v[2:5]
	v_mfma_f32_16x16x32_bf16 v[2:5], v[220:223], v[94:97], v[200:203]
	v_mfma_f32_16x16x32_bf16 v[18:21], v[224:227], v[228:231], v[2:5]
	s_barrier
	v_mfma_f32_16x16x32_bf16 v[2:5], v[212:215], v[232:235], v[204:207]
	v_mfma_f32_16x16x32_bf16 v[6:9], v[216:219], v[236:239], v[2:5]
	v_mfma_f32_16x16x32_bf16 v[2:5], v[220:223], v[232:235], v[208:211]
	v_mfma_f32_16x16x32_bf16 v[2:5], v[224:227], v[236:239], v[2:5]
	s_add_u32 s46, s46, 0x160180
	s_addc_u32 s47, s47, 0
	s_add_u32 s57, s58, 0x200
	s_addc_u32 s58, s59, 0
	s_mov_b32 s59, 0
.LBB0_2965:
	ds_read_b128 v[82:85], v1
	ds_read_b128 v[86:89], v1 offset:1024
	ds_read_b128 v[94:97], v1 offset:2048
	ds_read_b128 v[102:105], v1 offset:3072
	ds_read_b128 v[146:149], v168
	ds_read_b128 v[160:163], v168 offset:1024
	ds_read_b128 v[164:167], v168 offset:2048
	ds_read_b128 v[172:175], v168 offset:3072
	s_add_u32 s0, s46, 0xffea0080
	s_addc_u32 s1, s47, -1
	s_cmpk_eq_i32 s59, 0x54
	s_cselect_b32 s1, s11, s1
	s_cselect_b32 s0, s10, s0
	s_cselect_b32 s65, s45, s58
	s_cselect_b32 s64, s44, s57
	s_mov_b32 m0, s81
	v_lshl_add_u64 v[208:209], s[46:47], 0, v[154:155]
	ds_read_b128 v[176:179], v169
	ds_read_b128 v[180:183], v169 offset:1024
	ds_read_b128 v[184:187], v169 offset:2048
	ds_read_b128 v[188:191], v169 offset:3072
	ds_read_b128 v[192:195], v169 offset:4096
	ds_read_b128 v[196:199], v169 offset:5120
	ds_read_b128 v[200:203], v169 offset:6144
	ds_read_b128 v[204:207], v169 offset:7168
	global_load_lds_dwordx4 v[208:209], off
	v_lshl_add_u64 v[208:209], v[208:209], 0, s[30:31]
	s_mov_b32 m0, s82
	s_nop 0
	global_load_lds_dwordx4 v[208:209], off
	s_waitcnt vmcnt(8)
	s_waitcnt lgkmcnt(0)
	s_barrier
	s_waitcnt lgkmcnt(0)
	v_mfma_f32_16x16x32_bf16 v[138:141], v[82:85], v[176:179], v[138:141]
	v_mfma_f32_16x16x32_bf16 v[134:137], v[94:97], v[176:179], v[134:137]
	v_mfma_f32_16x16x32_bf16 v[126:129], v[82:85], v[184:187], v[126:129]
	v_mfma_f32_16x16x32_bf16 v[122:125], v[94:97], v[184:187], v[122:125]
	v_mfma_f32_16x16x32_bf16 v[110:113], v[82:85], v[192:195], v[110:113]
	v_mfma_f32_16x16x32_bf16 v[106:109], v[94:97], v[192:195], v[106:109]
	v_mfma_f32_16x16x32_bf16 v[78:81], v[82:85], v[200:203], v[78:81]
	v_mfma_f32_16x16x32_bf16 v[74:77], v[94:97], v[200:203], v[74:77]
	v_mfma_f32_16x16x32_bf16 v[138:141], v[86:89], v[180:183], v[138:141]
	v_mfma_f32_16x16x32_bf16 v[134:137], v[102:105], v[180:183], v[134:137]
	v_mfma_f32_16x16x32_bf16 v[126:129], v[86:89], v[188:191], v[126:129]
	v_mfma_f32_16x16x32_bf16 v[122:125], v[102:105], v[188:191], v[122:125]
	v_mfma_f32_16x16x32_bf16 v[110:113], v[86:89], v[196:199], v[110:113]
	v_mfma_f32_16x16x32_bf16 v[106:109], v[102:105], v[196:199], v[106:109]
	v_mfma_f32_16x16x32_bf16 v[78:81], v[86:89], v[204:207], v[78:81]
	v_mfma_f32_16x16x32_bf16 v[74:77], v[102:105], v[204:207], v[74:77]
	v_mfma_f32_16x16x32_bf16 v[142:145], v[146:149], v[176:179], v[142:145]
	v_mfma_f32_16x16x32_bf16 v[130:133], v[164:167], v[176:179], v[130:133]
	v_mfma_f32_16x16x32_bf16 v[118:121], v[146:149], v[184:187], v[118:121]
	v_mfma_f32_16x16x32_bf16 v[114:117], v[164:167], v[184:187], v[114:117]
	v_mfma_f32_16x16x32_bf16 v[98:101], v[146:149], v[192:195], v[98:101]
	v_mfma_f32_16x16x32_bf16 v[90:93], v[164:167], v[192:195], v[90:93]
	v_mfma_f32_16x16x32_bf16 v[70:73], v[146:149], v[200:203], v[70:73]
	v_mfma_f32_16x16x32_bf16 v[66:69], v[164:167], v[200:203], v[66:69]
	v_mfma_f32_16x16x32_bf16 v[142:145], v[160:163], v[180:183], v[142:145]
	v_mfma_f32_16x16x32_bf16 v[130:133], v[172:175], v[180:183], v[130:133]
	v_mfma_f32_16x16x32_bf16 v[118:121], v[160:163], v[188:191], v[118:121]
	v_mfma_f32_16x16x32_bf16 v[114:117], v[172:175], v[188:191], v[114:117]
	s_barrier
	v_mfma_f32_16x16x32_bf16 v[98:101], v[160:163], v[196:199], v[98:101]
	v_mfma_f32_16x16x32_bf16 v[90:93], v[172:175], v[196:199], v[90:93]
	v_mfma_f32_16x16x32_bf16 v[70:73], v[160:163], v[204:207], v[70:73]
	v_mfma_f32_16x16x32_bf16 v[66:69], v[172:175], v[204:207], v[66:69]
	s_mov_b32 m0, s83
	v_lshl_add_u64 v[208:209], s[64:65], 0, v[152:153]
	ds_read_b128 v[176:179], v169 offset:16384
	ds_read_b128 v[180:183], v169 offset:17408
	ds_read_b128 v[184:187], v169 offset:18432
	ds_read_b128 v[188:191], v169 offset:19456
	ds_read_b128 v[192:195], v169 offset:20480
	ds_read_b128 v[196:199], v169 offset:21504
	ds_read_b128 v[200:203], v169 offset:22528
	ds_read_b128 v[204:207], v169 offset:23552
	global_load_lds_dwordx4 v[208:209], off
	v_lshl_add_u64 v[210:211], v[208:209], 0, s[30:31]
	s_mov_b32 m0, s84
	s_nop 0
	global_load_lds_dwordx4 v[210:211], off
	v_lshl_add_u64 v[210:211], v[208:209], 0, s[34:35]
	s_mov_b32 m0, s85
	s_nop 0
	global_load_lds_dwordx4 v[210:211], off
	v_lshl_add_u64 v[210:211], v[208:209], 0, s[36:37]
	s_mov_b32 m0, s87
	s_nop 0
	global_load_lds_dwordx4 v[210:211], off
	v_lshl_add_u64 v[210:211], s[0:1], 0, v[150:151]
	s_mov_b32 m0, s53
	v_lshl_add_u64 v[212:213], v[210:211], 0, s[30:31]
	global_load_lds_dwordx4 v[210:211], off
	s_mov_b32 m0, s54
	s_nop 0
	global_load_lds_dwordx4 v[212:213], off
	s_waitcnt vmcnt(8)
	s_waitcnt lgkmcnt(0)
	s_barrier
	s_waitcnt lgkmcnt(0)
	v_mfma_f32_16x16x32_bf16 v[62:65], v[82:85], v[176:179], v[62:65]
	v_mfma_f32_16x16x32_bf16 v[58:61], v[94:97], v[176:179], v[58:61]
	v_mfma_f32_16x16x32_bf16 v[46:49], v[82:85], v[184:187], v[46:49]
	v_mfma_f32_16x16x32_bf16 v[42:45], v[94:97], v[184:187], v[42:45]
	v_mfma_f32_16x16x32_bf16 v[30:33], v[82:85], v[192:195], v[30:33]
	v_mfma_f32_16x16x32_bf16 v[26:29], v[94:97], v[192:195], v[26:29]
	v_mfma_f32_16x16x32_bf16 v[14:17], v[82:85], v[200:203], v[14:17]
	v_mfma_f32_16x16x32_bf16 v[10:13], v[94:97], v[200:203], v[10:13]
	v_mfma_f32_16x16x32_bf16 v[62:65], v[86:89], v[180:183], v[62:65]
	v_mfma_f32_16x16x32_bf16 v[58:61], v[102:105], v[180:183], v[58:61]
	v_mfma_f32_16x16x32_bf16 v[46:49], v[86:89], v[188:191], v[46:49]
	v_mfma_f32_16x16x32_bf16 v[42:45], v[102:105], v[188:191], v[42:45]
	v_mfma_f32_16x16x32_bf16 v[30:33], v[86:89], v[196:199], v[30:33]
	v_mfma_f32_16x16x32_bf16 v[26:29], v[102:105], v[196:199], v[26:29]
	v_mfma_f32_16x16x32_bf16 v[14:17], v[86:89], v[204:207], v[14:17]
	v_mfma_f32_16x16x32_bf16 v[10:13], v[102:105], v[204:207], v[10:13]
	v_mfma_f32_16x16x32_bf16 v[54:57], v[146:149], v[176:179], v[54:57]
	v_mfma_f32_16x16x32_bf16 v[50:53], v[164:167], v[176:179], v[50:53]
	v_mfma_f32_16x16x32_bf16 v[38:41], v[146:149], v[184:187], v[38:41]
	v_mfma_f32_16x16x32_bf16 v[34:37], v[164:167], v[184:187], v[34:37]
	v_mfma_f32_16x16x32_bf16 v[22:25], v[146:149], v[192:195], v[22:25]
	v_mfma_f32_16x16x32_bf16 v[18:21], v[164:167], v[192:195], v[18:21]
	v_mfma_f32_16x16x32_bf16 v[6:9], v[146:149], v[200:203], v[6:9]
	v_mfma_f32_16x16x32_bf16 v[2:5], v[164:167], v[200:203], v[2:5]
	v_mfma_f32_16x16x32_bf16 v[54:57], v[160:163], v[180:183], v[54:57]
	v_mfma_f32_16x16x32_bf16 v[50:53], v[172:175], v[180:183], v[50:53]
	v_mfma_f32_16x16x32_bf16 v[38:41], v[160:163], v[188:191], v[38:41]
	v_mfma_f32_16x16x32_bf16 v[34:37], v[172:175], v[188:191], v[34:37]
	s_barrier
	v_mfma_f32_16x16x32_bf16 v[22:25], v[160:163], v[196:199], v[22:25]
	v_mfma_f32_16x16x32_bf16 v[18:21], v[172:175], v[196:199], v[18:21]
	v_mfma_f32_16x16x32_bf16 v[6:9], v[160:163], v[204:207], v[6:9]
	v_mfma_f32_16x16x32_bf16 v[2:5], v[172:175], v[204:207], v[2:5]
	ds_read_b128 v[82:85], v170
	ds_read_b128 v[86:89], v170 offset:1024
	ds_read_b128 v[94:97], v170 offset:2048
	ds_read_b128 v[102:105], v170 offset:3072
	ds_read_b128 v[146:149], v171
	ds_read_b128 v[160:163], v171 offset:1024
	ds_read_b128 v[164:167], v171 offset:2048
	ds_read_b128 v[172:175], v171 offset:3072
	s_mov_b32 m0, s55
	v_lshl_add_u64 v[212:213], v[210:211], 0, s[34:35]
	ds_read_b128 v[176:179], v169 offset:32768
	ds_read_b128 v[180:183], v169 offset:33792
	ds_read_b128 v[184:187], v169 offset:34816
	ds_read_b128 v[188:191], v169 offset:35840
	ds_read_b128 v[192:195], v169 offset:36864
	ds_read_b128 v[196:199], v169 offset:37888
	ds_read_b128 v[200:203], v169 offset:38912
	ds_read_b128 v[204:207], v169 offset:39936
	global_load_lds_dwordx4 v[212:213], off
	v_lshl_add_u64 v[212:213], v[210:211], 0, s[36:37]
	s_mov_b32 m0, s62
	s_nop 0
	global_load_lds_dwordx4 v[212:213], off
	s_waitcnt vmcnt(8)
	s_waitcnt lgkmcnt(0)
	s_barrier
	s_waitcnt lgkmcnt(0)
	v_mfma_f32_16x16x32_bf16 v[138:141], v[82:85], v[176:179], v[138:141]
	v_mfma_f32_16x16x32_bf16 v[134:137], v[94:97], v[176:179], v[134:137]
	v_mfma_f32_16x16x32_bf16 v[126:129], v[82:85], v[184:187], v[126:129]
	v_mfma_f32_16x16x32_bf16 v[122:125], v[94:97], v[184:187], v[122:125]
	v_mfma_f32_16x16x32_bf16 v[110:113], v[82:85], v[192:195], v[110:113]
	v_mfma_f32_16x16x32_bf16 v[106:109], v[94:97], v[192:195], v[106:109]
	v_mfma_f32_16x16x32_bf16 v[78:81], v[82:85], v[200:203], v[78:81]
	v_mfma_f32_16x16x32_bf16 v[74:77], v[94:97], v[200:203], v[74:77]
	v_mfma_f32_16x16x32_bf16 v[138:141], v[86:89], v[180:183], v[138:141]
	v_mfma_f32_16x16x32_bf16 v[134:137], v[102:105], v[180:183], v[134:137]
	v_mfma_f32_16x16x32_bf16 v[126:129], v[86:89], v[188:191], v[126:129]
	v_mfma_f32_16x16x32_bf16 v[122:125], v[102:105], v[188:191], v[122:125]
	v_mfma_f32_16x16x32_bf16 v[110:113], v[86:89], v[196:199], v[110:113]
	v_mfma_f32_16x16x32_bf16 v[106:109], v[102:105], v[196:199], v[106:109]
	v_mfma_f32_16x16x32_bf16 v[78:81], v[86:89], v[204:207], v[78:81]
	v_mfma_f32_16x16x32_bf16 v[74:77], v[102:105], v[204:207], v[74:77]
	v_mfma_f32_16x16x32_bf16 v[142:145], v[146:149], v[176:179], v[142:145]
	v_mfma_f32_16x16x32_bf16 v[130:133], v[164:167], v[176:179], v[130:133]
	v_mfma_f32_16x16x32_bf16 v[118:121], v[146:149], v[184:187], v[118:121]
	v_mfma_f32_16x16x32_bf16 v[114:117], v[164:167], v[184:187], v[114:117]
	v_mfma_f32_16x16x32_bf16 v[98:101], v[146:149], v[192:195], v[98:101]
	v_mfma_f32_16x16x32_bf16 v[90:93], v[164:167], v[192:195], v[90:93]
	v_mfma_f32_16x16x32_bf16 v[70:73], v[146:149], v[200:203], v[70:73]
	v_mfma_f32_16x16x32_bf16 v[66:69], v[164:167], v[200:203], v[66:69]
	v_mfma_f32_16x16x32_bf16 v[142:145], v[160:163], v[180:183], v[142:145]
	v_mfma_f32_16x16x32_bf16 v[130:133], v[172:175], v[180:183], v[130:133]
	v_mfma_f32_16x16x32_bf16 v[118:121], v[160:163], v[188:191], v[118:121]
	v_mfma_f32_16x16x32_bf16 v[114:117], v[172:175], v[188:191], v[114:117]
	s_barrier
	v_mfma_f32_16x16x32_bf16 v[98:101], v[160:163], v[196:199], v[98:101]
	v_mfma_f32_16x16x32_bf16 v[90:93], v[172:175], v[196:199], v[90:93]
	v_mfma_f32_16x16x32_bf16 v[70:73], v[160:163], v[204:207], v[70:73]
	v_mfma_f32_16x16x32_bf16 v[66:69], v[172:175], v[204:207], v[66:69]
	s_mov_b32 m0, s50
	v_lshl_add_u64 v[212:213], v[208:209], 0, s[38:39]
	ds_read_b128 v[176:179], v169 offset:49152
	ds_read_b128 v[180:183], v169 offset:50176
	ds_read_b128 v[184:187], v169 offset:51200
	ds_read_b128 v[188:191], v169 offset:52224
	ds_read_b128 v[192:195], v169 offset:53248
	ds_read_b128 v[196:199], v169 offset:54272
	ds_read_b128 v[200:203], v169 offset:55296
	ds_read_b128 v[204:207], v169 offset:56320
	global_load_lds_dwordx4 v[212:213], off
	v_lshl_add_u64 v[212:213], v[208:209], 0, s[40:41]
	s_mov_b32 m0, s51
	s_nop 0
	global_load_lds_dwordx4 v[212:213], off
	v_lshl_add_u64 v[212:213], v[208:209], 0, s[14:15]
	s_mov_b32 m0, s33
	v_lshl_add_u64 v[208:209], v[208:209], 0, s[16:17]
	global_load_lds_dwordx4 v[212:213], off
	s_mov_b32 m0, s56
	s_nop 0
	global_load_lds_dwordx4 v[208:209], off
	v_lshl_add_u64 v[208:209], v[210:211], 0, s[38:39]
	s_mov_b32 m0, s63
	s_nop 0
	global_load_lds_dwordx4 v[208:209], off
	v_lshl_add_u64 v[208:209], v[210:211], 0, s[40:41]
	s_mov_b32 m0, s66
	s_nop 0
	global_load_lds_dwordx4 v[208:209], off
	s_waitcnt vmcnt(8)
	s_waitcnt lgkmcnt(0)
	s_barrier
	s_waitcnt lgkmcnt(0)
	v_mfma_f32_16x16x32_bf16 v[62:65], v[82:85], v[176:179], v[62:65]
	v_mfma_f32_16x16x32_bf16 v[58:61], v[94:97], v[176:179], v[58:61]
	v_mfma_f32_16x16x32_bf16 v[46:49], v[82:85], v[184:187], v[46:49]
	v_mfma_f32_16x16x32_bf16 v[42:45], v[94:97], v[184:187], v[42:45]
	v_mfma_f32_16x16x32_bf16 v[30:33], v[82:85], v[192:195], v[30:33]
	v_mfma_f32_16x16x32_bf16 v[26:29], v[94:97], v[192:195], v[26:29]
	v_mfma_f32_16x16x32_bf16 v[14:17], v[82:85], v[200:203], v[14:17]
	v_mfma_f32_16x16x32_bf16 v[10:13], v[94:97], v[200:203], v[10:13]
	v_mfma_f32_16x16x32_bf16 v[62:65], v[86:89], v[180:183], v[62:65]
	v_mfma_f32_16x16x32_bf16 v[58:61], v[102:105], v[180:183], v[58:61]
	v_mfma_f32_16x16x32_bf16 v[46:49], v[86:89], v[188:191], v[46:49]
	v_mfma_f32_16x16x32_bf16 v[42:45], v[102:105], v[188:191], v[42:45]
	v_mfma_f32_16x16x32_bf16 v[30:33], v[86:89], v[196:199], v[30:33]
	v_mfma_f32_16x16x32_bf16 v[26:29], v[102:105], v[196:199], v[26:29]
	v_mfma_f32_16x16x32_bf16 v[14:17], v[86:89], v[204:207], v[14:17]
	v_mfma_f32_16x16x32_bf16 v[10:13], v[102:105], v[204:207], v[10:13]
	v_mfma_f32_16x16x32_bf16 v[54:57], v[146:149], v[176:179], v[54:57]
	v_mfma_f32_16x16x32_bf16 v[50:53], v[164:167], v[176:179], v[50:53]
	v_mfma_f32_16x16x32_bf16 v[38:41], v[146:149], v[184:187], v[38:41]
	v_mfma_f32_16x16x32_bf16 v[34:37], v[164:167], v[184:187], v[34:37]
	v_mfma_f32_16x16x32_bf16 v[22:25], v[146:149], v[192:195], v[22:25]
	v_mfma_f32_16x16x32_bf16 v[18:21], v[164:167], v[192:195], v[18:21]
	v_mfma_f32_16x16x32_bf16 v[6:9], v[146:149], v[200:203], v[6:9]
	v_mfma_f32_16x16x32_bf16 v[2:5], v[164:167], v[200:203], v[2:5]
	v_mfma_f32_16x16x32_bf16 v[54:57], v[160:163], v[180:183], v[54:57]
	v_mfma_f32_16x16x32_bf16 v[50:53], v[172:175], v[180:183], v[50:53]
	v_mfma_f32_16x16x32_bf16 v[38:41], v[160:163], v[188:191], v[38:41]
	v_mfma_f32_16x16x32_bf16 v[34:37], v[172:175], v[188:191], v[34:37]
	s_barrier
	v_mfma_f32_16x16x32_bf16 v[22:25], v[160:163], v[196:199], v[22:25]
	v_mfma_f32_16x16x32_bf16 v[18:21], v[172:175], v[196:199], v[18:21]
	v_mfma_f32_16x16x32_bf16 v[6:9], v[160:163], v[204:207], v[6:9]
	v_mfma_f32_16x16x32_bf16 v[2:5], v[172:175], v[204:207], v[2:5]
	s_add_i32 s59, s59, 2
	s_add_u32 s46, s46, 0x100
	s_addc_u32 s47, s47, 0
	s_add_u32 s57, s57, 0x100
	s_addc_u32 s58, s58, 0
	s_cmpk_gt_u32 s59, 0x55
	s_cbranch_scc0 .LBB0_2965
	s_and_b64 vcc, exec, s[12:13]
	s_cbranch_vccz .LBB0_2968
	s_barrier
